# K-loop back-edge rotation: loop-back branch taken before the loop-end barrier (12 of 14 GEMM loops), exit path keeps its own barrier
# speedup vs baseline: 1.0064x; 1.0046x over previous
; template <class Epi>
; __device__ __forceinline__ void gemm_phase(LAS unsigned char* lds, const bf16_t* A, int lda, const bf16_t* Bt, int ldb, int M, int N, int K, int asel, const Epi& E, const int fixed_round = -1) {
;     ...
;         const bool has_next = (fixed_round < 0) && S.next(ui + 1, nxt);
;         const char* nA = has_next ? PG8_ABASE(nxt) : cA; const char* nB = has_next ? (const char*)Bt + (size_t)nxt.pn * tstepB : cB;
;     ...
; #pragma unroll
;         for (int a = 0; a < 2; ++a)
; #pragma unroll
;             for (int b = 0; b < 2; ++b)
; #pragma unroll
;                 for (int m = 0; m < 4; ++m)
; #pragma unroll
;                     for (int n = 0; n < 2; ++n) acc[a][b][m][n] = (f32x4){0.f, 0.f, 0.f, 0.f};
;         cur = nxt; cA = nA; cB = nB; ++ui;
.LBB0_198:
	s_ashr_i32 s21, s20, 31
	v_cmp_lt_i64_e32 vcc, s[22:23], v[144:145]
	s_lshl_b64 s[22:23], s[20:21], 20
	s_add_u32 s22, s72, s22
	s_addc_u32 s23, s73, s23
	s_and_b64 s[24:25], vcc, exec
	s_cselect_b32 s4, s23, s29
	s_cselect_b32 s21, s22, s28
	s_ashr_i32 s19, s18, 31
	s_lshl_b64 s[24:25], s[18:19], 20
	s_add_u32 s24, s36, s24
	s_addc_u32 s25, s37, s25
	s_and_b64 s[34:35], vcc, exec
	s_cselect_b32 s19, s25, s31
	s_cselect_b32 s55, s24, s30
	s_add_u32 s28, s28, 0x80080
	s_addc_u32 s29, s29, 0
	s_add_u32 s56, s30, 0x100
	v_mov_b32_e32 v0, 0
	s_addc_u32 s57, s31, 0
	s_mov_b32 s58, -2
	v_mov_b32_e32 v1, v0
	v_mov_b32_e32 v2, v0
	v_mov_b32_e32 v3, v0
	v_mov_b32_e32 v4, v0
	v_mov_b32_e32 v5, v0
	v_mov_b32_e32 v6, v0
	v_mov_b32_e32 v7, v0
	v_mov_b32_e32 v8, v0
	v_mov_b32_e32 v9, v0
	v_mov_b32_e32 v10, v0
	v_mov_b32_e32 v11, v0
	v_mov_b32_e32 v16, v0
	v_mov_b32_e32 v17, v0
	v_mov_b32_e32 v18, v0
	v_mov_b32_e32 v19, v0
	v_mov_b32_e32 v24, v0
	v_mov_b32_e32 v25, v0
	v_mov_b32_e32 v26, v0
	v_mov_b32_e32 v27, v0
	v_mov_b32_e32 v32, v0
	v_mov_b32_e32 v33, v0
	v_mov_b32_e32 v34, v0
	v_mov_b32_e32 v35, v0
	v_mov_b32_e32 v40, v0
	v_mov_b32_e32 v41, v0
	v_mov_b32_e32 v42, v0
	v_mov_b32_e32 v43, v0
	v_mov_b32_e32 v48, v0
	v_mov_b32_e32 v49, v0
	v_mov_b32_e32 v50, v0
	v_mov_b32_e32 v51, v0
	v_mov_b32_e32 v12, v0
	v_mov_b32_e32 v13, v0
	v_mov_b32_e32 v14, v0
	v_mov_b32_e32 v15, v0
	v_mov_b32_e32 v20, v0
	v_mov_b32_e32 v21, v0
	v_mov_b32_e32 v22, v0
	v_mov_b32_e32 v23, v0
	v_mov_b32_e32 v28, v0
	v_mov_b32_e32 v29, v0
	v_mov_b32_e32 v30, v0
	v_mov_b32_e32 v31, v0
	v_mov_b32_e32 v36, v0
	v_mov_b32_e32 v37, v0
	v_mov_b32_e32 v38, v0
	v_mov_b32_e32 v39, v0
	v_mov_b32_e32 v44, v0
	v_mov_b32_e32 v45, v0
	v_mov_b32_e32 v46, v0
	v_mov_b32_e32 v47, v0
	v_mov_b32_e32 v52, v0
	v_mov_b32_e32 v53, v0
	v_mov_b32_e32 v54, v0
	v_mov_b32_e32 v55, v0
	v_mov_b32_e32 v56, v0
	v_mov_b32_e32 v57, v0
	v_mov_b32_e32 v58, v0
	v_mov_b32_e32 v59, v0
	v_mov_b32_e32 v60, v0
	v_mov_b32_e32 v61, v0
	v_mov_b32_e32 v62, v0
	v_mov_b32_e32 v63, v0
	v_mov_b32_e32 v64, v0
	v_mov_b32_e32 v65, v0
	v_mov_b32_e32 v66, v0
	v_mov_b32_e32 v67, v0
	v_mov_b32_e32 v68, v0
	v_mov_b32_e32 v69, v0
	v_mov_b32_e32 v70, v0
	v_mov_b32_e32 v71, v0
	v_mov_b32_e32 v72, v0
	v_mov_b32_e32 v73, v0
	v_mov_b32_e32 v74, v0
	v_mov_b32_e32 v75, v0
	v_mov_b32_e32 v80, v0
	v_mov_b32_e32 v81, v0
	v_mov_b32_e32 v82, v0
	v_mov_b32_e32 v83, v0
	v_mov_b32_e32 v88, v0
	v_mov_b32_e32 v89, v0
	v_mov_b32_e32 v90, v0
	v_mov_b32_e32 v91, v0
	v_mov_b32_e32 v96, v0
	v_mov_b32_e32 v97, v0
	v_mov_b32_e32 v98, v0
	v_mov_b32_e32 v99, v0
	v_mov_b32_e32 v104, v0
	v_mov_b32_e32 v105, v0
	v_mov_b32_e32 v106, v0
	v_mov_b32_e32 v107, v0
	v_mov_b32_e32 v116, v0
	v_mov_b32_e32 v117, v0
	v_mov_b32_e32 v118, v0
	v_mov_b32_e32 v119, v0
	v_mov_b32_e32 v76, v0
	v_mov_b32_e32 v77, v0
	v_mov_b32_e32 v78, v0
	v_mov_b32_e32 v79, v0
	v_mov_b32_e32 v84, v0
	v_mov_b32_e32 v85, v0
	v_mov_b32_e32 v86, v0
	v_mov_b32_e32 v87, v0
	v_mov_b32_e32 v92, v0
	v_mov_b32_e32 v93, v0
	v_mov_b32_e32 v94, v0
	v_mov_b32_e32 v95, v0
	v_mov_b32_e32 v100, v0
	v_mov_b32_e32 v101, v0
	v_mov_b32_e32 v102, v0
	v_mov_b32_e32 v103, v0
	v_mov_b32_e32 v108, v0
	v_mov_b32_e32 v109, v0
	v_mov_b32_e32 v110, v0
	v_mov_b32_e32 v111, v0
	v_mov_b32_e32 v112, v0
	v_mov_b32_e32 v113, v0
	v_mov_b32_e32 v114, v0
	v_mov_b32_e32 v115, v0
	v_mov_b32_e32 v120, v0
	v_mov_b32_e32 v121, v0
	v_mov_b32_e32 v122, v0
	v_mov_b32_e32 v123, v0
	v_mov_b32_e32 v124, v0
	v_mov_b32_e32 v125, v0
	v_mov_b32_e32 v126, v0
	v_mov_b32_e32 v127, v0
	s_branch .LBB0_199

; #define PG8_STAGE(bufoff, gbase, voff) do { _Pragma("unroll") for (int _i = 0; _i < 2; ++_i) \
;         __builtin_amdgcn_global_load_lds((const unsigned*)((const char*)(gbase) + (voff)[_i]), (LAS unsigned*)(lds + (bufoff) + ldsw + _i * 8192), 16, 0, 0); } while (0)
; #define PG8_LDA(dst, b, h) do { _Pragma("unroll") for (int m = 0; m < 4; ++m) _Pragma("unroll") for (int k = 0; k < 2; ++k) dst[m][k] = *(const LAS bf16x8*)(lds + PG8_SA(b, h) + aoff + m * 2048 + k * 1024); } while (0)
; #define PG8_LDB(dst, b, h) do { _Pragma("unroll") for (int n = 0; n < 2; ++n) _Pragma("unroll") for (int k = 0; k < 2; ++k) dst[n][k] = *(const LAS bf16x8*)(lds + PG8_SB(b, h) + boff + n * 2048 + k * 1024); } while (0)
; #define PG8_WAIT_V(n) asm volatile("s_waitcnt vmcnt(" #n ")" ::: "memory")
; #define PG8_WAIT_L(n) asm volatile("s_waitcnt lgkmcnt(" #n ")" ::: "memory")
; #define PG8_BAR __builtin_amdgcn_s_barrier()
; #define PG8_SCHED __builtin_amdgcn_sched_barrier(0)
; template <class Epi>
; __device__ __forceinline__ void gemm_phase(LAS unsigned char* lds, const bf16_t* A, int lda, const bf16_t* Bt, int ldb, int M, int N, int K, int asel, const Epi& E, const int fixed_round = -1) {
;     ...
;         for (int t = 0; t < nt; t += 2) {
;             const bool last = (t == nt - 2);
;             const char* a1 = cA + (size_t)(t + 1) * kstep;
;             const char* a2 = last ? nA : cA + (size_t)(t + 2) * kstep; const char* b2 = last ? nB : cB + (size_t)(t + 2) * kstep;
;             const char* a3 = a2 + kstep; const char* b3 = b2 + kstep;
;             PG8_LDB(B0, 0, 0); PG8_SCHED; PG8_LDA(At, 0, 0); PG8_STAGE(PG8_SA(1, 1), a1 + hstepA, voffA);
;             PG8_WAIT_L(8); PG8_BAR; PG8_WAIT_L(0); PG8_MMA(0, 0, At, B0); PG8_BAR; PG8_SCHED;
;             PG8_LDB(B1, 0, 1); PG8_STAGE(PG8_SB(0, 0), b2, voffB);
;             PG8_BAR; PG8_WAIT_L(0); PG8_MMA(0, 1, At, B1); PG8_BAR;
;             PG8_LDA(At, 0, 1); PG8_STAGE(PG8_SA(0, 0), a2, voffA);
;             PG8_BAR; PG8_WAIT_L(0); PG8_MMA(1, 0, At, B0); PG8_BAR; PG8_SCHED;
;             PG8_STAGE(PG8_SB(0, 1), b2 + hstepB, voffB);
;             PG8_WAIT_V(6); PG8_BAR; PG8_MMA(1, 1, At, B1); PG8_BAR;
.LBB0_199:
	ds_read_b128 v[148:151], v161
	ds_read_b128 v[152:155], v161 offset:1024
	ds_read_b128 v[156:159], v161 offset:2048
	ds_read_b128 v[166:169], v161 offset:3072
	s_add_u32 s30, s28, 0xfff80080
	s_addc_u32 s31, s29, -1
	s_cmp_eq_u32 s58, 28
	s_cselect_b32 s35, s4, s31
	s_cselect_b32 s34, s21, s30
	s_cselect_b32 s31, s19, s57
	s_cselect_b32 s30, s55, s56
	s_add_i32 m0, s39, 0xc000
	ds_read_b128 v[170:173], v162
	ds_read_b128 v[174:177], v162 offset:1024
	ds_read_b128 v[178:181], v162 offset:2048
	ds_read_b128 v[182:185], v162 offset:3072
	ds_read_b128 v[186:189], v162 offset:4096
	ds_read_b128 v[190:193], v162 offset:5120
	ds_read_b128 v[196:199], v162 offset:6144
	ds_read_b128 v[202:205], v162 offset:7168
	global_load_lds_dwordx4 v140, s[28:29]
	s_add_i32 m0, s39, 0xe000
	s_nop 0
	global_load_lds_dwordx4 v142, s[28:29]
	s_waitcnt lgkmcnt(8)
	s_barrier
	s_waitcnt lgkmcnt(0)
	s_setprio 1
	s_waitcnt lgkmcnt(0)
	v_mfma_f32_16x16x32_bf16 v[124:127], v[148:151], v[170:173], v[124:127]
	v_mfma_f32_16x16x32_bf16 v[120:123], v[156:159], v[170:173], v[120:123]
	v_mfma_f32_16x16x32_bf16 v[112:115], v[148:151], v[178:181], v[112:115]
	v_mfma_f32_16x16x32_bf16 v[108:111], v[156:159], v[178:181], v[108:111]
	v_mfma_f32_16x16x32_bf16 v[100:103], v[148:151], v[186:189], v[100:103]
	v_mfma_f32_16x16x32_bf16 v[92:95], v[156:159], v[186:189], v[92:95]
	v_mfma_f32_16x16x32_bf16 v[84:87], v[148:151], v[196:199], v[84:87]
	v_mfma_f32_16x16x32_bf16 v[76:79], v[156:159], v[196:199], v[76:79]
	v_mfma_f32_16x16x32_bf16 v[124:127], v[152:155], v[174:177], v[124:127]
	v_mfma_f32_16x16x32_bf16 v[120:123], v[166:169], v[174:177], v[120:123]
	v_mfma_f32_16x16x32_bf16 v[112:115], v[152:155], v[182:185], v[112:115]
	v_mfma_f32_16x16x32_bf16 v[108:111], v[166:169], v[182:185], v[108:111]
	v_mfma_f32_16x16x32_bf16 v[100:103], v[152:155], v[190:193], v[100:103]
	v_mfma_f32_16x16x32_bf16 v[92:95], v[166:169], v[190:193], v[92:95]
	v_mfma_f32_16x16x32_bf16 v[84:87], v[152:155], v[202:205], v[84:87]
	v_mfma_f32_16x16x32_bf16 v[76:79], v[166:169], v[202:205], v[76:79]
	s_setprio 0
	s_barrier
	s_add_i32 s59, s46, s38
	s_add_u32 s98, s30, s6
	s_addc_u32 s99, s31, s7
	s_mov_b32 m0, s59
	ds_read_b128 v[206:209], v163
	ds_read_b128 v[210:213], v163 offset:1024
	ds_read_b128 v[214:217], v163 offset:2048
	ds_read_b128 v[218:221], v163 offset:3072
	global_load_lds_dwordx4 v130, s[30:31]
	s_add_i32 m0, s59, 0x2000
	s_nop 0
	global_load_lds_dwordx4 v134, s[30:31]
	s_barrier
	s_waitcnt lgkmcnt(0)
	s_setprio 1
	s_waitcnt lgkmcnt(0)
	v_mfma_f32_16x16x32_bf16 v[116:119], v[206:209], v[170:173], v[116:119]
	v_mfma_f32_16x16x32_bf16 v[104:107], v[214:217], v[170:173], v[104:107]
	v_mfma_f32_16x16x32_bf16 v[96:99], v[206:209], v[178:181], v[96:99]
	v_mfma_f32_16x16x32_bf16 v[88:91], v[214:217], v[178:181], v[88:91]
	v_mfma_f32_16x16x32_bf16 v[80:83], v[206:209], v[186:189], v[80:83]
	v_mfma_f32_16x16x32_bf16 v[72:75], v[214:217], v[186:189], v[72:75]
	v_mfma_f32_16x16x32_bf16 v[68:71], v[206:209], v[196:199], v[68:71]
	v_mfma_f32_16x16x32_bf16 v[64:67], v[214:217], v[196:199], v[64:67]
	v_mfma_f32_16x16x32_bf16 v[116:119], v[210:213], v[174:177], v[116:119]
	v_mfma_f32_16x16x32_bf16 v[104:107], v[218:221], v[174:177], v[104:107]
	v_mfma_f32_16x16x32_bf16 v[96:99], v[210:213], v[182:185], v[96:99]
	v_mfma_f32_16x16x32_bf16 v[88:91], v[218:221], v[182:185], v[88:91]
	v_mfma_f32_16x16x32_bf16 v[80:83], v[210:213], v[190:193], v[80:83]
	v_mfma_f32_16x16x32_bf16 v[72:75], v[218:221], v[190:193], v[72:75]
	v_mfma_f32_16x16x32_bf16 v[68:71], v[210:213], v[202:205], v[68:71]
	v_mfma_f32_16x16x32_bf16 v[64:67], v[218:221], v[202:205], v[64:67]
	s_setprio 0
	s_mov_b32 m0, s39
	s_add_u32 s100, s34, s6
	s_addc_u32 s101, s35, s7
	s_barrier
	ds_read_b128 v[170:173], v162 offset:16384
	ds_read_b128 v[174:177], v162 offset:17408
	ds_read_b128 v[178:181], v162 offset:18432
	ds_read_b128 v[182:185], v162 offset:19456
	ds_read_b128 v[186:189], v162 offset:20480
	ds_read_b128 v[190:193], v162 offset:21504
	ds_read_b128 v[196:199], v162 offset:22528
	ds_read_b128 v[202:205], v162 offset:23552
	global_load_lds_dwordx4 v128, s[34:35]
	s_mov_b32 m0, s40
	s_nop 0
	global_load_lds_dwordx4 v132, s[34:35]
	s_barrier
	s_waitcnt lgkmcnt(0)
	s_setprio 1
	s_waitcnt lgkmcnt(0)
	v_mfma_f32_16x16x32_bf16 v[60:63], v[148:151], v[170:173], v[60:63]
	v_mfma_f32_16x16x32_bf16 v[56:59], v[156:159], v[170:173], v[56:59]
	v_mfma_f32_16x16x32_bf16 v[52:55], v[148:151], v[178:181], v[52:55]
	v_mfma_f32_16x16x32_bf16 v[44:47], v[156:159], v[178:181], v[44:47]
	v_mfma_f32_16x16x32_bf16 v[36:39], v[148:151], v[186:189], v[36:39]
	v_mfma_f32_16x16x32_bf16 v[28:31], v[156:159], v[186:189], v[28:31]
	v_mfma_f32_16x16x32_bf16 v[20:23], v[148:151], v[196:199], v[20:23]
	v_mfma_f32_16x16x32_bf16 v[12:15], v[156:159], v[196:199], v[12:15]
	v_mfma_f32_16x16x32_bf16 v[60:63], v[152:155], v[174:177], v[60:63]
	v_mfma_f32_16x16x32_bf16 v[56:59], v[166:169], v[174:177], v[56:59]
	v_mfma_f32_16x16x32_bf16 v[52:55], v[152:155], v[182:185], v[52:55]
	v_mfma_f32_16x16x32_bf16 v[44:47], v[166:169], v[182:185], v[44:47]
	v_mfma_f32_16x16x32_bf16 v[36:39], v[152:155], v[190:193], v[36:39]
	v_mfma_f32_16x16x32_bf16 v[28:31], v[166:169], v[190:193], v[28:31]
	v_mfma_f32_16x16x32_bf16 v[20:23], v[152:155], v[202:205], v[20:23]
	v_mfma_f32_16x16x32_bf16 v[12:15], v[166:169], v[202:205], v[12:15]
	s_setprio 0
	s_barrier
	s_add_u32 s60, s30, 0x80000
	s_addc_u32 s61, s31, 0
	s_add_i32 s59, s47, s38
	s_mov_b32 m0, s59
	s_nop 0
	global_load_lds_dwordx4 v130, s[60:61]
	s_add_i32 m0, s59, 0x2000
	s_nop 0
	global_load_lds_dwordx4 v134, s[60:61]
	s_waitcnt vmcnt(6)
	s_barrier
; #define PG8_STAGE(bufoff, gbase, voff) do { _Pragma("unroll") for (int _i = 0; _i < 2; ++_i) \
;         __builtin_amdgcn_global_load_lds((const unsigned*)((const char*)(gbase) + (voff)[_i]), (LAS unsigned*)(lds + (bufoff) + ldsw + _i * 8192), 16, 0, 0); } while (0)
; #define PG8_LDA(dst, b, h) do { _Pragma("unroll") for (int m = 0; m < 4; ++m) _Pragma("unroll") for (int k = 0; k < 2; ++k) dst[m][k] = *(const LAS bf16x8*)(lds + PG8_SA(b, h) + aoff + m * 2048 + k * 1024); } while (0)
; #define PG8_LDB(dst, b, h) do { _Pragma("unroll") for (int n = 0; n < 2; ++n) _Pragma("unroll") for (int k = 0; k < 2; ++k) dst[n][k] = *(const LAS bf16x8*)(lds + PG8_SB(b, h) + boff + n * 2048 + k * 1024); } while (0)
; #define PG8_WAIT_V(n) asm volatile("s_waitcnt vmcnt(" #n ")" ::: "memory")
; #define PG8_WAIT_L(n) asm volatile("s_waitcnt lgkmcnt(" #n ")" ::: "memory")
; #define PG8_BAR __builtin_amdgcn_s_barrier()
; #define PG8_SCHED __builtin_amdgcn_sched_barrier(0)
; template <class Epi>
; __device__ __forceinline__ void gemm_phase(LAS unsigned char* lds, const bf16_t* A, int lda, const bf16_t* Bt, int ldb, int M, int N, int K, int asel, const Epi& E, const int fixed_round = -1) {
;     ...
;             PG8_WAIT_V(6); PG8_BAR; PG8_MMA(1, 1, At, B1); PG8_BAR;
;             PG8_LDB(B0, 1, 0); PG8_SCHED; PG8_LDA(At, 1, 0); PG8_STAGE(PG8_SA(0, 1), a2 + hstepA, voffA);
;             PG8_WAIT_L(8); PG8_BAR; PG8_WAIT_L(0); PG8_MMA(0, 0, At, B0); PG8_BAR; PG8_SCHED;
;             PG8_LDB(B1, 1, 1); PG8_STAGE(PG8_SB(1, 0), b3, voffB);
;             PG8_BAR; PG8_WAIT_L(0); PG8_MMA(0, 1, At, B1); PG8_BAR;
;             PG8_LDA(At, 1, 1); PG8_STAGE(PG8_SA(1, 0), a3, voffA);
;             PG8_BAR; PG8_WAIT_L(0); PG8_MMA(1, 0, At, B0); PG8_BAR; PG8_SCHED;
	s_setprio 1
	v_mfma_f32_16x16x32_bf16 v[48:51], v[206:209], v[170:173], v[48:51]
	v_mfma_f32_16x16x32_bf16 v[40:43], v[214:217], v[170:173], v[40:43]
	v_mfma_f32_16x16x32_bf16 v[32:35], v[206:209], v[178:181], v[32:35]
	v_mfma_f32_16x16x32_bf16 v[24:27], v[214:217], v[178:181], v[24:27]
	v_mfma_f32_16x16x32_bf16 v[16:19], v[206:209], v[186:189], v[16:19]
	v_mfma_f32_16x16x32_bf16 v[8:11], v[214:217], v[186:189], v[8:11]
	v_mfma_f32_16x16x32_bf16 v[4:7], v[206:209], v[196:199], v[4:7]
	v_mfma_f32_16x16x32_bf16 v[0:3], v[214:217], v[196:199], v[0:3]
	v_mfma_f32_16x16x32_bf16 v[48:51], v[210:213], v[174:177], v[48:51]
	v_mfma_f32_16x16x32_bf16 v[40:43], v[218:221], v[174:177], v[40:43]
	v_mfma_f32_16x16x32_bf16 v[32:35], v[210:213], v[182:185], v[32:35]
	v_mfma_f32_16x16x32_bf16 v[24:27], v[218:221], v[182:185], v[24:27]
	v_mfma_f32_16x16x32_bf16 v[16:19], v[210:213], v[190:193], v[16:19]
	v_mfma_f32_16x16x32_bf16 v[8:11], v[218:221], v[190:193], v[8:11]
	v_mfma_f32_16x16x32_bf16 v[4:7], v[210:213], v[202:205], v[4:7]
	v_mfma_f32_16x16x32_bf16 v[0:3], v[218:221], v[202:205], v[0:3]
	s_setprio 0
	s_add_i32 s59, 0, 0x18000
	v_add_u32_e32 v136, s59, v160
	s_barrier
	ds_read_b128 v[148:151], v136
	ds_read_b128 v[152:155], v136 offset:1024
	ds_read_b128 v[156:159], v136 offset:2048
	ds_read_b128 v[166:169], v136 offset:3072
	s_add_u32 s34, s34, 0x80000
	s_addc_u32 s35, s35, 0
	s_mov_b32 m0, s41
	ds_read_b128 v[170:173], v162 offset:32768
	ds_read_b128 v[174:177], v162 offset:33792
	ds_read_b128 v[178:181], v162 offset:34816
	ds_read_b128 v[182:185], v162 offset:35840
	ds_read_b128 v[186:189], v162 offset:36864
	ds_read_b128 v[190:193], v162 offset:37888
	ds_read_b128 v[196:199], v162 offset:38912
	ds_read_b128 v[202:205], v162 offset:39936
	global_load_lds_dwordx4 v128, s[34:35]
	s_mov_b32 m0, s42
	s_nop 0
	global_load_lds_dwordx4 v132, s[34:35]
	s_waitcnt lgkmcnt(8)
	s_barrier
	s_waitcnt lgkmcnt(0)
	s_setprio 1
	s_waitcnt lgkmcnt(0)
	v_mfma_f32_16x16x32_bf16 v[124:127], v[148:151], v[170:173], v[124:127]
	v_mfma_f32_16x16x32_bf16 v[120:123], v[156:159], v[170:173], v[120:123]
	v_mfma_f32_16x16x32_bf16 v[112:115], v[148:151], v[178:181], v[112:115]
	v_mfma_f32_16x16x32_bf16 v[108:111], v[156:159], v[178:181], v[108:111]
	v_mfma_f32_16x16x32_bf16 v[100:103], v[148:151], v[186:189], v[100:103]
	v_mfma_f32_16x16x32_bf16 v[92:95], v[156:159], v[186:189], v[92:95]
	v_mfma_f32_16x16x32_bf16 v[84:87], v[148:151], v[196:199], v[84:87]
	v_mfma_f32_16x16x32_bf16 v[76:79], v[156:159], v[196:199], v[76:79]
	v_mfma_f32_16x16x32_bf16 v[124:127], v[152:155], v[174:177], v[124:127]
	v_mfma_f32_16x16x32_bf16 v[120:123], v[166:169], v[174:177], v[120:123]
	v_mfma_f32_16x16x32_bf16 v[112:115], v[152:155], v[182:185], v[112:115]
	v_mfma_f32_16x16x32_bf16 v[108:111], v[166:169], v[182:185], v[108:111]
	v_mfma_f32_16x16x32_bf16 v[100:103], v[152:155], v[190:193], v[100:103]
	v_mfma_f32_16x16x32_bf16 v[92:95], v[166:169], v[190:193], v[92:95]
	v_mfma_f32_16x16x32_bf16 v[84:87], v[152:155], v[202:205], v[84:87]
	v_mfma_f32_16x16x32_bf16 v[76:79], v[166:169], v[202:205], v[76:79]
	s_setprio 0
	s_barrier
	s_add_i32 s34, 0, 0x1c000
	s_add_i32 s35, s59, s38
	v_add_u32_e32 v136, s34, v160
	s_mov_b32 m0, s35
	ds_read_b128 v[206:209], v136
	ds_read_b128 v[210:213], v136 offset:1024
	ds_read_b128 v[214:217], v136 offset:2048
	ds_read_b128 v[218:221], v136 offset:3072
	global_load_lds_dwordx4 v130, s[98:99]
	s_add_i32 m0, s35, 0x2000
	s_nop 0
	global_load_lds_dwordx4 v134, s[98:99]
	s_barrier
	s_waitcnt lgkmcnt(0)
	s_setprio 1
	s_waitcnt lgkmcnt(0)
	v_mfma_f32_16x16x32_bf16 v[116:119], v[206:209], v[170:173], v[116:119]
	v_mfma_f32_16x16x32_bf16 v[104:107], v[214:217], v[170:173], v[104:107]
	v_mfma_f32_16x16x32_bf16 v[96:99], v[206:209], v[178:181], v[96:99]
	v_mfma_f32_16x16x32_bf16 v[88:91], v[214:217], v[178:181], v[88:91]
	v_mfma_f32_16x16x32_bf16 v[80:83], v[206:209], v[186:189], v[80:83]
	v_mfma_f32_16x16x32_bf16 v[72:75], v[214:217], v[186:189], v[72:75]
	v_mfma_f32_16x16x32_bf16 v[68:71], v[206:209], v[196:199], v[68:71]
	v_mfma_f32_16x16x32_bf16 v[64:67], v[214:217], v[196:199], v[64:67]
	v_mfma_f32_16x16x32_bf16 v[116:119], v[210:213], v[174:177], v[116:119]
	v_mfma_f32_16x16x32_bf16 v[104:107], v[218:221], v[174:177], v[104:107]
	v_mfma_f32_16x16x32_bf16 v[96:99], v[210:213], v[182:185], v[96:99]
	v_mfma_f32_16x16x32_bf16 v[88:91], v[218:221], v[182:185], v[88:91]
	v_mfma_f32_16x16x32_bf16 v[80:83], v[210:213], v[190:193], v[80:83]
	v_mfma_f32_16x16x32_bf16 v[72:75], v[218:221], v[190:193], v[72:75]
	v_mfma_f32_16x16x32_bf16 v[68:71], v[210:213], v[202:205], v[68:71]
	v_mfma_f32_16x16x32_bf16 v[64:67], v[218:221], v[202:205], v[64:67]
	s_setprio 0
	s_mov_b32 m0, s43
	s_barrier
	ds_read_b128 v[170:173], v162 offset:49152
	ds_read_b128 v[174:177], v162 offset:50176
	ds_read_b128 v[178:181], v162 offset:51200
	ds_read_b128 v[182:185], v162 offset:52224
	ds_read_b128 v[186:189], v162 offset:53248
	ds_read_b128 v[190:193], v162 offset:54272
	ds_read_b128 v[196:199], v162 offset:55296
	ds_read_b128 v[202:205], v162 offset:56320
	global_load_lds_dwordx4 v128, s[100:101]
	s_mov_b32 m0, s44
	s_nop 0
	global_load_lds_dwordx4 v132, s[100:101]
	s_barrier
; __device__ __forceinline__ unsigned cvt_pk_bf16(float lo, float hi) { const bf16x2_t r = __builtin_convertvector((f32x2){lo, hi}, bf16x2_t); return __builtin_bit_cast(unsigned, r); }
; #define PG8_STAGE(bufoff, gbase, voff) do { _Pragma("unroll") for (int _i = 0; _i < 2; ++_i) \
;         __builtin_amdgcn_global_load_lds((const unsigned*)((const char*)(gbase) + (voff)[_i]), (LAS unsigned*)(lds + (bufoff) + ldsw + _i * 8192), 16, 0, 0); } while (0)
; #define PG8_WAIT_V(n) asm volatile("s_waitcnt vmcnt(" #n ")" ::: "memory")
; #define PG8_WAIT_L(n) asm volatile("s_waitcnt lgkmcnt(" #n ")" ::: "memory")
; #define PG8_BAR __builtin_amdgcn_s_barrier()
; #define PG8_SCHED __builtin_amdgcn_sched_barrier(0)
; template <class Epi>
; __device__ __forceinline__ void gemm_phase(LAS unsigned char* lds, const bf16_t* A, int lda, const bf16_t* Bt, int ldb, int M, int N, int K, int asel, const Epi& E, const int fixed_round = -1) {
;     ...
;             PG8_BAR; PG8_WAIT_L(0); PG8_MMA(1, 0, At, B0); PG8_BAR; PG8_SCHED;
;             PG8_STAGE(PG8_SB(1, 1), b3 + hstepB, voffB);
;             PG8_WAIT_V(6); PG8_BAR; PG8_MMA(1, 1, At, B1); PG8_BAR;
;     __device__ __forceinline__ void operator()(const AccT& acc, const Unit& u, int wr, int wc, int fr, int fq) const {
;     ...
;         if (pn < 8) {
;             bf16_t* base = pn < 4 ? Q : Kn; const int colt = (pn & 3) * BM; const float sc = pn < 4 ? 0.08838834764831845f : 1.0f;
; #pragma unroll
;             for (int ai = 0; ai < 2; ++ai)
; #pragma unroll
;                 for (int m = 0; m < 4; ++m) { bf16_t* rowp = base + (size_t)(row0 + ai * HALF + m * 16) * 1024 + colt + cl;
; #pragma unroll
;                     for (int bj = 0; bj < 2; ++bj) { const f32x4 v0 = acc[ai][bj][m][0] * sc, v1 = acc[ai][bj][m][1] * sc;
;                         u32x4 w; w.x = cvt_pk_bf16(v0[0], v0[1]); w.y = cvt_pk_bf16(v0[2], v0[3]); w.z = cvt_pk_bf16(v1[0], v1[1]); w.w = cvt_pk_bf16(v1[2], v1[3]);
;                         *(u32x4*)(rowp + bj * HALF) = w; } }
	s_waitcnt lgkmcnt(0)
	s_setprio 1
	s_waitcnt lgkmcnt(0)
	v_mfma_f32_16x16x32_bf16 v[60:63], v[148:151], v[170:173], v[60:63]
	v_mfma_f32_16x16x32_bf16 v[56:59], v[156:159], v[170:173], v[56:59]
	v_mfma_f32_16x16x32_bf16 v[52:55], v[148:151], v[178:181], v[52:55]
	v_mfma_f32_16x16x32_bf16 v[44:47], v[156:159], v[178:181], v[44:47]
	v_mfma_f32_16x16x32_bf16 v[36:39], v[148:151], v[186:189], v[36:39]
	v_mfma_f32_16x16x32_bf16 v[28:31], v[156:159], v[186:189], v[28:31]
	v_mfma_f32_16x16x32_bf16 v[20:23], v[148:151], v[196:199], v[20:23]
	v_mfma_f32_16x16x32_bf16 v[12:15], v[156:159], v[196:199], v[12:15]
	v_mfma_f32_16x16x32_bf16 v[60:63], v[152:155], v[174:177], v[60:63]
	v_mfma_f32_16x16x32_bf16 v[56:59], v[166:169], v[174:177], v[56:59]
	v_mfma_f32_16x16x32_bf16 v[52:55], v[152:155], v[182:185], v[52:55]
	v_mfma_f32_16x16x32_bf16 v[44:47], v[166:169], v[182:185], v[44:47]
	v_mfma_f32_16x16x32_bf16 v[36:39], v[152:155], v[190:193], v[36:39]
	v_mfma_f32_16x16x32_bf16 v[28:31], v[166:169], v[190:193], v[28:31]
	v_mfma_f32_16x16x32_bf16 v[20:23], v[152:155], v[202:205], v[20:23]
	v_mfma_f32_16x16x32_bf16 v[12:15], v[166:169], v[202:205], v[12:15]
	s_setprio 0
	s_barrier
	s_add_u32 s30, s30, 0x80080
	s_addc_u32 s31, s31, 0
	s_add_i32 s34, s34, s38
	s_mov_b32 m0, s34
	s_nop 0
	global_load_lds_dwordx4 v130, s[30:31]
	s_add_i32 m0, s34, 0x2000
	s_nop 0
	global_load_lds_dwordx4 v134, s[30:31]
	s_waitcnt vmcnt(6)
	s_barrier
	s_setprio 1
	v_mfma_f32_16x16x32_bf16 v[48:51], v[206:209], v[170:173], v[48:51]
	v_mfma_f32_16x16x32_bf16 v[40:43], v[214:217], v[170:173], v[40:43]
	v_mfma_f32_16x16x32_bf16 v[32:35], v[206:209], v[178:181], v[32:35]
	v_mfma_f32_16x16x32_bf16 v[24:27], v[214:217], v[178:181], v[24:27]
	v_mfma_f32_16x16x32_bf16 v[16:19], v[206:209], v[186:189], v[16:19]
	v_mfma_f32_16x16x32_bf16 v[8:11], v[214:217], v[186:189], v[8:11]
	v_mfma_f32_16x16x32_bf16 v[4:7], v[206:209], v[196:199], v[4:7]
	v_mfma_f32_16x16x32_bf16 v[0:3], v[214:217], v[196:199], v[0:3]
	v_mfma_f32_16x16x32_bf16 v[48:51], v[210:213], v[174:177], v[48:51]
	v_mfma_f32_16x16x32_bf16 v[40:43], v[218:221], v[174:177], v[40:43]
	v_mfma_f32_16x16x32_bf16 v[32:35], v[210:213], v[182:185], v[32:35]
	v_mfma_f32_16x16x32_bf16 v[24:27], v[218:221], v[182:185], v[24:27]
	v_mfma_f32_16x16x32_bf16 v[16:19], v[210:213], v[190:193], v[16:19]
	v_mfma_f32_16x16x32_bf16 v[8:11], v[218:221], v[190:193], v[8:11]
	v_mfma_f32_16x16x32_bf16 v[4:7], v[210:213], v[202:205], v[4:7]
	v_mfma_f32_16x16x32_bf16 v[0:3], v[218:221], v[202:205], v[0:3]
	s_setprio 0
	s_add_i32 s58, s58, 2
	s_add_u32 s28, s28, 0x100
	s_addc_u32 s29, s29, 0
	s_add_u32 s56, s56, 0x100
	s_addc_u32 s57, s57, 0
	s_cmp_gt_u32 s58, 29
	s_cbranch_scc0 .Lrot_1
	s_barrier
	s_lshl_b32 s19, s26, 8
	v_add_u32_e32 v154, s19, v139
	s_cmp_lt_i32 s27, 8
	v_or_b32_e32 v152, 16, v154
	v_or_b32_e32 v150, 32, v154
	v_or_b32_e32 v148, 48, v154
	s_cselect_b64 s[28:29], -1, 0
	s_cmp_gt_i32 s27, 7
	v_ashrrev_i32_e32 v155, 31, v154
	v_lshlrev_b32_e32 v136, 1, v138
	v_ashrrev_i32_e32 v153, 31, v152
	v_ashrrev_i32_e32 v151, 31, v150
	v_ashrrev_i32_e32 v149, 31, v148
	s_cbranch_scc1 .LBB0_203
	s_cmp_lt_i32 s27, 4
	s_cselect_b64 vcc, -1, 0
	s_and_b64 s[30:31], vcc, exec
	s_cselect_b32 s4, s89, s81
	s_cselect_b32 s21, s88, s91
	s_lshl_b32 s30, s27, 9
	s_and_b32 s30, s30, 0x600
	s_add_u32 s30, s21, s30
	v_cndmask_b32_e32 v156, 1.0, v164, vcc
	s_addc_u32 s31, s4, 0
	v_lshl_add_u64 v[170:171], s[30:31], 0, v[136:137]
	v_lshlrev_b64 v[158:159], 11, v[154:155]
	v_pk_mul_f32 v[168:169], v[156:157], v[126:127] op_sel_hi:[0,1]
	v_pk_mul_f32 v[166:167], v[156:157], v[124:125] op_sel_hi:[0,1]
	v_pk_mul_f32 v[172:173], v[156:157], v[122:123] op_sel_hi:[0,1]
	v_pk_mul_f32 v[174:175], v[156:157], v[120:121] op_sel_hi:[0,1]
	v_lshl_add_u64 v[158:159], v[170:171], 0, v[158:159]
	v_cvt_pk_bf16_f32 v166, v166, v167
	v_cvt_pk_bf16_f32 v167, v168, v169
	v_cvt_pk_bf16_f32 v168, v174, v175
	v_cvt_pk_bf16_f32 v169, v172, v173
	global_store_dwordx4 v[158:159], v[166:169], off
	v_pk_mul_f32 v[172:173], v[156:157], v[106:107] op_sel_hi:[0,1]
	v_pk_mul_f32 v[174:175], v[156:157], v[104:105] op_sel_hi:[0,1]
	v_pk_mul_f32 v[168:169], v[156:157], v[118:119] op_sel_hi:[0,1]
	v_pk_mul_f32 v[166:167], v[156:157], v[116:117] op_sel_hi:[0,1]
	v_cvt_pk_bf16_f32 v166, v166, v167
	v_cvt_pk_bf16_f32 v167, v168, v169
	v_cvt_pk_bf16_f32 v168, v174, v175
	v_cvt_pk_bf16_f32 v169, v172, v173
	global_store_dwordx4 v[158:159], v[166:169], off offset:256
	v_pk_mul_f32 v[174:175], v[156:157], v[110:111] op_sel_hi:[0,1]
	v_pk_mul_f32 v[176:177], v[156:157], v[108:109] op_sel_hi:[0,1]
	v_lshlrev_b64 v[166:167], 11, v[152:153]
	v_lshl_add_u64 v[172:173], v[170:171], 0, v[166:167]
	v_pk_mul_f32 v[168:169], v[156:157], v[114:115] op_sel_hi:[0,1]
	v_pk_mul_f32 v[166:167], v[156:157], v[112:113] op_sel_hi:[0,1]
	v_cvt_pk_bf16_f32 v166, v166, v167
	v_cvt_pk_bf16_f32 v167, v168, v169
	v_cvt_pk_bf16_f32 v168, v176, v177
	v_cvt_pk_bf16_f32 v169, v174, v175
	global_store_dwordx4 v[172:173], v[166:169], off
	v_pk_mul_f32 v[174:175], v[156:157], v[90:91] op_sel_hi:[0,1]
	v_pk_mul_f32 v[176:177], v[156:157], v[88:89] op_sel_hi:[0,1]
	v_pk_mul_f32 v[168:169], v[156:157], v[98:99] op_sel_hi:[0,1]
	v_pk_mul_f32 v[166:167], v[156:157], v[96:97] op_sel_hi:[0,1]
	v_cvt_pk_bf16_f32 v166, v166, v167
	v_cvt_pk_bf16_f32 v167, v168, v169
	v_cvt_pk_bf16_f32 v168, v176, v177
	v_cvt_pk_bf16_f32 v169, v174, v175
	global_store_dwordx4 v[172:173], v[166:169], off offset:256
	v_pk_mul_f32 v[174:175], v[156:157], v[94:95] op_sel_hi:[0,1]
	v_pk_mul_f32 v[176:177], v[156:157], v[92:93] op_sel_hi:[0,1]
	v_lshlrev_b64 v[166:167], 11, v[150:151]
; __device__ __forceinline__ unsigned cvt_pk_bf16(float lo, float hi) { const bf16x2_t r = __builtin_convertvector((f32x2){lo, hi}, bf16x2_t); return __builtin_bit_cast(unsigned, r); }
;     __device__ __forceinline__ void operator()(const AccT& acc, const Unit& u, int wr, int wc, int fr, int fq) const {
;     ...
;         if (pn < 8) {
;             bf16_t* base = pn < 4 ? Q : Kn; const int colt = (pn & 3) * BM; const float sc = pn < 4 ? 0.08838834764831845f : 1.0f;
; #pragma unroll
;             for (int ai = 0; ai < 2; ++ai)
; #pragma unroll
;                 for (int m = 0; m < 4; ++m) { bf16_t* rowp = base + (size_t)(row0 + ai * HALF + m * 16) * 1024 + colt + cl;
; #pragma unroll
;                     for (int bj = 0; bj < 2; ++bj) { const f32x4 v0 = acc[ai][bj][m][0] * sc, v1 = acc[ai][bj][m][1] * sc;
;                         u32x4 w; w.x = cvt_pk_bf16(v0[0], v0[1]); w.y = cvt_pk_bf16(v0[2], v0[3]); w.z = cvt_pk_bf16(v1[0], v1[1]); w.w = cvt_pk_bf16(v1[2], v1[3]);
;                         *(u32x4*)(rowp + bj * HALF) = w; } }
;         }
;         if (pn >= 16) {
	v_lshl_add_u64 v[172:173], v[170:171], 0, v[166:167]
	v_pk_mul_f32 v[168:169], v[156:157], v[102:103] op_sel_hi:[0,1]
	v_pk_mul_f32 v[166:167], v[156:157], v[100:101] op_sel_hi:[0,1]
	v_cvt_pk_bf16_f32 v166, v166, v167
	v_cvt_pk_bf16_f32 v167, v168, v169
	v_cvt_pk_bf16_f32 v168, v176, v177
	v_cvt_pk_bf16_f32 v169, v174, v175
	global_store_dwordx4 v[172:173], v[166:169], off
	v_pk_mul_f32 v[174:175], v[156:157], v[74:75] op_sel_hi:[0,1]
	v_pk_mul_f32 v[176:177], v[156:157], v[72:73] op_sel_hi:[0,1]
	v_pk_mul_f32 v[168:169], v[156:157], v[82:83] op_sel_hi:[0,1]
	v_pk_mul_f32 v[166:167], v[156:157], v[80:81] op_sel_hi:[0,1]
	v_cvt_pk_bf16_f32 v166, v166, v167
	v_cvt_pk_bf16_f32 v167, v168, v169
	v_cvt_pk_bf16_f32 v168, v176, v177
	v_cvt_pk_bf16_f32 v169, v174, v175
	global_store_dwordx4 v[172:173], v[166:169], off offset:256
	v_pk_mul_f32 v[172:173], v[156:157], v[78:79] op_sel_hi:[0,1]
	v_pk_mul_f32 v[174:175], v[156:157], v[76:77] op_sel_hi:[0,1]
	v_lshlrev_b64 v[166:167], 11, v[148:149]
	v_lshl_add_u64 v[170:171], v[170:171], 0, v[166:167]
	v_pk_mul_f32 v[168:169], v[156:157], v[86:87] op_sel_hi:[0,1]
	v_pk_mul_f32 v[166:167], v[156:157], v[84:85] op_sel_hi:[0,1]
	v_cvt_pk_bf16_f32 v166, v166, v167
	v_cvt_pk_bf16_f32 v167, v168, v169
	v_cvt_pk_bf16_f32 v168, v174, v175
	v_cvt_pk_bf16_f32 v169, v172, v173
	global_store_dwordx4 v[170:171], v[166:169], off
	v_pk_mul_f32 v[172:173], v[156:157], v[66:67] op_sel_hi:[0,1]
	v_pk_mul_f32 v[174:175], v[156:157], v[64:65] op_sel_hi:[0,1]
	v_pk_mul_f32 v[168:169], v[156:157], v[70:71] op_sel_hi:[0,1]
	v_pk_mul_f32 v[166:167], v[156:157], v[68:69] op_sel_hi:[0,1]
	v_cvt_pk_bf16_f32 v166, v166, v167
	v_cvt_pk_bf16_f32 v167, v168, v169
	v_cvt_pk_bf16_f32 v168, v174, v175
	v_cvt_pk_bf16_f32 v169, v172, v173
	global_store_dwordx4 v[170:171], v[166:169], off offset:256
	v_pk_mul_f32 v[172:173], v[156:157], v[58:59] op_sel_hi:[0,1]
	s_mov_b32 s4, 0x40000
	v_pk_mul_f32 v[168:169], v[156:157], v[62:63] op_sel_hi:[0,1]
	v_pk_mul_f32 v[166:167], v[156:157], v[60:61] op_sel_hi:[0,1]
	v_pk_mul_f32 v[174:175], v[156:157], v[56:57] op_sel_hi:[0,1]
	v_cvt_pk_bf16_f32 v166, v166, v167
	v_cvt_pk_bf16_f32 v167, v168, v169
	v_cvt_pk_bf16_f32 v169, v172, v173
	v_add_co_u32_e32 v172, vcc, s4, v158
	v_cvt_pk_bf16_f32 v168, v174, v175
	s_nop 0
	v_addc_co_u32_e32 v173, vcc, 0, v159, vcc
	s_mov_b64 s[30:31], 0x40000
	global_store_dwordx4 v[172:173], v[166:169], off
	v_pk_mul_f32 v[172:173], v[156:157], v[42:43] op_sel_hi:[0,1]
	v_pk_mul_f32 v[174:175], v[156:157], v[40:41] op_sel_hi:[0,1]
	v_pk_mul_f32 v[168:169], v[156:157], v[50:51] op_sel_hi:[0,1]
	v_pk_mul_f32 v[166:167], v[156:157], v[48:49] op_sel_hi:[0,1]
	v_lshl_add_u64 v[170:171], v[158:159], 0, s[30:31]
	v_cvt_pk_bf16_f32 v166, v166, v167
	v_cvt_pk_bf16_f32 v167, v168, v169
	v_cvt_pk_bf16_f32 v168, v174, v175
	v_cvt_pk_bf16_f32 v169, v172, v173
	global_store_dwordx4 v[170:171], v[166:169], off offset:256
	v_pk_mul_f32 v[172:173], v[156:157], v[46:47] op_sel_hi:[0,1]
	s_mov_b32 s4, 0x48000
	v_pk_mul_f32 v[168:169], v[156:157], v[54:55] op_sel_hi:[0,1]
	v_pk_mul_f32 v[166:167], v[156:157], v[52:53] op_sel_hi:[0,1]
	v_pk_mul_f32 v[174:175], v[156:157], v[44:45] op_sel_hi:[0,1]
	v_cvt_pk_bf16_f32 v166, v166, v167
	v_cvt_pk_bf16_f32 v167, v168, v169
	v_cvt_pk_bf16_f32 v169, v172, v173
	v_add_co_u32_e32 v172, vcc, s4, v158
	v_cvt_pk_bf16_f32 v168, v174, v175
	s_nop 0
	v_addc_co_u32_e32 v173, vcc, 0, v159, vcc
	s_mov_b64 s[30:31], 0x48000
	global_store_dwordx4 v[172:173], v[166:169], off
	v_pk_mul_f32 v[172:173], v[156:157], v[26:27] op_sel_hi:[0,1]
	v_pk_mul_f32 v[174:175], v[156:157], v[24:25] op_sel_hi:[0,1]
	v_pk_mul_f32 v[168:169], v[156:157], v[34:35] op_sel_hi:[0,1]
	v_pk_mul_f32 v[166:167], v[156:157], v[32:33] op_sel_hi:[0,1]
	v_lshl_add_u64 v[170:171], v[158:159], 0, s[30:31]
	v_cvt_pk_bf16_f32 v166, v166, v167
	v_cvt_pk_bf16_f32 v167, v168, v169
	v_cvt_pk_bf16_f32 v168, v174, v175
	v_cvt_pk_bf16_f32 v169, v172, v173
	global_store_dwordx4 v[170:171], v[166:169], off offset:256
	v_pk_mul_f32 v[172:173], v[156:157], v[30:31] op_sel_hi:[0,1]
	v_pk_mul_f32 v[174:175], v[156:157], v[28:29] op_sel_hi:[0,1]
	v_pk_mul_f32 v[168:169], v[156:157], v[38:39] op_sel_hi:[0,1]
	v_pk_mul_f32 v[166:167], v[156:157], v[36:37] op_sel_hi:[0,1]
	v_cvt_pk_bf16_f32 v166, v166, v167
	v_cvt_pk_bf16_f32 v167, v168, v169
	v_cvt_pk_bf16_f32 v169, v172, v173
	v_add_co_u32_e32 v172, vcc, s48, v158
	v_cvt_pk_bf16_f32 v168, v174, v175
	s_nop 0
	v_addc_co_u32_e32 v173, vcc, 0, v159, vcc
	global_store_dwordx4 v[172:173], v[166:169], off
	v_pk_mul_f32 v[172:173], v[156:157], v[10:11] op_sel_hi:[0,1]
	v_pk_mul_f32 v[174:175], v[156:157], v[8:9] op_sel_hi:[0,1]
	v_pk_mul_f32 v[168:169], v[156:157], v[18:19] op_sel_hi:[0,1]
	v_pk_mul_f32 v[166:167], v[156:157], v[16:17] op_sel_hi:[0,1]
	v_lshl_add_u64 v[170:171], v[158:159], 0, s[8:9]
	v_cvt_pk_bf16_f32 v166, v166, v167
	v_cvt_pk_bf16_f32 v167, v168, v169
	v_cvt_pk_bf16_f32 v168, v174, v175
	v_cvt_pk_bf16_f32 v169, v172, v173
	global_store_dwordx4 v[170:171], v[166:169], off offset:256
	v_lshl_add_u64 v[170:171], v[158:159], 0, s[10:11]
	v_pk_mul_f32 v[172:173], v[156:157], v[14:15] op_sel_hi:[0,1]
	v_pk_mul_f32 v[168:169], v[156:157], v[22:23] op_sel_hi:[0,1]
	v_pk_mul_f32 v[166:167], v[156:157], v[20:21] op_sel_hi:[0,1]
	v_pk_mul_f32 v[174:175], v[156:157], v[12:13] op_sel_hi:[0,1]
	v_add_co_u32_e32 v158, vcc, s49, v158
	v_cvt_pk_bf16_f32 v166, v166, v167
	v_cvt_pk_bf16_f32 v167, v168, v169
	v_cvt_pk_bf16_f32 v168, v174, v175
	v_cvt_pk_bf16_f32 v169, v172, v173
	v_addc_co_u32_e32 v159, vcc, 0, v159, vcc
	global_store_dwordx4 v[158:159], v[166:169], off
	v_pk_mul_f32 v[158:159], v[156:157], v[6:7] op_sel_hi:[0,1]
	v_pk_mul_f32 v[172:173], v[156:157], v[0:1] op_sel_hi:[0,1]
	v_pk_mul_f32 v[166:167], v[156:157], v[4:5] op_sel_hi:[0,1]
	v_pk_mul_f32 v[168:169], v[156:157], v[2:3] op_sel_hi:[0,1]
	v_cvt_pk_bf16_f32 v156, v166, v167
	v_cvt_pk_bf16_f32 v157, v158, v159
	v_cvt_pk_bf16_f32 v158, v172, v173
	v_cvt_pk_bf16_f32 v159, v168, v169
	global_store_dwordx4 v[170:171], v[156:159], off offset:256
	s_cmp_lt_i32 s27, 16
	s_cbranch_scc0 .LBB0_204

; template <class Epi>
; __device__ __forceinline__ void gemm_phase(LAS unsigned char* lds, const bf16_t* A, int lda, const bf16_t* Bt, int ldb, int M, int N, int K, int asel, const Epi& E, const int fixed_round = -1) {
;     ...
;         const bool has_next = (fixed_round < 0) && S.next(ui + 1, nxt);
;         const char* nA = has_next ? PG8_ABASE(nxt) : cA; const char* nB = has_next ? (const char*)Bt + (size_t)nxt.pn * tstepB : cB;
;     ...
; #pragma unroll
;         for (int a = 0; a < 2; ++a)
; #pragma unroll
;             for (int b = 0; b < 2; ++b)
; #pragma unroll
;                 for (int m = 0; m < 4; ++m)
; #pragma unroll
;                     for (int n = 0; n < 2; ++n) acc[a][b][m][n] = (f32x4){0.f, 0.f, 0.f, 0.f};
;         cur = nxt; cA = nA; cB = nB; ++ui;
.LBB0_223:
	s_ashr_i32 s11, s10, 31
	v_cmp_lt_i64_e32 vcc, s[12:13], v[136:137]
	s_lshl_b64 s[12:13], s[10:11], 20
	s_add_u32 s12, s72, s12
	s_addc_u32 s13, s73, s13
	s_and_b64 s[14:15], vcc, exec
	s_cselect_b32 s11, s13, s17
	s_cselect_b32 s37, s12, s16
	s_ashr_i32 s9, s8, 31
	s_lshl_b64 s[14:15], s[8:9], 20
	s_add_u32 s14, s23, s14
	s_addc_u32 s15, s24, s15
	s_and_b64 s[20:21], vcc, exec
	s_cselect_b32 s9, s15, s19
	s_cselect_b32 s38, s14, s18
	s_add_u32 s16, s16, 0x80080
	s_addc_u32 s17, s17, 0
	s_add_u32 s39, s18, 0x100
	v_mov_b32_e32 v0, 0
	s_addc_u32 s40, s19, 0
	s_mov_b32 s41, -2
	v_mov_b32_e32 v1, v0
	v_mov_b32_e32 v2, v0
	v_mov_b32_e32 v3, v0
	v_mov_b32_e32 v16, v0
	v_mov_b32_e32 v17, v0
	v_mov_b32_e32 v18, v0
	v_mov_b32_e32 v19, v0
	v_mov_b32_e32 v4, v0
	v_mov_b32_e32 v5, v0
	v_mov_b32_e32 v6, v0
	v_mov_b32_e32 v7, v0
	v_mov_b32_e32 v20, v0
	v_mov_b32_e32 v21, v0
	v_mov_b32_e32 v22, v0
	v_mov_b32_e32 v23, v0
	v_mov_b32_e32 v8, v0
	v_mov_b32_e32 v9, v0
	v_mov_b32_e32 v10, v0
	v_mov_b32_e32 v11, v0
	v_mov_b32_e32 v24, v0
	v_mov_b32_e32 v25, v0
	v_mov_b32_e32 v26, v0
	v_mov_b32_e32 v27, v0
	v_mov_b32_e32 v12, v0
	v_mov_b32_e32 v13, v0
	v_mov_b32_e32 v14, v0
	v_mov_b32_e32 v15, v0
	v_mov_b32_e32 v32, v0
	v_mov_b32_e32 v33, v0
	v_mov_b32_e32 v34, v0
	v_mov_b32_e32 v35, v0
	v_mov_b32_e32 v44, v0
	v_mov_b32_e32 v45, v0
	v_mov_b32_e32 v46, v0
	v_mov_b32_e32 v47, v0
	v_mov_b32_e32 v76, v0
	v_mov_b32_e32 v77, v0
	v_mov_b32_e32 v78, v0
	v_mov_b32_e32 v79, v0
	v_mov_b32_e32 v56, v0
	v_mov_b32_e32 v57, v0
	v_mov_b32_e32 v58, v0
	v_mov_b32_e32 v59, v0
	v_mov_b32_e32 v84, v0
	v_mov_b32_e32 v85, v0
	v_mov_b32_e32 v86, v0
	v_mov_b32_e32 v87, v0
	v_mov_b32_e32 v64, v0
	v_mov_b32_e32 v65, v0
	v_mov_b32_e32 v66, v0
	v_mov_b32_e32 v67, v0
	v_mov_b32_e32 v88, v0
	v_mov_b32_e32 v89, v0
	v_mov_b32_e32 v90, v0
	v_mov_b32_e32 v91, v0
	v_mov_b32_e32 v72, v0
	v_mov_b32_e32 v73, v0
	v_mov_b32_e32 v74, v0
	v_mov_b32_e32 v75, v0
	v_mov_b32_e32 v96, v0
	v_mov_b32_e32 v97, v0
	v_mov_b32_e32 v98, v0
	v_mov_b32_e32 v99, v0
	v_mov_b32_e32 v28, v0
	v_mov_b32_e32 v29, v0
	v_mov_b32_e32 v30, v0
	v_mov_b32_e32 v31, v0
	v_mov_b32_e32 v52, v0
	v_mov_b32_e32 v53, v0
	v_mov_b32_e32 v54, v0
	v_mov_b32_e32 v55, v0
	v_mov_b32_e32 v36, v0
	v_mov_b32_e32 v37, v0
	v_mov_b32_e32 v38, v0
	v_mov_b32_e32 v39, v0
	v_mov_b32_e32 v60, v0
	v_mov_b32_e32 v61, v0
	v_mov_b32_e32 v62, v0
	v_mov_b32_e32 v63, v0
	v_mov_b32_e32 v40, v0
	v_mov_b32_e32 v41, v0
	v_mov_b32_e32 v42, v0
	v_mov_b32_e32 v43, v0
	v_mov_b32_e32 v68, v0
	v_mov_b32_e32 v69, v0
	v_mov_b32_e32 v70, v0
	v_mov_b32_e32 v71, v0
	v_mov_b32_e32 v48, v0
	v_mov_b32_e32 v49, v0
	v_mov_b32_e32 v50, v0
	v_mov_b32_e32 v51, v0
	v_mov_b32_e32 v80, v0
	v_mov_b32_e32 v81, v0
	v_mov_b32_e32 v82, v0
	v_mov_b32_e32 v83, v0
	v_mov_b32_e32 v92, v0
	v_mov_b32_e32 v93, v0
	v_mov_b32_e32 v94, v0
	v_mov_b32_e32 v95, v0
	v_mov_b32_e32 v112, v0
	v_mov_b32_e32 v113, v0
	v_mov_b32_e32 v114, v0
	v_mov_b32_e32 v115, v0
	v_mov_b32_e32 v100, v0
	v_mov_b32_e32 v101, v0
	v_mov_b32_e32 v102, v0
	v_mov_b32_e32 v103, v0
	v_mov_b32_e32 v116, v0
	v_mov_b32_e32 v117, v0
	v_mov_b32_e32 v118, v0
	v_mov_b32_e32 v119, v0
	v_mov_b32_e32 v104, v0
	v_mov_b32_e32 v105, v0
	v_mov_b32_e32 v106, v0
	v_mov_b32_e32 v107, v0
	v_mov_b32_e32 v120, v0
	v_mov_b32_e32 v121, v0
	v_mov_b32_e32 v122, v0
	v_mov_b32_e32 v123, v0
	v_mov_b32_e32 v108, v0
	v_mov_b32_e32 v109, v0
	v_mov_b32_e32 v110, v0
	v_mov_b32_e32 v111, v0
	v_mov_b32_e32 v124, v0
	v_mov_b32_e32 v125, v0
	v_mov_b32_e32 v126, v0
	v_mov_b32_e32 v127, v0
	s_branch .LBB0_224

; #define PG8_STAGE(bufoff, gbase, voff) do { _Pragma("unroll") for (int _i = 0; _i < 2; ++_i) \
;         __builtin_amdgcn_global_load_lds((const unsigned*)((const char*)(gbase) + (voff)[_i]), (LAS unsigned*)(lds + (bufoff) + ldsw + _i * 8192), 16, 0, 0); } while (0)
; #define PG8_LDA(dst, b, h) do { _Pragma("unroll") for (int m = 0; m < 4; ++m) _Pragma("unroll") for (int k = 0; k < 2; ++k) dst[m][k] = *(const LAS bf16x8*)(lds + PG8_SA(b, h) + aoff + m * 2048 + k * 1024); } while (0)
; #define PG8_LDB(dst, b, h) do { _Pragma("unroll") for (int n = 0; n < 2; ++n) _Pragma("unroll") for (int k = 0; k < 2; ++k) dst[n][k] = *(const LAS bf16x8*)(lds + PG8_SB(b, h) + boff + n * 2048 + k * 1024); } while (0)
; #define PG8_WAIT_V(n) asm volatile("s_waitcnt vmcnt(" #n ")" ::: "memory")
; #define PG8_WAIT_L(n) asm volatile("s_waitcnt lgkmcnt(" #n ")" ::: "memory")
; #define PG8_BAR __builtin_amdgcn_s_barrier()
; #define PG8_SCHED __builtin_amdgcn_sched_barrier(0)
; template <class Epi>
; __device__ __forceinline__ void gemm_phase(LAS unsigned char* lds, const bf16_t* A, int lda, const bf16_t* Bt, int ldb, int M, int N, int K, int asel, const Epi& E, const int fixed_round = -1) {
;     ...
;         for (int t = 0; t < nt; t += 2) {
;             const bool last = (t == nt - 2);
;             const char* a1 = cA + (size_t)(t + 1) * kstep;
;             const char* a2 = last ? nA : cA + (size_t)(t + 2) * kstep; const char* b2 = last ? nB : cB + (size_t)(t + 2) * kstep;
;             const char* a3 = a2 + kstep; const char* b3 = b2 + kstep;
;             PG8_LDB(B0, 0, 0); PG8_SCHED; PG8_LDA(At, 0, 0); PG8_STAGE(PG8_SA(1, 1), a1 + hstepA, voffA);
;             PG8_WAIT_L(8); PG8_BAR; PG8_WAIT_L(0); PG8_MMA(0, 0, At, B0); PG8_BAR; PG8_SCHED;
;             PG8_LDB(B1, 0, 1); PG8_STAGE(PG8_SB(0, 0), b2, voffB);
;             PG8_BAR; PG8_WAIT_L(0); PG8_MMA(0, 1, At, B1); PG8_BAR;
;             PG8_LDA(At, 0, 1); PG8_STAGE(PG8_SA(0, 0), a2, voffA);
;             PG8_BAR; PG8_WAIT_L(0); PG8_MMA(1, 0, At, B0); PG8_BAR; PG8_SCHED;
;             PG8_STAGE(PG8_SB(0, 1), b2 + hstepB, voffB);
;             PG8_WAIT_V(6); PG8_BAR; PG8_MMA(1, 1, At, B1); PG8_BAR;
.LBB0_224:
	ds_read_b128 v[146:149], v143
	ds_read_b128 v[150:153], v143 offset:1024
	ds_read_b128 v[154:157], v143 offset:2048
	ds_read_b128 v[158:161], v143 offset:3072
	s_add_u32 s18, s16, 0xfff80080
	s_addc_u32 s19, s17, -1
	s_cmp_eq_u32 s41, 28
	s_cselect_b32 s21, s11, s19
	s_cselect_b32 s20, s37, s18
	s_cselect_b32 s19, s9, s40
	s_cselect_b32 s18, s38, s39
	s_add_i32 m0, s7, 0xc000
	ds_read_b128 v[162:165], v144
	ds_read_b128 v[166:169], v144 offset:1024
	ds_read_b128 v[170:173], v144 offset:2048
	ds_read_b128 v[174:177], v144 offset:3072
	ds_read_b128 v[178:181], v144 offset:4096
	ds_read_b128 v[182:185], v144 offset:5120
	ds_read_b128 v[186:189], v144 offset:6144
	ds_read_b128 v[190:193], v144 offset:7168
	global_load_lds_dwordx4 v132, s[16:17]
	s_add_i32 m0, s7, 0xe000
	s_nop 0
	global_load_lds_dwordx4 v134, s[16:17]
	s_waitcnt lgkmcnt(8)
	s_barrier
	s_waitcnt lgkmcnt(0)
	s_setprio 1
	s_waitcnt lgkmcnt(0)
	v_mfma_f32_16x16x32_bf16 v[124:127], v[162:165], v[146:149], v[124:127]
	v_mfma_f32_16x16x32_bf16 v[108:111], v[162:165], v[154:157], v[108:111]
	v_mfma_f32_16x16x32_bf16 v[120:123], v[170:173], v[146:149], v[120:123]
	v_mfma_f32_16x16x32_bf16 v[104:107], v[170:173], v[154:157], v[104:107]
	v_mfma_f32_16x16x32_bf16 v[116:119], v[178:181], v[146:149], v[116:119]
	v_mfma_f32_16x16x32_bf16 v[100:103], v[178:181], v[154:157], v[100:103]
	v_mfma_f32_16x16x32_bf16 v[112:115], v[186:189], v[146:149], v[112:115]
	v_mfma_f32_16x16x32_bf16 v[92:95], v[186:189], v[154:157], v[92:95]
	v_mfma_f32_16x16x32_bf16 v[124:127], v[166:169], v[150:153], v[124:127]
	v_mfma_f32_16x16x32_bf16 v[108:111], v[166:169], v[158:161], v[108:111]
	v_mfma_f32_16x16x32_bf16 v[120:123], v[174:177], v[150:153], v[120:123]
	v_mfma_f32_16x16x32_bf16 v[104:107], v[174:177], v[158:161], v[104:107]
	v_mfma_f32_16x16x32_bf16 v[116:119], v[182:185], v[150:153], v[116:119]
	v_mfma_f32_16x16x32_bf16 v[100:103], v[182:185], v[158:161], v[100:103]
	v_mfma_f32_16x16x32_bf16 v[112:115], v[190:193], v[150:153], v[112:115]
	v_mfma_f32_16x16x32_bf16 v[92:95], v[190:193], v[158:161], v[92:95]
	s_setprio 0
	s_barrier
	s_add_i32 s42, s34, s25
	s_add_u32 s98, s18, s2
	s_addc_u32 s99, s19, s3
	s_mov_b32 m0, s42
	ds_read_b128 v[196:199], v145
	ds_read_b128 v[202:205], v145 offset:1024
	ds_read_b128 v[206:209], v145 offset:2048
	ds_read_b128 v[210:213], v145 offset:3072
	global_load_lds_dwordx4 v128, s[18:19]
	s_add_i32 m0, s42, 0x2000
	s_nop 0
	global_load_lds_dwordx4 v130, s[18:19]
	s_barrier
	s_waitcnt lgkmcnt(0)
	s_setprio 1
	s_waitcnt lgkmcnt(0)
	v_mfma_f32_16x16x32_bf16 v[80:83], v[162:165], v[196:199], v[80:83]
	v_mfma_f32_16x16x32_bf16 v[48:51], v[162:165], v[206:209], v[48:51]
	v_mfma_f32_16x16x32_bf16 v[68:71], v[170:173], v[196:199], v[68:71]
	v_mfma_f32_16x16x32_bf16 v[40:43], v[170:173], v[206:209], v[40:43]
	v_mfma_f32_16x16x32_bf16 v[60:63], v[178:181], v[196:199], v[60:63]
	v_mfma_f32_16x16x32_bf16 v[36:39], v[178:181], v[206:209], v[36:39]
	v_mfma_f32_16x16x32_bf16 v[52:55], v[186:189], v[196:199], v[52:55]
	v_mfma_f32_16x16x32_bf16 v[28:31], v[186:189], v[206:209], v[28:31]
	v_mfma_f32_16x16x32_bf16 v[80:83], v[166:169], v[202:205], v[80:83]
	v_mfma_f32_16x16x32_bf16 v[48:51], v[166:169], v[210:213], v[48:51]
	v_mfma_f32_16x16x32_bf16 v[68:71], v[174:177], v[202:205], v[68:71]
	v_mfma_f32_16x16x32_bf16 v[40:43], v[174:177], v[210:213], v[40:43]
	v_mfma_f32_16x16x32_bf16 v[60:63], v[182:185], v[202:205], v[60:63]
	v_mfma_f32_16x16x32_bf16 v[36:39], v[182:185], v[210:213], v[36:39]
	v_mfma_f32_16x16x32_bf16 v[52:55], v[190:193], v[202:205], v[52:55]
	v_mfma_f32_16x16x32_bf16 v[28:31], v[190:193], v[210:213], v[28:31]
	s_setprio 0
	s_mov_b32 m0, s7
	s_add_u32 s100, s20, s2
	s_addc_u32 s101, s21, s3
	s_barrier
	ds_read_b128 v[162:165], v144 offset:16384
	ds_read_b128 v[166:169], v144 offset:17408
	ds_read_b128 v[170:173], v144 offset:18432
	ds_read_b128 v[174:177], v144 offset:19456
	ds_read_b128 v[178:181], v144 offset:20480
	ds_read_b128 v[182:185], v144 offset:21504
	ds_read_b128 v[186:189], v144 offset:22528
	ds_read_b128 v[190:193], v144 offset:23552
	global_load_lds_dwordx4 v128, s[20:21]
	s_mov_b32 m0, s26
	s_nop 0
	global_load_lds_dwordx4 v130, s[20:21]
	s_barrier
	s_waitcnt lgkmcnt(0)
	s_setprio 1
	s_waitcnt lgkmcnt(0)
	v_mfma_f32_16x16x32_bf16 v[96:99], v[162:165], v[146:149], v[96:99]
	v_mfma_f32_16x16x32_bf16 v[72:75], v[162:165], v[154:157], v[72:75]
	v_mfma_f32_16x16x32_bf16 v[88:91], v[170:173], v[146:149], v[88:91]
	v_mfma_f32_16x16x32_bf16 v[64:67], v[170:173], v[154:157], v[64:67]
	v_mfma_f32_16x16x32_bf16 v[84:87], v[178:181], v[146:149], v[84:87]
	v_mfma_f32_16x16x32_bf16 v[56:59], v[178:181], v[154:157], v[56:59]
	v_mfma_f32_16x16x32_bf16 v[76:79], v[186:189], v[146:149], v[76:79]
	v_mfma_f32_16x16x32_bf16 v[44:47], v[186:189], v[154:157], v[44:47]
	v_mfma_f32_16x16x32_bf16 v[96:99], v[166:169], v[150:153], v[96:99]
	v_mfma_f32_16x16x32_bf16 v[72:75], v[166:169], v[158:161], v[72:75]
	v_mfma_f32_16x16x32_bf16 v[88:91], v[174:177], v[150:153], v[88:91]
	v_mfma_f32_16x16x32_bf16 v[64:67], v[174:177], v[158:161], v[64:67]
	v_mfma_f32_16x16x32_bf16 v[84:87], v[182:185], v[150:153], v[84:87]
	v_mfma_f32_16x16x32_bf16 v[56:59], v[182:185], v[158:161], v[56:59]
	v_mfma_f32_16x16x32_bf16 v[76:79], v[190:193], v[150:153], v[76:79]
	v_mfma_f32_16x16x32_bf16 v[44:47], v[190:193], v[158:161], v[44:47]
	s_setprio 0
	s_barrier
	s_add_u32 s42, s18, 0x80000
	s_addc_u32 s43, s19, 0
	s_add_i32 s44, s35, s25
	s_mov_b32 m0, s44
	s_nop 0
	global_load_lds_dwordx4 v128, s[42:43]
	s_add_i32 m0, s44, 0x2000
	s_nop 0
	global_load_lds_dwordx4 v130, s[42:43]
	s_waitcnt vmcnt(6)
	s_barrier
; #define PG8_STAGE(bufoff, gbase, voff) do { _Pragma("unroll") for (int _i = 0; _i < 2; ++_i) \
;         __builtin_amdgcn_global_load_lds((const unsigned*)((const char*)(gbase) + (voff)[_i]), (LAS unsigned*)(lds + (bufoff) + ldsw + _i * 8192), 16, 0, 0); } while (0)
; #define PG8_LDA(dst, b, h) do { _Pragma("unroll") for (int m = 0; m < 4; ++m) _Pragma("unroll") for (int k = 0; k < 2; ++k) dst[m][k] = *(const LAS bf16x8*)(lds + PG8_SA(b, h) + aoff + m * 2048 + k * 1024); } while (0)
; #define PG8_LDB(dst, b, h) do { _Pragma("unroll") for (int n = 0; n < 2; ++n) _Pragma("unroll") for (int k = 0; k < 2; ++k) dst[n][k] = *(const LAS bf16x8*)(lds + PG8_SB(b, h) + boff + n * 2048 + k * 1024); } while (0)
; #define PG8_WAIT_V(n) asm volatile("s_waitcnt vmcnt(" #n ")" ::: "memory")
; #define PG8_WAIT_L(n) asm volatile("s_waitcnt lgkmcnt(" #n ")" ::: "memory")
; #define PG8_BAR __builtin_amdgcn_s_barrier()
; #define PG8_SCHED __builtin_amdgcn_sched_barrier(0)
; template <class Epi>
; __device__ __forceinline__ void gemm_phase(LAS unsigned char* lds, const bf16_t* A, int lda, const bf16_t* Bt, int ldb, int M, int N, int K, int asel, const Epi& E, const int fixed_round = -1) {
;     ...
;             PG8_WAIT_V(6); PG8_BAR; PG8_MMA(1, 1, At, B1); PG8_BAR;
;             PG8_LDB(B0, 1, 0); PG8_SCHED; PG8_LDA(At, 1, 0); PG8_STAGE(PG8_SA(0, 1), a2 + hstepA, voffA);
;             PG8_WAIT_L(8); PG8_BAR; PG8_WAIT_L(0); PG8_MMA(0, 0, At, B0); PG8_BAR; PG8_SCHED;
;             PG8_LDB(B1, 1, 1); PG8_STAGE(PG8_SB(1, 0), b3, voffB);
;             PG8_BAR; PG8_WAIT_L(0); PG8_MMA(0, 1, At, B1); PG8_BAR;
;             PG8_LDA(At, 1, 1); PG8_STAGE(PG8_SA(1, 0), a3, voffA);
;             PG8_BAR; PG8_WAIT_L(0); PG8_MMA(1, 0, At, B0); PG8_BAR; PG8_SCHED;
	s_setprio 1
	v_mfma_f32_16x16x32_bf16 v[32:35], v[162:165], v[196:199], v[32:35]
	v_mfma_f32_16x16x32_bf16 v[12:15], v[162:165], v[206:209], v[12:15]
	v_mfma_f32_16x16x32_bf16 v[24:27], v[170:173], v[196:199], v[24:27]
	v_mfma_f32_16x16x32_bf16 v[8:11], v[170:173], v[206:209], v[8:11]
	v_mfma_f32_16x16x32_bf16 v[20:23], v[178:181], v[196:199], v[20:23]
	v_mfma_f32_16x16x32_bf16 v[4:7], v[178:181], v[206:209], v[4:7]
	v_mfma_f32_16x16x32_bf16 v[16:19], v[186:189], v[196:199], v[16:19]
	v_mfma_f32_16x16x32_bf16 v[0:3], v[186:189], v[206:209], v[0:3]
	v_mfma_f32_16x16x32_bf16 v[32:35], v[166:169], v[202:205], v[32:35]
	v_mfma_f32_16x16x32_bf16 v[12:15], v[166:169], v[210:213], v[12:15]
	v_mfma_f32_16x16x32_bf16 v[24:27], v[174:177], v[202:205], v[24:27]
	v_mfma_f32_16x16x32_bf16 v[8:11], v[174:177], v[210:213], v[8:11]
	v_mfma_f32_16x16x32_bf16 v[20:23], v[182:185], v[202:205], v[20:23]
	v_mfma_f32_16x16x32_bf16 v[4:7], v[182:185], v[210:213], v[4:7]
	v_mfma_f32_16x16x32_bf16 v[16:19], v[190:193], v[202:205], v[16:19]
	v_mfma_f32_16x16x32_bf16 v[0:3], v[190:193], v[210:213], v[0:3]
	s_setprio 0
	s_add_i32 s42, 0, 0x18000
	v_add_u32_e32 v158, s42, v140
	s_barrier
	ds_read_b128 v[146:149], v158
	ds_read_b128 v[150:153], v158 offset:1024
	ds_read_b128 v[154:157], v158 offset:2048
	ds_read_b128 v[158:161], v158 offset:3072
	s_add_u32 s20, s20, 0x80000
	s_addc_u32 s21, s21, 0
	s_mov_b32 m0, s27
	ds_read_b128 v[162:165], v144 offset:32768
	ds_read_b128 v[166:169], v144 offset:33792
	ds_read_b128 v[170:173], v144 offset:34816
	ds_read_b128 v[174:177], v144 offset:35840
	ds_read_b128 v[178:181], v144 offset:36864
	ds_read_b128 v[182:185], v144 offset:37888
	ds_read_b128 v[186:189], v144 offset:38912
	ds_read_b128 v[190:193], v144 offset:39936
	global_load_lds_dwordx4 v128, s[20:21]
	s_mov_b32 m0, s28
	s_nop 0
	global_load_lds_dwordx4 v130, s[20:21]
	s_waitcnt lgkmcnt(8)
	s_barrier
	s_waitcnt lgkmcnt(0)
	s_setprio 1
	s_waitcnt lgkmcnt(0)
	v_mfma_f32_16x16x32_bf16 v[124:127], v[162:165], v[146:149], v[124:127]
	v_mfma_f32_16x16x32_bf16 v[108:111], v[162:165], v[154:157], v[108:111]
	v_mfma_f32_16x16x32_bf16 v[120:123], v[170:173], v[146:149], v[120:123]
	v_mfma_f32_16x16x32_bf16 v[104:107], v[170:173], v[154:157], v[104:107]
	v_mfma_f32_16x16x32_bf16 v[116:119], v[178:181], v[146:149], v[116:119]
	v_mfma_f32_16x16x32_bf16 v[100:103], v[178:181], v[154:157], v[100:103]
	v_mfma_f32_16x16x32_bf16 v[112:115], v[186:189], v[146:149], v[112:115]
	v_mfma_f32_16x16x32_bf16 v[92:95], v[186:189], v[154:157], v[92:95]
	v_mfma_f32_16x16x32_bf16 v[124:127], v[166:169], v[150:153], v[124:127]
	v_mfma_f32_16x16x32_bf16 v[108:111], v[166:169], v[158:161], v[108:111]
	v_mfma_f32_16x16x32_bf16 v[120:123], v[174:177], v[150:153], v[120:123]
	v_mfma_f32_16x16x32_bf16 v[104:107], v[174:177], v[158:161], v[104:107]
	v_mfma_f32_16x16x32_bf16 v[116:119], v[182:185], v[150:153], v[116:119]
	v_mfma_f32_16x16x32_bf16 v[100:103], v[182:185], v[158:161], v[100:103]
	v_mfma_f32_16x16x32_bf16 v[112:115], v[190:193], v[150:153], v[112:115]
	v_mfma_f32_16x16x32_bf16 v[92:95], v[190:193], v[158:161], v[92:95]
	s_setprio 0
	s_barrier
	s_add_i32 s20, 0, 0x1c000
	s_add_i32 s21, s42, s25
	v_add_u32_e32 v195, s20, v140
	s_mov_b32 m0, s21
	ds_read_b128 v[196:199], v195
	ds_read_b128 v[202:205], v195 offset:1024
	ds_read_b128 v[206:209], v195 offset:2048
	ds_read_b128 v[210:213], v195 offset:3072
	global_load_lds_dwordx4 v128, s[98:99]
	s_add_i32 m0, s21, 0x2000
	s_nop 0
	global_load_lds_dwordx4 v130, s[98:99]
	s_barrier
	s_waitcnt lgkmcnt(0)
	s_setprio 1
	s_waitcnt lgkmcnt(0)
	v_mfma_f32_16x16x32_bf16 v[80:83], v[162:165], v[196:199], v[80:83]
	v_mfma_f32_16x16x32_bf16 v[48:51], v[162:165], v[206:209], v[48:51]
	v_mfma_f32_16x16x32_bf16 v[68:71], v[170:173], v[196:199], v[68:71]
	v_mfma_f32_16x16x32_bf16 v[40:43], v[170:173], v[206:209], v[40:43]
	v_mfma_f32_16x16x32_bf16 v[60:63], v[178:181], v[196:199], v[60:63]
	v_mfma_f32_16x16x32_bf16 v[36:39], v[178:181], v[206:209], v[36:39]
	v_mfma_f32_16x16x32_bf16 v[52:55], v[186:189], v[196:199], v[52:55]
	v_mfma_f32_16x16x32_bf16 v[28:31], v[186:189], v[206:209], v[28:31]
	v_mfma_f32_16x16x32_bf16 v[80:83], v[166:169], v[202:205], v[80:83]
	v_mfma_f32_16x16x32_bf16 v[48:51], v[166:169], v[210:213], v[48:51]
	v_mfma_f32_16x16x32_bf16 v[68:71], v[174:177], v[202:205], v[68:71]
	v_mfma_f32_16x16x32_bf16 v[40:43], v[174:177], v[210:213], v[40:43]
	v_mfma_f32_16x16x32_bf16 v[60:63], v[182:185], v[202:205], v[60:63]
	v_mfma_f32_16x16x32_bf16 v[36:39], v[182:185], v[210:213], v[36:39]
	v_mfma_f32_16x16x32_bf16 v[52:55], v[190:193], v[202:205], v[52:55]
	v_mfma_f32_16x16x32_bf16 v[28:31], v[190:193], v[210:213], v[28:31]
	s_setprio 0
	s_mov_b32 m0, s30
	s_barrier
	ds_read_b128 v[162:165], v144 offset:49152
	ds_read_b128 v[166:169], v144 offset:50176
	ds_read_b128 v[170:173], v144 offset:51200
	ds_read_b128 v[174:177], v144 offset:52224
	ds_read_b128 v[178:181], v144 offset:53248
	ds_read_b128 v[182:185], v144 offset:54272
	ds_read_b128 v[186:189], v144 offset:55296
	ds_read_b128 v[190:193], v144 offset:56320
	global_load_lds_dwordx4 v128, s[100:101]
	s_mov_b32 m0, s31
	s_nop 0
	global_load_lds_dwordx4 v130, s[100:101]
	s_barrier
; #define PG8_STAGE(bufoff, gbase, voff) do { _Pragma("unroll") for (int _i = 0; _i < 2; ++_i) \
;         __builtin_amdgcn_global_load_lds((const unsigned*)((const char*)(gbase) + (voff)[_i]), (LAS unsigned*)(lds + (bufoff) + ldsw + _i * 8192), 16, 0, 0); } while (0)
; #define PG8_WAIT_V(n) asm volatile("s_waitcnt vmcnt(" #n ")" ::: "memory")
; #define PG8_WAIT_L(n) asm volatile("s_waitcnt lgkmcnt(" #n ")" ::: "memory")
; #define PG8_BAR __builtin_amdgcn_s_barrier()
; #define PG8_SCHED __builtin_amdgcn_sched_barrier(0)
; template <class Epi>
; __device__ __forceinline__ void gemm_phase(LAS unsigned char* lds, const bf16_t* A, int lda, const bf16_t* Bt, int ldb, int M, int N, int K, int asel, const Epi& E, const int fixed_round = -1) {
;     ...
;             PG8_BAR; PG8_WAIT_L(0); PG8_MMA(1, 0, At, B0); PG8_BAR; PG8_SCHED;
;             PG8_STAGE(PG8_SB(1, 1), b3 + hstepB, voffB);
;             PG8_WAIT_V(6); PG8_BAR; PG8_MMA(1, 1, At, B1); PG8_BAR;
	s_waitcnt lgkmcnt(0)
	s_setprio 1
	s_waitcnt lgkmcnt(0)
	v_mfma_f32_16x16x32_bf16 v[96:99], v[162:165], v[146:149], v[96:99]
	v_mfma_f32_16x16x32_bf16 v[72:75], v[162:165], v[154:157], v[72:75]
	v_mfma_f32_16x16x32_bf16 v[88:91], v[170:173], v[146:149], v[88:91]
	v_mfma_f32_16x16x32_bf16 v[64:67], v[170:173], v[154:157], v[64:67]
	v_mfma_f32_16x16x32_bf16 v[84:87], v[178:181], v[146:149], v[84:87]
	v_mfma_f32_16x16x32_bf16 v[56:59], v[178:181], v[154:157], v[56:59]
	v_mfma_f32_16x16x32_bf16 v[76:79], v[186:189], v[146:149], v[76:79]
	v_mfma_f32_16x16x32_bf16 v[44:47], v[186:189], v[154:157], v[44:47]
	v_mfma_f32_16x16x32_bf16 v[96:99], v[166:169], v[150:153], v[96:99]
	v_mfma_f32_16x16x32_bf16 v[72:75], v[166:169], v[158:161], v[72:75]
	v_mfma_f32_16x16x32_bf16 v[88:91], v[174:177], v[150:153], v[88:91]
	v_mfma_f32_16x16x32_bf16 v[64:67], v[174:177], v[158:161], v[64:67]
	v_mfma_f32_16x16x32_bf16 v[84:87], v[182:185], v[150:153], v[84:87]
	v_mfma_f32_16x16x32_bf16 v[56:59], v[182:185], v[158:161], v[56:59]
	v_mfma_f32_16x16x32_bf16 v[76:79], v[190:193], v[150:153], v[76:79]
	v_mfma_f32_16x16x32_bf16 v[44:47], v[190:193], v[158:161], v[44:47]
	s_setprio 0
	s_barrier
	s_add_u32 s18, s18, 0x80080
	s_addc_u32 s19, s19, 0
	s_add_i32 s20, s20, s25
	s_mov_b32 m0, s20
	s_nop 0
	global_load_lds_dwordx4 v128, s[18:19]
	s_add_i32 m0, s20, 0x2000
	s_nop 0
	global_load_lds_dwordx4 v130, s[18:19]
	s_waitcnt vmcnt(6)
	s_barrier
	s_setprio 1
	v_mfma_f32_16x16x32_bf16 v[32:35], v[162:165], v[196:199], v[32:35]
	v_mfma_f32_16x16x32_bf16 v[12:15], v[162:165], v[206:209], v[12:15]
	v_mfma_f32_16x16x32_bf16 v[24:27], v[170:173], v[196:199], v[24:27]
	v_mfma_f32_16x16x32_bf16 v[8:11], v[170:173], v[206:209], v[8:11]
	v_mfma_f32_16x16x32_bf16 v[20:23], v[178:181], v[196:199], v[20:23]
	v_mfma_f32_16x16x32_bf16 v[4:7], v[178:181], v[206:209], v[4:7]
	v_mfma_f32_16x16x32_bf16 v[16:19], v[186:189], v[196:199], v[16:19]
	v_mfma_f32_16x16x32_bf16 v[0:3], v[186:189], v[206:209], v[0:3]
	v_mfma_f32_16x16x32_bf16 v[32:35], v[166:169], v[202:205], v[32:35]
	v_mfma_f32_16x16x32_bf16 v[12:15], v[166:169], v[210:213], v[12:15]
	v_mfma_f32_16x16x32_bf16 v[24:27], v[174:177], v[202:205], v[24:27]
	v_mfma_f32_16x16x32_bf16 v[8:11], v[174:177], v[210:213], v[8:11]
	v_mfma_f32_16x16x32_bf16 v[20:23], v[182:185], v[202:205], v[20:23]
	v_mfma_f32_16x16x32_bf16 v[4:7], v[182:185], v[210:213], v[4:7]
	v_mfma_f32_16x16x32_bf16 v[16:19], v[190:193], v[202:205], v[16:19]
	v_mfma_f32_16x16x32_bf16 v[0:3], v[190:193], v[210:213], v[0:3]
	s_setprio 0
	s_add_i32 s41, s41, 2
	s_add_u32 s16, s16, 0x100
	s_addc_u32 s17, s17, 0
	s_add_u32 s39, s39, 0x100
	s_addc_u32 s40, s40, 0
	s_cmp_gt_u32 s41, 29
	s_cbranch_scc0 .Lrot_2
	s_barrier
; __device__ __forceinline__ unsigned cvt_pk_bf16(float lo, float hi) { const bf16x2_t r = __builtin_convertvector((f32x2){lo, hi}, bf16x2_t); return __builtin_bit_cast(unsigned, r); }
; template <class Epi>
; __device__ __forceinline__ void gemm_phase(LAS unsigned char* lds, const bf16_t* A, int lda, const bf16_t* Bt, int ldb, int M, int N, int K, int asel, const Epi& E, const int fixed_round = -1) {
;     ...
;         if (!has_next) break;
;     __device__ __forceinline__ void operator()(const AccT& acc, const Unit& u, int wr, int wc, int fr, int fq) const {
;         const int bb = u.pm >> 4, s0 = (u.pm & 15) * BM + wr * 64 + 4 * fq, feat0 = u.pn * BM + wc * 32 + fr;
; #pragma unroll
;         for (int bj = 0; bj < 2; ++bj)
; #pragma unroll
;             for (int n = 0; n < 2; ++n) { bf16_t* fp = VT + ((size_t)bb * 2048 + feat0 + bj * HALF + n * 16) * SEQ + s0;
; #pragma unroll
;                 for (int ai = 0; ai < 2; ++ai)
; #pragma unroll
;                     for (int m = 0; m < 4; ++m) { const f32x4 v = acc[ai][bj][m][n]; u32x2 w; w.x = cvt_pk_bf16(v[0], v[1]); w.y = cvt_pk_bf16(v[2], v[3]);
;                         *(u32x2*)(fp + ai * HALF + m * 16) = w; } }
;     }
	s_ashr_i32 s16, s6, 4
	v_lshl_or_b32 v148, s36, 8, v142
	s_lshl_b32 s6, s6, 8
	s_ashr_i32 s17, s16, 31
	v_ashrrev_i32_e32 v149, 31, v148
	s_and_b32 s6, s6, 0xf00
	s_lshl_b64 s[16:17], s[16:17], 24
	v_lshlrev_b64 v[148:149], 13, v[148:149]
	v_add_u32_e32 v146, s6, v141
	v_lshl_add_u64 v[148:149], v[148:149], 0, s[16:17]
	v_readlane_b32 s16, v254, 47
	v_ashrrev_i32_e32 v147, 31, v146
	v_readlane_b32 s17, v254, 48
	v_lshlrev_b64 v[146:147], 1, v[146:147]
	v_cvt_pk_bf16_f32 v76, v76, v77
	v_lshl_add_u64 v[150:151], s[16:17], 0, v[148:149]
	v_lshl_add_u64 v[150:151], v[150:151], 0, v[146:147]
	v_cvt_pk_bf16_f32 v77, v78, v79
	global_store_dwordx2 v[150:151], v[76:77], off offset:352
	v_or_b32_e32 v76, 0x20000, v148
	v_mov_b32_e32 v77, v149
	v_lshl_add_u64 v[76:77], s[16:17], 0, v[76:77]
	v_cvt_pk_bf16_f32 v124, v124, v125
	v_cvt_pk_bf16_f32 v125, v126, v127
	v_cvt_pk_bf16_f32 v120, v120, v121
	v_cvt_pk_bf16_f32 v121, v122, v123
	v_cvt_pk_bf16_f32 v116, v116, v117
	v_cvt_pk_bf16_f32 v117, v118, v119
	v_cvt_pk_bf16_f32 v112, v112, v113
	v_cvt_pk_bf16_f32 v113, v114, v115
	v_cvt_pk_bf16_f32 v96, v96, v97
	v_cvt_pk_bf16_f32 v97, v98, v99
	v_cvt_pk_bf16_f32 v88, v88, v89
	v_cvt_pk_bf16_f32 v89, v90, v91
	v_cvt_pk_bf16_f32 v84, v84, v85
	v_cvt_pk_bf16_f32 v85, v86, v87
	v_lshl_add_u64 v[76:77], v[76:77], 0, v[146:147]
	v_cvt_pk_bf16_f32 v78, v108, v109
	v_cvt_pk_bf16_f32 v79, v110, v111
	v_cvt_pk_bf16_f32 v44, v44, v45
	v_cvt_pk_bf16_f32 v45, v46, v47
	global_store_dwordx2 v[150:151], v[124:125], off
	global_store_dwordx2 v[150:151], v[120:121], off offset:32
	global_store_dwordx2 v[150:151], v[116:117], off offset:64
	global_store_dwordx2 v[150:151], v[112:113], off offset:96
	global_store_dwordx2 v[150:151], v[96:97], off offset:256
	global_store_dwordx2 v[150:151], v[88:89], off offset:288
	global_store_dwordx2 v[150:151], v[84:85], off offset:320
	global_store_dwordx2 v[76:77], v[78:79], off
	v_cvt_pk_bf16_f32 v78, v104, v105
	v_cvt_pk_bf16_f32 v79, v106, v107
	global_store_dwordx2 v[76:77], v[44:45], off offset:352
	v_or_b32_e32 v44, 0x100000, v148
	v_mov_b32_e32 v45, v149
	global_store_dwordx2 v[76:77], v[78:79], off offset:32
	v_cvt_pk_bf16_f32 v78, v100, v101
	v_cvt_pk_bf16_f32 v79, v102, v103
	v_lshl_add_u64 v[44:45], s[16:17], 0, v[44:45]
	global_store_dwordx2 v[76:77], v[78:79], off offset:64
	v_cvt_pk_bf16_f32 v78, v92, v93
	v_cvt_pk_bf16_f32 v79, v94, v95
	v_cvt_pk_bf16_f32 v72, v72, v73
	v_cvt_pk_bf16_f32 v73, v74, v75
	v_cvt_pk_bf16_f32 v64, v64, v65
	v_cvt_pk_bf16_f32 v65, v66, v67
	v_cvt_pk_bf16_f32 v56, v56, v57
	v_cvt_pk_bf16_f32 v57, v58, v59
	v_lshl_add_u64 v[44:45], v[44:45], 0, v[146:147]
	v_cvt_pk_bf16_f32 v46, v80, v81
	v_cvt_pk_bf16_f32 v47, v82, v83
	global_store_dwordx2 v[76:77], v[78:79], off offset:96
	global_store_dwordx2 v[76:77], v[72:73], off offset:256
	global_store_dwordx2 v[76:77], v[64:65], off offset:288
	global_store_dwordx2 v[76:77], v[56:57], off offset:320
	global_store_dwordx2 v[44:45], v[46:47], off
	v_cvt_pk_bf16_f32 v46, v68, v69
	v_cvt_pk_bf16_f32 v47, v70, v71
	v_cvt_pk_bf16_f32 v16, v16, v17
	v_cvt_pk_bf16_f32 v17, v18, v19
	v_or_b32_e32 v148, 0x120000, v148
	global_store_dwordx2 v[44:45], v[46:47], off offset:32
	v_cvt_pk_bf16_f32 v46, v60, v61
	v_cvt_pk_bf16_f32 v47, v62, v63
	global_store_dwordx2 v[44:45], v[16:17], off offset:352
	v_lshl_add_u64 v[16:17], s[16:17], 0, v[148:149]
	global_store_dwordx2 v[44:45], v[46:47], off offset:64
	v_cvt_pk_bf16_f32 v46, v52, v53
	v_cvt_pk_bf16_f32 v47, v54, v55
	v_cvt_pk_bf16_f32 v32, v32, v33
	v_cvt_pk_bf16_f32 v33, v34, v35
	v_cvt_pk_bf16_f32 v24, v24, v25
	v_cvt_pk_bf16_f32 v25, v26, v27
	v_cvt_pk_bf16_f32 v20, v20, v21
	v_cvt_pk_bf16_f32 v21, v22, v23
	v_lshl_add_u64 v[16:17], v[16:17], 0, v[146:147]
	v_cvt_pk_bf16_f32 v18, v48, v49
	v_cvt_pk_bf16_f32 v19, v50, v51
	global_store_dwordx2 v[44:45], v[46:47], off offset:96
	global_store_dwordx2 v[44:45], v[32:33], off offset:256
	global_store_dwordx2 v[44:45], v[24:25], off offset:288
	global_store_dwordx2 v[44:45], v[20:21], off offset:320
	global_store_dwordx2 v[16:17], v[18:19], off
	v_cvt_pk_bf16_f32 v18, v40, v41
	v_cvt_pk_bf16_f32 v19, v42, v43
	global_store_dwordx2 v[16:17], v[18:19], off offset:32
	v_cvt_pk_bf16_f32 v18, v36, v37
	v_cvt_pk_bf16_f32 v19, v38, v39
	global_store_dwordx2 v[16:17], v[18:19], off offset:64
	v_cvt_pk_bf16_f32 v18, v28, v29
	v_cvt_pk_bf16_f32 v19, v30, v31
	v_cvt_pk_bf16_f32 v12, v12, v13
	v_cvt_pk_bf16_f32 v13, v14, v15
	v_cvt_pk_bf16_f32 v8, v8, v9
	v_cvt_pk_bf16_f32 v9, v10, v11
	v_cvt_pk_bf16_f32 v4, v4, v5
	v_cvt_pk_bf16_f32 v5, v6, v7
	v_cvt_pk_bf16_f32 v0, v0, v1
	v_cvt_pk_bf16_f32 v1, v2, v3
	s_and_b64 vcc, exec, s[4:5]
	s_mov_b32 s36, s8
	s_mov_b32 s6, s10
	s_mov_b64 s[18:19], s[14:15]
	s_mov_b64 s[16:17], s[12:13]
	global_store_dwordx2 v[16:17], v[18:19], off offset:96
	global_store_dwordx2 v[16:17], v[12:13], off offset:256
	global_store_dwordx2 v[16:17], v[8:9], off offset:288
	global_store_dwordx2 v[16:17], v[4:5], off offset:320
	global_store_dwordx2 v[16:17], v[0:1], off offset:352
	s_cbranch_vccz .LBB0_217
	s_waitcnt vmcnt(0)
	s_cmpk_gt_u32 s22, 0xff
	s_cbranch_scc1 .LBB0_228
	s_barrier

; template <class Epi>
; __device__ __forceinline__ void gemm_phase(LAS unsigned char* lds, const bf16_t* A, int lda, const bf16_t* Bt, int ldb, int M, int N, int K, int asel, const Epi& E, const int fixed_round = -1) {
;     ...
;         const bool has_next = (fixed_round < 0) && S.next(ui + 1, nxt);
;         const char* nA = has_next ? PG8_ABASE(nxt) : cA; const char* nB = has_next ? (const char*)Bt + (size_t)nxt.pn * tstepB : cB;
;     ...
; #pragma unroll
;         for (int a = 0; a < 2; ++a)
; #pragma unroll
;             for (int b = 0; b < 2; ++b)
; #pragma unroll
;                 for (int m = 0; m < 4; ++m)
; #pragma unroll
;                     for (int n = 0; n < 2; ++n) acc[a][b][m][n] = (f32x4){0.f, 0.f, 0.f, 0.f};
;         cur = nxt; cA = nA; cB = nB; ++ui;
.LBB0_244:
	s_ashr_i32 s19, s18, 31
	v_cmp_lt_i64_e32 vcc, s[20:21], v[144:145]
	s_lshl_b64 s[20:21], s[18:19], 20
	s_add_u32 s20, s72, s20
	s_addc_u32 s21, s73, s21
	s_and_b64 s[22:23], vcc, exec
	s_cselect_b32 s2, s21, s27
	s_cselect_b32 s19, s20, s26
	s_ashr_i32 s17, s16, 31
	s_lshl_b64 s[22:23], s[16:17], 20
	s_add_u32 s22, s34, s22
	s_addc_u32 s23, s35, s23
	s_and_b64 s[30:31], vcc, exec
	s_cselect_b32 s17, s23, s29
	s_cselect_b32 s54, s22, s28
	s_add_u32 s26, s26, 0x80080
	s_addc_u32 s27, s27, 0
	s_add_u32 s55, s28, 0x100
	v_mov_b32_e32 v0, 0
	s_addc_u32 s56, s29, 0
	s_mov_b32 s57, -2
	v_mov_b32_e32 v1, v0
	v_mov_b32_e32 v2, v0
	v_mov_b32_e32 v3, v0
	v_mov_b32_e32 v4, v0
	v_mov_b32_e32 v5, v0
	v_mov_b32_e32 v6, v0
	v_mov_b32_e32 v7, v0
	v_mov_b32_e32 v8, v0
	v_mov_b32_e32 v9, v0
	v_mov_b32_e32 v10, v0
	v_mov_b32_e32 v11, v0
	v_mov_b32_e32 v16, v0
	v_mov_b32_e32 v17, v0
	v_mov_b32_e32 v18, v0
	v_mov_b32_e32 v19, v0
	v_mov_b32_e32 v24, v0
	v_mov_b32_e32 v25, v0
	v_mov_b32_e32 v26, v0
	v_mov_b32_e32 v27, v0
	v_mov_b32_e32 v32, v0
	v_mov_b32_e32 v33, v0
	v_mov_b32_e32 v34, v0
	v_mov_b32_e32 v35, v0
	v_mov_b32_e32 v40, v0
	v_mov_b32_e32 v41, v0
	v_mov_b32_e32 v42, v0
	v_mov_b32_e32 v43, v0
	v_mov_b32_e32 v48, v0
	v_mov_b32_e32 v49, v0
	v_mov_b32_e32 v50, v0
	v_mov_b32_e32 v51, v0
	v_mov_b32_e32 v12, v0
	v_mov_b32_e32 v13, v0
	v_mov_b32_e32 v14, v0
	v_mov_b32_e32 v15, v0
	v_mov_b32_e32 v20, v0
	v_mov_b32_e32 v21, v0
	v_mov_b32_e32 v22, v0
	v_mov_b32_e32 v23, v0
	v_mov_b32_e32 v28, v0
	v_mov_b32_e32 v29, v0
	v_mov_b32_e32 v30, v0
	v_mov_b32_e32 v31, v0
	v_mov_b32_e32 v36, v0
	v_mov_b32_e32 v37, v0
	v_mov_b32_e32 v38, v0
	v_mov_b32_e32 v39, v0
	v_mov_b32_e32 v44, v0
	v_mov_b32_e32 v45, v0
	v_mov_b32_e32 v46, v0
	v_mov_b32_e32 v47, v0
	v_mov_b32_e32 v52, v0
	v_mov_b32_e32 v53, v0
	v_mov_b32_e32 v54, v0
	v_mov_b32_e32 v55, v0
	v_mov_b32_e32 v56, v0
	v_mov_b32_e32 v57, v0
	v_mov_b32_e32 v58, v0
	v_mov_b32_e32 v59, v0
	v_mov_b32_e32 v60, v0
	v_mov_b32_e32 v61, v0
	v_mov_b32_e32 v62, v0
	v_mov_b32_e32 v63, v0
	v_mov_b32_e32 v64, v0
	v_mov_b32_e32 v65, v0
	v_mov_b32_e32 v66, v0
	v_mov_b32_e32 v67, v0
	v_mov_b32_e32 v68, v0
	v_mov_b32_e32 v69, v0
	v_mov_b32_e32 v70, v0
	v_mov_b32_e32 v71, v0
	v_mov_b32_e32 v72, v0
	v_mov_b32_e32 v73, v0
	v_mov_b32_e32 v74, v0
	v_mov_b32_e32 v75, v0
	v_mov_b32_e32 v80, v0
	v_mov_b32_e32 v81, v0
	v_mov_b32_e32 v82, v0
	v_mov_b32_e32 v83, v0
	v_mov_b32_e32 v88, v0
	v_mov_b32_e32 v89, v0
	v_mov_b32_e32 v90, v0
	v_mov_b32_e32 v91, v0
	v_mov_b32_e32 v96, v0
	v_mov_b32_e32 v97, v0
	v_mov_b32_e32 v98, v0
	v_mov_b32_e32 v99, v0
	v_mov_b32_e32 v104, v0
	v_mov_b32_e32 v105, v0
	v_mov_b32_e32 v106, v0
	v_mov_b32_e32 v107, v0
	v_mov_b32_e32 v116, v0
	v_mov_b32_e32 v117, v0
	v_mov_b32_e32 v118, v0
	v_mov_b32_e32 v119, v0
	v_mov_b32_e32 v76, v0
	v_mov_b32_e32 v77, v0
	v_mov_b32_e32 v78, v0
	v_mov_b32_e32 v79, v0
	v_mov_b32_e32 v84, v0
	v_mov_b32_e32 v85, v0
	v_mov_b32_e32 v86, v0
	v_mov_b32_e32 v87, v0
	v_mov_b32_e32 v92, v0
	v_mov_b32_e32 v93, v0
	v_mov_b32_e32 v94, v0
	v_mov_b32_e32 v95, v0
	v_mov_b32_e32 v100, v0
	v_mov_b32_e32 v101, v0
	v_mov_b32_e32 v102, v0
	v_mov_b32_e32 v103, v0
	v_mov_b32_e32 v108, v0
	v_mov_b32_e32 v109, v0
	v_mov_b32_e32 v110, v0
	v_mov_b32_e32 v111, v0
	v_mov_b32_e32 v112, v0
	v_mov_b32_e32 v113, v0
	v_mov_b32_e32 v114, v0
	v_mov_b32_e32 v115, v0
	v_mov_b32_e32 v120, v0
	v_mov_b32_e32 v121, v0
	v_mov_b32_e32 v122, v0
	v_mov_b32_e32 v123, v0
	v_mov_b32_e32 v124, v0
	v_mov_b32_e32 v125, v0
	v_mov_b32_e32 v126, v0
	v_mov_b32_e32 v127, v0
	s_branch .LBB0_245

; #define PG8_STAGE(bufoff, gbase, voff) do { _Pragma("unroll") for (int _i = 0; _i < 2; ++_i) \
;         __builtin_amdgcn_global_load_lds((const unsigned*)((const char*)(gbase) + (voff)[_i]), (LAS unsigned*)(lds + (bufoff) + ldsw + _i * 8192), 16, 0, 0); } while (0)
; #define PG8_LDA(dst, b, h) do { _Pragma("unroll") for (int m = 0; m < 4; ++m) _Pragma("unroll") for (int k = 0; k < 2; ++k) dst[m][k] = *(const LAS bf16x8*)(lds + PG8_SA(b, h) + aoff + m * 2048 + k * 1024); } while (0)
; #define PG8_LDB(dst, b, h) do { _Pragma("unroll") for (int n = 0; n < 2; ++n) _Pragma("unroll") for (int k = 0; k < 2; ++k) dst[n][k] = *(const LAS bf16x8*)(lds + PG8_SB(b, h) + boff + n * 2048 + k * 1024); } while (0)
; #define PG8_WAIT_V(n) asm volatile("s_waitcnt vmcnt(" #n ")" ::: "memory")
; #define PG8_WAIT_L(n) asm volatile("s_waitcnt lgkmcnt(" #n ")" ::: "memory")
; #define PG8_BAR __builtin_amdgcn_s_barrier()
; template <class Epi>
; __device__ __forceinline__ void gemm_phase(LAS unsigned char* lds, const bf16_t* A, int lda, const bf16_t* Bt, int ldb, int M, int N, int K, int asel, const Epi& E, const int fixed_round = -1) {
;     ...
;             PG8_LDB(B0, 0, 0); PG8_SCHED; PG8_LDA(At, 0, 0); PG8_STAGE(PG8_SA(1, 1), a1 + hstepA, voffA);
;             PG8_WAIT_L(8); PG8_BAR; PG8_WAIT_L(0); PG8_MMA(0, 0, At, B0); PG8_BAR; PG8_SCHED;
;             PG8_LDB(B1, 0, 1); PG8_STAGE(PG8_SB(0, 0), b2, voffB);
;             PG8_BAR; PG8_WAIT_L(0); PG8_MMA(0, 1, At, B1); PG8_BAR;
;             PG8_LDA(At, 0, 1); PG8_STAGE(PG8_SA(0, 0), a2, voffA);
;             PG8_BAR; PG8_WAIT_L(0); PG8_MMA(1, 0, At, B0); PG8_BAR; PG8_SCHED;
;             PG8_STAGE(PG8_SB(0, 1), b2 + hstepB, voffB);
;             PG8_WAIT_V(6); PG8_BAR; PG8_MMA(1, 1, At, B1); PG8_BAR;
;             PG8_LDB(B0, 1, 0); PG8_SCHED; PG8_LDA(At, 1, 0); PG8_STAGE(PG8_SA(0, 1), a2 + hstepA, voffA);
;             PG8_WAIT_L(8); PG8_BAR; PG8_WAIT_L(0); PG8_MMA(0, 0, At, B0); PG8_BAR; PG8_SCHED;
;             PG8_LDB(B1, 1, 1); PG8_STAGE(PG8_SB(1, 0), b3, voffB);
;             PG8_BAR; PG8_WAIT_L(0); PG8_MMA(0, 1, At, B1); PG8_BAR;
;             PG8_LDA(At, 1, 1); PG8_STAGE(PG8_SA(1, 0), a3, voffA);
;             PG8_BAR; PG8_WAIT_L(0); PG8_MMA(1, 0, At, B0); PG8_BAR; PG8_SCHED;
;             PG8_STAGE(PG8_SB(1, 1), b3 + hstepB, voffB);
;             PG8_WAIT_V(6); PG8_BAR; PG8_MMA(1, 1, At, B1); PG8_BAR;
.LBB0_245:
	ds_read_b128 v[148:151], v161
	ds_read_b128 v[152:155], v161 offset:1024
	ds_read_b128 v[156:159], v161 offset:2048
	ds_read_b128 v[166:169], v161 offset:3072
	s_add_u32 s28, s26, 0xfff80080
	s_addc_u32 s29, s27, -1
	s_cmp_eq_u32 s57, 28
	s_cselect_b32 s31, s2, s29
	s_cselect_b32 s30, s19, s28
	s_cselect_b32 s29, s17, s56
	s_cselect_b32 s28, s54, s55
	s_add_i32 m0, s37, 0xc000
	ds_read_b128 v[170:173], v162
	ds_read_b128 v[174:177], v162 offset:1024
	ds_read_b128 v[178:181], v162 offset:2048
	ds_read_b128 v[182:185], v162 offset:3072
	ds_read_b128 v[186:189], v162 offset:4096
	ds_read_b128 v[190:193], v162 offset:5120
	ds_read_b128 v[196:199], v162 offset:6144
	ds_read_b128 v[202:205], v162 offset:7168
	global_load_lds_dwordx4 v140, s[26:27]
	s_add_i32 m0, s37, 0xe000
	s_nop 0
	global_load_lds_dwordx4 v142, s[26:27]
	s_waitcnt lgkmcnt(8)
	s_barrier
	s_waitcnt lgkmcnt(0)
	s_setprio 1
	s_waitcnt lgkmcnt(0)
	v_mfma_f32_16x16x32_bf16 v[124:127], v[148:151], v[170:173], v[124:127]
	v_mfma_f32_16x16x32_bf16 v[120:123], v[156:159], v[170:173], v[120:123]
	v_mfma_f32_16x16x32_bf16 v[112:115], v[148:151], v[178:181], v[112:115]
	v_mfma_f32_16x16x32_bf16 v[108:111], v[156:159], v[178:181], v[108:111]
	v_mfma_f32_16x16x32_bf16 v[100:103], v[148:151], v[186:189], v[100:103]
	v_mfma_f32_16x16x32_bf16 v[92:95], v[156:159], v[186:189], v[92:95]
	v_mfma_f32_16x16x32_bf16 v[84:87], v[148:151], v[196:199], v[84:87]
	v_mfma_f32_16x16x32_bf16 v[76:79], v[156:159], v[196:199], v[76:79]
	v_mfma_f32_16x16x32_bf16 v[124:127], v[152:155], v[174:177], v[124:127]
	v_mfma_f32_16x16x32_bf16 v[120:123], v[166:169], v[174:177], v[120:123]
	v_mfma_f32_16x16x32_bf16 v[112:115], v[152:155], v[182:185], v[112:115]
	v_mfma_f32_16x16x32_bf16 v[108:111], v[166:169], v[182:185], v[108:111]
	v_mfma_f32_16x16x32_bf16 v[100:103], v[152:155], v[190:193], v[100:103]
	v_mfma_f32_16x16x32_bf16 v[92:95], v[166:169], v[190:193], v[92:95]
	v_mfma_f32_16x16x32_bf16 v[84:87], v[152:155], v[202:205], v[84:87]
	v_mfma_f32_16x16x32_bf16 v[76:79], v[166:169], v[202:205], v[76:79]
	s_setprio 0
	s_barrier
	s_add_i32 s58, s44, s36
	s_add_u32 s98, s28, s4
	s_addc_u32 s99, s29, s5
	s_mov_b32 m0, s58
	ds_read_b128 v[206:209], v163
	ds_read_b128 v[210:213], v163 offset:1024
	ds_read_b128 v[214:217], v163 offset:2048
	ds_read_b128 v[218:221], v163 offset:3072
	global_load_lds_dwordx4 v130, s[28:29]
	s_add_i32 m0, s58, 0x2000
	s_nop 0
	global_load_lds_dwordx4 v134, s[28:29]
	s_barrier
	s_waitcnt lgkmcnt(0)
	s_setprio 1
	s_waitcnt lgkmcnt(0)
	v_mfma_f32_16x16x32_bf16 v[116:119], v[206:209], v[170:173], v[116:119]
	v_mfma_f32_16x16x32_bf16 v[104:107], v[214:217], v[170:173], v[104:107]
	v_mfma_f32_16x16x32_bf16 v[96:99], v[206:209], v[178:181], v[96:99]
	v_mfma_f32_16x16x32_bf16 v[88:91], v[214:217], v[178:181], v[88:91]
	v_mfma_f32_16x16x32_bf16 v[80:83], v[206:209], v[186:189], v[80:83]
	v_mfma_f32_16x16x32_bf16 v[72:75], v[214:217], v[186:189], v[72:75]
	v_mfma_f32_16x16x32_bf16 v[68:71], v[206:209], v[196:199], v[68:71]
	v_mfma_f32_16x16x32_bf16 v[64:67], v[214:217], v[196:199], v[64:67]
	v_mfma_f32_16x16x32_bf16 v[116:119], v[210:213], v[174:177], v[116:119]
	v_mfma_f32_16x16x32_bf16 v[104:107], v[218:221], v[174:177], v[104:107]
	v_mfma_f32_16x16x32_bf16 v[96:99], v[210:213], v[182:185], v[96:99]
	v_mfma_f32_16x16x32_bf16 v[88:91], v[218:221], v[182:185], v[88:91]
	v_mfma_f32_16x16x32_bf16 v[80:83], v[210:213], v[190:193], v[80:83]
	v_mfma_f32_16x16x32_bf16 v[72:75], v[218:221], v[190:193], v[72:75]
	v_mfma_f32_16x16x32_bf16 v[68:71], v[210:213], v[202:205], v[68:71]
	v_mfma_f32_16x16x32_bf16 v[64:67], v[218:221], v[202:205], v[64:67]
	s_setprio 0
	s_mov_b32 m0, s37
	s_add_u32 s100, s30, s4
	s_addc_u32 s101, s31, s5
	s_barrier
	ds_read_b128 v[170:173], v162 offset:16384
	ds_read_b128 v[174:177], v162 offset:17408
	ds_read_b128 v[178:181], v162 offset:18432
	ds_read_b128 v[182:185], v162 offset:19456
	ds_read_b128 v[186:189], v162 offset:20480
	ds_read_b128 v[190:193], v162 offset:21504
	ds_read_b128 v[196:199], v162 offset:22528
	ds_read_b128 v[202:205], v162 offset:23552
	global_load_lds_dwordx4 v128, s[30:31]
	s_mov_b32 m0, s38
	s_nop 0
	global_load_lds_dwordx4 v132, s[30:31]
	s_barrier
	s_waitcnt lgkmcnt(0)
	s_setprio 1
	s_waitcnt lgkmcnt(0)
	v_mfma_f32_16x16x32_bf16 v[60:63], v[148:151], v[170:173], v[60:63]
	v_mfma_f32_16x16x32_bf16 v[56:59], v[156:159], v[170:173], v[56:59]
	v_mfma_f32_16x16x32_bf16 v[52:55], v[148:151], v[178:181], v[52:55]
	v_mfma_f32_16x16x32_bf16 v[44:47], v[156:159], v[178:181], v[44:47]
	v_mfma_f32_16x16x32_bf16 v[36:39], v[148:151], v[186:189], v[36:39]
	v_mfma_f32_16x16x32_bf16 v[28:31], v[156:159], v[186:189], v[28:31]
	v_mfma_f32_16x16x32_bf16 v[20:23], v[148:151], v[196:199], v[20:23]
	v_mfma_f32_16x16x32_bf16 v[12:15], v[156:159], v[196:199], v[12:15]
	v_mfma_f32_16x16x32_bf16 v[60:63], v[152:155], v[174:177], v[60:63]
	v_mfma_f32_16x16x32_bf16 v[56:59], v[166:169], v[174:177], v[56:59]
	v_mfma_f32_16x16x32_bf16 v[52:55], v[152:155], v[182:185], v[52:55]
	v_mfma_f32_16x16x32_bf16 v[44:47], v[166:169], v[182:185], v[44:47]
	v_mfma_f32_16x16x32_bf16 v[36:39], v[152:155], v[190:193], v[36:39]
	v_mfma_f32_16x16x32_bf16 v[28:31], v[166:169], v[190:193], v[28:31]
	v_mfma_f32_16x16x32_bf16 v[20:23], v[152:155], v[202:205], v[20:23]
	v_mfma_f32_16x16x32_bf16 v[12:15], v[166:169], v[202:205], v[12:15]
	s_setprio 0
	s_barrier
	s_add_u32 s58, s28, 0x80000
	s_addc_u32 s59, s29, 0
	s_add_i32 s60, s45, s36
	s_mov_b32 m0, s60
	s_nop 0
	global_load_lds_dwordx4 v130, s[58:59]
	s_add_i32 m0, s60, 0x2000
	s_nop 0
	global_load_lds_dwordx4 v134, s[58:59]
	s_waitcnt vmcnt(6)
	s_barrier
; #define PG8_STAGE(bufoff, gbase, voff) do { _Pragma("unroll") for (int _i = 0; _i < 2; ++_i) \
;         __builtin_amdgcn_global_load_lds((const unsigned*)((const char*)(gbase) + (voff)[_i]), (LAS unsigned*)(lds + (bufoff) + ldsw + _i * 8192), 16, 0, 0); } while (0)
; #define PG8_LDA(dst, b, h) do { _Pragma("unroll") for (int m = 0; m < 4; ++m) _Pragma("unroll") for (int k = 0; k < 2; ++k) dst[m][k] = *(const LAS bf16x8*)(lds + PG8_SA(b, h) + aoff + m * 2048 + k * 1024); } while (0)
; #define PG8_LDB(dst, b, h) do { _Pragma("unroll") for (int n = 0; n < 2; ++n) _Pragma("unroll") for (int k = 0; k < 2; ++k) dst[n][k] = *(const LAS bf16x8*)(lds + PG8_SB(b, h) + boff + n * 2048 + k * 1024); } while (0)
; #define PG8_WAIT_V(n) asm volatile("s_waitcnt vmcnt(" #n ")" ::: "memory")
; #define PG8_WAIT_L(n) asm volatile("s_waitcnt lgkmcnt(" #n ")" ::: "memory")
; #define PG8_BAR __builtin_amdgcn_s_barrier()
; template <class Epi>
; __device__ __forceinline__ void gemm_phase(LAS unsigned char* lds, const bf16_t* A, int lda, const bf16_t* Bt, int ldb, int M, int N, int K, int asel, const Epi& E, const int fixed_round = -1) {
;     ...
;             PG8_LDB(B0, 0, 0); PG8_SCHED; PG8_LDA(At, 0, 0); PG8_STAGE(PG8_SA(1, 1), a1 + hstepA, voffA);
;             PG8_WAIT_L(8); PG8_BAR; PG8_WAIT_L(0); PG8_MMA(0, 0, At, B0); PG8_BAR; PG8_SCHED;
;             PG8_LDB(B1, 0, 1); PG8_STAGE(PG8_SB(0, 0), b2, voffB);
;             PG8_BAR; PG8_WAIT_L(0); PG8_MMA(0, 1, At, B1); PG8_BAR;
;             PG8_LDA(At, 0, 1); PG8_STAGE(PG8_SA(0, 0), a2, voffA);
;             PG8_BAR; PG8_WAIT_L(0); PG8_MMA(1, 0, At, B0); PG8_BAR; PG8_SCHED;
;             PG8_STAGE(PG8_SB(0, 1), b2 + hstepB, voffB);
;             PG8_WAIT_V(6); PG8_BAR; PG8_MMA(1, 1, At, B1); PG8_BAR;
;             PG8_LDB(B0, 1, 0); PG8_SCHED; PG8_LDA(At, 1, 0); PG8_STAGE(PG8_SA(0, 1), a2 + hstepA, voffA);
;             PG8_WAIT_L(8); PG8_BAR; PG8_WAIT_L(0); PG8_MMA(0, 0, At, B0); PG8_BAR; PG8_SCHED;
;             PG8_LDB(B1, 1, 1); PG8_STAGE(PG8_SB(1, 0), b3, voffB);
;             PG8_BAR; PG8_WAIT_L(0); PG8_MMA(0, 1, At, B1); PG8_BAR;
;             PG8_LDA(At, 1, 1); PG8_STAGE(PG8_SA(1, 0), a3, voffA);
;             PG8_BAR; PG8_WAIT_L(0); PG8_MMA(1, 0, At, B0); PG8_BAR; PG8_SCHED;
;             PG8_STAGE(PG8_SB(1, 1), b3 + hstepB, voffB);
;             PG8_WAIT_V(6); PG8_BAR; PG8_MMA(1, 1, At, B1); PG8_BAR;
	s_setprio 1
	v_mfma_f32_16x16x32_bf16 v[48:51], v[206:209], v[170:173], v[48:51]
	v_mfma_f32_16x16x32_bf16 v[40:43], v[214:217], v[170:173], v[40:43]
	v_mfma_f32_16x16x32_bf16 v[32:35], v[206:209], v[178:181], v[32:35]
	v_mfma_f32_16x16x32_bf16 v[24:27], v[214:217], v[178:181], v[24:27]
	v_mfma_f32_16x16x32_bf16 v[16:19], v[206:209], v[186:189], v[16:19]
	v_mfma_f32_16x16x32_bf16 v[8:11], v[214:217], v[186:189], v[8:11]
	v_mfma_f32_16x16x32_bf16 v[4:7], v[206:209], v[196:199], v[4:7]
	v_mfma_f32_16x16x32_bf16 v[0:3], v[214:217], v[196:199], v[0:3]
	v_mfma_f32_16x16x32_bf16 v[48:51], v[210:213], v[174:177], v[48:51]
	v_mfma_f32_16x16x32_bf16 v[40:43], v[218:221], v[174:177], v[40:43]
	v_mfma_f32_16x16x32_bf16 v[32:35], v[210:213], v[182:185], v[32:35]
	v_mfma_f32_16x16x32_bf16 v[24:27], v[218:221], v[182:185], v[24:27]
	v_mfma_f32_16x16x32_bf16 v[16:19], v[210:213], v[190:193], v[16:19]
	v_mfma_f32_16x16x32_bf16 v[8:11], v[218:221], v[190:193], v[8:11]
	v_mfma_f32_16x16x32_bf16 v[4:7], v[210:213], v[202:205], v[4:7]
	v_mfma_f32_16x16x32_bf16 v[0:3], v[218:221], v[202:205], v[0:3]
	s_setprio 0
	s_add_i32 s58, 0, 0x18000
	v_add_u32_e32 v136, s58, v160
	s_barrier
	ds_read_b128 v[148:151], v136
	ds_read_b128 v[152:155], v136 offset:1024
	ds_read_b128 v[156:159], v136 offset:2048
	ds_read_b128 v[166:169], v136 offset:3072
	s_add_u32 s30, s30, 0x80000
	s_addc_u32 s31, s31, 0
	s_mov_b32 m0, s39
	ds_read_b128 v[170:173], v162 offset:32768
	ds_read_b128 v[174:177], v162 offset:33792
	ds_read_b128 v[178:181], v162 offset:34816
	ds_read_b128 v[182:185], v162 offset:35840
	ds_read_b128 v[186:189], v162 offset:36864
	ds_read_b128 v[190:193], v162 offset:37888
	ds_read_b128 v[196:199], v162 offset:38912
	ds_read_b128 v[202:205], v162 offset:39936
	global_load_lds_dwordx4 v128, s[30:31]
	s_mov_b32 m0, s40
	s_nop 0
	global_load_lds_dwordx4 v132, s[30:31]
	s_waitcnt lgkmcnt(8)
	s_barrier
	s_waitcnt lgkmcnt(0)
	s_setprio 1
	s_waitcnt lgkmcnt(0)
	v_mfma_f32_16x16x32_bf16 v[124:127], v[148:151], v[170:173], v[124:127]
	v_mfma_f32_16x16x32_bf16 v[120:123], v[156:159], v[170:173], v[120:123]
	v_mfma_f32_16x16x32_bf16 v[112:115], v[148:151], v[178:181], v[112:115]
	v_mfma_f32_16x16x32_bf16 v[108:111], v[156:159], v[178:181], v[108:111]
	v_mfma_f32_16x16x32_bf16 v[100:103], v[148:151], v[186:189], v[100:103]
	v_mfma_f32_16x16x32_bf16 v[92:95], v[156:159], v[186:189], v[92:95]
	v_mfma_f32_16x16x32_bf16 v[84:87], v[148:151], v[196:199], v[84:87]
	v_mfma_f32_16x16x32_bf16 v[76:79], v[156:159], v[196:199], v[76:79]
	v_mfma_f32_16x16x32_bf16 v[124:127], v[152:155], v[174:177], v[124:127]
	v_mfma_f32_16x16x32_bf16 v[120:123], v[166:169], v[174:177], v[120:123]
	v_mfma_f32_16x16x32_bf16 v[112:115], v[152:155], v[182:185], v[112:115]
	v_mfma_f32_16x16x32_bf16 v[108:111], v[166:169], v[182:185], v[108:111]
	v_mfma_f32_16x16x32_bf16 v[100:103], v[152:155], v[190:193], v[100:103]
	v_mfma_f32_16x16x32_bf16 v[92:95], v[166:169], v[190:193], v[92:95]
	v_mfma_f32_16x16x32_bf16 v[84:87], v[152:155], v[202:205], v[84:87]
	v_mfma_f32_16x16x32_bf16 v[76:79], v[166:169], v[202:205], v[76:79]
	s_setprio 0
	s_barrier
	s_add_i32 s30, 0, 0x1c000
	s_add_i32 s31, s58, s36
	v_add_u32_e32 v136, s30, v160
	s_mov_b32 m0, s31
	ds_read_b128 v[206:209], v136
	ds_read_b128 v[210:213], v136 offset:1024
	ds_read_b128 v[214:217], v136 offset:2048
	ds_read_b128 v[218:221], v136 offset:3072
	global_load_lds_dwordx4 v130, s[98:99]
	s_add_i32 m0, s31, 0x2000
	s_nop 0
	global_load_lds_dwordx4 v134, s[98:99]
	s_barrier
	s_waitcnt lgkmcnt(0)
	s_setprio 1
	s_waitcnt lgkmcnt(0)
	v_mfma_f32_16x16x32_bf16 v[116:119], v[206:209], v[170:173], v[116:119]
	v_mfma_f32_16x16x32_bf16 v[104:107], v[214:217], v[170:173], v[104:107]
	v_mfma_f32_16x16x32_bf16 v[96:99], v[206:209], v[178:181], v[96:99]
	v_mfma_f32_16x16x32_bf16 v[88:91], v[214:217], v[178:181], v[88:91]
	v_mfma_f32_16x16x32_bf16 v[80:83], v[206:209], v[186:189], v[80:83]
	v_mfma_f32_16x16x32_bf16 v[72:75], v[214:217], v[186:189], v[72:75]
	v_mfma_f32_16x16x32_bf16 v[68:71], v[206:209], v[196:199], v[68:71]
	v_mfma_f32_16x16x32_bf16 v[64:67], v[214:217], v[196:199], v[64:67]
	v_mfma_f32_16x16x32_bf16 v[116:119], v[210:213], v[174:177], v[116:119]
	v_mfma_f32_16x16x32_bf16 v[104:107], v[218:221], v[174:177], v[104:107]
	v_mfma_f32_16x16x32_bf16 v[96:99], v[210:213], v[182:185], v[96:99]
	v_mfma_f32_16x16x32_bf16 v[88:91], v[218:221], v[182:185], v[88:91]
	v_mfma_f32_16x16x32_bf16 v[80:83], v[210:213], v[190:193], v[80:83]
	v_mfma_f32_16x16x32_bf16 v[72:75], v[218:221], v[190:193], v[72:75]
	v_mfma_f32_16x16x32_bf16 v[68:71], v[210:213], v[202:205], v[68:71]
	v_mfma_f32_16x16x32_bf16 v[64:67], v[218:221], v[202:205], v[64:67]
	s_setprio 0
	s_mov_b32 m0, s41
	s_barrier
	ds_read_b128 v[170:173], v162 offset:49152
	ds_read_b128 v[174:177], v162 offset:50176
	ds_read_b128 v[178:181], v162 offset:51200
	ds_read_b128 v[182:185], v162 offset:52224
	ds_read_b128 v[186:189], v162 offset:53248
	ds_read_b128 v[190:193], v162 offset:54272
	ds_read_b128 v[196:199], v162 offset:55296
	ds_read_b128 v[202:205], v162 offset:56320
	global_load_lds_dwordx4 v128, s[100:101]
	s_mov_b32 m0, s42
	s_nop 0
	global_load_lds_dwordx4 v132, s[100:101]
	s_barrier
; __device__ __forceinline__ unsigned cvt_pk_bf16(float lo, float hi) { const bf16x2_t r = __builtin_convertvector((f32x2){lo, hi}, bf16x2_t); return __builtin_bit_cast(unsigned, r); }
; #define PG8_STAGE(bufoff, gbase, voff) do { _Pragma("unroll") for (int _i = 0; _i < 2; ++_i) \
;         __builtin_amdgcn_global_load_lds((const unsigned*)((const char*)(gbase) + (voff)[_i]), (LAS unsigned*)(lds + (bufoff) + ldsw + _i * 8192), 16, 0, 0); } while (0)
; #define PG8_WAIT_V(n) asm volatile("s_waitcnt vmcnt(" #n ")" ::: "memory")
; #define PG8_WAIT_L(n) asm volatile("s_waitcnt lgkmcnt(" #n ")" ::: "memory")
; template <class Epi>
; __device__ __forceinline__ void gemm_phase(LAS unsigned char* lds, const bf16_t* A, int lda, const bf16_t* Bt, int ldb, int M, int N, int K, int asel, const Epi& E, const int fixed_round = -1) {
;     ...
;             PG8_WAIT_V(6); PG8_BAR; PG8_MMA(1, 1, At, B1); PG8_BAR;
;             PG8_LDB(B0, 1, 0); PG8_SCHED; PG8_LDA(At, 1, 0); PG8_STAGE(PG8_SA(0, 1), a2 + hstepA, voffA);
;             PG8_WAIT_L(8); PG8_BAR; PG8_WAIT_L(0); PG8_MMA(0, 0, At, B0); PG8_BAR; PG8_SCHED;
;             PG8_LDB(B1, 1, 1); PG8_STAGE(PG8_SB(1, 0), b3, voffB);
;             PG8_BAR; PG8_WAIT_L(0); PG8_MMA(0, 1, At, B1); PG8_BAR;
;             PG8_LDA(At, 1, 1); PG8_STAGE(PG8_SA(1, 0), a3, voffA);
;             PG8_BAR; PG8_WAIT_L(0); PG8_MMA(1, 0, At, B0); PG8_BAR; PG8_SCHED;
;             PG8_STAGE(PG8_SB(1, 1), b3 + hstepB, voffB);
;             PG8_WAIT_V(6); PG8_BAR; PG8_MMA(1, 1, At, B1); PG8_BAR;
;     __device__ __forceinline__ void operator()(const AccT& acc, const Unit& u, int wr, int wc, int fr, int fq) const {
;     ...
;         if (pn < 8) {
;             bf16_t* base = pn < 4 ? Q : Kn; const int colt = (pn & 3) * BM; const float sc = pn < 4 ? 0.08838834764831845f : 1.0f;
; #pragma unroll
;             for (int ai = 0; ai < 2; ++ai)
; #pragma unroll
;                 for (int m = 0; m < 4; ++m) { bf16_t* rowp = base + (size_t)(row0 + ai * HALF + m * 16) * 1024 + colt + cl;
; #pragma unroll
;                     for (int bj = 0; bj < 2; ++bj) { const f32x4 v0 = acc[ai][bj][m][0] * sc, v1 = acc[ai][bj][m][1] * sc;
;                         u32x4 w; w.x = cvt_pk_bf16(v0[0], v0[1]); w.y = cvt_pk_bf16(v0[2], v0[3]); w.z = cvt_pk_bf16(v1[0], v1[1]); w.w = cvt_pk_bf16(v1[2], v1[3]);
;                         *(u32x4*)(rowp + bj * HALF) = w; } }
	s_waitcnt lgkmcnt(0)
	s_setprio 1
	s_waitcnt lgkmcnt(0)
	v_mfma_f32_16x16x32_bf16 v[60:63], v[148:151], v[170:173], v[60:63]
	v_mfma_f32_16x16x32_bf16 v[56:59], v[156:159], v[170:173], v[56:59]
	v_mfma_f32_16x16x32_bf16 v[52:55], v[148:151], v[178:181], v[52:55]
	v_mfma_f32_16x16x32_bf16 v[44:47], v[156:159], v[178:181], v[44:47]
	v_mfma_f32_16x16x32_bf16 v[36:39], v[148:151], v[186:189], v[36:39]
	v_mfma_f32_16x16x32_bf16 v[28:31], v[156:159], v[186:189], v[28:31]
	v_mfma_f32_16x16x32_bf16 v[20:23], v[148:151], v[196:199], v[20:23]
	v_mfma_f32_16x16x32_bf16 v[12:15], v[156:159], v[196:199], v[12:15]
	v_mfma_f32_16x16x32_bf16 v[60:63], v[152:155], v[174:177], v[60:63]
	v_mfma_f32_16x16x32_bf16 v[56:59], v[166:169], v[174:177], v[56:59]
	v_mfma_f32_16x16x32_bf16 v[52:55], v[152:155], v[182:185], v[52:55]
	v_mfma_f32_16x16x32_bf16 v[44:47], v[166:169], v[182:185], v[44:47]
	v_mfma_f32_16x16x32_bf16 v[36:39], v[152:155], v[190:193], v[36:39]
	v_mfma_f32_16x16x32_bf16 v[28:31], v[166:169], v[190:193], v[28:31]
	v_mfma_f32_16x16x32_bf16 v[20:23], v[152:155], v[202:205], v[20:23]
	v_mfma_f32_16x16x32_bf16 v[12:15], v[166:169], v[202:205], v[12:15]
	s_setprio 0
	s_barrier
	s_add_u32 s28, s28, 0x80080
	s_addc_u32 s29, s29, 0
	s_add_i32 s30, s30, s36
	s_mov_b32 m0, s30
	s_nop 0
	global_load_lds_dwordx4 v130, s[28:29]
	s_add_i32 m0, s30, 0x2000
	s_nop 0
	global_load_lds_dwordx4 v134, s[28:29]
	s_waitcnt vmcnt(6)
	s_barrier
	s_setprio 1
	v_mfma_f32_16x16x32_bf16 v[48:51], v[206:209], v[170:173], v[48:51]
	v_mfma_f32_16x16x32_bf16 v[40:43], v[214:217], v[170:173], v[40:43]
	v_mfma_f32_16x16x32_bf16 v[32:35], v[206:209], v[178:181], v[32:35]
	v_mfma_f32_16x16x32_bf16 v[24:27], v[214:217], v[178:181], v[24:27]
	v_mfma_f32_16x16x32_bf16 v[16:19], v[206:209], v[186:189], v[16:19]
	v_mfma_f32_16x16x32_bf16 v[8:11], v[214:217], v[186:189], v[8:11]
	v_mfma_f32_16x16x32_bf16 v[4:7], v[206:209], v[196:199], v[4:7]
	v_mfma_f32_16x16x32_bf16 v[0:3], v[214:217], v[196:199], v[0:3]
	v_mfma_f32_16x16x32_bf16 v[48:51], v[210:213], v[174:177], v[48:51]
	v_mfma_f32_16x16x32_bf16 v[40:43], v[218:221], v[174:177], v[40:43]
	v_mfma_f32_16x16x32_bf16 v[32:35], v[210:213], v[182:185], v[32:35]
	v_mfma_f32_16x16x32_bf16 v[24:27], v[218:221], v[182:185], v[24:27]
	v_mfma_f32_16x16x32_bf16 v[16:19], v[210:213], v[190:193], v[16:19]
	v_mfma_f32_16x16x32_bf16 v[8:11], v[218:221], v[190:193], v[8:11]
	v_mfma_f32_16x16x32_bf16 v[4:7], v[210:213], v[202:205], v[4:7]
	v_mfma_f32_16x16x32_bf16 v[0:3], v[218:221], v[202:205], v[0:3]
	s_setprio 0
	s_add_i32 s57, s57, 2
	s_add_u32 s26, s26, 0x100
	s_addc_u32 s27, s27, 0
	s_add_u32 s55, s55, 0x100
	s_addc_u32 s56, s56, 0
	s_cmp_gt_u32 s57, 29
	s_cbranch_scc0 .Lrot_3
	s_barrier
	s_lshl_b32 s17, s24, 8
	v_add_u32_e32 v154, s17, v139
	s_cmp_lt_i32 s25, -8
	v_or_b32_e32 v152, 16, v154
	v_or_b32_e32 v150, 32, v154
	v_or_b32_e32 v148, 48, v154
	s_cselect_b64 s[26:27], -1, 0
	s_cmp_gt_i32 s25, -9
	v_ashrrev_i32_e32 v155, 31, v154
	v_lshlrev_b32_e32 v136, 1, v138
	v_ashrrev_i32_e32 v153, 31, v152
	v_ashrrev_i32_e32 v151, 31, v150
	v_ashrrev_i32_e32 v149, 31, v148
	s_cbranch_scc1 .LBB0_248
	s_cmp_lt_u32 s25, -12
	s_cselect_b64 vcc, -1, 0
	s_and_b64 s[28:29], vcc, exec
	s_cselect_b32 s2, s89, s81
	s_cselect_b32 s19, s88, s91
	s_lshl_b32 s28, s25, 9
	s_and_b32 s28, s28, 0x600
	s_add_u32 s28, s19, s28
	v_cndmask_b32_e32 v156, 1.0, v164, vcc
	s_addc_u32 s29, s2, 0
	v_lshl_add_u64 v[170:171], s[28:29], 0, v[136:137]
	v_lshlrev_b64 v[158:159], 11, v[154:155]
	v_pk_mul_f32 v[168:169], v[156:157], v[126:127] op_sel_hi:[0,1]
	v_pk_mul_f32 v[166:167], v[156:157], v[124:125] op_sel_hi:[0,1]
	v_pk_mul_f32 v[172:173], v[156:157], v[122:123] op_sel_hi:[0,1]
	v_pk_mul_f32 v[174:175], v[156:157], v[120:121] op_sel_hi:[0,1]
	v_lshl_add_u64 v[158:159], v[170:171], 0, v[158:159]
	v_cvt_pk_bf16_f32 v166, v166, v167
	v_cvt_pk_bf16_f32 v167, v168, v169
	v_cvt_pk_bf16_f32 v168, v174, v175
	v_cvt_pk_bf16_f32 v169, v172, v173
	global_store_dwordx4 v[158:159], v[166:169], off
	v_pk_mul_f32 v[172:173], v[156:157], v[106:107] op_sel_hi:[0,1]
	v_pk_mul_f32 v[174:175], v[156:157], v[104:105] op_sel_hi:[0,1]
	v_pk_mul_f32 v[168:169], v[156:157], v[118:119] op_sel_hi:[0,1]
	v_pk_mul_f32 v[166:167], v[156:157], v[116:117] op_sel_hi:[0,1]
	v_cvt_pk_bf16_f32 v166, v166, v167
	v_cvt_pk_bf16_f32 v167, v168, v169
	v_cvt_pk_bf16_f32 v168, v174, v175
	v_cvt_pk_bf16_f32 v169, v172, v173
	global_store_dwordx4 v[158:159], v[166:169], off offset:256
	v_pk_mul_f32 v[174:175], v[156:157], v[110:111] op_sel_hi:[0,1]
	v_pk_mul_f32 v[176:177], v[156:157], v[108:109] op_sel_hi:[0,1]
	v_lshlrev_b64 v[166:167], 11, v[152:153]
	v_lshl_add_u64 v[172:173], v[170:171], 0, v[166:167]
	v_pk_mul_f32 v[168:169], v[156:157], v[114:115] op_sel_hi:[0,1]
	v_pk_mul_f32 v[166:167], v[156:157], v[112:113] op_sel_hi:[0,1]
	v_cvt_pk_bf16_f32 v166, v166, v167
	v_cvt_pk_bf16_f32 v167, v168, v169
	v_cvt_pk_bf16_f32 v168, v176, v177
	v_cvt_pk_bf16_f32 v169, v174, v175
	global_store_dwordx4 v[172:173], v[166:169], off
	v_pk_mul_f32 v[174:175], v[156:157], v[90:91] op_sel_hi:[0,1]
	v_pk_mul_f32 v[176:177], v[156:157], v[88:89] op_sel_hi:[0,1]
	v_pk_mul_f32 v[168:169], v[156:157], v[98:99] op_sel_hi:[0,1]
	v_pk_mul_f32 v[166:167], v[156:157], v[96:97] op_sel_hi:[0,1]
	v_cvt_pk_bf16_f32 v166, v166, v167
	v_cvt_pk_bf16_f32 v167, v168, v169
	v_cvt_pk_bf16_f32 v168, v176, v177
	v_cvt_pk_bf16_f32 v169, v174, v175
	global_store_dwordx4 v[172:173], v[166:169], off offset:256
	v_pk_mul_f32 v[174:175], v[156:157], v[94:95] op_sel_hi:[0,1]
	v_pk_mul_f32 v[176:177], v[156:157], v[92:93] op_sel_hi:[0,1]
	v_lshlrev_b64 v[166:167], 11, v[150:151]
; __device__ __forceinline__ unsigned cvt_pk_bf16(float lo, float hi) { const bf16x2_t r = __builtin_convertvector((f32x2){lo, hi}, bf16x2_t); return __builtin_bit_cast(unsigned, r); }
;     __device__ __forceinline__ void operator()(const AccT& acc, const Unit& u, int wr, int wc, int fr, int fq) const {
;     ...
;             bf16_t* base = pn < 4 ? Q : Kn; const int colt = (pn & 3) * BM; const float sc = pn < 4 ? 0.08838834764831845f : 1.0f;
; #pragma unroll
;             for (int ai = 0; ai < 2; ++ai)
; #pragma unroll
;                 for (int m = 0; m < 4; ++m) { bf16_t* rowp = base + (size_t)(row0 + ai * HALF + m * 16) * 1024 + colt + cl;
; #pragma unroll
;                     for (int bj = 0; bj < 2; ++bj) { const f32x4 v0 = acc[ai][bj][m][0] * sc, v1 = acc[ai][bj][m][1] * sc;
;                         u32x4 w; w.x = cvt_pk_bf16(v0[0], v0[1]); w.y = cvt_pk_bf16(v0[2], v0[3]); w.z = cvt_pk_bf16(v1[0], v1[1]); w.w = cvt_pk_bf16(v1[2], v1[3]);
;                         *(u32x4*)(rowp + bj * HALF) = w; } }
	v_lshl_add_u64 v[172:173], v[170:171], 0, v[166:167]
	v_pk_mul_f32 v[168:169], v[156:157], v[102:103] op_sel_hi:[0,1]
	v_pk_mul_f32 v[166:167], v[156:157], v[100:101] op_sel_hi:[0,1]
	v_cvt_pk_bf16_f32 v166, v166, v167
	v_cvt_pk_bf16_f32 v167, v168, v169
	v_cvt_pk_bf16_f32 v168, v176, v177
	v_cvt_pk_bf16_f32 v169, v174, v175
	global_store_dwordx4 v[172:173], v[166:169], off
	v_pk_mul_f32 v[174:175], v[156:157], v[74:75] op_sel_hi:[0,1]
	v_pk_mul_f32 v[176:177], v[156:157], v[72:73] op_sel_hi:[0,1]
	v_pk_mul_f32 v[168:169], v[156:157], v[82:83] op_sel_hi:[0,1]
	v_pk_mul_f32 v[166:167], v[156:157], v[80:81] op_sel_hi:[0,1]
	v_cvt_pk_bf16_f32 v166, v166, v167
	v_cvt_pk_bf16_f32 v167, v168, v169
	v_cvt_pk_bf16_f32 v168, v176, v177
	v_cvt_pk_bf16_f32 v169, v174, v175
	global_store_dwordx4 v[172:173], v[166:169], off offset:256
	v_pk_mul_f32 v[172:173], v[156:157], v[78:79] op_sel_hi:[0,1]
	v_pk_mul_f32 v[174:175], v[156:157], v[76:77] op_sel_hi:[0,1]
	v_lshlrev_b64 v[166:167], 11, v[148:149]
	v_lshl_add_u64 v[170:171], v[170:171], 0, v[166:167]
	v_pk_mul_f32 v[168:169], v[156:157], v[86:87] op_sel_hi:[0,1]
	v_pk_mul_f32 v[166:167], v[156:157], v[84:85] op_sel_hi:[0,1]
	v_cvt_pk_bf16_f32 v166, v166, v167
	v_cvt_pk_bf16_f32 v167, v168, v169
	v_cvt_pk_bf16_f32 v168, v174, v175
	v_cvt_pk_bf16_f32 v169, v172, v173
	global_store_dwordx4 v[170:171], v[166:169], off
	v_pk_mul_f32 v[172:173], v[156:157], v[66:67] op_sel_hi:[0,1]
	v_pk_mul_f32 v[174:175], v[156:157], v[64:65] op_sel_hi:[0,1]
	v_pk_mul_f32 v[168:169], v[156:157], v[70:71] op_sel_hi:[0,1]
	v_pk_mul_f32 v[166:167], v[156:157], v[68:69] op_sel_hi:[0,1]
	v_cvt_pk_bf16_f32 v166, v166, v167
	v_cvt_pk_bf16_f32 v167, v168, v169
	v_cvt_pk_bf16_f32 v168, v174, v175
	v_cvt_pk_bf16_f32 v169, v172, v173
	global_store_dwordx4 v[170:171], v[166:169], off offset:256
	v_pk_mul_f32 v[172:173], v[156:157], v[58:59] op_sel_hi:[0,1]
	s_mov_b32 s2, 0x40000
	v_pk_mul_f32 v[168:169], v[156:157], v[62:63] op_sel_hi:[0,1]
	v_pk_mul_f32 v[166:167], v[156:157], v[60:61] op_sel_hi:[0,1]
	v_pk_mul_f32 v[174:175], v[156:157], v[56:57] op_sel_hi:[0,1]
	v_cvt_pk_bf16_f32 v166, v166, v167
	v_cvt_pk_bf16_f32 v167, v168, v169
	v_cvt_pk_bf16_f32 v169, v172, v173
	v_add_co_u32_e32 v172, vcc, s2, v158
	v_cvt_pk_bf16_f32 v168, v174, v175
	s_nop 0
	v_addc_co_u32_e32 v173, vcc, 0, v159, vcc
	s_mov_b64 s[28:29], 0x40000
	global_store_dwordx4 v[172:173], v[166:169], off
	v_pk_mul_f32 v[172:173], v[156:157], v[42:43] op_sel_hi:[0,1]
	v_pk_mul_f32 v[174:175], v[156:157], v[40:41] op_sel_hi:[0,1]
	v_pk_mul_f32 v[168:169], v[156:157], v[50:51] op_sel_hi:[0,1]
	v_pk_mul_f32 v[166:167], v[156:157], v[48:49] op_sel_hi:[0,1]
	v_lshl_add_u64 v[170:171], v[158:159], 0, s[28:29]
	v_cvt_pk_bf16_f32 v166, v166, v167
	v_cvt_pk_bf16_f32 v167, v168, v169
	v_cvt_pk_bf16_f32 v168, v174, v175
	v_cvt_pk_bf16_f32 v169, v172, v173
	global_store_dwordx4 v[170:171], v[166:169], off offset:256
	v_pk_mul_f32 v[172:173], v[156:157], v[46:47] op_sel_hi:[0,1]
	v_pk_mul_f32 v[174:175], v[156:157], v[44:45] op_sel_hi:[0,1]
	v_pk_mul_f32 v[168:169], v[156:157], v[54:55] op_sel_hi:[0,1]
	v_pk_mul_f32 v[166:167], v[156:157], v[52:53] op_sel_hi:[0,1]
	v_cvt_pk_bf16_f32 v166, v166, v167
	v_cvt_pk_bf16_f32 v167, v168, v169
	v_cvt_pk_bf16_f32 v169, v172, v173
	v_add_co_u32_e32 v172, vcc, s46, v158
	v_cvt_pk_bf16_f32 v168, v174, v175
	s_nop 0
	v_addc_co_u32_e32 v173, vcc, 0, v159, vcc
	s_mov_b64 s[28:29], 0x48000
	global_store_dwordx4 v[172:173], v[166:169], off
	v_pk_mul_f32 v[172:173], v[156:157], v[26:27] op_sel_hi:[0,1]
	v_pk_mul_f32 v[174:175], v[156:157], v[24:25] op_sel_hi:[0,1]
	v_pk_mul_f32 v[168:169], v[156:157], v[34:35] op_sel_hi:[0,1]
	v_pk_mul_f32 v[166:167], v[156:157], v[32:33] op_sel_hi:[0,1]
	v_lshl_add_u64 v[170:171], v[158:159], 0, s[28:29]
	v_cvt_pk_bf16_f32 v166, v166, v167
	v_cvt_pk_bf16_f32 v167, v168, v169
	v_cvt_pk_bf16_f32 v168, v174, v175
	v_cvt_pk_bf16_f32 v169, v172, v173
	global_store_dwordx4 v[170:171], v[166:169], off offset:256
	v_pk_mul_f32 v[172:173], v[156:157], v[30:31] op_sel_hi:[0,1]
	v_pk_mul_f32 v[174:175], v[156:157], v[28:29] op_sel_hi:[0,1]
	v_pk_mul_f32 v[168:169], v[156:157], v[38:39] op_sel_hi:[0,1]
	v_pk_mul_f32 v[166:167], v[156:157], v[36:37] op_sel_hi:[0,1]
	v_cvt_pk_bf16_f32 v166, v166, v167
	v_cvt_pk_bf16_f32 v167, v168, v169
	v_cvt_pk_bf16_f32 v169, v172, v173
	v_add_co_u32_e32 v172, vcc, s47, v158
	v_cvt_pk_bf16_f32 v168, v174, v175
	s_nop 0
	v_addc_co_u32_e32 v173, vcc, 0, v159, vcc
	global_store_dwordx4 v[172:173], v[166:169], off
	v_pk_mul_f32 v[172:173], v[156:157], v[10:11] op_sel_hi:[0,1]
	v_pk_mul_f32 v[174:175], v[156:157], v[8:9] op_sel_hi:[0,1]
	v_pk_mul_f32 v[168:169], v[156:157], v[18:19] op_sel_hi:[0,1]
	v_pk_mul_f32 v[166:167], v[156:157], v[16:17] op_sel_hi:[0,1]
	v_lshl_add_u64 v[170:171], v[158:159], 0, s[6:7]
	v_cvt_pk_bf16_f32 v166, v166, v167
	v_cvt_pk_bf16_f32 v167, v168, v169
	v_cvt_pk_bf16_f32 v168, v174, v175
	v_cvt_pk_bf16_f32 v169, v172, v173
	global_store_dwordx4 v[170:171], v[166:169], off offset:256
	v_lshl_add_u64 v[170:171], v[158:159], 0, s[8:9]
	v_pk_mul_f32 v[172:173], v[156:157], v[14:15] op_sel_hi:[0,1]
	v_pk_mul_f32 v[168:169], v[156:157], v[22:23] op_sel_hi:[0,1]
	v_pk_mul_f32 v[166:167], v[156:157], v[20:21] op_sel_hi:[0,1]
	v_pk_mul_f32 v[174:175], v[156:157], v[12:13] op_sel_hi:[0,1]
	v_add_co_u32_e32 v158, vcc, s48, v158
	v_cvt_pk_bf16_f32 v166, v166, v167
	v_cvt_pk_bf16_f32 v167, v168, v169
	v_cvt_pk_bf16_f32 v168, v174, v175
	v_cvt_pk_bf16_f32 v169, v172, v173
	v_addc_co_u32_e32 v159, vcc, 0, v159, vcc
	global_store_dwordx4 v[158:159], v[166:169], off
	v_pk_mul_f32 v[158:159], v[156:157], v[6:7] op_sel_hi:[0,1]
	v_pk_mul_f32 v[172:173], v[156:157], v[0:1] op_sel_hi:[0,1]
	v_pk_mul_f32 v[166:167], v[156:157], v[4:5] op_sel_hi:[0,1]
	v_pk_mul_f32 v[168:169], v[156:157], v[2:3] op_sel_hi:[0,1]
	v_cvt_pk_bf16_f32 v156, v166, v167
	v_cvt_pk_bf16_f32 v157, v158, v159
	v_cvt_pk_bf16_f32 v158, v172, v173
	v_cvt_pk_bf16_f32 v159, v168, v169
	global_store_dwordx4 v[170:171], v[156:159], off offset:256

; template <class Epi>
; __device__ __forceinline__ void gemm_phase(LAS unsigned char* lds, const bf16_t* A, int lda, const bf16_t* Bt, int ldb, int M, int N, int K, int asel, const Epi& E, const int fixed_round = -1) {
;     ...
;         const bool has_next = (fixed_round < 0) && S.next(ui + 1, nxt);
;         const char* nA = has_next ? PG8_ABASE(nxt) : cA; const char* nB = has_next ? (const char*)Bt + (size_t)nxt.pn * tstepB : cB;
;     ...
; #pragma unroll
;         for (int a = 0; a < 2; ++a)
; #pragma unroll
;             for (int b = 0; b < 2; ++b)
; #pragma unroll
;                 for (int m = 0; m < 4; ++m)
; #pragma unroll
;                     for (int n = 0; n < 2; ++n) acc[a][b][m][n] = (f32x4){0.f, 0.f, 0.f, 0.f};
;         cur = nxt; cA = nA; cB = nB; ++ui;
.LBB0_590:
	s_ashr_i32 s7, s6, 31
	v_cmp_lt_i64_e32 vcc, s[18:19], v[140:141]
	s_lshl_b64 s[18:19], s[6:7], 20
	s_add_u32 s18, s38, s18
	s_addc_u32 s19, s39, s19
	s_and_b64 s[20:21], vcc, exec
	s_cselect_b32 s7, s19, s31
	s_cselect_b32 s52, s18, s30
	s_ashr_i32 s5, s4, 31
	s_lshl_b64 s[20:21], s[4:5], 20
	s_add_u32 s20, s40, s20
	s_addc_u32 s21, s41, s21
	s_and_b64 s[28:29], vcc, exec
	s_cselect_b32 s5, s21, s35
	s_cselect_b32 s53, s20, s34
	s_add_u32 s30, s30, 0x80080
	s_addc_u32 s31, s31, 0
	s_add_u32 s54, s34, 0x100
	v_mov_b32_e32 v0, 0
	s_addc_u32 s55, s35, 0
	s_mov_b32 s56, -2
	v_mov_b32_e32 v1, v0
	v_mov_b32_e32 v2, v0
	v_mov_b32_e32 v3, v0
	v_mov_b32_e32 v4, v0
	v_mov_b32_e32 v5, v0
	v_mov_b32_e32 v6, v0
	v_mov_b32_e32 v7, v0
	v_mov_b32_e32 v16, v0
	v_mov_b32_e32 v17, v0
	v_mov_b32_e32 v18, v0
	v_mov_b32_e32 v19, v0
	v_mov_b32_e32 v20, v0
	v_mov_b32_e32 v21, v0
	v_mov_b32_e32 v22, v0
	v_mov_b32_e32 v23, v0
	v_mov_b32_e32 v32, v0
	v_mov_b32_e32 v33, v0
	v_mov_b32_e32 v34, v0
	v_mov_b32_e32 v35, v0
	v_mov_b32_e32 v36, v0
	v_mov_b32_e32 v37, v0
	v_mov_b32_e32 v38, v0
	v_mov_b32_e32 v39, v0
	v_mov_b32_e32 v48, v0
	v_mov_b32_e32 v49, v0
	v_mov_b32_e32 v50, v0
	v_mov_b32_e32 v51, v0
	v_mov_b32_e32 v52, v0
	v_mov_b32_e32 v53, v0
	v_mov_b32_e32 v54, v0
	v_mov_b32_e32 v55, v0
	v_mov_b32_e32 v8, v0
	v_mov_b32_e32 v9, v0
	v_mov_b32_e32 v10, v0
	v_mov_b32_e32 v11, v0
	v_mov_b32_e32 v12, v0
	v_mov_b32_e32 v13, v0
	v_mov_b32_e32 v14, v0
	v_mov_b32_e32 v15, v0
	v_mov_b32_e32 v24, v0
	v_mov_b32_e32 v25, v0
	v_mov_b32_e32 v26, v0
	v_mov_b32_e32 v27, v0
	v_mov_b32_e32 v28, v0
	v_mov_b32_e32 v29, v0
	v_mov_b32_e32 v30, v0
	v_mov_b32_e32 v31, v0
	v_mov_b32_e32 v40, v0
	v_mov_b32_e32 v41, v0
	v_mov_b32_e32 v42, v0
	v_mov_b32_e32 v43, v0
	v_mov_b32_e32 v44, v0
	v_mov_b32_e32 v45, v0
	v_mov_b32_e32 v46, v0
	v_mov_b32_e32 v47, v0
	v_mov_b32_e32 v56, v0
	v_mov_b32_e32 v57, v0
	v_mov_b32_e32 v58, v0
	v_mov_b32_e32 v59, v0
	v_mov_b32_e32 v60, v0
	v_mov_b32_e32 v61, v0
	v_mov_b32_e32 v62, v0
	v_mov_b32_e32 v63, v0
	v_mov_b32_e32 v64, v0
	v_mov_b32_e32 v65, v0
	v_mov_b32_e32 v66, v0
	v_mov_b32_e32 v67, v0
	v_mov_b32_e32 v68, v0
	v_mov_b32_e32 v69, v0
	v_mov_b32_e32 v70, v0
	v_mov_b32_e32 v71, v0
	v_mov_b32_e32 v80, v0
	v_mov_b32_e32 v81, v0
	v_mov_b32_e32 v82, v0
	v_mov_b32_e32 v83, v0
	v_mov_b32_e32 v84, v0
	v_mov_b32_e32 v85, v0
	v_mov_b32_e32 v86, v0
	v_mov_b32_e32 v87, v0
	v_mov_b32_e32 v96, v0
	v_mov_b32_e32 v97, v0
	v_mov_b32_e32 v98, v0
	v_mov_b32_e32 v99, v0
	v_mov_b32_e32 v100, v0
	v_mov_b32_e32 v101, v0
	v_mov_b32_e32 v102, v0
	v_mov_b32_e32 v103, v0
	v_mov_b32_e32 v112, v0
	v_mov_b32_e32 v113, v0
	v_mov_b32_e32 v114, v0
	v_mov_b32_e32 v115, v0
	v_mov_b32_e32 v116, v0
	v_mov_b32_e32 v117, v0
	v_mov_b32_e32 v118, v0
	v_mov_b32_e32 v119, v0
	v_mov_b32_e32 v72, v0
	v_mov_b32_e32 v73, v0
	v_mov_b32_e32 v74, v0
	v_mov_b32_e32 v75, v0
	v_mov_b32_e32 v76, v0
	v_mov_b32_e32 v77, v0
	v_mov_b32_e32 v78, v0
	v_mov_b32_e32 v79, v0
	v_mov_b32_e32 v88, v0
	v_mov_b32_e32 v89, v0
	v_mov_b32_e32 v90, v0
	v_mov_b32_e32 v91, v0
	v_mov_b32_e32 v92, v0
	v_mov_b32_e32 v93, v0
	v_mov_b32_e32 v94, v0
	v_mov_b32_e32 v95, v0
	v_mov_b32_e32 v104, v0
	v_mov_b32_e32 v105, v0
	v_mov_b32_e32 v106, v0
	v_mov_b32_e32 v107, v0
	v_mov_b32_e32 v108, v0
	v_mov_b32_e32 v109, v0
	v_mov_b32_e32 v110, v0
	v_mov_b32_e32 v111, v0
	v_mov_b32_e32 v120, v0
	v_mov_b32_e32 v121, v0
	v_mov_b32_e32 v122, v0
	v_mov_b32_e32 v123, v0
	v_mov_b32_e32 v124, v0
	v_mov_b32_e32 v125, v0
	v_mov_b32_e32 v126, v0
	v_mov_b32_e32 v127, v0
	s_branch .LBB0_591

; #define PG8_STAGE(bufoff, gbase, voff) do { _Pragma("unroll") for (int _i = 0; _i < 2; ++_i) \
;         __builtin_amdgcn_global_load_lds((const unsigned*)((const char*)(gbase) + (voff)[_i]), (LAS unsigned*)(lds + (bufoff) + ldsw + _i * 8192), 16, 0, 0); } while (0)
; #define PG8_LDA(dst, b, h) do { _Pragma("unroll") for (int m = 0; m < 4; ++m) _Pragma("unroll") for (int k = 0; k < 2; ++k) dst[m][k] = *(const LAS bf16x8*)(lds + PG8_SA(b, h) + aoff + m * 2048 + k * 1024); } while (0)
; #define PG8_LDB(dst, b, h) do { _Pragma("unroll") for (int n = 0; n < 2; ++n) _Pragma("unroll") for (int k = 0; k < 2; ++k) dst[n][k] = *(const LAS bf16x8*)(lds + PG8_SB(b, h) + boff + n * 2048 + k * 1024); } while (0)
; #define PG8_WAIT_V(n) asm volatile("s_waitcnt vmcnt(" #n ")" ::: "memory")
; #define PG8_WAIT_L(n) asm volatile("s_waitcnt lgkmcnt(" #n ")" ::: "memory")
; #define PG8_BAR __builtin_amdgcn_s_barrier()
; template <class Epi>
; __device__ __forceinline__ void gemm_phase(LAS unsigned char* lds, const bf16_t* A, int lda, const bf16_t* Bt, int ldb, int M, int N, int K, int asel, const Epi& E, const int fixed_round = -1) {
;     ...
;             PG8_LDB(B0, 0, 0); PG8_SCHED; PG8_LDA(At, 0, 0); PG8_STAGE(PG8_SA(1, 1), a1 + hstepA, voffA);
;             PG8_WAIT_L(8); PG8_BAR; PG8_WAIT_L(0); PG8_MMA(0, 0, At, B0); PG8_BAR; PG8_SCHED;
;             PG8_LDB(B1, 0, 1); PG8_STAGE(PG8_SB(0, 0), b2, voffB);
;             PG8_BAR; PG8_WAIT_L(0); PG8_MMA(0, 1, At, B1); PG8_BAR;
;             PG8_LDA(At, 0, 1); PG8_STAGE(PG8_SA(0, 0), a2, voffA);
;             PG8_BAR; PG8_WAIT_L(0); PG8_MMA(1, 0, At, B0); PG8_BAR; PG8_SCHED;
;             PG8_STAGE(PG8_SB(0, 1), b2 + hstepB, voffB);
;             PG8_WAIT_V(6); PG8_BAR; PG8_MMA(1, 1, At, B1); PG8_BAR;
;             PG8_LDB(B0, 1, 0); PG8_SCHED; PG8_LDA(At, 1, 0); PG8_STAGE(PG8_SA(0, 1), a2 + hstepA, voffA);
;             PG8_WAIT_L(8); PG8_BAR; PG8_WAIT_L(0); PG8_MMA(0, 0, At, B0); PG8_BAR; PG8_SCHED;
;             PG8_LDB(B1, 1, 1); PG8_STAGE(PG8_SB(1, 0), b3, voffB);
;             PG8_BAR; PG8_WAIT_L(0); PG8_MMA(0, 1, At, B1); PG8_BAR;
;             PG8_LDA(At, 1, 1); PG8_STAGE(PG8_SA(1, 0), a3, voffA);
;             PG8_BAR; PG8_WAIT_L(0); PG8_MMA(1, 0, At, B0); PG8_BAR; PG8_SCHED;
;             PG8_STAGE(PG8_SB(1, 1), b3 + hstepB, voffB);
;             PG8_WAIT_V(6); PG8_BAR; PG8_MMA(1, 1, At, B1); PG8_BAR;
.LBB0_591:
	ds_read_b128 v[152:155], v149
	ds_read_b128 v[156:159], v149 offset:1024
	ds_read_b128 v[160:163], v149 offset:2048
	ds_read_b128 v[164:167], v149 offset:3072
	s_add_u32 s28, s30, 0xfff80080
	s_addc_u32 s29, s31, -1
	s_cmp_eq_u32 s56, 28
	s_cselect_b32 s37, s7, s29
	s_cselect_b32 s36, s52, s28
	s_cselect_b32 s35, s5, s55
	s_cselect_b32 s34, s53, s54
	s_add_i32 m0, s27, 0xc000
	ds_read_b128 v[168:171], v150
	ds_read_b128 v[172:175], v150 offset:1024
	ds_read_b128 v[176:179], v150 offset:2048
	ds_read_b128 v[180:183], v150 offset:3072
	ds_read_b128 v[184:187], v150 offset:4096
	ds_read_b128 v[188:191], v150 offset:5120
	ds_read_b128 v[192:195], v150 offset:6144
	ds_read_b128 v[196:199], v150 offset:7168
	global_load_lds_dwordx4 v136, s[30:31]
	s_add_i32 m0, s27, 0xe000
	s_nop 0
	global_load_lds_dwordx4 v138, s[30:31]
	s_waitcnt lgkmcnt(8)
	s_barrier
	s_waitcnt lgkmcnt(0)
	s_setprio 1
	s_waitcnt lgkmcnt(0)
	v_mfma_f32_16x16x32_bf16 v[124:127], v[152:155], v[168:171], v[124:127]
	v_mfma_f32_16x16x32_bf16 v[120:123], v[160:163], v[168:171], v[120:123]
	v_mfma_f32_16x16x32_bf16 v[108:111], v[152:155], v[176:179], v[108:111]
	v_mfma_f32_16x16x32_bf16 v[104:107], v[160:163], v[176:179], v[104:107]
	v_mfma_f32_16x16x32_bf16 v[92:95], v[152:155], v[184:187], v[92:95]
	v_mfma_f32_16x16x32_bf16 v[88:91], v[160:163], v[184:187], v[88:91]
	v_mfma_f32_16x16x32_bf16 v[76:79], v[152:155], v[192:195], v[76:79]
	v_mfma_f32_16x16x32_bf16 v[72:75], v[160:163], v[192:195], v[72:75]
	v_mfma_f32_16x16x32_bf16 v[124:127], v[156:159], v[172:175], v[124:127]
	v_mfma_f32_16x16x32_bf16 v[120:123], v[164:167], v[172:175], v[120:123]
	v_mfma_f32_16x16x32_bf16 v[108:111], v[156:159], v[180:183], v[108:111]
	v_mfma_f32_16x16x32_bf16 v[104:107], v[164:167], v[180:183], v[104:107]
	v_mfma_f32_16x16x32_bf16 v[92:95], v[156:159], v[188:191], v[92:95]
	v_mfma_f32_16x16x32_bf16 v[88:91], v[164:167], v[188:191], v[88:91]
	v_mfma_f32_16x16x32_bf16 v[76:79], v[156:159], v[196:199], v[76:79]
	v_mfma_f32_16x16x32_bf16 v[72:75], v[164:167], v[196:199], v[72:75]
	s_setprio 0
	s_barrier
	s_add_i32 s28, s81, s42
	s_add_u32 s98, s34, s2
	s_addc_u32 s99, s35, s3
	s_mov_b32 m0, s28
	ds_read_b128 v[202:205], v151
	ds_read_b128 v[206:209], v151 offset:1024
	ds_read_b128 v[210:213], v151 offset:2048
	ds_read_b128 v[214:217], v151 offset:3072
	global_load_lds_dwordx4 v130, s[34:35]
	s_add_i32 m0, s28, 0x2000
	s_nop 0
	global_load_lds_dwordx4 v134, s[34:35]
	s_barrier
	s_waitcnt lgkmcnt(0)
	s_setprio 1
	s_waitcnt lgkmcnt(0)
	v_mfma_f32_16x16x32_bf16 v[116:119], v[202:205], v[168:171], v[116:119]
	v_mfma_f32_16x16x32_bf16 v[112:115], v[210:213], v[168:171], v[112:115]
	v_mfma_f32_16x16x32_bf16 v[100:103], v[202:205], v[176:179], v[100:103]
	v_mfma_f32_16x16x32_bf16 v[96:99], v[210:213], v[176:179], v[96:99]
	v_mfma_f32_16x16x32_bf16 v[84:87], v[202:205], v[184:187], v[84:87]
	v_mfma_f32_16x16x32_bf16 v[80:83], v[210:213], v[184:187], v[80:83]
	v_mfma_f32_16x16x32_bf16 v[68:71], v[202:205], v[192:195], v[68:71]
	v_mfma_f32_16x16x32_bf16 v[64:67], v[210:213], v[192:195], v[64:67]
	v_mfma_f32_16x16x32_bf16 v[116:119], v[206:209], v[172:175], v[116:119]
	v_mfma_f32_16x16x32_bf16 v[112:115], v[214:217], v[172:175], v[112:115]
	v_mfma_f32_16x16x32_bf16 v[100:103], v[206:209], v[180:183], v[100:103]
	v_mfma_f32_16x16x32_bf16 v[96:99], v[214:217], v[180:183], v[96:99]
	v_mfma_f32_16x16x32_bf16 v[84:87], v[206:209], v[188:191], v[84:87]
	v_mfma_f32_16x16x32_bf16 v[80:83], v[214:217], v[188:191], v[80:83]
	v_mfma_f32_16x16x32_bf16 v[68:71], v[206:209], v[196:199], v[68:71]
	v_mfma_f32_16x16x32_bf16 v[64:67], v[214:217], v[196:199], v[64:67]
	s_setprio 0
	s_mov_b32 m0, s27
	s_add_u32 s100, s36, s2
	s_addc_u32 s101, s37, s3
	s_barrier
	ds_read_b128 v[168:171], v150 offset:16384
	ds_read_b128 v[172:175], v150 offset:17408
	ds_read_b128 v[176:179], v150 offset:18432
	ds_read_b128 v[180:183], v150 offset:19456
	ds_read_b128 v[184:187], v150 offset:20480
	ds_read_b128 v[188:191], v150 offset:21504
	ds_read_b128 v[192:195], v150 offset:22528
	ds_read_b128 v[196:199], v150 offset:23552
	global_load_lds_dwordx4 v128, s[36:37]
	s_mov_b32 m0, s43
	s_nop 0
	global_load_lds_dwordx4 v132, s[36:37]
	s_barrier
	s_waitcnt lgkmcnt(0)
	s_setprio 1
	s_waitcnt lgkmcnt(0)
	v_mfma_f32_16x16x32_bf16 v[60:63], v[152:155], v[168:171], v[60:63]
	v_mfma_f32_16x16x32_bf16 v[56:59], v[160:163], v[168:171], v[56:59]
	v_mfma_f32_16x16x32_bf16 v[44:47], v[152:155], v[176:179], v[44:47]
	v_mfma_f32_16x16x32_bf16 v[40:43], v[160:163], v[176:179], v[40:43]
	v_mfma_f32_16x16x32_bf16 v[28:31], v[152:155], v[184:187], v[28:31]
	v_mfma_f32_16x16x32_bf16 v[24:27], v[160:163], v[184:187], v[24:27]
	v_mfma_f32_16x16x32_bf16 v[12:15], v[152:155], v[192:195], v[12:15]
	v_mfma_f32_16x16x32_bf16 v[8:11], v[160:163], v[192:195], v[8:11]
	v_mfma_f32_16x16x32_bf16 v[60:63], v[156:159], v[172:175], v[60:63]
	v_mfma_f32_16x16x32_bf16 v[56:59], v[164:167], v[172:175], v[56:59]
	v_mfma_f32_16x16x32_bf16 v[44:47], v[156:159], v[180:183], v[44:47]
	v_mfma_f32_16x16x32_bf16 v[40:43], v[164:167], v[180:183], v[40:43]
	v_mfma_f32_16x16x32_bf16 v[28:31], v[156:159], v[188:191], v[28:31]
	v_mfma_f32_16x16x32_bf16 v[24:27], v[164:167], v[188:191], v[24:27]
	v_mfma_f32_16x16x32_bf16 v[12:15], v[156:159], v[196:199], v[12:15]
	v_mfma_f32_16x16x32_bf16 v[8:11], v[164:167], v[196:199], v[8:11]
	s_setprio 0
	s_barrier
	s_add_u32 s28, s34, 0x80000
	s_addc_u32 s29, s35, 0
	s_add_i32 s57, s82, s42
	s_mov_b32 m0, s57
	s_nop 0
	global_load_lds_dwordx4 v130, s[28:29]
	s_add_i32 m0, s57, 0x2000
	s_nop 0
	global_load_lds_dwordx4 v134, s[28:29]
	s_waitcnt vmcnt(6)
	s_barrier
; #define PG8_STAGE(bufoff, gbase, voff) do { _Pragma("unroll") for (int _i = 0; _i < 2; ++_i) \
;         __builtin_amdgcn_global_load_lds((const unsigned*)((const char*)(gbase) + (voff)[_i]), (LAS unsigned*)(lds + (bufoff) + ldsw + _i * 8192), 16, 0, 0); } while (0)
; #define PG8_LDA(dst, b, h) do { _Pragma("unroll") for (int m = 0; m < 4; ++m) _Pragma("unroll") for (int k = 0; k < 2; ++k) dst[m][k] = *(const LAS bf16x8*)(lds + PG8_SA(b, h) + aoff + m * 2048 + k * 1024); } while (0)
; #define PG8_LDB(dst, b, h) do { _Pragma("unroll") for (int n = 0; n < 2; ++n) _Pragma("unroll") for (int k = 0; k < 2; ++k) dst[n][k] = *(const LAS bf16x8*)(lds + PG8_SB(b, h) + boff + n * 2048 + k * 1024); } while (0)
; #define PG8_WAIT_V(n) asm volatile("s_waitcnt vmcnt(" #n ")" ::: "memory")
; #define PG8_WAIT_L(n) asm volatile("s_waitcnt lgkmcnt(" #n ")" ::: "memory")
; #define PG8_BAR __builtin_amdgcn_s_barrier()
; template <class Epi>
; __device__ __forceinline__ void gemm_phase(LAS unsigned char* lds, const bf16_t* A, int lda, const bf16_t* Bt, int ldb, int M, int N, int K, int asel, const Epi& E, const int fixed_round = -1) {
;     ...
;             PG8_LDB(B0, 0, 0); PG8_SCHED; PG8_LDA(At, 0, 0); PG8_STAGE(PG8_SA(1, 1), a1 + hstepA, voffA);
;             PG8_WAIT_L(8); PG8_BAR; PG8_WAIT_L(0); PG8_MMA(0, 0, At, B0); PG8_BAR; PG8_SCHED;
;             PG8_LDB(B1, 0, 1); PG8_STAGE(PG8_SB(0, 0), b2, voffB);
;             PG8_BAR; PG8_WAIT_L(0); PG8_MMA(0, 1, At, B1); PG8_BAR;
;             PG8_LDA(At, 0, 1); PG8_STAGE(PG8_SA(0, 0), a2, voffA);
;             PG8_BAR; PG8_WAIT_L(0); PG8_MMA(1, 0, At, B0); PG8_BAR; PG8_SCHED;
;             PG8_STAGE(PG8_SB(0, 1), b2 + hstepB, voffB);
;             PG8_WAIT_V(6); PG8_BAR; PG8_MMA(1, 1, At, B1); PG8_BAR;
;             PG8_LDB(B0, 1, 0); PG8_SCHED; PG8_LDA(At, 1, 0); PG8_STAGE(PG8_SA(0, 1), a2 + hstepA, voffA);
;             PG8_WAIT_L(8); PG8_BAR; PG8_WAIT_L(0); PG8_MMA(0, 0, At, B0); PG8_BAR; PG8_SCHED;
;             PG8_LDB(B1, 1, 1); PG8_STAGE(PG8_SB(1, 0), b3, voffB);
;             PG8_BAR; PG8_WAIT_L(0); PG8_MMA(0, 1, At, B1); PG8_BAR;
;             PG8_LDA(At, 1, 1); PG8_STAGE(PG8_SA(1, 0), a3, voffA);
;             PG8_BAR; PG8_WAIT_L(0); PG8_MMA(1, 0, At, B0); PG8_BAR; PG8_SCHED;
;             PG8_STAGE(PG8_SB(1, 1), b3 + hstepB, voffB);
;             PG8_WAIT_V(6); PG8_BAR; PG8_MMA(1, 1, At, B1); PG8_BAR;
	s_setprio 1
	v_mfma_f32_16x16x32_bf16 v[52:55], v[202:205], v[168:171], v[52:55]
	v_mfma_f32_16x16x32_bf16 v[48:51], v[210:213], v[168:171], v[48:51]
	v_mfma_f32_16x16x32_bf16 v[36:39], v[202:205], v[176:179], v[36:39]
	v_mfma_f32_16x16x32_bf16 v[32:35], v[210:213], v[176:179], v[32:35]
	v_mfma_f32_16x16x32_bf16 v[20:23], v[202:205], v[184:187], v[20:23]
	v_mfma_f32_16x16x32_bf16 v[16:19], v[210:213], v[184:187], v[16:19]
	v_mfma_f32_16x16x32_bf16 v[4:7], v[202:205], v[192:195], v[4:7]
	v_mfma_f32_16x16x32_bf16 v[0:3], v[210:213], v[192:195], v[0:3]
	v_mfma_f32_16x16x32_bf16 v[52:55], v[206:209], v[172:175], v[52:55]
	v_mfma_f32_16x16x32_bf16 v[48:51], v[214:217], v[172:175], v[48:51]
	v_mfma_f32_16x16x32_bf16 v[36:39], v[206:209], v[180:183], v[36:39]
	v_mfma_f32_16x16x32_bf16 v[32:35], v[214:217], v[180:183], v[32:35]
	v_mfma_f32_16x16x32_bf16 v[20:23], v[206:209], v[188:191], v[20:23]
	v_mfma_f32_16x16x32_bf16 v[16:19], v[214:217], v[188:191], v[16:19]
	v_mfma_f32_16x16x32_bf16 v[4:7], v[206:209], v[196:199], v[4:7]
	v_mfma_f32_16x16x32_bf16 v[0:3], v[214:217], v[196:199], v[0:3]
	s_setprio 0
	v_add_u32_e32 v164, s83, v147
	s_barrier
	ds_read_b128 v[152:155], v164
	ds_read_b128 v[156:159], v164 offset:1024
	ds_read_b128 v[160:163], v164 offset:2048
	ds_read_b128 v[164:167], v164 offset:3072
	s_add_u32 s28, s36, 0x80000
	s_addc_u32 s29, s37, 0
	s_mov_b32 m0, s44
	ds_read_b128 v[168:171], v150 offset:32768
	ds_read_b128 v[172:175], v150 offset:33792
	ds_read_b128 v[176:179], v150 offset:34816
	ds_read_b128 v[180:183], v150 offset:35840
	ds_read_b128 v[184:187], v150 offset:36864
	ds_read_b128 v[188:191], v150 offset:37888
	ds_read_b128 v[192:195], v150 offset:38912
	ds_read_b128 v[196:199], v150 offset:39936
	global_load_lds_dwordx4 v128, s[28:29]
	s_mov_b32 m0, s45
	s_nop 0
	global_load_lds_dwordx4 v132, s[28:29]
	s_waitcnt lgkmcnt(8)
	s_barrier
	s_waitcnt lgkmcnt(0)
	s_setprio 1
	s_waitcnt lgkmcnt(0)
	v_mfma_f32_16x16x32_bf16 v[124:127], v[152:155], v[168:171], v[124:127]
	v_mfma_f32_16x16x32_bf16 v[120:123], v[160:163], v[168:171], v[120:123]
	v_mfma_f32_16x16x32_bf16 v[108:111], v[152:155], v[176:179], v[108:111]
	v_mfma_f32_16x16x32_bf16 v[104:107], v[160:163], v[176:179], v[104:107]
	v_mfma_f32_16x16x32_bf16 v[92:95], v[152:155], v[184:187], v[92:95]
	v_mfma_f32_16x16x32_bf16 v[88:91], v[160:163], v[184:187], v[88:91]
	v_mfma_f32_16x16x32_bf16 v[76:79], v[152:155], v[192:195], v[76:79]
	v_mfma_f32_16x16x32_bf16 v[72:75], v[160:163], v[192:195], v[72:75]
	v_mfma_f32_16x16x32_bf16 v[124:127], v[156:159], v[172:175], v[124:127]
	v_mfma_f32_16x16x32_bf16 v[120:123], v[164:167], v[172:175], v[120:123]
	v_mfma_f32_16x16x32_bf16 v[108:111], v[156:159], v[180:183], v[108:111]
	v_mfma_f32_16x16x32_bf16 v[104:107], v[164:167], v[180:183], v[104:107]
	v_mfma_f32_16x16x32_bf16 v[92:95], v[156:159], v[188:191], v[92:95]
	v_mfma_f32_16x16x32_bf16 v[88:91], v[164:167], v[188:191], v[88:91]
	v_mfma_f32_16x16x32_bf16 v[76:79], v[156:159], v[196:199], v[76:79]
	v_mfma_f32_16x16x32_bf16 v[72:75], v[164:167], v[196:199], v[72:75]
	s_setprio 0
	s_barrier
	s_add_i32 s28, s83, s42
	v_add_u32_e32 v214, s84, v147
	s_mov_b32 m0, s28
	ds_read_b128 v[202:205], v214
	ds_read_b128 v[206:209], v214 offset:1024
	ds_read_b128 v[210:213], v214 offset:2048
	ds_read_b128 v[214:217], v214 offset:3072
	global_load_lds_dwordx4 v130, s[98:99]
	s_add_i32 m0, s28, 0x2000
	s_nop 0
	global_load_lds_dwordx4 v134, s[98:99]
	s_barrier
	s_waitcnt lgkmcnt(0)
	s_setprio 1
	s_waitcnt lgkmcnt(0)
	v_mfma_f32_16x16x32_bf16 v[116:119], v[202:205], v[168:171], v[116:119]
	v_mfma_f32_16x16x32_bf16 v[112:115], v[210:213], v[168:171], v[112:115]
	v_mfma_f32_16x16x32_bf16 v[100:103], v[202:205], v[176:179], v[100:103]
	v_mfma_f32_16x16x32_bf16 v[96:99], v[210:213], v[176:179], v[96:99]
	v_mfma_f32_16x16x32_bf16 v[84:87], v[202:205], v[184:187], v[84:87]
	v_mfma_f32_16x16x32_bf16 v[80:83], v[210:213], v[184:187], v[80:83]
	v_mfma_f32_16x16x32_bf16 v[68:71], v[202:205], v[192:195], v[68:71]
	v_mfma_f32_16x16x32_bf16 v[64:67], v[210:213], v[192:195], v[64:67]
	v_mfma_f32_16x16x32_bf16 v[116:119], v[206:209], v[172:175], v[116:119]
	v_mfma_f32_16x16x32_bf16 v[112:115], v[214:217], v[172:175], v[112:115]
	v_mfma_f32_16x16x32_bf16 v[100:103], v[206:209], v[180:183], v[100:103]
	v_mfma_f32_16x16x32_bf16 v[96:99], v[214:217], v[180:183], v[96:99]
	v_mfma_f32_16x16x32_bf16 v[84:87], v[206:209], v[188:191], v[84:87]
	v_mfma_f32_16x16x32_bf16 v[80:83], v[214:217], v[188:191], v[80:83]
	v_mfma_f32_16x16x32_bf16 v[68:71], v[206:209], v[196:199], v[68:71]
	v_mfma_f32_16x16x32_bf16 v[64:67], v[214:217], v[196:199], v[64:67]
	s_setprio 0
	s_mov_b32 m0, s47
	s_barrier
	ds_read_b128 v[168:171], v150 offset:49152
	ds_read_b128 v[172:175], v150 offset:50176
	ds_read_b128 v[176:179], v150 offset:51200
	ds_read_b128 v[180:183], v150 offset:52224
	ds_read_b128 v[184:187], v150 offset:53248
	ds_read_b128 v[188:191], v150 offset:54272
	ds_read_b128 v[192:195], v150 offset:55296
	ds_read_b128 v[196:199], v150 offset:56320
	global_load_lds_dwordx4 v128, s[100:101]
	s_mov_b32 m0, s48
	s_nop 0
	global_load_lds_dwordx4 v132, s[100:101]
	s_barrier
; __device__ __forceinline__ unsigned cvt_pk_bf16(float lo, float hi) { const bf16x2_t r = __builtin_convertvector((f32x2){lo, hi}, bf16x2_t); return __builtin_bit_cast(unsigned, r); }
; #define PG8_STAGE(bufoff, gbase, voff) do { _Pragma("unroll") for (int _i = 0; _i < 2; ++_i) \
;         __builtin_amdgcn_global_load_lds((const unsigned*)((const char*)(gbase) + (voff)[_i]), (LAS unsigned*)(lds + (bufoff) + ldsw + _i * 8192), 16, 0, 0); } while (0)
; #define PG8_WAIT_V(n) asm volatile("s_waitcnt vmcnt(" #n ")" ::: "memory")
; #define PG8_BAR __builtin_amdgcn_s_barrier()
; template <class Epi>
; __device__ __forceinline__ void gemm_phase(LAS unsigned char* lds, const bf16_t* A, int lda, const bf16_t* Bt, int ldb, int M, int N, int K, int asel, const Epi& E, const int fixed_round = -1) {
;     ...
;             PG8_WAIT_V(6); PG8_BAR; PG8_MMA(1, 1, At, B1); PG8_BAR;
;             PG8_LDB(B0, 1, 0); PG8_SCHED; PG8_LDA(At, 1, 0); PG8_STAGE(PG8_SA(0, 1), a2 + hstepA, voffA);
;             PG8_WAIT_L(8); PG8_BAR; PG8_WAIT_L(0); PG8_MMA(0, 0, At, B0); PG8_BAR; PG8_SCHED;
;             PG8_LDB(B1, 1, 1); PG8_STAGE(PG8_SB(1, 0), b3, voffB);
;             PG8_BAR; PG8_WAIT_L(0); PG8_MMA(0, 1, At, B1); PG8_BAR;
;             PG8_LDA(At, 1, 1); PG8_STAGE(PG8_SA(1, 0), a3, voffA);
;             PG8_BAR; PG8_WAIT_L(0); PG8_MMA(1, 0, At, B0); PG8_BAR; PG8_SCHED;
;             PG8_STAGE(PG8_SB(1, 1), b3 + hstepB, voffB);
;             PG8_WAIT_V(6); PG8_BAR; PG8_MMA(1, 1, At, B1); PG8_BAR;
;     __device__ __forceinline__ void operator()(const AccT& acc, const Unit& u, int wr, int wc, int fr, int fq) const {
;         const int row0 = u.pm * BM + wr * 64 + fr, col0 = u.pn * BM + wc * 32 + 8 * fq;
; #pragma unroll
;         for (int ai = 0; ai < 2; ++ai)
; #pragma unroll
;             for (int m = 0; m < 4; ++m) { bf16_t* rowp = O + (size_t)(row0 + ai * HALF + m * 16) * DFF + col0;
; #pragma unroll
;                 for (int bj = 0; bj < 2; ++bj) { f32x4 v0 = acc[ai][bj][m][0], v1 = acc[ai][bj][m][1];
; #pragma unroll
;                     for (int j = 0; j < 4; ++j) { float a = fmaxf(v0[j], 0.f), b = fmaxf(v1[j], 0.f); v0[j] = a * a; v1[j] = b * b; }
;                     u32x4 w; w.x = cvt_pk_bf16(v0[0], v0[1]); w.y = cvt_pk_bf16(v0[2], v0[3]); w.z = cvt_pk_bf16(v1[0], v1[1]); w.w = cvt_pk_bf16(v1[2], v1[3]);
;                     *(u32x4*)(rowp + bj * HALF) = w; } }
	s_waitcnt lgkmcnt(0)
	s_setprio 1
	s_waitcnt lgkmcnt(0)
	v_mfma_f32_16x16x32_bf16 v[60:63], v[152:155], v[168:171], v[60:63]
	v_mfma_f32_16x16x32_bf16 v[56:59], v[160:163], v[168:171], v[56:59]
	v_mfma_f32_16x16x32_bf16 v[44:47], v[152:155], v[176:179], v[44:47]
	v_mfma_f32_16x16x32_bf16 v[40:43], v[160:163], v[176:179], v[40:43]
	v_mfma_f32_16x16x32_bf16 v[28:31], v[152:155], v[184:187], v[28:31]
	v_mfma_f32_16x16x32_bf16 v[24:27], v[160:163], v[184:187], v[24:27]
	v_mfma_f32_16x16x32_bf16 v[12:15], v[152:155], v[192:195], v[12:15]
	v_mfma_f32_16x16x32_bf16 v[8:11], v[160:163], v[192:195], v[8:11]
	v_mfma_f32_16x16x32_bf16 v[60:63], v[156:159], v[172:175], v[60:63]
	v_mfma_f32_16x16x32_bf16 v[56:59], v[164:167], v[172:175], v[56:59]
	v_mfma_f32_16x16x32_bf16 v[44:47], v[156:159], v[180:183], v[44:47]
	v_mfma_f32_16x16x32_bf16 v[40:43], v[164:167], v[180:183], v[40:43]
	v_mfma_f32_16x16x32_bf16 v[28:31], v[156:159], v[188:191], v[28:31]
	v_mfma_f32_16x16x32_bf16 v[24:27], v[164:167], v[188:191], v[24:27]
	v_mfma_f32_16x16x32_bf16 v[12:15], v[156:159], v[196:199], v[12:15]
	v_mfma_f32_16x16x32_bf16 v[8:11], v[164:167], v[196:199], v[8:11]
	s_setprio 0
	s_barrier
	s_add_u32 s28, s34, 0x80080
	s_addc_u32 s29, s35, 0
	s_add_i32 s34, s84, s42
	s_mov_b32 m0, s34
	s_nop 0
	global_load_lds_dwordx4 v130, s[28:29]
	s_add_i32 m0, s34, 0x2000
	s_nop 0
	global_load_lds_dwordx4 v134, s[28:29]
	s_waitcnt vmcnt(6)
	s_barrier
	s_setprio 1
	v_mfma_f32_16x16x32_bf16 v[52:55], v[202:205], v[168:171], v[52:55]
	v_mfma_f32_16x16x32_bf16 v[48:51], v[210:213], v[168:171], v[48:51]
	v_mfma_f32_16x16x32_bf16 v[36:39], v[202:205], v[176:179], v[36:39]
	v_mfma_f32_16x16x32_bf16 v[32:35], v[210:213], v[176:179], v[32:35]
	v_mfma_f32_16x16x32_bf16 v[20:23], v[202:205], v[184:187], v[20:23]
	v_mfma_f32_16x16x32_bf16 v[16:19], v[210:213], v[184:187], v[16:19]
	v_mfma_f32_16x16x32_bf16 v[4:7], v[202:205], v[192:195], v[4:7]
	v_mfma_f32_16x16x32_bf16 v[0:3], v[210:213], v[192:195], v[0:3]
	v_mfma_f32_16x16x32_bf16 v[52:55], v[206:209], v[172:175], v[52:55]
	v_mfma_f32_16x16x32_bf16 v[48:51], v[214:217], v[172:175], v[48:51]
	v_mfma_f32_16x16x32_bf16 v[36:39], v[206:209], v[180:183], v[36:39]
	v_mfma_f32_16x16x32_bf16 v[32:35], v[214:217], v[180:183], v[32:35]
	v_mfma_f32_16x16x32_bf16 v[20:23], v[206:209], v[188:191], v[20:23]
	v_mfma_f32_16x16x32_bf16 v[16:19], v[214:217], v[188:191], v[16:19]
	v_mfma_f32_16x16x32_bf16 v[4:7], v[206:209], v[196:199], v[4:7]
	v_mfma_f32_16x16x32_bf16 v[0:3], v[214:217], v[196:199], v[0:3]
	s_setprio 0
	s_add_i32 s56, s56, 2
	s_add_u32 s30, s30, 0x100
	s_addc_u32 s31, s31, 0
	s_add_u32 s54, s54, 0x100
	s_addc_u32 s55, s55, 0
	s_cmp_gt_u32 s56, 29
	s_cbranch_scc0 .Lrot_4
	s_barrier
	v_lshl_add_u32 v152, s26, 8, v146
	v_lshl_or_b32 v144, s51, 8, v148
	v_ashrrev_i32_e32 v153, 31, v152
	v_ashrrev_i32_e32 v145, 31, v144
	v_lshlrev_b64 v[154:155], 14, v[152:153]
	v_lshl_add_u64 v[154:155], s[88:89], 0, v[154:155]
	v_lshlrev_b64 v[156:157], 1, v[144:145]
	v_max_f32_e32 v120, 0, v120
	v_max_f32_e32 v121, 0, v121
	v_lshl_add_u64 v[144:145], v[154:155], 0, v[156:157]
	v_pk_mul_f32 v[154:155], v[120:121], v[120:121]
	v_max_f32_e32 v121, v122, v122
	v_max_f32_e32 v120, v126, v126
	v_max_f32_e32 v122, 0, v121
	v_max_f32_e32 v121, v127, v127
	v_max_f32_e32 v124, 0, v124
	v_max_f32_e32 v125, 0, v125
	v_max_f32_e32 v120, 0, v120
	v_max_f32_e32 v121, 0, v121
	v_max_f32_e32 v123, 0, v123
	v_pk_mul_f32 v[124:125], v[124:125], v[124:125]
	v_pk_mul_f32 v[126:127], v[120:121], v[120:121]
	v_pk_mul_f32 v[158:159], v[122:123], v[122:123]
	v_cvt_pk_bf16_f32 v120, v124, v125
	v_cvt_pk_bf16_f32 v121, v126, v127
	v_cvt_pk_bf16_f32 v122, v154, v155
	v_cvt_pk_bf16_f32 v123, v158, v159
	v_max_f32_e32 v112, 0, v112
	v_max_f32_e32 v113, 0, v113
	global_store_dwordx4 v[144:145], v[120:123], off
	s_nop 1
	v_pk_mul_f32 v[120:121], v[112:113], v[112:113]
	v_max_f32_e32 v113, v114, v114
	v_max_f32_e32 v112, v118, v118
	v_max_f32_e32 v114, 0, v113
	v_max_f32_e32 v113, v119, v119
	v_max_f32_e32 v116, 0, v116
	v_max_f32_e32 v117, 0, v117
	v_max_f32_e32 v112, 0, v112
	v_max_f32_e32 v113, 0, v113
	v_max_f32_e32 v115, 0, v115
	v_pk_mul_f32 v[116:117], v[116:117], v[116:117]
	v_pk_mul_f32 v[118:119], v[112:113], v[112:113]
	v_pk_mul_f32 v[122:123], v[114:115], v[114:115]
	v_cvt_pk_bf16_f32 v112, v116, v117
	v_cvt_pk_bf16_f32 v113, v118, v119
	v_cvt_pk_bf16_f32 v114, v120, v121
	v_cvt_pk_bf16_f32 v115, v122, v123
	v_max_f32_e32 v104, 0, v104
	v_max_f32_e32 v105, 0, v105
	global_store_dwordx4 v[144:145], v[112:115], off offset:256
	s_nop 1
	v_or_b32_e32 v112, 16, v152
	v_pk_mul_f32 v[114:115], v[104:105], v[104:105]
	v_max_f32_e32 v105, v106, v106
	v_ashrrev_i32_e32 v113, 31, v112
	v_max_f32_e32 v104, v110, v110
	v_max_f32_e32 v106, 0, v105
	v_max_f32_e32 v105, v111, v111
	v_lshlrev_b64 v[112:113], 14, v[112:113]
	v_max_f32_e32 v108, 0, v108
	v_max_f32_e32 v109, 0, v109
	v_max_f32_e32 v104, 0, v104
	v_max_f32_e32 v105, 0, v105
	v_max_f32_e32 v107, 0, v107
	v_lshl_add_u64 v[112:113], s[88:89], 0, v[112:113]
	v_pk_mul_f32 v[108:109], v[108:109], v[108:109]
	v_pk_mul_f32 v[110:111], v[104:105], v[104:105]
	v_pk_mul_f32 v[116:117], v[106:107], v[106:107]
	v_lshl_add_u64 v[112:113], v[112:113], 0, v[156:157]
	v_cvt_pk_bf16_f32 v104, v108, v109
	v_cvt_pk_bf16_f32 v105, v110, v111
	v_cvt_pk_bf16_f32 v106, v114, v115
	v_cvt_pk_bf16_f32 v107, v116, v117
	v_max_f32_e32 v96, 0, v96
	v_max_f32_e32 v97, 0, v97
	global_store_dwordx4 v[112:113], v[104:107], off
	s_nop 1
	v_pk_mul_f32 v[104:105], v[96:97], v[96:97]
	v_max_f32_e32 v97, v98, v98
	v_max_f32_e32 v96, v102, v102
	v_max_f32_e32 v98, 0, v97
; __device__ __forceinline__ unsigned cvt_pk_bf16(float lo, float hi) { const bf16x2_t r = __builtin_convertvector((f32x2){lo, hi}, bf16x2_t); return __builtin_bit_cast(unsigned, r); }
;     __device__ __forceinline__ void operator()(const AccT& acc, const Unit& u, int wr, int wc, int fr, int fq) const {
;     ...
;         for (int ai = 0; ai < 2; ++ai)
; #pragma unroll
;             for (int m = 0; m < 4; ++m) { bf16_t* rowp = O + (size_t)(row0 + ai * HALF + m * 16) * DFF + col0;
; #pragma unroll
;                 for (int bj = 0; bj < 2; ++bj) { f32x4 v0 = acc[ai][bj][m][0], v1 = acc[ai][bj][m][1];
; #pragma unroll
;                     for (int j = 0; j < 4; ++j) { float a = fmaxf(v0[j], 0.f), b = fmaxf(v1[j], 0.f); v0[j] = a * a; v1[j] = b * b; }
;                     u32x4 w; w.x = cvt_pk_bf16(v0[0], v0[1]); w.y = cvt_pk_bf16(v0[2], v0[3]); w.z = cvt_pk_bf16(v1[0], v1[1]); w.w = cvt_pk_bf16(v1[2], v1[3]);
;                     *(u32x4*)(rowp + bj * HALF) = w; } }
	v_max_f32_e32 v97, v103, v103
	v_max_f32_e32 v100, 0, v100
	v_max_f32_e32 v101, 0, v101
	v_max_f32_e32 v96, 0, v96
	v_max_f32_e32 v97, 0, v97
	v_max_f32_e32 v99, 0, v99
	v_pk_mul_f32 v[100:101], v[100:101], v[100:101]
	v_pk_mul_f32 v[102:103], v[96:97], v[96:97]
	v_pk_mul_f32 v[106:107], v[98:99], v[98:99]
	v_cvt_pk_bf16_f32 v96, v100, v101
	v_cvt_pk_bf16_f32 v97, v102, v103
	v_cvt_pk_bf16_f32 v98, v104, v105
	v_cvt_pk_bf16_f32 v99, v106, v107
	v_max_f32_e32 v88, 0, v88
	v_max_f32_e32 v89, 0, v89
	global_store_dwordx4 v[112:113], v[96:99], off offset:256
	s_nop 1
	v_or_b32_e32 v96, 32, v152
	v_pk_mul_f32 v[98:99], v[88:89], v[88:89]
	v_max_f32_e32 v89, v90, v90
	v_ashrrev_i32_e32 v97, 31, v96
	v_max_f32_e32 v88, v94, v94
	v_max_f32_e32 v90, 0, v89
	v_max_f32_e32 v89, v95, v95
	v_lshlrev_b64 v[96:97], 14, v[96:97]
	v_max_f32_e32 v92, 0, v92
	v_max_f32_e32 v93, 0, v93
	v_max_f32_e32 v88, 0, v88
	v_max_f32_e32 v89, 0, v89
	v_max_f32_e32 v91, 0, v91
	v_lshl_add_u64 v[96:97], s[88:89], 0, v[96:97]
	v_pk_mul_f32 v[92:93], v[92:93], v[92:93]
	v_pk_mul_f32 v[94:95], v[88:89], v[88:89]
	v_pk_mul_f32 v[100:101], v[90:91], v[90:91]
	v_lshl_add_u64 v[96:97], v[96:97], 0, v[156:157]
	v_cvt_pk_bf16_f32 v88, v92, v93
	v_cvt_pk_bf16_f32 v89, v94, v95
	v_cvt_pk_bf16_f32 v90, v98, v99
	v_cvt_pk_bf16_f32 v91, v100, v101
	v_max_f32_e32 v80, 0, v80
	v_max_f32_e32 v81, 0, v81
	global_store_dwordx4 v[96:97], v[88:91], off
	s_nop 1
	v_pk_mul_f32 v[88:89], v[80:81], v[80:81]
	v_max_f32_e32 v81, v82, v82
	v_max_f32_e32 v80, v86, v86
	v_max_f32_e32 v82, 0, v81
	v_max_f32_e32 v81, v87, v87
	v_max_f32_e32 v84, 0, v84
	v_max_f32_e32 v85, 0, v85
	v_max_f32_e32 v80, 0, v80
	v_max_f32_e32 v81, 0, v81
	v_max_f32_e32 v83, 0, v83
	v_pk_mul_f32 v[84:85], v[84:85], v[84:85]
	v_pk_mul_f32 v[86:87], v[80:81], v[80:81]
	v_pk_mul_f32 v[90:91], v[82:83], v[82:83]
	v_cvt_pk_bf16_f32 v80, v84, v85
	v_cvt_pk_bf16_f32 v81, v86, v87
	v_cvt_pk_bf16_f32 v82, v88, v89
	v_cvt_pk_bf16_f32 v83, v90, v91
	v_max_f32_e32 v72, 0, v72
	v_max_f32_e32 v73, 0, v73
	global_store_dwordx4 v[96:97], v[80:83], off offset:256
	s_nop 1
	v_or_b32_e32 v80, 48, v152
	v_pk_mul_f32 v[82:83], v[72:73], v[72:73]
	v_max_f32_e32 v73, v74, v74
	v_ashrrev_i32_e32 v81, 31, v80
	v_max_f32_e32 v72, v78, v78
	v_max_f32_e32 v74, 0, v73
	v_max_f32_e32 v73, v79, v79
	v_lshlrev_b64 v[80:81], 14, v[80:81]
	v_max_f32_e32 v76, 0, v76
	v_max_f32_e32 v77, 0, v77
	v_max_f32_e32 v72, 0, v72
	v_max_f32_e32 v73, 0, v73
	v_max_f32_e32 v75, 0, v75
	v_lshl_add_u64 v[80:81], s[88:89], 0, v[80:81]
	v_pk_mul_f32 v[76:77], v[76:77], v[76:77]
	v_pk_mul_f32 v[78:79], v[72:73], v[72:73]
	v_pk_mul_f32 v[84:85], v[74:75], v[74:75]
	v_lshl_add_u64 v[80:81], v[80:81], 0, v[156:157]
	v_cvt_pk_bf16_f32 v72, v76, v77
	v_cvt_pk_bf16_f32 v73, v78, v79
	v_cvt_pk_bf16_f32 v74, v82, v83
	v_cvt_pk_bf16_f32 v75, v84, v85
	v_max_f32_e32 v64, 0, v64
	v_max_f32_e32 v65, 0, v65
	global_store_dwordx4 v[80:81], v[72:75], off
	s_nop 1
	v_pk_mul_f32 v[72:73], v[64:65], v[64:65]
	v_max_f32_e32 v65, v66, v66
	v_max_f32_e32 v64, v70, v70
	v_max_f32_e32 v66, 0, v65
	v_max_f32_e32 v65, v71, v71
	v_max_f32_e32 v68, 0, v68
	v_max_f32_e32 v69, 0, v69
	v_max_f32_e32 v64, 0, v64
	v_max_f32_e32 v65, 0, v65
	v_max_f32_e32 v67, 0, v67
	v_pk_mul_f32 v[68:69], v[68:69], v[68:69]
	v_pk_mul_f32 v[70:71], v[64:65], v[64:65]
	v_pk_mul_f32 v[74:75], v[66:67], v[66:67]
	v_cvt_pk_bf16_f32 v64, v68, v69
	v_cvt_pk_bf16_f32 v65, v70, v71
	v_cvt_pk_bf16_f32 v66, v72, v73
	v_cvt_pk_bf16_f32 v67, v74, v75
	v_max_f32_e32 v56, 0, v56
	v_max_f32_e32 v57, 0, v57
	global_store_dwordx4 v[80:81], v[64:67], off offset:256
	s_nop 1
	v_pk_mul_f32 v[66:67], v[56:57], v[56:57]
	v_max_f32_e32 v57, v58, v58
	v_max_f32_e32 v60, 0, v60
	v_max_f32_e32 v61, 0, v61
	v_max_f32_e32 v56, v62, v62
	v_max_f32_e32 v58, 0, v57
	v_max_f32_e32 v57, v63, v63
	v_pk_mul_f32 v[60:61], v[60:61], v[60:61]
	v_max_f32_e32 v56, 0, v56
	v_max_f32_e32 v57, 0, v57
	v_max_f32_e32 v59, 0, v59
	s_mov_b32 s5, 0x200000
	v_pk_mul_f32 v[62:63], v[56:57], v[56:57]
	v_pk_mul_f32 v[68:69], v[58:59], v[58:59]
	v_cvt_pk_bf16_f32 v56, v60, v61
	v_add_co_u32_e32 v60, vcc, s5, v144
	v_cvt_pk_bf16_f32 v57, v62, v63
	v_cvt_pk_bf16_f32 v58, v66, v67
	v_cvt_pk_bf16_f32 v59, v68, v69
	v_addc_co_u32_e32 v61, vcc, 0, v145, vcc
	v_max_f32_e32 v48, 0, v48
	v_max_f32_e32 v49, 0, v49
	global_store_dwordx4 v[60:61], v[56:59], off
	s_nop 1
	v_pk_mul_f32 v[56:57], v[48:49], v[48:49]
	v_max_f32_e32 v49, v50, v50
	v_max_f32_e32 v48, v54, v54
	v_max_f32_e32 v50, 0, v49
	v_max_f32_e32 v49, v55, v55
	v_max_f32_e32 v52, 0, v52
	v_max_f32_e32 v53, 0, v53
	v_max_f32_e32 v48, 0, v48
	v_max_f32_e32 v49, 0, v49
	v_max_f32_e32 v51, 0, v51
	s_mov_b64 s[28:29], 0x200000
	v_pk_mul_f32 v[52:53], v[52:53], v[52:53]
	v_pk_mul_f32 v[54:55], v[48:49], v[48:49]
	v_pk_mul_f32 v[58:59], v[50:51], v[50:51]
	v_lshl_add_u64 v[64:65], v[144:145], 0, s[28:29]
; __device__ __forceinline__ unsigned cvt_pk_bf16(float lo, float hi) { const bf16x2_t r = __builtin_convertvector((f32x2){lo, hi}, bf16x2_t); return __builtin_bit_cast(unsigned, r); }
; #define PG8_WAIT_V(n) asm volatile("s_waitcnt vmcnt(" #n ")" ::: "memory")
; #define PG8_BAR __builtin_amdgcn_s_barrier()
; template <class Epi>
; __device__ __forceinline__ void gemm_phase(LAS unsigned char* lds, const bf16_t* A, int lda, const bf16_t* Bt, int ldb, int M, int N, int K, int asel, const Epi& E, const int fixed_round = -1) {
;     ...
;     PG8_WAIT_V(0);
;     if (wr == 0) PG8_BAR;
;     PG8_BAR;
;     __device__ __forceinline__ void operator()(const AccT& acc, const Unit& u, int wr, int wc, int fr, int fq) const {
;     ...
;         for (int ai = 0; ai < 2; ++ai)
; #pragma unroll
;             for (int m = 0; m < 4; ++m) { bf16_t* rowp = O + (size_t)(row0 + ai * HALF + m * 16) * DFF + col0;
; #pragma unroll
;                 for (int bj = 0; bj < 2; ++bj) { f32x4 v0 = acc[ai][bj][m][0], v1 = acc[ai][bj][m][1];
; #pragma unroll
;                     for (int j = 0; j < 4; ++j) { float a = fmaxf(v0[j], 0.f), b = fmaxf(v1[j], 0.f); v0[j] = a * a; v1[j] = b * b; }
;                     u32x4 w; w.x = cvt_pk_bf16(v0[0], v0[1]); w.y = cvt_pk_bf16(v0[2], v0[3]); w.z = cvt_pk_bf16(v1[0], v1[1]); w.w = cvt_pk_bf16(v1[2], v1[3]);
;                     *(u32x4*)(rowp + bj * HALF) = w; } }
	v_cvt_pk_bf16_f32 v48, v52, v53
	v_cvt_pk_bf16_f32 v49, v54, v55
	v_cvt_pk_bf16_f32 v50, v56, v57
	v_cvt_pk_bf16_f32 v51, v58, v59
	v_max_f32_e32 v40, 0, v40
	v_max_f32_e32 v41, 0, v41
	global_store_dwordx4 v[64:65], v[48:51], off offset:256
	s_nop 1
	v_pk_mul_f32 v[50:51], v[40:41], v[40:41]
	v_max_f32_e32 v41, v42, v42
	v_max_f32_e32 v44, 0, v44
	v_max_f32_e32 v45, 0, v45
	v_max_f32_e32 v40, v46, v46
	v_max_f32_e32 v42, 0, v41
	v_max_f32_e32 v41, v47, v47
	v_pk_mul_f32 v[44:45], v[44:45], v[44:45]
	v_max_f32_e32 v40, 0, v40
	v_max_f32_e32 v41, 0, v41
	v_max_f32_e32 v43, 0, v43
	s_mov_b32 s5, 0x240000
	v_pk_mul_f32 v[46:47], v[40:41], v[40:41]
	v_pk_mul_f32 v[52:53], v[42:43], v[42:43]
	v_cvt_pk_bf16_f32 v40, v44, v45
	v_add_co_u32_e32 v44, vcc, s5, v144
	v_cvt_pk_bf16_f32 v41, v46, v47
	v_cvt_pk_bf16_f32 v42, v50, v51
	v_cvt_pk_bf16_f32 v43, v52, v53
	v_addc_co_u32_e32 v45, vcc, 0, v145, vcc
	v_max_f32_e32 v32, 0, v32
	v_max_f32_e32 v33, 0, v33
	global_store_dwordx4 v[44:45], v[40:43], off
	s_nop 1
	v_pk_mul_f32 v[40:41], v[32:33], v[32:33]
	v_max_f32_e32 v33, v34, v34
	v_max_f32_e32 v32, v38, v38
	v_max_f32_e32 v34, 0, v33
	v_max_f32_e32 v33, v39, v39
	v_max_f32_e32 v36, 0, v36
	v_max_f32_e32 v37, 0, v37
	v_max_f32_e32 v32, 0, v32
	v_max_f32_e32 v33, 0, v33
	v_max_f32_e32 v35, 0, v35
	s_mov_b64 s[28:29], 0x240000
	v_pk_mul_f32 v[36:37], v[36:37], v[36:37]
	v_pk_mul_f32 v[38:39], v[32:33], v[32:33]
	v_pk_mul_f32 v[42:43], v[34:35], v[34:35]
	v_lshl_add_u64 v[48:49], v[144:145], 0, s[28:29]
	v_cvt_pk_bf16_f32 v32, v36, v37
	v_cvt_pk_bf16_f32 v33, v38, v39
	v_cvt_pk_bf16_f32 v34, v40, v41
	v_cvt_pk_bf16_f32 v35, v42, v43
	v_max_f32_e32 v24, 0, v24
	v_max_f32_e32 v25, 0, v25
	global_store_dwordx4 v[48:49], v[32:35], off offset:256
	s_nop 1
	v_pk_mul_f32 v[34:35], v[24:25], v[24:25]
	v_max_f32_e32 v25, v26, v26
	v_max_f32_e32 v28, 0, v28
	v_max_f32_e32 v29, 0, v29
	v_max_f32_e32 v24, v30, v30
	v_max_f32_e32 v26, 0, v25
	v_max_f32_e32 v25, v31, v31
	v_pk_mul_f32 v[28:29], v[28:29], v[28:29]
	v_max_f32_e32 v24, 0, v24
	v_max_f32_e32 v25, 0, v25
	v_max_f32_e32 v27, 0, v27
	s_mov_b32 s5, 0x280000
	v_pk_mul_f32 v[30:31], v[24:25], v[24:25]
	v_pk_mul_f32 v[36:37], v[26:27], v[26:27]
	v_cvt_pk_bf16_f32 v24, v28, v29
	v_add_co_u32_e32 v28, vcc, s5, v144
	v_cvt_pk_bf16_f32 v25, v30, v31
	v_cvt_pk_bf16_f32 v26, v34, v35
	v_cvt_pk_bf16_f32 v27, v36, v37
	v_addc_co_u32_e32 v29, vcc, 0, v145, vcc
	v_max_f32_e32 v16, 0, v16
	v_max_f32_e32 v17, 0, v17
	global_store_dwordx4 v[28:29], v[24:27], off
	s_nop 1
	v_pk_mul_f32 v[24:25], v[16:17], v[16:17]
	v_max_f32_e32 v17, v18, v18
	v_max_f32_e32 v16, v22, v22
	v_max_f32_e32 v18, 0, v17
	v_max_f32_e32 v17, v23, v23
	v_max_f32_e32 v20, 0, v20
	v_max_f32_e32 v21, 0, v21
	v_max_f32_e32 v16, 0, v16
	v_max_f32_e32 v17, 0, v17
	v_max_f32_e32 v19, 0, v19
	s_mov_b64 s[28:29], 0x280000
	v_pk_mul_f32 v[20:21], v[20:21], v[20:21]
	v_pk_mul_f32 v[22:23], v[16:17], v[16:17]
	v_pk_mul_f32 v[26:27], v[18:19], v[18:19]
	v_lshl_add_u64 v[32:33], v[144:145], 0, s[28:29]
	v_cvt_pk_bf16_f32 v16, v20, v21
	v_cvt_pk_bf16_f32 v17, v22, v23
	v_cvt_pk_bf16_f32 v18, v24, v25
	v_cvt_pk_bf16_f32 v19, v26, v27
	v_max_f32_e32 v8, 0, v8
	v_max_f32_e32 v9, 0, v9
	global_store_dwordx4 v[32:33], v[16:19], off offset:256
	s_nop 1
	v_pk_mul_f32 v[18:19], v[8:9], v[8:9]
	v_max_f32_e32 v9, v10, v10
	v_max_f32_e32 v12, 0, v12
	v_max_f32_e32 v13, 0, v13
	v_max_f32_e32 v8, v14, v14
	v_max_f32_e32 v10, 0, v9
	v_max_f32_e32 v9, v15, v15
	v_pk_mul_f32 v[12:13], v[12:13], v[12:13]
	v_max_f32_e32 v8, 0, v8
	v_max_f32_e32 v9, 0, v9
	v_max_f32_e32 v11, 0, v11
	v_pk_mul_f32 v[14:15], v[8:9], v[8:9]
	v_pk_mul_f32 v[20:21], v[10:11], v[10:11]
	v_cvt_pk_bf16_f32 v8, v12, v13
	v_add_co_u32_e32 v12, vcc, s50, v144
	v_cvt_pk_bf16_f32 v9, v14, v15
	v_cvt_pk_bf16_f32 v10, v18, v19
	v_cvt_pk_bf16_f32 v11, v20, v21
	v_addc_co_u32_e32 v13, vcc, 0, v145, vcc
	v_max_f32_e32 v0, 0, v0
	v_max_f32_e32 v1, 0, v1
	global_store_dwordx4 v[12:13], v[8:11], off
	s_nop 1
	v_pk_mul_f32 v[8:9], v[0:1], v[0:1]
	v_max_f32_e32 v1, v2, v2
	v_max_f32_e32 v0, v6, v6
	v_max_f32_e32 v2, 0, v1
	v_max_f32_e32 v1, v7, v7
	v_max_f32_e32 v4, 0, v4
	v_max_f32_e32 v5, 0, v5
	v_max_f32_e32 v0, 0, v0
	v_max_f32_e32 v1, 0, v1
	v_max_f32_e32 v3, 0, v3
	s_mov_b64 s[28:29], 0x2c0000
	v_pk_mul_f32 v[4:5], v[4:5], v[4:5]
	v_pk_mul_f32 v[6:7], v[0:1], v[0:1]
	v_pk_mul_f32 v[10:11], v[2:3], v[2:3]
	v_lshl_add_u64 v[16:17], v[144:145], 0, s[28:29]
	v_cvt_pk_bf16_f32 v0, v4, v5
	v_cvt_pk_bf16_f32 v1, v6, v7
	v_cvt_pk_bf16_f32 v2, v8, v9
	v_cvt_pk_bf16_f32 v3, v10, v11
	s_and_b64 vcc, exec, s[0:1]
	s_mov_b32 s51, s4
	s_mov_b32 s26, s6
	s_mov_b64 s[34:35], s[20:21]
	s_mov_b64 s[30:31], s[18:19]
	global_store_dwordx4 v[16:17], v[0:3], off offset:256
	s_cbranch_vccz .LBB0_584
	s_waitcnt vmcnt(0)
	s_cmpk_gt_u32 s33, 0xff
	s_cbranch_scc1 .LBB0_595
	s_barrier

; #define PG8_STAGE(bufoff, gbase, voff) do { _Pragma("unroll") for (int _i = 0; _i < 2; ++_i) \
;         __builtin_amdgcn_global_load_lds((const unsigned*)((const char*)(gbase) + (voff)[_i]), (LAS unsigned*)(lds + (bufoff) + ldsw + _i * 8192), 16, 0, 0); } while (0)
; #define PG8_WAIT_V(n) asm volatile("s_waitcnt vmcnt(" #n ")" ::: "memory")
; #define PG8_BAR __builtin_amdgcn_s_barrier()
; template <class Epi>
; __device__ __forceinline__ void gemm_phase(LAS unsigned char* lds, const bf16_t* A, int lda, const bf16_t* Bt, int ldb, int M, int N, int K, int asel, const Epi& E, const int fixed_round = -1) {
;     ...
;     for (int i = 0; i < 2; ++i) { int R, C; stage_rc(tid * 16 + i * 8192, R, C); const int Rb = Epi::PERM ? ((R & ~31) + perm32(R & 31)) : R;
;         voffA[i] = (unsigned)(R * lda + C) * 2u; voffB[i] = (unsigned)(Rb * ldb + C) * 2u; }
;     const size_t kstep = (size_t)(BK * 2);
;     const size_t hstepA = (size_t)HALF * lda * 2, hstepB = (size_t)HALF * ldb * 2;
;     const size_t tstepA = 2 * hstepA, tstepB = 2 * hstepB;
;     const unsigned ldsw = (unsigned)wid * 1024u;
;     const int aoff = lds_byte(wr * 64 + fr, fq * 8), boff = lds_byte(wc * 32 + fr, fq * 8);
;     ...
;     Unit cur, nxt; int ui = 0;
;     if (fixed_round < 0) { if (!S.next(0, cur)) return; }
;     else { const int c = blockIdx.x; cur.pm = 32 * fixed_round + 4 * (c & 7) + (c >> 6); cur.pn = (c >> 3) & 7; }
;     f32x4 acc[2][2][4][2];
; #pragma unroll
;     for (int a = 0; a < 2; ++a)
; #pragma unroll
;         for (int b = 0; b < 2; ++b)
; #pragma unroll
;             for (int m = 0; m < 4; ++m)
; #pragma unroll
;                 for (int n = 0; n < 2; ++n) acc[a][b][m][n] = (f32x4){0.f, 0.f, 0.f, 0.f};
;     bf16x8 At[4][2], B0[2][2], B1[2][2];
;     const char* cA = PG8_ABASE(cur); const char* cB = (const char*)Bt + (size_t)cur.pn * tstepB;
;     PG8_STAGE(PG8_SB(0, 0), cB, voffB); PG8_STAGE(PG8_SA(0, 0), cA, voffA); PG8_STAGE(PG8_SB(0, 1), cB + hstepB, voffB); PG8_STAGE(PG8_SA(0, 1), cA + hstepA, voffA);
;     if (wr == 1) PG8_BAR;
;     PG8_WAIT_V(4); PG8_BAR;
;     PG8_STAGE(PG8_SB(1, 0), cB + kstep, voffB); PG8_STAGE(PG8_SA(1, 0), cA + kstep, voffA); PG8_STAGE(PG8_SB(1, 1), cB + hstepB + kstep, voffB);
;     PG8_WAIT_V(6); PG8_BAR;
.LBB0_650:
	v_bfe_u32 v155, v12, 4, 2
	v_and_b32_e32 v164, 15, v12
	v_lshlrev_b32_e32 v15, 4, v155
	v_lshlrev_b32_e32 v12, 2, v12
	s_and_b32 s33, s0, 3
	v_lshl_or_b32 v15, v164, 6, v15
	s_lshl_b32 s0, s1, 13
	v_and_b32_e32 v12, 32, v12
	v_bitop3_b32 v16, v15, s0, v12 bitop3:0xde
	s_lshl_b32 s0, s33, 12
	s_lshl_b32 s40, s1, 6
	v_bitop3_b32 v12, v15, s0, v12 bitop3:0xde
	s_mov_b64 s[0:1], 0x80
	s_add_i32 m0, s42, 0x18000
	v_lshl_add_u64 v[6:7], v[6:7], 0, s[0:1]
	s_waitcnt vmcnt(4)
	s_barrier
	global_load_lds_dwordx4 v[6:7], off
	v_lshl_add_u64 v[4:5], v[4:5], 0, s[0:1]
	s_add_i32 m0, s42, 0x1a000
	s_add_i32 s46, s42, 0x8000
	s_add_i32 s47, s42, 0xa000
	global_load_lds_dwordx4 v[4:5], off
	v_lshl_add_u64 v[2:3], v[2:3], 0, s[0:1]
	s_mov_b32 m0, s46
	s_add_u32 s6, s2, 0x200080
	global_load_lds_dwordx4 v[2:3], off
	v_lshl_add_u64 v[0:1], v[0:1], 0, s[0:1]
	s_mov_b32 m0, s47
	s_addc_u32 s7, s3, 0
	global_load_lds_dwordx4 v[0:1], off
	s_add_i32 m0, s42, 0x1c000
	v_lshl_add_u64 v[0:1], s[6:7], 0, v[130:131]
	global_load_lds_dwordx4 v[0:1], off
	v_lshl_add_u64 v[0:1], s[6:7], 0, v[134:135]
	s_add_i32 m0, s42, 0x1e000
	s_add_u32 s20, s78, s8
	global_load_lds_dwordx4 v[0:1], off
	v_lshlrev_b32_e32 v0, 17, v8
	v_and_b32_e32 v0, 0xfffc0000, v0
	v_lshl_add_u32 v0, v9, 14, v0
	v_and_b32_e32 v1, 1, v8
	v_lshl_or_b32 v0, v1, 6, v0
	v_lshl_add_u32 v0, v10, 1, v0
	v_mov_b32_e32 v1, v131
	s_addc_u32 s21, s79, s9
	v_lshl_add_u64 v[136:137], s[20:21], 0, v[0:1]
	v_lshlrev_b32_e32 v0, 17, v11
	v_and_b32_e32 v0, 0xfffc0000, v0
	v_lshl_add_u32 v0, v13, 14, v0
	v_and_b32_e32 v1, 1, v11
	s_waitcnt vmcnt(6)
	v_lshl_or_b32 v0, v1, 6, v0
	v_lshl_add_u32 v0, v14, 1, v0
	v_mov_b32_e32 v1, v131
	s_add_i32 s51, s81, s28
	s_add_i32 s53, s82, s28
	s_add_i32 s55, s83, s28
	s_add_i32 s57, s84, s28
	v_or_b32_e32 v158, s40, v164
	v_lshl_add_u64 v[138:139], s[20:21], 0, v[0:1]
	s_mov_b32 s48, -2
	s_mov_b64 s[20:21], 0x18700080
	v_add_u32_e32 v140, s81, v12
	v_add_u32_e32 v141, 0, v16
	s_add_i32 s49, s42, 0xc000
	s_add_i32 s50, s42, 0xe000
	v_add_u32_e32 v142, s82, v12
	s_add_i32 s52, s51, 0x2000
	s_add_i32 s54, s53, 0x2000
	v_add_u32_e32 v143, s83, v12
	v_add_u32_e32 v144, s84, v12
	s_add_i32 s56, s55, 0x2000
	s_add_i32 s58, s57, 0x2000
	v_mov_b32_e32 v0, v131
	v_mov_b32_e32 v2, v131
	v_mov_b32_e32 v3, v131
	v_mov_b32_e32 v4, v131
	v_mov_b32_e32 v5, v131
	v_mov_b32_e32 v6, v131
	v_mov_b32_e32 v7, v131
	v_mov_b32_e32 v12, v131
	v_mov_b32_e32 v13, v131
	v_mov_b32_e32 v14, v131
	v_mov_b32_e32 v15, v131
	v_mov_b32_e32 v20, v131
	v_mov_b32_e32 v21, v131
	v_mov_b32_e32 v22, v131
	v_mov_b32_e32 v23, v131
	v_mov_b32_e32 v28, v131
	v_mov_b32_e32 v29, v131
	v_mov_b32_e32 v30, v131
	v_mov_b32_e32 v31, v131
	v_mov_b32_e32 v36, v131
	v_mov_b32_e32 v37, v131
	v_mov_b32_e32 v38, v131
	v_mov_b32_e32 v39, v131
	v_mov_b32_e32 v44, v131
	v_mov_b32_e32 v45, v131
	v_mov_b32_e32 v46, v131
	v_mov_b32_e32 v47, v131
	v_mov_b32_e32 v52, v131
	v_mov_b32_e32 v53, v131
	v_mov_b32_e32 v54, v131
	v_mov_b32_e32 v55, v131
	v_mov_b32_e32 v8, v131
	v_mov_b32_e32 v9, v131
	v_mov_b32_e32 v10, v131
	v_mov_b32_e32 v11, v131
	v_mov_b32_e32 v16, v131
	v_mov_b32_e32 v17, v131
	v_mov_b32_e32 v18, v131
	v_mov_b32_e32 v19, v131
	v_mov_b32_e32 v24, v131
	v_mov_b32_e32 v25, v131
	v_mov_b32_e32 v26, v131
	v_mov_b32_e32 v27, v131
	v_mov_b32_e32 v32, v131
	v_mov_b32_e32 v33, v131
	v_mov_b32_e32 v34, v131
	v_mov_b32_e32 v35, v131
	v_mov_b32_e32 v40, v131
	v_mov_b32_e32 v41, v131
	v_mov_b32_e32 v42, v131
	v_mov_b32_e32 v43, v131
	v_mov_b32_e32 v48, v131
	v_mov_b32_e32 v49, v131
	v_mov_b32_e32 v50, v131
	v_mov_b32_e32 v51, v131
	v_mov_b32_e32 v56, v131
	v_mov_b32_e32 v57, v131
	v_mov_b32_e32 v58, v131
	v_mov_b32_e32 v59, v131
	v_mov_b32_e32 v60, v131
	v_mov_b32_e32 v61, v131
	v_mov_b32_e32 v62, v131
	v_mov_b32_e32 v63, v131
	v_mov_b32_e32 v64, v131
	v_mov_b32_e32 v65, v131
	v_mov_b32_e32 v66, v131
	v_mov_b32_e32 v67, v131
	v_mov_b32_e32 v68, v131
	v_mov_b32_e32 v69, v131
	v_mov_b32_e32 v70, v131
	v_mov_b32_e32 v71, v131
	v_mov_b32_e32 v76, v131
	v_mov_b32_e32 v77, v131
	v_mov_b32_e32 v78, v131
	v_mov_b32_e32 v79, v131
	v_mov_b32_e32 v84, v131
	v_mov_b32_e32 v85, v131
	v_mov_b32_e32 v86, v131
	v_mov_b32_e32 v87, v131
	v_mov_b32_e32 v92, v131
	v_mov_b32_e32 v93, v131
	v_mov_b32_e32 v94, v131
	v_mov_b32_e32 v95, v131
	v_mov_b32_e32 v100, v131
	v_mov_b32_e32 v101, v131
	v_mov_b32_e32 v102, v131
	v_mov_b32_e32 v103, v131
	v_mov_b32_e32 v108, v131
	v_mov_b32_e32 v109, v131
	v_mov_b32_e32 v110, v131
	v_mov_b32_e32 v111, v131
	v_mov_b32_e32 v116, v131
	v_mov_b32_e32 v117, v131
	v_mov_b32_e32 v118, v131
	v_mov_b32_e32 v119, v131
	v_mov_b32_e32 v72, v131
	v_mov_b32_e32 v73, v131
	v_mov_b32_e32 v74, v131
	v_mov_b32_e32 v75, v131
	v_mov_b32_e32 v80, v131
	v_mov_b32_e32 v81, v131
	v_mov_b32_e32 v82, v131
	v_mov_b32_e32 v83, v131
	v_mov_b32_e32 v88, v131
	v_mov_b32_e32 v89, v131
	v_mov_b32_e32 v90, v131
	v_mov_b32_e32 v91, v131
	v_mov_b32_e32 v96, v131
	v_mov_b32_e32 v97, v131
	v_mov_b32_e32 v98, v131
	v_mov_b32_e32 v99, v131
	v_mov_b32_e32 v104, v131
	v_mov_b32_e32 v105, v131
	v_mov_b32_e32 v106, v131
	v_mov_b32_e32 v107, v131
	v_mov_b32_e32 v112, v131
	v_mov_b32_e32 v113, v131
	v_mov_b32_e32 v114, v131
	v_mov_b32_e32 v115, v131
	v_mov_b32_e32 v120, v131
	v_mov_b32_e32 v121, v131
	v_mov_b32_e32 v122, v131
	v_mov_b32_e32 v123, v131
	v_mov_b32_e32 v124, v131
	v_mov_b32_e32 v125, v131
	v_mov_b32_e32 v126, v131
	v_mov_b32_e32 v127, v131
.Lrot_5:
	s_barrier
; #define PG8_STAGE(bufoff, gbase, voff) do { _Pragma("unroll") for (int _i = 0; _i < 2; ++_i) \
;         __builtin_amdgcn_global_load_lds((const unsigned*)((const char*)(gbase) + (voff)[_i]), (LAS unsigned*)(lds + (bufoff) + ldsw + _i * 8192), 16, 0, 0); } while (0)
; #define PG8_LDA(dst, b, h) do { _Pragma("unroll") for (int m = 0; m < 4; ++m) _Pragma("unroll") for (int k = 0; k < 2; ++k) dst[m][k] = *(const LAS bf16x8*)(lds + PG8_SA(b, h) + aoff + m * 2048 + k * 1024); } while (0)
; #define PG8_LDB(dst, b, h) do { _Pragma("unroll") for (int n = 0; n < 2; ++n) _Pragma("unroll") for (int k = 0; k < 2; ++k) dst[n][k] = *(const LAS bf16x8*)(lds + PG8_SB(b, h) + boff + n * 2048 + k * 1024); } while (0)
; #define PG8_WAIT_V(n) asm volatile("s_waitcnt vmcnt(" #n ")" ::: "memory")
; #define PG8_WAIT_L(n) asm volatile("s_waitcnt lgkmcnt(" #n ")" ::: "memory")
; #define PG8_BAR __builtin_amdgcn_s_barrier()
; #define PG8_SCHED __builtin_amdgcn_sched_barrier(0)
; template <class Epi>
; __device__ __forceinline__ void gemm_phase(LAS unsigned char* lds, const bf16_t* A, int lda, const bf16_t* Bt, int ldb, int M, int N, int K, int asel, const Epi& E, const int fixed_round = -1) {
;     ...
;             PG8_LDB(B0, 0, 0); PG8_SCHED; PG8_LDA(At, 0, 0); PG8_STAGE(PG8_SA(1, 1), a1 + hstepA, voffA);
;             PG8_WAIT_L(8); PG8_BAR; PG8_WAIT_L(0); PG8_MMA(0, 0, At, B0); PG8_BAR; PG8_SCHED;
;             PG8_LDB(B1, 0, 1); PG8_STAGE(PG8_SB(0, 0), b2, voffB);
;             PG8_BAR; PG8_WAIT_L(0); PG8_MMA(0, 1, At, B1); PG8_BAR;
;             PG8_LDA(At, 0, 1); PG8_STAGE(PG8_SA(0, 0), a2, voffA);
;             PG8_BAR; PG8_WAIT_L(0); PG8_MMA(1, 0, At, B0); PG8_BAR; PG8_SCHED;
;             PG8_STAGE(PG8_SB(0, 1), b2 + hstepB, voffB);
;             PG8_WAIT_V(6); PG8_BAR; PG8_MMA(1, 1, At, B1); PG8_BAR;
;             PG8_LDB(B0, 1, 0); PG8_SCHED; PG8_LDA(At, 1, 0); PG8_STAGE(PG8_SA(0, 1), a2 + hstepA, voffA);
;             PG8_WAIT_L(8); PG8_BAR; PG8_WAIT_L(0); PG8_MMA(0, 0, At, B0); PG8_BAR; PG8_SCHED;
;             PG8_LDB(B1, 1, 1); PG8_STAGE(PG8_SB(1, 0), b3, voffB);
;             PG8_BAR; PG8_WAIT_L(0); PG8_MMA(0, 1, At, B1); PG8_BAR;
.LBB0_651:
	s_add_u32 s28, s20, 0xe7900080
	ds_read_b128 v[146:149], v140
	ds_read_b128 v[150:153], v140 offset:1024
	ds_read_b128 v[160:163], v140 offset:2048
	ds_read_b128 v[166:169], v140 offset:3072
	s_addc_u32 s29, s21, -1
	s_cmpk_lg_i32 s48, 0x7c
	s_cselect_b32 s28, s28, 0
	s_cselect_b32 s29, s29, 0
	s_add_u32 s36, s86, s28
	s_addc_u32 s37, s87, s29
	s_add_u32 s34, s2, s28
	s_addc_u32 s35, s3, s29
	s_mov_b32 m0, s49
	v_lshl_add_u64 v[156:157], v[136:137], 0, s[20:21]
	ds_read_b128 v[170:173], v141
	ds_read_b128 v[174:177], v141 offset:1024
	ds_read_b128 v[178:181], v141 offset:2048
	ds_read_b128 v[182:185], v141 offset:3072
	ds_read_b128 v[186:189], v141 offset:4096
	ds_read_b128 v[190:193], v141 offset:5120
	ds_read_b128 v[194:197], v141 offset:6144
	ds_read_b128 v[202:205], v141 offset:7168
	global_load_lds_dwordx4 v[156:157], off
	v_lshl_add_u64 v[156:157], v[138:139], 0, s[20:21]
	s_mov_b32 m0, s50
	s_nop 0
	global_load_lds_dwordx4 v[156:157], off
	s_waitcnt lgkmcnt(8)
	s_barrier
	s_waitcnt lgkmcnt(0)
	s_setprio 1
	s_waitcnt lgkmcnt(0)
	v_mfma_f32_16x16x32_bf16 v[124:127], v[146:149], v[170:173], v[124:127]
	v_mfma_f32_16x16x32_bf16 v[120:123], v[160:163], v[170:173], v[120:123]
	v_mfma_f32_16x16x32_bf16 v[112:115], v[146:149], v[178:181], v[112:115]
	v_mfma_f32_16x16x32_bf16 v[104:107], v[160:163], v[178:181], v[104:107]
	v_mfma_f32_16x16x32_bf16 v[96:99], v[146:149], v[186:189], v[96:99]
	v_mfma_f32_16x16x32_bf16 v[88:91], v[160:163], v[186:189], v[88:91]
	v_mfma_f32_16x16x32_bf16 v[80:83], v[146:149], v[194:197], v[80:83]
	v_mfma_f32_16x16x32_bf16 v[72:75], v[160:163], v[194:197], v[72:75]
	v_mfma_f32_16x16x32_bf16 v[124:127], v[150:153], v[174:177], v[124:127]
	v_mfma_f32_16x16x32_bf16 v[120:123], v[166:169], v[174:177], v[120:123]
	v_mfma_f32_16x16x32_bf16 v[112:115], v[150:153], v[182:185], v[112:115]
	v_mfma_f32_16x16x32_bf16 v[104:107], v[166:169], v[182:185], v[104:107]
	v_mfma_f32_16x16x32_bf16 v[96:99], v[150:153], v[190:193], v[96:99]
	v_mfma_f32_16x16x32_bf16 v[88:91], v[166:169], v[190:193], v[88:91]
	v_mfma_f32_16x16x32_bf16 v[80:83], v[150:153], v[202:205], v[80:83]
	v_mfma_f32_16x16x32_bf16 v[72:75], v[166:169], v[202:205], v[72:75]
	s_setprio 0
	s_barrier
	s_mov_b32 m0, s51
	s_add_u32 s98, s34, s0
	s_addc_u32 s99, s35, s1
	ds_read_b128 v[206:209], v142
	ds_read_b128 v[210:213], v142 offset:1024
	ds_read_b128 v[214:217], v142 offset:2048
	ds_read_b128 v[218:221], v142 offset:3072
	global_load_lds_dwordx4 v130, s[34:35]
	s_mov_b32 m0, s52
	s_nop 0
	global_load_lds_dwordx4 v134, s[34:35]
	s_barrier
	s_waitcnt lgkmcnt(0)
	s_setprio 1
	s_waitcnt lgkmcnt(0)
	v_mfma_f32_16x16x32_bf16 v[116:119], v[206:209], v[170:173], v[116:119]
	v_mfma_f32_16x16x32_bf16 v[108:111], v[214:217], v[170:173], v[108:111]
	v_mfma_f32_16x16x32_bf16 v[100:103], v[206:209], v[178:181], v[100:103]
	v_mfma_f32_16x16x32_bf16 v[92:95], v[214:217], v[178:181], v[92:95]
	v_mfma_f32_16x16x32_bf16 v[84:87], v[206:209], v[186:189], v[84:87]
	v_mfma_f32_16x16x32_bf16 v[76:79], v[214:217], v[186:189], v[76:79]
	v_mfma_f32_16x16x32_bf16 v[68:71], v[206:209], v[194:197], v[68:71]
	v_mfma_f32_16x16x32_bf16 v[64:67], v[214:217], v[194:197], v[64:67]
	v_mfma_f32_16x16x32_bf16 v[116:119], v[210:213], v[174:177], v[116:119]
	v_mfma_f32_16x16x32_bf16 v[108:111], v[218:221], v[174:177], v[108:111]
	v_mfma_f32_16x16x32_bf16 v[100:103], v[210:213], v[182:185], v[100:103]
	v_mfma_f32_16x16x32_bf16 v[92:95], v[218:221], v[182:185], v[92:95]
	v_mfma_f32_16x16x32_bf16 v[84:87], v[210:213], v[190:193], v[84:87]
	v_mfma_f32_16x16x32_bf16 v[76:79], v[218:221], v[190:193], v[76:79]
	v_mfma_f32_16x16x32_bf16 v[68:71], v[210:213], v[202:205], v[68:71]
	v_mfma_f32_16x16x32_bf16 v[64:67], v[218:221], v[202:205], v[64:67]
	s_setprio 0
	s_mov_b32 m0, s42
	s_add_u32 s100, s36, s0
	s_addc_u32 s101, s37, s1
	s_barrier
	ds_read_b128 v[170:173], v141 offset:16384
	ds_read_b128 v[174:177], v141 offset:17408
	ds_read_b128 v[178:181], v141 offset:18432
	ds_read_b128 v[182:185], v141 offset:19456
	ds_read_b128 v[186:189], v141 offset:20480
	ds_read_b128 v[190:193], v141 offset:21504
	ds_read_b128 v[194:197], v141 offset:22528
	ds_read_b128 v[202:205], v141 offset:23552
	global_load_lds_dwordx4 v128, s[36:37]
	s_mov_b32 m0, s43
	s_nop 0
	global_load_lds_dwordx4 v132, s[36:37]
	s_barrier
	s_waitcnt lgkmcnt(0)
	s_setprio 1
	s_waitcnt lgkmcnt(0)
	v_mfma_f32_16x16x32_bf16 v[60:63], v[146:149], v[170:173], v[60:63]
	v_mfma_f32_16x16x32_bf16 v[56:59], v[160:163], v[170:173], v[56:59]
	v_mfma_f32_16x16x32_bf16 v[48:51], v[146:149], v[178:181], v[48:51]
	v_mfma_f32_16x16x32_bf16 v[40:43], v[160:163], v[178:181], v[40:43]
	v_mfma_f32_16x16x32_bf16 v[32:35], v[146:149], v[186:189], v[32:35]
	v_mfma_f32_16x16x32_bf16 v[24:27], v[160:163], v[186:189], v[24:27]
	v_mfma_f32_16x16x32_bf16 v[16:19], v[146:149], v[194:197], v[16:19]
	v_mfma_f32_16x16x32_bf16 v[8:11], v[160:163], v[194:197], v[8:11]
	v_mfma_f32_16x16x32_bf16 v[60:63], v[150:153], v[174:177], v[60:63]
	v_mfma_f32_16x16x32_bf16 v[56:59], v[166:169], v[174:177], v[56:59]
	v_mfma_f32_16x16x32_bf16 v[48:51], v[150:153], v[182:185], v[48:51]
	v_mfma_f32_16x16x32_bf16 v[40:43], v[166:169], v[182:185], v[40:43]
	v_mfma_f32_16x16x32_bf16 v[32:35], v[150:153], v[190:193], v[32:35]
	v_mfma_f32_16x16x32_bf16 v[24:27], v[166:169], v[190:193], v[24:27]
	v_mfma_f32_16x16x32_bf16 v[16:19], v[150:153], v[202:205], v[16:19]
	v_mfma_f32_16x16x32_bf16 v[8:11], v[166:169], v[202:205], v[8:11]
	s_setprio 0
	s_barrier
	s_add_u32 s28, s34, 0x200000
	s_addc_u32 s29, s35, 0
	s_mov_b32 m0, s53
	s_nop 0
	global_load_lds_dwordx4 v130, s[28:29]
	s_mov_b32 m0, s54
	s_nop 0
	global_load_lds_dwordx4 v134, s[28:29]
	s_waitcnt vmcnt(6)
	s_barrier
; #define PG8_STAGE(bufoff, gbase, voff) do { _Pragma("unroll") for (int _i = 0; _i < 2; ++_i) \
;         __builtin_amdgcn_global_load_lds((const unsigned*)((const char*)(gbase) + (voff)[_i]), (LAS unsigned*)(lds + (bufoff) + ldsw + _i * 8192), 16, 0, 0); } while (0)
; #define PG8_LDA(dst, b, h) do { _Pragma("unroll") for (int m = 0; m < 4; ++m) _Pragma("unroll") for (int k = 0; k < 2; ++k) dst[m][k] = *(const LAS bf16x8*)(lds + PG8_SA(b, h) + aoff + m * 2048 + k * 1024); } while (0)
; #define PG8_LDB(dst, b, h) do { _Pragma("unroll") for (int n = 0; n < 2; ++n) _Pragma("unroll") for (int k = 0; k < 2; ++k) dst[n][k] = *(const LAS bf16x8*)(lds + PG8_SB(b, h) + boff + n * 2048 + k * 1024); } while (0)
; #define PG8_WAIT_V(n) asm volatile("s_waitcnt vmcnt(" #n ")" ::: "memory")
; #define PG8_WAIT_L(n) asm volatile("s_waitcnt lgkmcnt(" #n ")" ::: "memory")
; #define PG8_BAR __builtin_amdgcn_s_barrier()
; #define PG8_SCHED __builtin_amdgcn_sched_barrier(0)
; template <class Epi>
; __device__ __forceinline__ void gemm_phase(LAS unsigned char* lds, const bf16_t* A, int lda, const bf16_t* Bt, int ldb, int M, int N, int K, int asel, const Epi& E, const int fixed_round = -1) {
;     ...
;             PG8_BAR; PG8_WAIT_L(0); PG8_MMA(1, 0, At, B0); PG8_BAR; PG8_SCHED;
;             PG8_STAGE(PG8_SB(0, 1), b2 + hstepB, voffB);
;             PG8_WAIT_V(6); PG8_BAR; PG8_MMA(1, 1, At, B1); PG8_BAR;
;             PG8_LDB(B0, 1, 0); PG8_SCHED; PG8_LDA(At, 1, 0); PG8_STAGE(PG8_SA(0, 1), a2 + hstepA, voffA);
;             PG8_WAIT_L(8); PG8_BAR; PG8_WAIT_L(0); PG8_MMA(0, 0, At, B0); PG8_BAR; PG8_SCHED;
;             PG8_LDB(B1, 1, 1); PG8_STAGE(PG8_SB(1, 0), b3, voffB);
;             PG8_BAR; PG8_WAIT_L(0); PG8_MMA(0, 1, At, B1); PG8_BAR;
	s_setprio 1
	v_mfma_f32_16x16x32_bf16 v[52:55], v[206:209], v[170:173], v[52:55]
	v_mfma_f32_16x16x32_bf16 v[44:47], v[214:217], v[170:173], v[44:47]
	v_mfma_f32_16x16x32_bf16 v[36:39], v[206:209], v[178:181], v[36:39]
	v_mfma_f32_16x16x32_bf16 v[28:31], v[214:217], v[178:181], v[28:31]
	v_mfma_f32_16x16x32_bf16 v[20:23], v[206:209], v[186:189], v[20:23]
	v_mfma_f32_16x16x32_bf16 v[12:15], v[214:217], v[186:189], v[12:15]
	v_mfma_f32_16x16x32_bf16 v[4:7], v[206:209], v[194:197], v[4:7]
	v_mfma_f32_16x16x32_bf16 v[0:3], v[214:217], v[194:197], v[0:3]
	v_mfma_f32_16x16x32_bf16 v[52:55], v[210:213], v[174:177], v[52:55]
	v_mfma_f32_16x16x32_bf16 v[44:47], v[218:221], v[174:177], v[44:47]
	v_mfma_f32_16x16x32_bf16 v[36:39], v[210:213], v[182:185], v[36:39]
	v_mfma_f32_16x16x32_bf16 v[28:31], v[218:221], v[182:185], v[28:31]
	v_mfma_f32_16x16x32_bf16 v[20:23], v[210:213], v[190:193], v[20:23]
	v_mfma_f32_16x16x32_bf16 v[12:15], v[218:221], v[190:193], v[12:15]
	v_mfma_f32_16x16x32_bf16 v[4:7], v[210:213], v[202:205], v[4:7]
	v_mfma_f32_16x16x32_bf16 v[0:3], v[218:221], v[202:205], v[0:3]
	s_setprio 0
	s_barrier
	ds_read_b128 v[146:149], v143
	ds_read_b128 v[150:153], v143 offset:1024
	ds_read_b128 v[160:163], v143 offset:2048
	ds_read_b128 v[166:169], v143 offset:3072
	s_add_u32 s28, s36, 0x200000
	s_addc_u32 s29, s37, 0
	s_mov_b32 m0, s44
	ds_read_b128 v[170:173], v141 offset:32768
	ds_read_b128 v[174:177], v141 offset:33792
	ds_read_b128 v[178:181], v141 offset:34816
	ds_read_b128 v[182:185], v141 offset:35840
	ds_read_b128 v[186:189], v141 offset:36864
	ds_read_b128 v[190:193], v141 offset:37888
	ds_read_b128 v[194:197], v141 offset:38912
	ds_read_b128 v[202:205], v141 offset:39936
	global_load_lds_dwordx4 v128, s[28:29]
	s_mov_b32 m0, s45
	s_nop 0
	global_load_lds_dwordx4 v132, s[28:29]
	s_waitcnt lgkmcnt(8)
	s_barrier
	s_waitcnt lgkmcnt(0)
	s_setprio 1
	s_waitcnt lgkmcnt(0)
	v_mfma_f32_16x16x32_bf16 v[124:127], v[146:149], v[170:173], v[124:127]
	v_mfma_f32_16x16x32_bf16 v[120:123], v[160:163], v[170:173], v[120:123]
	v_mfma_f32_16x16x32_bf16 v[112:115], v[146:149], v[178:181], v[112:115]
	v_mfma_f32_16x16x32_bf16 v[104:107], v[160:163], v[178:181], v[104:107]
	v_mfma_f32_16x16x32_bf16 v[96:99], v[146:149], v[186:189], v[96:99]
	v_mfma_f32_16x16x32_bf16 v[88:91], v[160:163], v[186:189], v[88:91]
	v_mfma_f32_16x16x32_bf16 v[80:83], v[146:149], v[194:197], v[80:83]
	v_mfma_f32_16x16x32_bf16 v[72:75], v[160:163], v[194:197], v[72:75]
	v_mfma_f32_16x16x32_bf16 v[124:127], v[150:153], v[174:177], v[124:127]
	v_mfma_f32_16x16x32_bf16 v[120:123], v[166:169], v[174:177], v[120:123]
	v_mfma_f32_16x16x32_bf16 v[112:115], v[150:153], v[182:185], v[112:115]
	v_mfma_f32_16x16x32_bf16 v[104:107], v[166:169], v[182:185], v[104:107]
	v_mfma_f32_16x16x32_bf16 v[96:99], v[150:153], v[190:193], v[96:99]
	v_mfma_f32_16x16x32_bf16 v[88:91], v[166:169], v[190:193], v[88:91]
	v_mfma_f32_16x16x32_bf16 v[80:83], v[150:153], v[202:205], v[80:83]
	v_mfma_f32_16x16x32_bf16 v[72:75], v[166:169], v[202:205], v[72:75]
	s_setprio 0
	s_barrier
	s_mov_b32 m0, s55
	ds_read_b128 v[206:209], v144
	ds_read_b128 v[210:213], v144 offset:1024
	ds_read_b128 v[214:217], v144 offset:2048
	ds_read_b128 v[218:221], v144 offset:3072
	global_load_lds_dwordx4 v130, s[98:99]
	s_mov_b32 m0, s56
	s_nop 0
	global_load_lds_dwordx4 v134, s[98:99]
	s_barrier
; #define PG8_STAGE(bufoff, gbase, voff) do { _Pragma("unroll") for (int _i = 0; _i < 2; ++_i) \
;         __builtin_amdgcn_global_load_lds((const unsigned*)((const char*)(gbase) + (voff)[_i]), (LAS unsigned*)(lds + (bufoff) + ldsw + _i * 8192), 16, 0, 0); } while (0)
; #define PG8_LDA(dst, b, h) do { _Pragma("unroll") for (int m = 0; m < 4; ++m) _Pragma("unroll") for (int k = 0; k < 2; ++k) dst[m][k] = *(const LAS bf16x8*)(lds + PG8_SA(b, h) + aoff + m * 2048 + k * 1024); } while (0)
; #define PG8_WAIT_V(n) asm volatile("s_waitcnt vmcnt(" #n ")" ::: "memory")
; #define PG8_WAIT_L(n) asm volatile("s_waitcnt lgkmcnt(" #n ")" ::: "memory")
; #define PG8_BAR __builtin_amdgcn_s_barrier()
; #define PG8_SCHED __builtin_amdgcn_sched_barrier(0)
; template <class Epi>
; __device__ __forceinline__ void gemm_phase(LAS unsigned char* lds, const bf16_t* A, int lda, const bf16_t* Bt, int ldb, int M, int N, int K, int asel, const Epi& E, const int fixed_round = -1) {
;     ...
;             PG8_BAR; PG8_WAIT_L(0); PG8_MMA(0, 1, At, B1); PG8_BAR;
;             PG8_LDA(At, 1, 1); PG8_STAGE(PG8_SA(1, 0), a3, voffA);
;             PG8_BAR; PG8_WAIT_L(0); PG8_MMA(1, 0, At, B0); PG8_BAR; PG8_SCHED;
;             PG8_STAGE(PG8_SB(1, 1), b3 + hstepB, voffB);
;             PG8_WAIT_V(6); PG8_BAR; PG8_MMA(1, 1, At, B1); PG8_BAR;
;     ...
;     PG8_WAIT_V(0);
;     if (wr == 0) PG8_BAR;
;     PG8_BAR;
	s_waitcnt lgkmcnt(0)
	s_setprio 1
	s_waitcnt lgkmcnt(0)
	v_mfma_f32_16x16x32_bf16 v[116:119], v[206:209], v[170:173], v[116:119]
	v_mfma_f32_16x16x32_bf16 v[108:111], v[214:217], v[170:173], v[108:111]
	v_mfma_f32_16x16x32_bf16 v[100:103], v[206:209], v[178:181], v[100:103]
	v_mfma_f32_16x16x32_bf16 v[92:95], v[214:217], v[178:181], v[92:95]
	v_mfma_f32_16x16x32_bf16 v[84:87], v[206:209], v[186:189], v[84:87]
	v_mfma_f32_16x16x32_bf16 v[76:79], v[214:217], v[186:189], v[76:79]
	v_mfma_f32_16x16x32_bf16 v[68:71], v[206:209], v[194:197], v[68:71]
	v_mfma_f32_16x16x32_bf16 v[64:67], v[214:217], v[194:197], v[64:67]
	v_mfma_f32_16x16x32_bf16 v[116:119], v[210:213], v[174:177], v[116:119]
	v_mfma_f32_16x16x32_bf16 v[108:111], v[218:221], v[174:177], v[108:111]
	v_mfma_f32_16x16x32_bf16 v[100:103], v[210:213], v[182:185], v[100:103]
	v_mfma_f32_16x16x32_bf16 v[92:95], v[218:221], v[182:185], v[92:95]
	v_mfma_f32_16x16x32_bf16 v[84:87], v[210:213], v[190:193], v[84:87]
	v_mfma_f32_16x16x32_bf16 v[76:79], v[218:221], v[190:193], v[76:79]
	v_mfma_f32_16x16x32_bf16 v[68:71], v[210:213], v[202:205], v[68:71]
	v_mfma_f32_16x16x32_bf16 v[64:67], v[218:221], v[202:205], v[64:67]
	s_setprio 0
	s_mov_b32 m0, s46
	s_barrier
	ds_read_b128 v[170:173], v141 offset:49152
	ds_read_b128 v[174:177], v141 offset:50176
	ds_read_b128 v[178:181], v141 offset:51200
	ds_read_b128 v[182:185], v141 offset:52224
	ds_read_b128 v[186:189], v141 offset:53248
	ds_read_b128 v[190:193], v141 offset:54272
	ds_read_b128 v[194:197], v141 offset:55296
	ds_read_b128 v[202:205], v141 offset:56320
	global_load_lds_dwordx4 v128, s[100:101]
	s_mov_b32 m0, s47
	s_nop 0
	global_load_lds_dwordx4 v132, s[100:101]
	s_barrier
	s_waitcnt lgkmcnt(0)
	s_setprio 1
	s_waitcnt lgkmcnt(0)
	v_mfma_f32_16x16x32_bf16 v[60:63], v[146:149], v[170:173], v[60:63]
	v_mfma_f32_16x16x32_bf16 v[56:59], v[160:163], v[170:173], v[56:59]
	v_mfma_f32_16x16x32_bf16 v[48:51], v[146:149], v[178:181], v[48:51]
	v_mfma_f32_16x16x32_bf16 v[40:43], v[160:163], v[178:181], v[40:43]
	v_mfma_f32_16x16x32_bf16 v[32:35], v[146:149], v[186:189], v[32:35]
	v_mfma_f32_16x16x32_bf16 v[24:27], v[160:163], v[186:189], v[24:27]
	v_mfma_f32_16x16x32_bf16 v[16:19], v[146:149], v[194:197], v[16:19]
	v_mfma_f32_16x16x32_bf16 v[8:11], v[160:163], v[194:197], v[8:11]
	v_mfma_f32_16x16x32_bf16 v[60:63], v[150:153], v[174:177], v[60:63]
	v_mfma_f32_16x16x32_bf16 v[56:59], v[166:169], v[174:177], v[56:59]
	v_mfma_f32_16x16x32_bf16 v[48:51], v[150:153], v[182:185], v[48:51]
	v_mfma_f32_16x16x32_bf16 v[40:43], v[166:169], v[182:185], v[40:43]
	v_mfma_f32_16x16x32_bf16 v[32:35], v[150:153], v[190:193], v[32:35]
	v_mfma_f32_16x16x32_bf16 v[24:27], v[166:169], v[190:193], v[24:27]
	v_mfma_f32_16x16x32_bf16 v[16:19], v[150:153], v[202:205], v[16:19]
	v_mfma_f32_16x16x32_bf16 v[8:11], v[166:169], v[202:205], v[8:11]
	s_setprio 0
	s_barrier
	s_add_u32 s28, s34, 0x200080
	s_addc_u32 s29, s35, 0
	s_mov_b32 m0, s57
	s_nop 0
	global_load_lds_dwordx4 v130, s[28:29]
	s_mov_b32 m0, s58
	s_nop 0
	global_load_lds_dwordx4 v134, s[28:29]
	s_waitcnt vmcnt(6)
	s_barrier
	s_setprio 1
	v_mfma_f32_16x16x32_bf16 v[52:55], v[206:209], v[170:173], v[52:55]
	v_mfma_f32_16x16x32_bf16 v[44:47], v[214:217], v[170:173], v[44:47]
	v_mfma_f32_16x16x32_bf16 v[36:39], v[206:209], v[178:181], v[36:39]
	v_mfma_f32_16x16x32_bf16 v[28:31], v[214:217], v[178:181], v[28:31]
	v_mfma_f32_16x16x32_bf16 v[20:23], v[206:209], v[186:189], v[20:23]
	v_mfma_f32_16x16x32_bf16 v[12:15], v[214:217], v[186:189], v[12:15]
	v_mfma_f32_16x16x32_bf16 v[4:7], v[206:209], v[194:197], v[4:7]
	v_mfma_f32_16x16x32_bf16 v[0:3], v[214:217], v[194:197], v[0:3]
	v_mfma_f32_16x16x32_bf16 v[52:55], v[210:213], v[174:177], v[52:55]
	v_mfma_f32_16x16x32_bf16 v[44:47], v[218:221], v[174:177], v[44:47]
	v_mfma_f32_16x16x32_bf16 v[36:39], v[210:213], v[182:185], v[36:39]
	v_mfma_f32_16x16x32_bf16 v[28:31], v[218:221], v[182:185], v[28:31]
	v_mfma_f32_16x16x32_bf16 v[20:23], v[210:213], v[190:193], v[20:23]
	v_mfma_f32_16x16x32_bf16 v[12:15], v[218:221], v[190:193], v[12:15]
	v_mfma_f32_16x16x32_bf16 v[4:7], v[210:213], v[202:205], v[4:7]
	v_mfma_f32_16x16x32_bf16 v[0:3], v[218:221], v[202:205], v[0:3]
	s_setprio 0
	s_add_i32 s48, s48, 2
	s_add_u32 s20, s20, 0x100
	s_addc_u32 s21, s21, 0
	s_cmpk_lt_u32 s48, 0x7e
	s_cbranch_scc1 .Lrot_5
	s_barrier
	s_waitcnt vmcnt(0)
	v_writelane_b32 v255, s8, 26
	s_cmpk_gt_u32 s41, 0xff
	s_nop 0
	v_writelane_b32 v255, s9, 27
	s_cbranch_scc1 .LBB0_654
	s_barrier

; #define PG8_STAGE(bufoff, gbase, voff) do { _Pragma("unroll") for (int _i = 0; _i < 2; ++_i) \
;         __builtin_amdgcn_global_load_lds((const unsigned*)((const char*)(gbase) + (voff)[_i]), (LAS unsigned*)(lds + (bufoff) + ldsw + _i * 8192), 16, 0, 0); } while (0)
; #define PG8_WAIT_V(n) asm volatile("s_waitcnt vmcnt(" #n ")" ::: "memory")
; #define PG8_BAR __builtin_amdgcn_s_barrier()
; template <class Epi>
; __device__ __forceinline__ void gemm_phase(LAS unsigned char* lds, const bf16_t* A, int lda, const bf16_t* Bt, int ldb, int M, int N, int K, int asel, const Epi& E, const int fixed_round = -1) {
;     ...
;     for (int i = 0; i < 2; ++i) { int R, C; stage_rc(tid * 16 + i * 8192, R, C); const int Rb = Epi::PERM ? ((R & ~31) + perm32(R & 31)) : R;
;         voffA[i] = (unsigned)(R * lda + C) * 2u; voffB[i] = (unsigned)(Rb * ldb + C) * 2u; }
;     const size_t kstep = (size_t)(BK * 2);
;     const size_t hstepA = (size_t)HALF * lda * 2, hstepB = (size_t)HALF * ldb * 2;
;     const size_t tstepA = 2 * hstepA, tstepB = 2 * hstepB;
;     const unsigned ldsw = (unsigned)wid * 1024u;
;     const int aoff = lds_byte(wr * 64 + fr, fq * 8), boff = lds_byte(wc * 32 + fr, fq * 8);
;     ...
;     Unit cur, nxt; int ui = 0;
;     if (fixed_round < 0) { if (!S.next(0, cur)) return; }
;     else { const int c = blockIdx.x; cur.pm = 32 * fixed_round + 4 * (c & 7) + (c >> 6); cur.pn = (c >> 3) & 7; }
;     f32x4 acc[2][2][4][2];
; #pragma unroll
;     for (int a = 0; a < 2; ++a)
; #pragma unroll
;         for (int b = 0; b < 2; ++b)
; #pragma unroll
;             for (int m = 0; m < 4; ++m)
; #pragma unroll
;                 for (int n = 0; n < 2; ++n) acc[a][b][m][n] = (f32x4){0.f, 0.f, 0.f, 0.f};
;     bf16x8 At[4][2], B0[2][2], B1[2][2];
;     const char* cA = PG8_ABASE(cur); const char* cB = (const char*)Bt + (size_t)cur.pn * tstepB;
;     PG8_STAGE(PG8_SB(0, 0), cB, voffB); PG8_STAGE(PG8_SA(0, 0), cA, voffA); PG8_STAGE(PG8_SB(0, 1), cB + hstepB, voffB); PG8_STAGE(PG8_SA(0, 1), cA + hstepA, voffA);
;     if (wr == 1) PG8_BAR;
;     PG8_WAIT_V(4); PG8_BAR;
;     PG8_STAGE(PG8_SB(1, 0), cB + kstep, voffB); PG8_STAGE(PG8_SA(1, 0), cA + kstep, voffA); PG8_STAGE(PG8_SB(1, 1), cB + hstepB + kstep, voffB);
;     PG8_WAIT_V(6); PG8_BAR;
.LBB0_689:
	v_bfe_u32 v155, v12, 4, 2
	v_and_b32_e32 v164, 15, v12
	v_lshlrev_b32_e32 v15, 4, v155
	v_lshlrev_b32_e32 v12, 2, v12
	s_and_b32 s50, s0, 3
	v_lshl_or_b32 v15, v164, 6, v15
	s_lshl_b32 s0, s1, 13
	v_and_b32_e32 v12, 32, v12
	v_bitop3_b32 v16, v15, s0, v12 bitop3:0xde
	s_lshl_b32 s0, s50, 12
	s_lshl_b32 s49, s1, 6
	v_bitop3_b32 v12, v15, s0, v12 bitop3:0xde
	s_mov_b64 s[0:1], 0x80
	s_add_i32 m0, s52, 0x18000
	v_lshl_add_u64 v[6:7], v[6:7], 0, s[0:1]
	s_waitcnt vmcnt(4)
	s_barrier
	global_load_lds_dwordx4 v[6:7], off
	v_lshl_add_u64 v[4:5], v[4:5], 0, s[0:1]
	s_add_i32 m0, s52, 0x1a000
	s_add_i32 s56, s52, 0x8000
	global_load_lds_dwordx4 v[4:5], off
	v_lshl_add_u64 v[0:1], v[0:1], 0, s[0:1]
	s_mov_b32 m0, s56
	s_add_i32 s57, s52, 0xa000
	global_load_lds_dwordx4 v[0:1], off
	v_lshl_add_u64 v[0:1], v[2:3], 0, s[0:1]
	s_mov_b32 m0, s57
	v_readlane_b32 s8, v255, 20
	global_load_lds_dwordx4 v[0:1], off
	s_add_i32 m0, s52, 0x1c000
	v_lshl_add_u64 v[0:1], s[6:7], 0, v[144:145]
	global_load_lds_dwordx4 v[0:1], off
	v_lshl_add_u64 v[0:1], s[6:7], 0, v[132:133]
	s_add_i32 m0, s52, 0x1e000
	s_add_u32 s4, s78, s34
	global_load_lds_dwordx4 v[0:1], off
	v_lshlrev_b32_e32 v0, 17, v8
	v_and_b32_e32 v0, 0xfffc0000, v0
	v_lshl_add_u32 v0, v9, 14, v0
	v_and_b32_e32 v1, 1, v8
	v_lshl_or_b32 v0, v1, 6, v0
	v_lshl_add_u32 v0, v10, 1, v0
	v_mov_b32_e32 v1, v145
	s_addc_u32 s5, s79, s35
	v_lshl_add_u64 v[134:135], s[4:5], 0, v[0:1]
	v_lshlrev_b32_e32 v0, 17, v11
	v_and_b32_e32 v0, 0xfffc0000, v0
	v_lshl_add_u32 v0, v13, 14, v0
	v_and_b32_e32 v1, 1, v11
	s_waitcnt vmcnt(6)
	v_lshl_or_b32 v0, v1, 6, v0
	v_lshl_add_u32 v0, v14, 1, v0
	v_mov_b32_e32 v1, v145
	s_add_i32 s61, s81, s28
	s_add_i32 s63, s82, s28
	s_add_i32 s65, s83, s28
	s_add_i32 s67, s84, s28
	v_or_b32_e32 v158, s49, v164
	v_lshl_add_u64 v[136:137], s[4:5], 0, v[0:1]
	s_mov_b32 s58, -2
	s_mov_b64 s[4:5], 0x18700080
	v_add_u32_e32 v138, s81, v12
	v_add_u32_e32 v139, 0, v16
	s_add_i32 s59, s52, 0xc000
	s_add_i32 s60, s52, 0xe000
	v_add_u32_e32 v140, s82, v12
	s_add_i32 s62, s61, 0x2000
	s_add_i32 s64, s63, 0x2000
	v_add_u32_e32 v141, s83, v12
	v_add_u32_e32 v142, s84, v12
	s_add_i32 s66, s65, 0x2000
	s_add_i32 s68, s67, 0x2000
	v_mov_b32_e32 v0, v145
	v_mov_b32_e32 v2, v145
	v_mov_b32_e32 v3, v145
	v_mov_b32_e32 v4, v145
	v_mov_b32_e32 v5, v145
	v_mov_b32_e32 v6, v145
	v_mov_b32_e32 v7, v145
	v_mov_b32_e32 v12, v145
	v_mov_b32_e32 v13, v145
	v_mov_b32_e32 v14, v145
	v_mov_b32_e32 v15, v145
	v_mov_b32_e32 v20, v145
	v_mov_b32_e32 v21, v145
	v_mov_b32_e32 v22, v145
	v_mov_b32_e32 v23, v145
	v_mov_b32_e32 v28, v145
	v_mov_b32_e32 v29, v145
	v_mov_b32_e32 v30, v145
	v_mov_b32_e32 v31, v145
	v_mov_b32_e32 v36, v145
	v_mov_b32_e32 v37, v145
	v_mov_b32_e32 v38, v145
	v_mov_b32_e32 v39, v145
	v_mov_b32_e32 v44, v145
	v_mov_b32_e32 v45, v145
	v_mov_b32_e32 v46, v145
	v_mov_b32_e32 v47, v145
	v_mov_b32_e32 v52, v145
	v_mov_b32_e32 v53, v145
	v_mov_b32_e32 v54, v145
	v_mov_b32_e32 v55, v145
	v_mov_b32_e32 v8, v145
	v_mov_b32_e32 v9, v145
	v_mov_b32_e32 v10, v145
	v_mov_b32_e32 v11, v145
	v_mov_b32_e32 v16, v145
	v_mov_b32_e32 v17, v145
	v_mov_b32_e32 v18, v145
	v_mov_b32_e32 v19, v145
	v_mov_b32_e32 v24, v145
	v_mov_b32_e32 v25, v145
	v_mov_b32_e32 v26, v145
	v_mov_b32_e32 v27, v145
	v_mov_b32_e32 v32, v145
	v_mov_b32_e32 v33, v145
	v_mov_b32_e32 v34, v145
	v_mov_b32_e32 v35, v145
	v_mov_b32_e32 v40, v145
	v_mov_b32_e32 v41, v145
	v_mov_b32_e32 v42, v145
	v_mov_b32_e32 v43, v145
	v_mov_b32_e32 v48, v145
	v_mov_b32_e32 v49, v145
	v_mov_b32_e32 v50, v145
	v_mov_b32_e32 v51, v145
	v_mov_b32_e32 v56, v145
	v_mov_b32_e32 v57, v145
	v_mov_b32_e32 v58, v145
	v_mov_b32_e32 v59, v145
	v_mov_b32_e32 v60, v145
	v_mov_b32_e32 v61, v145
	v_mov_b32_e32 v62, v145
	v_mov_b32_e32 v63, v145
	v_mov_b32_e32 v64, v145
	v_mov_b32_e32 v65, v145
	v_mov_b32_e32 v66, v145
	v_mov_b32_e32 v67, v145
	v_mov_b32_e32 v68, v145
	v_mov_b32_e32 v69, v145
	v_mov_b32_e32 v70, v145
	v_mov_b32_e32 v71, v145
	v_mov_b32_e32 v76, v145
	v_mov_b32_e32 v77, v145
	v_mov_b32_e32 v78, v145
	v_mov_b32_e32 v79, v145
	v_mov_b32_e32 v84, v145
	v_mov_b32_e32 v85, v145
	v_mov_b32_e32 v86, v145
	v_mov_b32_e32 v87, v145
	v_mov_b32_e32 v92, v145
	v_mov_b32_e32 v93, v145
	v_mov_b32_e32 v94, v145
	v_mov_b32_e32 v95, v145
	v_mov_b32_e32 v100, v145
	v_mov_b32_e32 v101, v145
	v_mov_b32_e32 v102, v145
	v_mov_b32_e32 v103, v145
	v_mov_b32_e32 v108, v145
	v_mov_b32_e32 v109, v145
	v_mov_b32_e32 v110, v145
	v_mov_b32_e32 v111, v145
	v_mov_b32_e32 v116, v145
	v_mov_b32_e32 v117, v145
	v_mov_b32_e32 v118, v145
	v_mov_b32_e32 v119, v145
	v_mov_b32_e32 v72, v145
	v_mov_b32_e32 v73, v145
	v_mov_b32_e32 v74, v145
	v_mov_b32_e32 v75, v145
	v_mov_b32_e32 v80, v145
	v_mov_b32_e32 v81, v145
	v_mov_b32_e32 v82, v145
	v_mov_b32_e32 v83, v145
	v_mov_b32_e32 v88, v145
	v_mov_b32_e32 v89, v145
	v_mov_b32_e32 v90, v145
	v_mov_b32_e32 v91, v145
	v_mov_b32_e32 v96, v145
	v_mov_b32_e32 v97, v145
	v_mov_b32_e32 v98, v145
	v_mov_b32_e32 v99, v145
	v_mov_b32_e32 v104, v145
	v_mov_b32_e32 v105, v145
	v_mov_b32_e32 v106, v145
	v_mov_b32_e32 v107, v145
	v_mov_b32_e32 v112, v145
	v_mov_b32_e32 v113, v145
	v_mov_b32_e32 v114, v145
	v_mov_b32_e32 v115, v145
	v_mov_b32_e32 v120, v145
	v_mov_b32_e32 v121, v145
	v_mov_b32_e32 v122, v145
	v_mov_b32_e32 v123, v145
	v_mov_b32_e32 v124, v145
	v_mov_b32_e32 v125, v145
	v_mov_b32_e32 v126, v145
	v_mov_b32_e32 v127, v145
	v_readlane_b32 s9, v255, 21
.Lrot_6:
	s_barrier
; #define PG8_STAGE(bufoff, gbase, voff) do { _Pragma("unroll") for (int _i = 0; _i < 2; ++_i) \
;         __builtin_amdgcn_global_load_lds((const unsigned*)((const char*)(gbase) + (voff)[_i]), (LAS unsigned*)(lds + (bufoff) + ldsw + _i * 8192), 16, 0, 0); } while (0)
; #define PG8_LDA(dst, b, h) do { _Pragma("unroll") for (int m = 0; m < 4; ++m) _Pragma("unroll") for (int k = 0; k < 2; ++k) dst[m][k] = *(const LAS bf16x8*)(lds + PG8_SA(b, h) + aoff + m * 2048 + k * 1024); } while (0)
; #define PG8_LDB(dst, b, h) do { _Pragma("unroll") for (int n = 0; n < 2; ++n) _Pragma("unroll") for (int k = 0; k < 2; ++k) dst[n][k] = *(const LAS bf16x8*)(lds + PG8_SB(b, h) + boff + n * 2048 + k * 1024); } while (0)
; #define PG8_WAIT_V(n) asm volatile("s_waitcnt vmcnt(" #n ")" ::: "memory")
; #define PG8_WAIT_L(n) asm volatile("s_waitcnt lgkmcnt(" #n ")" ::: "memory")
; #define PG8_BAR __builtin_amdgcn_s_barrier()
; #define PG8_SCHED __builtin_amdgcn_sched_barrier(0)
; template <class Epi>
; __device__ __forceinline__ void gemm_phase(LAS unsigned char* lds, const bf16_t* A, int lda, const bf16_t* Bt, int ldb, int M, int N, int K, int asel, const Epi& E, const int fixed_round = -1) {
;     ...
;             PG8_LDB(B0, 0, 0); PG8_SCHED; PG8_LDA(At, 0, 0); PG8_STAGE(PG8_SA(1, 1), a1 + hstepA, voffA);
;             PG8_WAIT_L(8); PG8_BAR; PG8_WAIT_L(0); PG8_MMA(0, 0, At, B0); PG8_BAR; PG8_SCHED;
;             PG8_LDB(B1, 0, 1); PG8_STAGE(PG8_SB(0, 0), b2, voffB);
;             PG8_BAR; PG8_WAIT_L(0); PG8_MMA(0, 1, At, B1); PG8_BAR;
;             PG8_LDA(At, 0, 1); PG8_STAGE(PG8_SA(0, 0), a2, voffA);
;             PG8_BAR; PG8_WAIT_L(0); PG8_MMA(1, 0, At, B0); PG8_BAR; PG8_SCHED;
;             PG8_STAGE(PG8_SB(0, 1), b2 + hstepB, voffB);
;             PG8_WAIT_V(6); PG8_BAR; PG8_MMA(1, 1, At, B1); PG8_BAR;
;             PG8_LDB(B0, 1, 0); PG8_SCHED; PG8_LDA(At, 1, 0); PG8_STAGE(PG8_SA(0, 1), a2 + hstepA, voffA);
;             PG8_WAIT_L(8); PG8_BAR; PG8_WAIT_L(0); PG8_MMA(0, 0, At, B0); PG8_BAR; PG8_SCHED;
;             PG8_LDB(B1, 1, 1); PG8_STAGE(PG8_SB(1, 0), b3, voffB);
;             PG8_BAR; PG8_WAIT_L(0); PG8_MMA(0, 1, At, B1); PG8_BAR;
.LBB0_690:
	s_add_u32 s6, s4, 0xe7900080
	ds_read_b128 v[146:149], v138
	ds_read_b128 v[150:153], v138 offset:1024
	ds_read_b128 v[160:163], v138 offset:2048
	ds_read_b128 v[166:169], v138 offset:3072
	s_addc_u32 s7, s5, -1
	s_cmpk_lg_i32 s58, 0x7c
	s_cselect_b32 s6, s6, 0
	s_cselect_b32 s7, s7, 0
	s_add_u32 s40, s8, s6
	s_addc_u32 s41, s9, s7
	s_add_u32 s6, s2, s6
	s_addc_u32 s7, s3, s7
	s_mov_b32 m0, s59
	v_lshl_add_u64 v[156:157], v[134:135], 0, s[4:5]
	ds_read_b128 v[170:173], v139
	ds_read_b128 v[174:177], v139 offset:1024
	ds_read_b128 v[178:181], v139 offset:2048
	ds_read_b128 v[182:185], v139 offset:3072
	ds_read_b128 v[186:189], v139 offset:4096
	ds_read_b128 v[190:193], v139 offset:5120
	ds_read_b128 v[194:197], v139 offset:6144
	ds_read_b128 v[202:205], v139 offset:7168
	global_load_lds_dwordx4 v[156:157], off
	v_lshl_add_u64 v[156:157], v[136:137], 0, s[4:5]
	s_mov_b32 m0, s60
	s_nop 0
	global_load_lds_dwordx4 v[156:157], off
	s_waitcnt lgkmcnt(8)
	s_barrier
	s_waitcnt lgkmcnt(0)
	s_setprio 1
	s_waitcnt lgkmcnt(0)
	v_mfma_f32_16x16x32_bf16 v[124:127], v[146:149], v[170:173], v[124:127]
	v_mfma_f32_16x16x32_bf16 v[120:123], v[160:163], v[170:173], v[120:123]
	v_mfma_f32_16x16x32_bf16 v[112:115], v[146:149], v[178:181], v[112:115]
	v_mfma_f32_16x16x32_bf16 v[104:107], v[160:163], v[178:181], v[104:107]
	v_mfma_f32_16x16x32_bf16 v[96:99], v[146:149], v[186:189], v[96:99]
	v_mfma_f32_16x16x32_bf16 v[88:91], v[160:163], v[186:189], v[88:91]
	v_mfma_f32_16x16x32_bf16 v[80:83], v[146:149], v[194:197], v[80:83]
	v_mfma_f32_16x16x32_bf16 v[72:75], v[160:163], v[194:197], v[72:75]
	v_mfma_f32_16x16x32_bf16 v[124:127], v[150:153], v[174:177], v[124:127]
	v_mfma_f32_16x16x32_bf16 v[120:123], v[166:169], v[174:177], v[120:123]
	v_mfma_f32_16x16x32_bf16 v[112:115], v[150:153], v[182:185], v[112:115]
	v_mfma_f32_16x16x32_bf16 v[104:107], v[166:169], v[182:185], v[104:107]
	v_mfma_f32_16x16x32_bf16 v[96:99], v[150:153], v[190:193], v[96:99]
	v_mfma_f32_16x16x32_bf16 v[88:91], v[166:169], v[190:193], v[88:91]
	v_mfma_f32_16x16x32_bf16 v[80:83], v[150:153], v[202:205], v[80:83]
	v_mfma_f32_16x16x32_bf16 v[72:75], v[166:169], v[202:205], v[72:75]
	s_setprio 0
	s_barrier
	s_mov_b32 m0, s61
	s_add_u32 s98, s6, s0
	s_addc_u32 s99, s7, s1
	ds_read_b128 v[206:209], v140
	ds_read_b128 v[210:213], v140 offset:1024
	ds_read_b128 v[214:217], v140 offset:2048
	ds_read_b128 v[218:221], v140 offset:3072
	global_load_lds_dwordx4 v144, s[6:7]
	s_mov_b32 m0, s62
	s_nop 0
	global_load_lds_dwordx4 v132, s[6:7]
	s_barrier
	s_waitcnt lgkmcnt(0)
	s_setprio 1
	s_waitcnt lgkmcnt(0)
	v_mfma_f32_16x16x32_bf16 v[116:119], v[206:209], v[170:173], v[116:119]
	v_mfma_f32_16x16x32_bf16 v[108:111], v[214:217], v[170:173], v[108:111]
	v_mfma_f32_16x16x32_bf16 v[100:103], v[206:209], v[178:181], v[100:103]
	v_mfma_f32_16x16x32_bf16 v[92:95], v[214:217], v[178:181], v[92:95]
	v_mfma_f32_16x16x32_bf16 v[84:87], v[206:209], v[186:189], v[84:87]
	v_mfma_f32_16x16x32_bf16 v[76:79], v[214:217], v[186:189], v[76:79]
	v_mfma_f32_16x16x32_bf16 v[68:71], v[206:209], v[194:197], v[68:71]
	v_mfma_f32_16x16x32_bf16 v[64:67], v[214:217], v[194:197], v[64:67]
	v_mfma_f32_16x16x32_bf16 v[116:119], v[210:213], v[174:177], v[116:119]
	v_mfma_f32_16x16x32_bf16 v[108:111], v[218:221], v[174:177], v[108:111]
	v_mfma_f32_16x16x32_bf16 v[100:103], v[210:213], v[182:185], v[100:103]
	v_mfma_f32_16x16x32_bf16 v[92:95], v[218:221], v[182:185], v[92:95]
	v_mfma_f32_16x16x32_bf16 v[84:87], v[210:213], v[190:193], v[84:87]
	v_mfma_f32_16x16x32_bf16 v[76:79], v[218:221], v[190:193], v[76:79]
	v_mfma_f32_16x16x32_bf16 v[68:71], v[210:213], v[202:205], v[68:71]
	v_mfma_f32_16x16x32_bf16 v[64:67], v[218:221], v[202:205], v[64:67]
	s_setprio 0
	s_mov_b32 m0, s52
	s_add_u32 s100, s40, s0
	s_addc_u32 s101, s41, s1
	s_barrier
	ds_read_b128 v[170:173], v139 offset:16384
	ds_read_b128 v[174:177], v139 offset:17408
	ds_read_b128 v[178:181], v139 offset:18432
	ds_read_b128 v[182:185], v139 offset:19456
	ds_read_b128 v[186:189], v139 offset:20480
	ds_read_b128 v[190:193], v139 offset:21504
	ds_read_b128 v[194:197], v139 offset:22528
	ds_read_b128 v[202:205], v139 offset:23552
	global_load_lds_dwordx4 v128, s[40:41]
	s_mov_b32 m0, s53
	s_nop 0
	global_load_lds_dwordx4 v130, s[40:41]
	s_barrier
	s_waitcnt lgkmcnt(0)
	s_setprio 1
	s_waitcnt lgkmcnt(0)
	v_mfma_f32_16x16x32_bf16 v[60:63], v[146:149], v[170:173], v[60:63]
	v_mfma_f32_16x16x32_bf16 v[56:59], v[160:163], v[170:173], v[56:59]
	v_mfma_f32_16x16x32_bf16 v[48:51], v[146:149], v[178:181], v[48:51]
	v_mfma_f32_16x16x32_bf16 v[40:43], v[160:163], v[178:181], v[40:43]
	v_mfma_f32_16x16x32_bf16 v[32:35], v[146:149], v[186:189], v[32:35]
	v_mfma_f32_16x16x32_bf16 v[24:27], v[160:163], v[186:189], v[24:27]
	v_mfma_f32_16x16x32_bf16 v[16:19], v[146:149], v[194:197], v[16:19]
	v_mfma_f32_16x16x32_bf16 v[8:11], v[160:163], v[194:197], v[8:11]
	v_mfma_f32_16x16x32_bf16 v[60:63], v[150:153], v[174:177], v[60:63]
	v_mfma_f32_16x16x32_bf16 v[56:59], v[166:169], v[174:177], v[56:59]
	v_mfma_f32_16x16x32_bf16 v[48:51], v[150:153], v[182:185], v[48:51]
	v_mfma_f32_16x16x32_bf16 v[40:43], v[166:169], v[182:185], v[40:43]
	v_mfma_f32_16x16x32_bf16 v[32:35], v[150:153], v[190:193], v[32:35]
	v_mfma_f32_16x16x32_bf16 v[24:27], v[166:169], v[190:193], v[24:27]
	v_mfma_f32_16x16x32_bf16 v[16:19], v[150:153], v[202:205], v[16:19]
	v_mfma_f32_16x16x32_bf16 v[8:11], v[166:169], v[202:205], v[8:11]
	s_setprio 0
	s_barrier
	s_add_u32 s28, s6, 0x200000
	s_addc_u32 s29, s7, 0
	s_mov_b32 m0, s63
	s_nop 0
	global_load_lds_dwordx4 v144, s[28:29]
	s_mov_b32 m0, s64
	s_nop 0
	global_load_lds_dwordx4 v132, s[28:29]
	s_waitcnt vmcnt(6)
	s_barrier
; #define PG8_STAGE(bufoff, gbase, voff) do { _Pragma("unroll") for (int _i = 0; _i < 2; ++_i) \
;         __builtin_amdgcn_global_load_lds((const unsigned*)((const char*)(gbase) + (voff)[_i]), (LAS unsigned*)(lds + (bufoff) + ldsw + _i * 8192), 16, 0, 0); } while (0)
; #define PG8_LDA(dst, b, h) do { _Pragma("unroll") for (int m = 0; m < 4; ++m) _Pragma("unroll") for (int k = 0; k < 2; ++k) dst[m][k] = *(const LAS bf16x8*)(lds + PG8_SA(b, h) + aoff + m * 2048 + k * 1024); } while (0)
; #define PG8_LDB(dst, b, h) do { _Pragma("unroll") for (int n = 0; n < 2; ++n) _Pragma("unroll") for (int k = 0; k < 2; ++k) dst[n][k] = *(const LAS bf16x8*)(lds + PG8_SB(b, h) + boff + n * 2048 + k * 1024); } while (0)
; #define PG8_WAIT_V(n) asm volatile("s_waitcnt vmcnt(" #n ")" ::: "memory")
; #define PG8_WAIT_L(n) asm volatile("s_waitcnt lgkmcnt(" #n ")" ::: "memory")
; #define PG8_BAR __builtin_amdgcn_s_barrier()
; #define PG8_SCHED __builtin_amdgcn_sched_barrier(0)
; template <class Epi>
; __device__ __forceinline__ void gemm_phase(LAS unsigned char* lds, const bf16_t* A, int lda, const bf16_t* Bt, int ldb, int M, int N, int K, int asel, const Epi& E, const int fixed_round = -1) {
;     ...
;             PG8_BAR; PG8_WAIT_L(0); PG8_MMA(1, 0, At, B0); PG8_BAR; PG8_SCHED;
;             PG8_STAGE(PG8_SB(0, 1), b2 + hstepB, voffB);
;             PG8_WAIT_V(6); PG8_BAR; PG8_MMA(1, 1, At, B1); PG8_BAR;
;             PG8_LDB(B0, 1, 0); PG8_SCHED; PG8_LDA(At, 1, 0); PG8_STAGE(PG8_SA(0, 1), a2 + hstepA, voffA);
;             PG8_WAIT_L(8); PG8_BAR; PG8_WAIT_L(0); PG8_MMA(0, 0, At, B0); PG8_BAR; PG8_SCHED;
;             PG8_LDB(B1, 1, 1); PG8_STAGE(PG8_SB(1, 0), b3, voffB);
;             PG8_BAR; PG8_WAIT_L(0); PG8_MMA(0, 1, At, B1); PG8_BAR;
	s_setprio 1
	v_mfma_f32_16x16x32_bf16 v[52:55], v[206:209], v[170:173], v[52:55]
	v_mfma_f32_16x16x32_bf16 v[44:47], v[214:217], v[170:173], v[44:47]
	v_mfma_f32_16x16x32_bf16 v[36:39], v[206:209], v[178:181], v[36:39]
	v_mfma_f32_16x16x32_bf16 v[28:31], v[214:217], v[178:181], v[28:31]
	v_mfma_f32_16x16x32_bf16 v[20:23], v[206:209], v[186:189], v[20:23]
	v_mfma_f32_16x16x32_bf16 v[12:15], v[214:217], v[186:189], v[12:15]
	v_mfma_f32_16x16x32_bf16 v[4:7], v[206:209], v[194:197], v[4:7]
	v_mfma_f32_16x16x32_bf16 v[0:3], v[214:217], v[194:197], v[0:3]
	v_mfma_f32_16x16x32_bf16 v[52:55], v[210:213], v[174:177], v[52:55]
	v_mfma_f32_16x16x32_bf16 v[44:47], v[218:221], v[174:177], v[44:47]
	v_mfma_f32_16x16x32_bf16 v[36:39], v[210:213], v[182:185], v[36:39]
	v_mfma_f32_16x16x32_bf16 v[28:31], v[218:221], v[182:185], v[28:31]
	v_mfma_f32_16x16x32_bf16 v[20:23], v[210:213], v[190:193], v[20:23]
	v_mfma_f32_16x16x32_bf16 v[12:15], v[218:221], v[190:193], v[12:15]
	v_mfma_f32_16x16x32_bf16 v[4:7], v[210:213], v[202:205], v[4:7]
	v_mfma_f32_16x16x32_bf16 v[0:3], v[218:221], v[202:205], v[0:3]
	s_setprio 0
	s_barrier
	ds_read_b128 v[146:149], v141
	ds_read_b128 v[150:153], v141 offset:1024
	ds_read_b128 v[160:163], v141 offset:2048
	ds_read_b128 v[166:169], v141 offset:3072
	s_add_u32 s28, s40, 0x200000
	s_addc_u32 s29, s41, 0
	s_mov_b32 m0, s54
	ds_read_b128 v[170:173], v139 offset:32768
	ds_read_b128 v[174:177], v139 offset:33792
	ds_read_b128 v[178:181], v139 offset:34816
	ds_read_b128 v[182:185], v139 offset:35840
	ds_read_b128 v[186:189], v139 offset:36864
	ds_read_b128 v[190:193], v139 offset:37888
	ds_read_b128 v[194:197], v139 offset:38912
	ds_read_b128 v[202:205], v139 offset:39936
	global_load_lds_dwordx4 v128, s[28:29]
	s_mov_b32 m0, s55
	s_nop 0
	global_load_lds_dwordx4 v130, s[28:29]
	s_waitcnt lgkmcnt(8)
	s_barrier
	s_waitcnt lgkmcnt(0)
	s_setprio 1
	s_waitcnt lgkmcnt(0)
	v_mfma_f32_16x16x32_bf16 v[124:127], v[146:149], v[170:173], v[124:127]
	v_mfma_f32_16x16x32_bf16 v[120:123], v[160:163], v[170:173], v[120:123]
	v_mfma_f32_16x16x32_bf16 v[112:115], v[146:149], v[178:181], v[112:115]
	v_mfma_f32_16x16x32_bf16 v[104:107], v[160:163], v[178:181], v[104:107]
	v_mfma_f32_16x16x32_bf16 v[96:99], v[146:149], v[186:189], v[96:99]
	v_mfma_f32_16x16x32_bf16 v[88:91], v[160:163], v[186:189], v[88:91]
	v_mfma_f32_16x16x32_bf16 v[80:83], v[146:149], v[194:197], v[80:83]
	v_mfma_f32_16x16x32_bf16 v[72:75], v[160:163], v[194:197], v[72:75]
	v_mfma_f32_16x16x32_bf16 v[124:127], v[150:153], v[174:177], v[124:127]
	v_mfma_f32_16x16x32_bf16 v[120:123], v[166:169], v[174:177], v[120:123]
	v_mfma_f32_16x16x32_bf16 v[112:115], v[150:153], v[182:185], v[112:115]
	v_mfma_f32_16x16x32_bf16 v[104:107], v[166:169], v[182:185], v[104:107]
	v_mfma_f32_16x16x32_bf16 v[96:99], v[150:153], v[190:193], v[96:99]
	v_mfma_f32_16x16x32_bf16 v[88:91], v[166:169], v[190:193], v[88:91]
	v_mfma_f32_16x16x32_bf16 v[80:83], v[150:153], v[202:205], v[80:83]
	v_mfma_f32_16x16x32_bf16 v[72:75], v[166:169], v[202:205], v[72:75]
	s_setprio 0
	s_barrier
	s_mov_b32 m0, s65
	ds_read_b128 v[206:209], v142
	ds_read_b128 v[210:213], v142 offset:1024
	ds_read_b128 v[214:217], v142 offset:2048
	ds_read_b128 v[218:221], v142 offset:3072
	global_load_lds_dwordx4 v144, s[98:99]
	s_mov_b32 m0, s66
	s_nop 0
	global_load_lds_dwordx4 v132, s[98:99]
	s_barrier
; #define PG8_STAGE(bufoff, gbase, voff) do { _Pragma("unroll") for (int _i = 0; _i < 2; ++_i) \
;         __builtin_amdgcn_global_load_lds((const unsigned*)((const char*)(gbase) + (voff)[_i]), (LAS unsigned*)(lds + (bufoff) + ldsw + _i * 8192), 16, 0, 0); } while (0)
; #define PG8_LDA(dst, b, h) do { _Pragma("unroll") for (int m = 0; m < 4; ++m) _Pragma("unroll") for (int k = 0; k < 2; ++k) dst[m][k] = *(const LAS bf16x8*)(lds + PG8_SA(b, h) + aoff + m * 2048 + k * 1024); } while (0)
; #define PG8_WAIT_V(n) asm volatile("s_waitcnt vmcnt(" #n ")" ::: "memory")
; #define PG8_WAIT_L(n) asm volatile("s_waitcnt lgkmcnt(" #n ")" ::: "memory")
; #define PG8_BAR __builtin_amdgcn_s_barrier()
; #define PG8_SCHED __builtin_amdgcn_sched_barrier(0)
; template <class Epi>
; __device__ __forceinline__ void gemm_phase(LAS unsigned char* lds, const bf16_t* A, int lda, const bf16_t* Bt, int ldb, int M, int N, int K, int asel, const Epi& E, const int fixed_round = -1) {
;     ...
;             PG8_BAR; PG8_WAIT_L(0); PG8_MMA(0, 1, At, B1); PG8_BAR;
;             PG8_LDA(At, 1, 1); PG8_STAGE(PG8_SA(1, 0), a3, voffA);
;             PG8_BAR; PG8_WAIT_L(0); PG8_MMA(1, 0, At, B0); PG8_BAR; PG8_SCHED;
;             PG8_STAGE(PG8_SB(1, 1), b3 + hstepB, voffB);
;             PG8_WAIT_V(6); PG8_BAR; PG8_MMA(1, 1, At, B1); PG8_BAR;
;     ...
;     PG8_WAIT_V(0);
;     if (wr == 0) PG8_BAR;
;     PG8_BAR;
	s_waitcnt lgkmcnt(0)
	s_setprio 1
	s_waitcnt lgkmcnt(0)
	v_mfma_f32_16x16x32_bf16 v[116:119], v[206:209], v[170:173], v[116:119]
	v_mfma_f32_16x16x32_bf16 v[108:111], v[214:217], v[170:173], v[108:111]
	v_mfma_f32_16x16x32_bf16 v[100:103], v[206:209], v[178:181], v[100:103]
	v_mfma_f32_16x16x32_bf16 v[92:95], v[214:217], v[178:181], v[92:95]
	v_mfma_f32_16x16x32_bf16 v[84:87], v[206:209], v[186:189], v[84:87]
	v_mfma_f32_16x16x32_bf16 v[76:79], v[214:217], v[186:189], v[76:79]
	v_mfma_f32_16x16x32_bf16 v[68:71], v[206:209], v[194:197], v[68:71]
	v_mfma_f32_16x16x32_bf16 v[64:67], v[214:217], v[194:197], v[64:67]
	v_mfma_f32_16x16x32_bf16 v[116:119], v[210:213], v[174:177], v[116:119]
	v_mfma_f32_16x16x32_bf16 v[108:111], v[218:221], v[174:177], v[108:111]
	v_mfma_f32_16x16x32_bf16 v[100:103], v[210:213], v[182:185], v[100:103]
	v_mfma_f32_16x16x32_bf16 v[92:95], v[218:221], v[182:185], v[92:95]
	v_mfma_f32_16x16x32_bf16 v[84:87], v[210:213], v[190:193], v[84:87]
	v_mfma_f32_16x16x32_bf16 v[76:79], v[218:221], v[190:193], v[76:79]
	v_mfma_f32_16x16x32_bf16 v[68:71], v[210:213], v[202:205], v[68:71]
	v_mfma_f32_16x16x32_bf16 v[64:67], v[218:221], v[202:205], v[64:67]
	s_setprio 0
	s_mov_b32 m0, s56
	s_barrier
	ds_read_b128 v[170:173], v139 offset:49152
	ds_read_b128 v[174:177], v139 offset:50176
	ds_read_b128 v[178:181], v139 offset:51200
	ds_read_b128 v[182:185], v139 offset:52224
	ds_read_b128 v[186:189], v139 offset:53248
	ds_read_b128 v[190:193], v139 offset:54272
	ds_read_b128 v[194:197], v139 offset:55296
	ds_read_b128 v[202:205], v139 offset:56320
	global_load_lds_dwordx4 v128, s[100:101]
	s_mov_b32 m0, s57
	s_nop 0
	global_load_lds_dwordx4 v130, s[100:101]
	s_barrier
	s_waitcnt lgkmcnt(0)
	s_setprio 1
	s_waitcnt lgkmcnt(0)
	v_mfma_f32_16x16x32_bf16 v[60:63], v[146:149], v[170:173], v[60:63]
	v_mfma_f32_16x16x32_bf16 v[56:59], v[160:163], v[170:173], v[56:59]
	v_mfma_f32_16x16x32_bf16 v[48:51], v[146:149], v[178:181], v[48:51]
	v_mfma_f32_16x16x32_bf16 v[40:43], v[160:163], v[178:181], v[40:43]
	v_mfma_f32_16x16x32_bf16 v[32:35], v[146:149], v[186:189], v[32:35]
	v_mfma_f32_16x16x32_bf16 v[24:27], v[160:163], v[186:189], v[24:27]
	v_mfma_f32_16x16x32_bf16 v[16:19], v[146:149], v[194:197], v[16:19]
	v_mfma_f32_16x16x32_bf16 v[8:11], v[160:163], v[194:197], v[8:11]
	v_mfma_f32_16x16x32_bf16 v[60:63], v[150:153], v[174:177], v[60:63]
	v_mfma_f32_16x16x32_bf16 v[56:59], v[166:169], v[174:177], v[56:59]
	v_mfma_f32_16x16x32_bf16 v[48:51], v[150:153], v[182:185], v[48:51]
	v_mfma_f32_16x16x32_bf16 v[40:43], v[166:169], v[182:185], v[40:43]
	v_mfma_f32_16x16x32_bf16 v[32:35], v[150:153], v[190:193], v[32:35]
	v_mfma_f32_16x16x32_bf16 v[24:27], v[166:169], v[190:193], v[24:27]
	v_mfma_f32_16x16x32_bf16 v[16:19], v[150:153], v[202:205], v[16:19]
	v_mfma_f32_16x16x32_bf16 v[8:11], v[166:169], v[202:205], v[8:11]
	s_setprio 0
	s_barrier
	s_add_u32 s6, s6, 0x200080
	s_addc_u32 s7, s7, 0
	s_mov_b32 m0, s67
	s_nop 0
	global_load_lds_dwordx4 v144, s[6:7]
	s_mov_b32 m0, s68
	s_nop 0
	global_load_lds_dwordx4 v132, s[6:7]
	s_waitcnt vmcnt(6)
	s_barrier
	s_setprio 1
	v_mfma_f32_16x16x32_bf16 v[52:55], v[206:209], v[170:173], v[52:55]
	v_mfma_f32_16x16x32_bf16 v[44:47], v[214:217], v[170:173], v[44:47]
	v_mfma_f32_16x16x32_bf16 v[36:39], v[206:209], v[178:181], v[36:39]
	v_mfma_f32_16x16x32_bf16 v[28:31], v[214:217], v[178:181], v[28:31]
	v_mfma_f32_16x16x32_bf16 v[20:23], v[206:209], v[186:189], v[20:23]
	v_mfma_f32_16x16x32_bf16 v[12:15], v[214:217], v[186:189], v[12:15]
	v_mfma_f32_16x16x32_bf16 v[4:7], v[206:209], v[194:197], v[4:7]
	v_mfma_f32_16x16x32_bf16 v[0:3], v[214:217], v[194:197], v[0:3]
	v_mfma_f32_16x16x32_bf16 v[52:55], v[210:213], v[174:177], v[52:55]
	v_mfma_f32_16x16x32_bf16 v[44:47], v[218:221], v[174:177], v[44:47]
	v_mfma_f32_16x16x32_bf16 v[36:39], v[210:213], v[182:185], v[36:39]
	v_mfma_f32_16x16x32_bf16 v[28:31], v[218:221], v[182:185], v[28:31]
	v_mfma_f32_16x16x32_bf16 v[20:23], v[210:213], v[190:193], v[20:23]
	v_mfma_f32_16x16x32_bf16 v[12:15], v[218:221], v[190:193], v[12:15]
	v_mfma_f32_16x16x32_bf16 v[4:7], v[210:213], v[202:205], v[4:7]
	v_mfma_f32_16x16x32_bf16 v[0:3], v[218:221], v[202:205], v[0:3]
	s_setprio 0
	s_add_i32 s58, s58, 2
	s_add_u32 s4, s4, 0x100
	s_addc_u32 s5, s5, 0
	s_cmpk_lt_u32 s58, 0x7e
	s_cbranch_scc1 .Lrot_6
	s_barrier
	s_waitcnt vmcnt(0)
	s_cmpk_gt_u32 s51, 0xff
	s_cbranch_scc1 .LBB0_693
	s_barrier

; template <class Epi>
; __device__ __forceinline__ void gemm_phase(LAS unsigned char* lds, const bf16_t* A, int lda, const bf16_t* Bt, int ldb, int M, int N, int K, int asel, const Epi& E, const int fixed_round = -1) {
;     ...
;         const bool has_next = (fixed_round < 0) && S.next(ui + 1, nxt);
;         const char* nA = has_next ? PG8_ABASE(nxt) : cA; const char* nB = has_next ? (const char*)Bt + (size_t)nxt.pn * tstepB : cB;
;     ...
; #pragma unroll
;         for (int a = 0; a < 2; ++a)
; #pragma unroll
;             for (int b = 0; b < 2; ++b)
; #pragma unroll
;                 for (int m = 0; m < 4; ++m)
; #pragma unroll
;                     for (int n = 0; n < 2; ++n) acc[a][b][m][n] = (f32x4){0.f, 0.f, 0.f, 0.f};
;         cur = nxt; cA = nA; cB = nB; ++ui;
.LBB0_798:
	s_ashr_i32 s41, s40, 31
	s_lshl_b64 s[28:29], s[40:41], 20
	v_cmp_lt_i64_e32 vcc, s[44:45], v[142:143]
	s_add_u32 s44, s72, s28
	s_addc_u32 s45, s73, s29
	s_and_b64 s[28:29], vcc, exec
	s_cselect_b32 s5, s45, s51
	s_cselect_b32 s41, s44, s50
	s_ashr_i32 s7, s6, 31
	s_lshl_b64 s[28:29], s[6:7], 20
	s_add_u32 s46, s56, s28
	s_addc_u32 s47, s57, s29
	s_and_b64 s[28:29], vcc, exec
	s_cselect_b32 s7, s47, s53
	s_cselect_b32 s65, s46, s52
	s_add_u32 s50, s50, 0x80080
	s_addc_u32 s51, s51, 0
	s_add_u32 s66, s52, 0x100
	v_mov_b32_e32 v0, 0
	s_addc_u32 s67, s53, 0
	s_mov_b32 s68, -2
	v_mov_b32_e32 v1, v0
	v_mov_b32_e32 v2, v0
	v_mov_b32_e32 v3, v0
	v_mov_b32_e32 v4, v0
	v_mov_b32_e32 v5, v0
	v_mov_b32_e32 v6, v0
	v_mov_b32_e32 v7, v0
	v_mov_b32_e32 v16, v0
	v_mov_b32_e32 v17, v0
	v_mov_b32_e32 v18, v0
	v_mov_b32_e32 v19, v0
	v_mov_b32_e32 v20, v0
	v_mov_b32_e32 v21, v0
	v_mov_b32_e32 v22, v0
	v_mov_b32_e32 v23, v0
	v_mov_b32_e32 v32, v0
	v_mov_b32_e32 v33, v0
	v_mov_b32_e32 v34, v0
	v_mov_b32_e32 v35, v0
	v_mov_b32_e32 v36, v0
	v_mov_b32_e32 v37, v0
	v_mov_b32_e32 v38, v0
	v_mov_b32_e32 v39, v0
	v_mov_b32_e32 v48, v0
	v_mov_b32_e32 v49, v0
	v_mov_b32_e32 v50, v0
	v_mov_b32_e32 v51, v0
	v_mov_b32_e32 v52, v0
	v_mov_b32_e32 v53, v0
	v_mov_b32_e32 v54, v0
	v_mov_b32_e32 v55, v0
	v_mov_b32_e32 v8, v0
	v_mov_b32_e32 v9, v0
	v_mov_b32_e32 v10, v0
	v_mov_b32_e32 v11, v0
	v_mov_b32_e32 v12, v0
	v_mov_b32_e32 v13, v0
	v_mov_b32_e32 v14, v0
	v_mov_b32_e32 v15, v0
	v_mov_b32_e32 v24, v0
	v_mov_b32_e32 v25, v0
	v_mov_b32_e32 v26, v0
	v_mov_b32_e32 v27, v0
	v_mov_b32_e32 v28, v0
	v_mov_b32_e32 v29, v0
	v_mov_b32_e32 v30, v0
	v_mov_b32_e32 v31, v0
	v_mov_b32_e32 v40, v0
	v_mov_b32_e32 v41, v0
	v_mov_b32_e32 v42, v0
	v_mov_b32_e32 v43, v0
	v_mov_b32_e32 v44, v0
	v_mov_b32_e32 v45, v0
	v_mov_b32_e32 v46, v0
	v_mov_b32_e32 v47, v0
	v_mov_b32_e32 v56, v0
	v_mov_b32_e32 v57, v0
	v_mov_b32_e32 v58, v0
	v_mov_b32_e32 v59, v0
	v_mov_b32_e32 v60, v0
	v_mov_b32_e32 v61, v0
	v_mov_b32_e32 v62, v0
	v_mov_b32_e32 v63, v0
	v_mov_b32_e32 v64, v0
	v_mov_b32_e32 v65, v0
	v_mov_b32_e32 v66, v0
	v_mov_b32_e32 v67, v0
	v_mov_b32_e32 v68, v0
	v_mov_b32_e32 v69, v0
	v_mov_b32_e32 v70, v0
	v_mov_b32_e32 v71, v0
	v_mov_b32_e32 v80, v0
	v_mov_b32_e32 v81, v0
	v_mov_b32_e32 v82, v0
	v_mov_b32_e32 v83, v0
	v_mov_b32_e32 v84, v0
	v_mov_b32_e32 v85, v0
	v_mov_b32_e32 v86, v0
	v_mov_b32_e32 v87, v0
	v_mov_b32_e32 v96, v0
	v_mov_b32_e32 v97, v0
	v_mov_b32_e32 v98, v0
	v_mov_b32_e32 v99, v0
	v_mov_b32_e32 v100, v0
	v_mov_b32_e32 v101, v0
	v_mov_b32_e32 v102, v0
	v_mov_b32_e32 v103, v0
	v_mov_b32_e32 v112, v0
	v_mov_b32_e32 v113, v0
	v_mov_b32_e32 v114, v0
	v_mov_b32_e32 v115, v0
	v_mov_b32_e32 v116, v0
	v_mov_b32_e32 v117, v0
	v_mov_b32_e32 v118, v0
	v_mov_b32_e32 v119, v0
	v_mov_b32_e32 v72, v0
	v_mov_b32_e32 v73, v0
	v_mov_b32_e32 v74, v0
	v_mov_b32_e32 v75, v0
	v_mov_b32_e32 v76, v0
	v_mov_b32_e32 v77, v0
	v_mov_b32_e32 v78, v0
	v_mov_b32_e32 v79, v0
	v_mov_b32_e32 v88, v0
	v_mov_b32_e32 v89, v0
	v_mov_b32_e32 v90, v0
	v_mov_b32_e32 v91, v0
	v_mov_b32_e32 v92, v0
	v_mov_b32_e32 v93, v0
	v_mov_b32_e32 v94, v0
	v_mov_b32_e32 v95, v0
	v_mov_b32_e32 v104, v0
	v_mov_b32_e32 v105, v0
	v_mov_b32_e32 v106, v0
	v_mov_b32_e32 v107, v0
	v_mov_b32_e32 v108, v0
	v_mov_b32_e32 v109, v0
	v_mov_b32_e32 v110, v0
	v_mov_b32_e32 v111, v0
	v_mov_b32_e32 v120, v0
	v_mov_b32_e32 v121, v0
	v_mov_b32_e32 v122, v0
	v_mov_b32_e32 v123, v0
	v_mov_b32_e32 v124, v0
	v_mov_b32_e32 v125, v0
	v_mov_b32_e32 v126, v0
	v_mov_b32_e32 v127, v0
	s_branch .LBB0_799

; #define PG8_STAGE(bufoff, gbase, voff) do { _Pragma("unroll") for (int _i = 0; _i < 2; ++_i) \
;         __builtin_amdgcn_global_load_lds((const unsigned*)((const char*)(gbase) + (voff)[_i]), (LAS unsigned*)(lds + (bufoff) + ldsw + _i * 8192), 16, 0, 0); } while (0)
; #define PG8_LDA(dst, b, h) do { _Pragma("unroll") for (int m = 0; m < 4; ++m) _Pragma("unroll") for (int k = 0; k < 2; ++k) dst[m][k] = *(const LAS bf16x8*)(lds + PG8_SA(b, h) + aoff + m * 2048 + k * 1024); } while (0)
; #define PG8_LDB(dst, b, h) do { _Pragma("unroll") for (int n = 0; n < 2; ++n) _Pragma("unroll") for (int k = 0; k < 2; ++k) dst[n][k] = *(const LAS bf16x8*)(lds + PG8_SB(b, h) + boff + n * 2048 + k * 1024); } while (0)
; #define PG8_WAIT_V(n) asm volatile("s_waitcnt vmcnt(" #n ")" ::: "memory")
; #define PG8_WAIT_L(n) asm volatile("s_waitcnt lgkmcnt(" #n ")" ::: "memory")
; #define PG8_BAR __builtin_amdgcn_s_barrier()
; template <class Epi>
; __device__ __forceinline__ void gemm_phase(LAS unsigned char* lds, const bf16_t* A, int lda, const bf16_t* Bt, int ldb, int M, int N, int K, int asel, const Epi& E, const int fixed_round = -1) {
;     ...
;             PG8_LDB(B0, 0, 0); PG8_SCHED; PG8_LDA(At, 0, 0); PG8_STAGE(PG8_SA(1, 1), a1 + hstepA, voffA);
;             PG8_WAIT_L(8); PG8_BAR; PG8_WAIT_L(0); PG8_MMA(0, 0, At, B0); PG8_BAR; PG8_SCHED;
;             PG8_LDB(B1, 0, 1); PG8_STAGE(PG8_SB(0, 0), b2, voffB);
;             PG8_BAR; PG8_WAIT_L(0); PG8_MMA(0, 1, At, B1); PG8_BAR;
;             PG8_LDA(At, 0, 1); PG8_STAGE(PG8_SA(0, 0), a2, voffA);
;             PG8_BAR; PG8_WAIT_L(0); PG8_MMA(1, 0, At, B0); PG8_BAR; PG8_SCHED;
;             PG8_STAGE(PG8_SB(0, 1), b2 + hstepB, voffB);
;             PG8_WAIT_V(6); PG8_BAR; PG8_MMA(1, 1, At, B1); PG8_BAR;
;             PG8_LDB(B0, 1, 0); PG8_SCHED; PG8_LDA(At, 1, 0); PG8_STAGE(PG8_SA(0, 1), a2 + hstepA, voffA);
;             PG8_WAIT_L(8); PG8_BAR; PG8_WAIT_L(0); PG8_MMA(0, 0, At, B0); PG8_BAR; PG8_SCHED;
;             PG8_LDB(B1, 1, 1); PG8_STAGE(PG8_SB(1, 0), b3, voffB);
;             PG8_BAR; PG8_WAIT_L(0); PG8_MMA(0, 1, At, B1); PG8_BAR;
;             PG8_LDA(At, 1, 1); PG8_STAGE(PG8_SA(1, 0), a3, voffA);
;             PG8_BAR; PG8_WAIT_L(0); PG8_MMA(1, 0, At, B0); PG8_BAR; PG8_SCHED;
;             PG8_STAGE(PG8_SB(1, 1), b3 + hstepB, voffB);
;             PG8_WAIT_V(6); PG8_BAR; PG8_MMA(1, 1, At, B1); PG8_BAR;
.LBB0_799:
	ds_read_b128 v[146:149], v155
	ds_read_b128 v[158:161], v155 offset:1024
	ds_read_b128 v[162:165], v155 offset:2048
	ds_read_b128 v[166:169], v155 offset:3072
	s_add_u32 s28, s50, 0xfff80080
	s_addc_u32 s29, s51, -1
	s_cmp_eq_u32 s68, 28
	s_cselect_b32 s55, s5, s29
	s_cselect_b32 s54, s41, s28
	s_cselect_b32 s53, s7, s67
	s_cselect_b32 s52, s65, s66
	s_add_i32 m0, s49, 0xc000
	ds_read_b128 v[170:173], v156
	ds_read_b128 v[174:177], v156 offset:1024
	ds_read_b128 v[178:181], v156 offset:2048
	ds_read_b128 v[182:185], v156 offset:3072
	ds_read_b128 v[186:189], v156 offset:4096
	ds_read_b128 v[190:193], v156 offset:5120
	ds_read_b128 v[194:197], v156 offset:6144
	ds_read_b128 v[202:205], v156 offset:7168
	global_load_lds_dwordx4 v138, s[50:51]
	s_add_i32 m0, s49, 0xe000
	s_nop 0
	global_load_lds_dwordx4 v140, s[50:51]
	s_waitcnt lgkmcnt(8)
	s_barrier
	s_waitcnt lgkmcnt(0)
	s_setprio 1
	s_waitcnt lgkmcnt(0)
	v_mfma_f32_16x16x32_bf16 v[124:127], v[146:149], v[170:173], v[124:127]
	v_mfma_f32_16x16x32_bf16 v[120:123], v[162:165], v[170:173], v[120:123]
	v_mfma_f32_16x16x32_bf16 v[108:111], v[146:149], v[178:181], v[108:111]
	v_mfma_f32_16x16x32_bf16 v[104:107], v[162:165], v[178:181], v[104:107]
	v_mfma_f32_16x16x32_bf16 v[92:95], v[146:149], v[186:189], v[92:95]
	v_mfma_f32_16x16x32_bf16 v[88:91], v[162:165], v[186:189], v[88:91]
	v_mfma_f32_16x16x32_bf16 v[76:79], v[146:149], v[194:197], v[76:79]
	v_mfma_f32_16x16x32_bf16 v[72:75], v[162:165], v[194:197], v[72:75]
	v_mfma_f32_16x16x32_bf16 v[124:127], v[158:161], v[174:177], v[124:127]
	v_mfma_f32_16x16x32_bf16 v[120:123], v[166:169], v[174:177], v[120:123]
	v_mfma_f32_16x16x32_bf16 v[108:111], v[158:161], v[182:185], v[108:111]
	v_mfma_f32_16x16x32_bf16 v[104:107], v[166:169], v[182:185], v[104:107]
	v_mfma_f32_16x16x32_bf16 v[92:95], v[158:161], v[190:193], v[92:95]
	v_mfma_f32_16x16x32_bf16 v[88:91], v[166:169], v[190:193], v[88:91]
	v_mfma_f32_16x16x32_bf16 v[76:79], v[158:161], v[202:205], v[76:79]
	v_mfma_f32_16x16x32_bf16 v[72:75], v[166:169], v[202:205], v[72:75]
	s_setprio 0
	s_barrier
	s_add_i32 s28, s81, s58
	s_add_u32 s98, s52, s2
	s_addc_u32 s99, s53, s3
	s_mov_b32 m0, s28
	ds_read_b128 v[206:209], v157
	ds_read_b128 v[210:213], v157 offset:1024
	ds_read_b128 v[214:217], v157 offset:2048
	ds_read_b128 v[218:221], v157 offset:3072
	global_load_lds_dwordx4 v130, s[52:53]
	s_add_i32 m0, s28, 0x2000
	s_nop 0
	global_load_lds_dwordx4 v134, s[52:53]
	s_barrier
	s_waitcnt lgkmcnt(0)
	s_setprio 1
	s_waitcnt lgkmcnt(0)
	v_mfma_f32_16x16x32_bf16 v[116:119], v[206:209], v[170:173], v[116:119]
	v_mfma_f32_16x16x32_bf16 v[112:115], v[214:217], v[170:173], v[112:115]
	v_mfma_f32_16x16x32_bf16 v[100:103], v[206:209], v[178:181], v[100:103]
	v_mfma_f32_16x16x32_bf16 v[96:99], v[214:217], v[178:181], v[96:99]
	v_mfma_f32_16x16x32_bf16 v[84:87], v[206:209], v[186:189], v[84:87]
	v_mfma_f32_16x16x32_bf16 v[80:83], v[214:217], v[186:189], v[80:83]
	v_mfma_f32_16x16x32_bf16 v[68:71], v[206:209], v[194:197], v[68:71]
	v_mfma_f32_16x16x32_bf16 v[64:67], v[214:217], v[194:197], v[64:67]
	v_mfma_f32_16x16x32_bf16 v[116:119], v[210:213], v[174:177], v[116:119]
	v_mfma_f32_16x16x32_bf16 v[112:115], v[218:221], v[174:177], v[112:115]
	v_mfma_f32_16x16x32_bf16 v[100:103], v[210:213], v[182:185], v[100:103]
	v_mfma_f32_16x16x32_bf16 v[96:99], v[218:221], v[182:185], v[96:99]
	v_mfma_f32_16x16x32_bf16 v[84:87], v[210:213], v[190:193], v[84:87]
	v_mfma_f32_16x16x32_bf16 v[80:83], v[218:221], v[190:193], v[80:83]
	v_mfma_f32_16x16x32_bf16 v[68:71], v[210:213], v[202:205], v[68:71]
	v_mfma_f32_16x16x32_bf16 v[64:67], v[218:221], v[202:205], v[64:67]
	s_setprio 0
	s_mov_b32 m0, s49
	s_add_u32 s100, s54, s2
	s_addc_u32 s101, s55, s3
	s_barrier
	ds_read_b128 v[170:173], v156 offset:16384
	ds_read_b128 v[174:177], v156 offset:17408
	ds_read_b128 v[178:181], v156 offset:18432
	ds_read_b128 v[182:185], v156 offset:19456
	ds_read_b128 v[186:189], v156 offset:20480
	ds_read_b128 v[190:193], v156 offset:21504
	ds_read_b128 v[194:197], v156 offset:22528
	ds_read_b128 v[202:205], v156 offset:23552
	global_load_lds_dwordx4 v128, s[54:55]
	s_mov_b32 m0, s59
	s_nop 0
	global_load_lds_dwordx4 v132, s[54:55]
	s_barrier
	s_waitcnt lgkmcnt(0)
	s_setprio 1
	s_waitcnt lgkmcnt(0)
	v_mfma_f32_16x16x32_bf16 v[60:63], v[146:149], v[170:173], v[60:63]
	v_mfma_f32_16x16x32_bf16 v[56:59], v[162:165], v[170:173], v[56:59]
	v_mfma_f32_16x16x32_bf16 v[44:47], v[146:149], v[178:181], v[44:47]
	v_mfma_f32_16x16x32_bf16 v[40:43], v[162:165], v[178:181], v[40:43]
	v_mfma_f32_16x16x32_bf16 v[28:31], v[146:149], v[186:189], v[28:31]
	v_mfma_f32_16x16x32_bf16 v[24:27], v[162:165], v[186:189], v[24:27]
	v_mfma_f32_16x16x32_bf16 v[12:15], v[146:149], v[194:197], v[12:15]
	v_mfma_f32_16x16x32_bf16 v[8:11], v[162:165], v[194:197], v[8:11]
	v_mfma_f32_16x16x32_bf16 v[60:63], v[158:161], v[174:177], v[60:63]
	v_mfma_f32_16x16x32_bf16 v[56:59], v[166:169], v[174:177], v[56:59]
	v_mfma_f32_16x16x32_bf16 v[44:47], v[158:161], v[182:185], v[44:47]
	v_mfma_f32_16x16x32_bf16 v[40:43], v[166:169], v[182:185], v[40:43]
	v_mfma_f32_16x16x32_bf16 v[28:31], v[158:161], v[190:193], v[28:31]
	v_mfma_f32_16x16x32_bf16 v[24:27], v[166:169], v[190:193], v[24:27]
	v_mfma_f32_16x16x32_bf16 v[12:15], v[158:161], v[202:205], v[12:15]
	v_mfma_f32_16x16x32_bf16 v[8:11], v[166:169], v[202:205], v[8:11]
	s_setprio 0
	s_barrier
	s_add_u32 s28, s52, 0x80000
	s_addc_u32 s29, s53, 0
	s_add_i32 s69, s82, s58
	s_mov_b32 m0, s69
	s_nop 0
	global_load_lds_dwordx4 v130, s[28:29]
	s_add_i32 m0, s69, 0x2000
	s_nop 0
	global_load_lds_dwordx4 v134, s[28:29]
	s_waitcnt vmcnt(6)
	s_barrier
; #define PG8_STAGE(bufoff, gbase, voff) do { _Pragma("unroll") for (int _i = 0; _i < 2; ++_i) \
;         __builtin_amdgcn_global_load_lds((const unsigned*)((const char*)(gbase) + (voff)[_i]), (LAS unsigned*)(lds + (bufoff) + ldsw + _i * 8192), 16, 0, 0); } while (0)
; #define PG8_LDA(dst, b, h) do { _Pragma("unroll") for (int m = 0; m < 4; ++m) _Pragma("unroll") for (int k = 0; k < 2; ++k) dst[m][k] = *(const LAS bf16x8*)(lds + PG8_SA(b, h) + aoff + m * 2048 + k * 1024); } while (0)
; #define PG8_LDB(dst, b, h) do { _Pragma("unroll") for (int n = 0; n < 2; ++n) _Pragma("unroll") for (int k = 0; k < 2; ++k) dst[n][k] = *(const LAS bf16x8*)(lds + PG8_SB(b, h) + boff + n * 2048 + k * 1024); } while (0)
; #define PG8_WAIT_V(n) asm volatile("s_waitcnt vmcnt(" #n ")" ::: "memory")
; #define PG8_WAIT_L(n) asm volatile("s_waitcnt lgkmcnt(" #n ")" ::: "memory")
; #define PG8_BAR __builtin_amdgcn_s_barrier()
; template <class Epi>
; __device__ __forceinline__ void gemm_phase(LAS unsigned char* lds, const bf16_t* A, int lda, const bf16_t* Bt, int ldb, int M, int N, int K, int asel, const Epi& E, const int fixed_round = -1) {
;     ...
;             PG8_LDB(B0, 0, 0); PG8_SCHED; PG8_LDA(At, 0, 0); PG8_STAGE(PG8_SA(1, 1), a1 + hstepA, voffA);
;             PG8_WAIT_L(8); PG8_BAR; PG8_WAIT_L(0); PG8_MMA(0, 0, At, B0); PG8_BAR; PG8_SCHED;
;             PG8_LDB(B1, 0, 1); PG8_STAGE(PG8_SB(0, 0), b2, voffB);
;             PG8_BAR; PG8_WAIT_L(0); PG8_MMA(0, 1, At, B1); PG8_BAR;
;             PG8_LDA(At, 0, 1); PG8_STAGE(PG8_SA(0, 0), a2, voffA);
;             PG8_BAR; PG8_WAIT_L(0); PG8_MMA(1, 0, At, B0); PG8_BAR; PG8_SCHED;
;             PG8_STAGE(PG8_SB(0, 1), b2 + hstepB, voffB);
;             PG8_WAIT_V(6); PG8_BAR; PG8_MMA(1, 1, At, B1); PG8_BAR;
;             PG8_LDB(B0, 1, 0); PG8_SCHED; PG8_LDA(At, 1, 0); PG8_STAGE(PG8_SA(0, 1), a2 + hstepA, voffA);
;             PG8_WAIT_L(8); PG8_BAR; PG8_WAIT_L(0); PG8_MMA(0, 0, At, B0); PG8_BAR; PG8_SCHED;
;             PG8_LDB(B1, 1, 1); PG8_STAGE(PG8_SB(1, 0), b3, voffB);
;             PG8_BAR; PG8_WAIT_L(0); PG8_MMA(0, 1, At, B1); PG8_BAR;
;             PG8_LDA(At, 1, 1); PG8_STAGE(PG8_SA(1, 0), a3, voffA);
;             PG8_BAR; PG8_WAIT_L(0); PG8_MMA(1, 0, At, B0); PG8_BAR; PG8_SCHED;
;             PG8_STAGE(PG8_SB(1, 1), b3 + hstepB, voffB);
;             PG8_WAIT_V(6); PG8_BAR; PG8_MMA(1, 1, At, B1); PG8_BAR;
	s_setprio 1
	v_mfma_f32_16x16x32_bf16 v[52:55], v[206:209], v[170:173], v[52:55]
	v_mfma_f32_16x16x32_bf16 v[48:51], v[214:217], v[170:173], v[48:51]
	v_mfma_f32_16x16x32_bf16 v[36:39], v[206:209], v[178:181], v[36:39]
	v_mfma_f32_16x16x32_bf16 v[32:35], v[214:217], v[178:181], v[32:35]
	v_mfma_f32_16x16x32_bf16 v[20:23], v[206:209], v[186:189], v[20:23]
	v_mfma_f32_16x16x32_bf16 v[16:19], v[214:217], v[186:189], v[16:19]
	v_mfma_f32_16x16x32_bf16 v[4:7], v[206:209], v[194:197], v[4:7]
	v_mfma_f32_16x16x32_bf16 v[0:3], v[214:217], v[194:197], v[0:3]
	v_mfma_f32_16x16x32_bf16 v[52:55], v[210:213], v[174:177], v[52:55]
	v_mfma_f32_16x16x32_bf16 v[48:51], v[218:221], v[174:177], v[48:51]
	v_mfma_f32_16x16x32_bf16 v[36:39], v[210:213], v[182:185], v[36:39]
	v_mfma_f32_16x16x32_bf16 v[32:35], v[218:221], v[182:185], v[32:35]
	v_mfma_f32_16x16x32_bf16 v[20:23], v[210:213], v[190:193], v[20:23]
	v_mfma_f32_16x16x32_bf16 v[16:19], v[218:221], v[190:193], v[16:19]
	v_mfma_f32_16x16x32_bf16 v[4:7], v[210:213], v[202:205], v[4:7]
	v_mfma_f32_16x16x32_bf16 v[0:3], v[218:221], v[202:205], v[0:3]
	s_setprio 0
	v_add_u32_e32 v136, s83, v153
	s_barrier
	ds_read_b128 v[146:149], v136
	ds_read_b128 v[158:161], v136 offset:1024
	ds_read_b128 v[162:165], v136 offset:2048
	ds_read_b128 v[166:169], v136 offset:3072
	s_add_u32 s28, s54, 0x80000
	s_addc_u32 s29, s55, 0
	s_mov_b32 m0, s60
	ds_read_b128 v[170:173], v156 offset:32768
	ds_read_b128 v[174:177], v156 offset:33792
	ds_read_b128 v[178:181], v156 offset:34816
	ds_read_b128 v[182:185], v156 offset:35840
	ds_read_b128 v[186:189], v156 offset:36864
	ds_read_b128 v[190:193], v156 offset:37888
	ds_read_b128 v[194:197], v156 offset:38912
	ds_read_b128 v[202:205], v156 offset:39936
	global_load_lds_dwordx4 v128, s[28:29]
	s_mov_b32 m0, s61
	s_nop 0
	global_load_lds_dwordx4 v132, s[28:29]
	s_waitcnt lgkmcnt(8)
	s_barrier
	s_waitcnt lgkmcnt(0)
	s_setprio 1
	s_waitcnt lgkmcnt(0)
	v_mfma_f32_16x16x32_bf16 v[124:127], v[146:149], v[170:173], v[124:127]
	v_mfma_f32_16x16x32_bf16 v[120:123], v[162:165], v[170:173], v[120:123]
	v_mfma_f32_16x16x32_bf16 v[108:111], v[146:149], v[178:181], v[108:111]
	v_mfma_f32_16x16x32_bf16 v[104:107], v[162:165], v[178:181], v[104:107]
	v_mfma_f32_16x16x32_bf16 v[92:95], v[146:149], v[186:189], v[92:95]
	v_mfma_f32_16x16x32_bf16 v[88:91], v[162:165], v[186:189], v[88:91]
	v_mfma_f32_16x16x32_bf16 v[76:79], v[146:149], v[194:197], v[76:79]
	v_mfma_f32_16x16x32_bf16 v[72:75], v[162:165], v[194:197], v[72:75]
	v_mfma_f32_16x16x32_bf16 v[124:127], v[158:161], v[174:177], v[124:127]
	v_mfma_f32_16x16x32_bf16 v[120:123], v[166:169], v[174:177], v[120:123]
	v_mfma_f32_16x16x32_bf16 v[108:111], v[158:161], v[182:185], v[108:111]
	v_mfma_f32_16x16x32_bf16 v[104:107], v[166:169], v[182:185], v[104:107]
	v_mfma_f32_16x16x32_bf16 v[92:95], v[158:161], v[190:193], v[92:95]
	v_mfma_f32_16x16x32_bf16 v[88:91], v[166:169], v[190:193], v[88:91]
	v_mfma_f32_16x16x32_bf16 v[76:79], v[158:161], v[202:205], v[76:79]
	v_mfma_f32_16x16x32_bf16 v[72:75], v[166:169], v[202:205], v[72:75]
	s_setprio 0
	s_barrier
	s_add_i32 s28, s83, s58
	v_add_u32_e32 v136, s84, v153
	s_mov_b32 m0, s28
	ds_read_b128 v[206:209], v136
	ds_read_b128 v[210:213], v136 offset:1024
	ds_read_b128 v[214:217], v136 offset:2048
	ds_read_b128 v[218:221], v136 offset:3072
	global_load_lds_dwordx4 v130, s[98:99]
	s_add_i32 m0, s28, 0x2000
	s_nop 0
	global_load_lds_dwordx4 v134, s[98:99]
	s_barrier
	s_waitcnt lgkmcnt(0)
	s_setprio 1
	s_waitcnt lgkmcnt(0)
	v_mfma_f32_16x16x32_bf16 v[116:119], v[206:209], v[170:173], v[116:119]
	v_mfma_f32_16x16x32_bf16 v[112:115], v[214:217], v[170:173], v[112:115]
	v_mfma_f32_16x16x32_bf16 v[100:103], v[206:209], v[178:181], v[100:103]
	v_mfma_f32_16x16x32_bf16 v[96:99], v[214:217], v[178:181], v[96:99]
	v_mfma_f32_16x16x32_bf16 v[84:87], v[206:209], v[186:189], v[84:87]
	v_mfma_f32_16x16x32_bf16 v[80:83], v[214:217], v[186:189], v[80:83]
	v_mfma_f32_16x16x32_bf16 v[68:71], v[206:209], v[194:197], v[68:71]
	v_mfma_f32_16x16x32_bf16 v[64:67], v[214:217], v[194:197], v[64:67]
	v_mfma_f32_16x16x32_bf16 v[116:119], v[210:213], v[174:177], v[116:119]
	v_mfma_f32_16x16x32_bf16 v[112:115], v[218:221], v[174:177], v[112:115]
	v_mfma_f32_16x16x32_bf16 v[100:103], v[210:213], v[182:185], v[100:103]
	v_mfma_f32_16x16x32_bf16 v[96:99], v[218:221], v[182:185], v[96:99]
	v_mfma_f32_16x16x32_bf16 v[84:87], v[210:213], v[190:193], v[84:87]
	v_mfma_f32_16x16x32_bf16 v[80:83], v[218:221], v[190:193], v[80:83]
	v_mfma_f32_16x16x32_bf16 v[68:71], v[210:213], v[202:205], v[68:71]
	v_mfma_f32_16x16x32_bf16 v[64:67], v[218:221], v[202:205], v[64:67]
	s_setprio 0
	s_mov_b32 m0, s63
	s_barrier
	ds_read_b128 v[170:173], v156 offset:49152
	ds_read_b128 v[174:177], v156 offset:50176
	ds_read_b128 v[178:181], v156 offset:51200
	ds_read_b128 v[182:185], v156 offset:52224
	ds_read_b128 v[186:189], v156 offset:53248
	ds_read_b128 v[190:193], v156 offset:54272
	ds_read_b128 v[194:197], v156 offset:55296
	ds_read_b128 v[202:205], v156 offset:56320
	global_load_lds_dwordx4 v128, s[100:101]
	s_mov_b32 m0, s64
	s_nop 0
	global_load_lds_dwordx4 v132, s[100:101]
	s_barrier
; #define PG8_STAGE(bufoff, gbase, voff) do { _Pragma("unroll") for (int _i = 0; _i < 2; ++_i) \
;         __builtin_amdgcn_global_load_lds((const unsigned*)((const char*)(gbase) + (voff)[_i]), (LAS unsigned*)(lds + (bufoff) + ldsw + _i * 8192), 16, 0, 0); } while (0)
; #define PG8_WAIT_V(n) asm volatile("s_waitcnt vmcnt(" #n ")" ::: "memory")
; #define PG8_WAIT_L(n) asm volatile("s_waitcnt lgkmcnt(" #n ")" ::: "memory")
; template <class Epi>
; __device__ __forceinline__ void gemm_phase(LAS unsigned char* lds, const bf16_t* A, int lda, const bf16_t* Bt, int ldb, int M, int N, int K, int asel, const Epi& E, const int fixed_round = -1) {
;     ...
;             PG8_WAIT_V(6); PG8_BAR; PG8_MMA(1, 1, At, B1); PG8_BAR;
;             PG8_LDB(B0, 1, 0); PG8_SCHED; PG8_LDA(At, 1, 0); PG8_STAGE(PG8_SA(0, 1), a2 + hstepA, voffA);
;             PG8_WAIT_L(8); PG8_BAR; PG8_WAIT_L(0); PG8_MMA(0, 0, At, B0); PG8_BAR; PG8_SCHED;
;             PG8_LDB(B1, 1, 1); PG8_STAGE(PG8_SB(1, 0), b3, voffB);
;             PG8_BAR; PG8_WAIT_L(0); PG8_MMA(0, 1, At, B1); PG8_BAR;
;             PG8_LDA(At, 1, 1); PG8_STAGE(PG8_SA(1, 0), a3, voffA);
;             PG8_BAR; PG8_WAIT_L(0); PG8_MMA(1, 0, At, B0); PG8_BAR; PG8_SCHED;
;             PG8_STAGE(PG8_SB(1, 1), b3 + hstepB, voffB);
;             PG8_WAIT_V(6); PG8_BAR; PG8_MMA(1, 1, At, B1); PG8_BAR;
;     __device__ __forceinline__ void operator()(const AccT& acc, const Unit& u, int wr, int wc, int fr, int fq) const {
;         const int row0 = u.pm * BM + wr * 64 + fr; const bool isg = u.pn >= 8;
;         bf16_t* base = isg ? GB : XB; const int col0 = (u.pn & 7) * BM + wc * 32 + 8 * fq;
; #pragma unroll
;         for (int ai = 0; ai < 2; ++ai)
; #pragma unroll
;             for (int m = 0; m < 4; ++m) { bf16_t* rowp = base + (size_t)(row0 + ai * HALF + m * 16) * DM + col0;
; #pragma unroll
;                 for (int bj = 0; bj < 2; ++bj) { f32x4 v0 = acc[ai][bj][m][0], v1 = acc[ai][bj][m][1];
;                     if (isg) {
; #pragma unroll
;                         for (int j = 0; j < 4; ++j) { float a = v0[j], b = v1[j];
;                             const float ta = 1.5957691216057308f * (a + 0.044715f * a * a * a), tb = 1.5957691216057308f * (b + 0.044715f * b * b * b);
;                             v0[j] = a * __builtin_amdgcn_rcpf(1.0f + __expf(-ta)); v1[j] = b * __builtin_amdgcn_rcpf(1.0f + __expf(-tb)); } }
	s_waitcnt lgkmcnt(0)
	s_setprio 1
	s_waitcnt lgkmcnt(0)
	v_mfma_f32_16x16x32_bf16 v[60:63], v[146:149], v[170:173], v[60:63]
	v_mfma_f32_16x16x32_bf16 v[56:59], v[162:165], v[170:173], v[56:59]
	v_mfma_f32_16x16x32_bf16 v[44:47], v[146:149], v[178:181], v[44:47]
	v_mfma_f32_16x16x32_bf16 v[40:43], v[162:165], v[178:181], v[40:43]
	v_mfma_f32_16x16x32_bf16 v[28:31], v[146:149], v[186:189], v[28:31]
	v_mfma_f32_16x16x32_bf16 v[24:27], v[162:165], v[186:189], v[24:27]
	v_mfma_f32_16x16x32_bf16 v[12:15], v[146:149], v[194:197], v[12:15]
	v_mfma_f32_16x16x32_bf16 v[8:11], v[162:165], v[194:197], v[8:11]
	v_mfma_f32_16x16x32_bf16 v[60:63], v[158:161], v[174:177], v[60:63]
	v_mfma_f32_16x16x32_bf16 v[56:59], v[166:169], v[174:177], v[56:59]
	v_mfma_f32_16x16x32_bf16 v[44:47], v[158:161], v[182:185], v[44:47]
	v_mfma_f32_16x16x32_bf16 v[40:43], v[166:169], v[182:185], v[40:43]
	v_mfma_f32_16x16x32_bf16 v[28:31], v[158:161], v[190:193], v[28:31]
	v_mfma_f32_16x16x32_bf16 v[24:27], v[166:169], v[190:193], v[24:27]
	v_mfma_f32_16x16x32_bf16 v[12:15], v[158:161], v[202:205], v[12:15]
	v_mfma_f32_16x16x32_bf16 v[8:11], v[166:169], v[202:205], v[8:11]
	s_setprio 0
	s_barrier
	s_add_u32 s28, s52, 0x80080
	s_addc_u32 s29, s53, 0
	s_add_i32 s52, s84, s58
	s_mov_b32 m0, s52
	s_nop 0
	global_load_lds_dwordx4 v130, s[28:29]
	s_add_i32 m0, s52, 0x2000
	s_nop 0
	global_load_lds_dwordx4 v134, s[28:29]
	s_waitcnt vmcnt(6)
	s_barrier
	s_setprio 1
	v_mfma_f32_16x16x32_bf16 v[52:55], v[206:209], v[170:173], v[52:55]
	v_mfma_f32_16x16x32_bf16 v[48:51], v[214:217], v[170:173], v[48:51]
	v_mfma_f32_16x16x32_bf16 v[36:39], v[206:209], v[178:181], v[36:39]
	v_mfma_f32_16x16x32_bf16 v[32:35], v[214:217], v[178:181], v[32:35]
	v_mfma_f32_16x16x32_bf16 v[20:23], v[206:209], v[186:189], v[20:23]
	v_mfma_f32_16x16x32_bf16 v[16:19], v[214:217], v[186:189], v[16:19]
	v_mfma_f32_16x16x32_bf16 v[4:7], v[206:209], v[194:197], v[4:7]
	v_mfma_f32_16x16x32_bf16 v[0:3], v[214:217], v[194:197], v[0:3]
	v_mfma_f32_16x16x32_bf16 v[52:55], v[210:213], v[174:177], v[52:55]
	v_mfma_f32_16x16x32_bf16 v[48:51], v[218:221], v[174:177], v[48:51]
	v_mfma_f32_16x16x32_bf16 v[36:39], v[210:213], v[182:185], v[36:39]
	v_mfma_f32_16x16x32_bf16 v[32:35], v[218:221], v[182:185], v[32:35]
	v_mfma_f32_16x16x32_bf16 v[20:23], v[210:213], v[190:193], v[20:23]
	v_mfma_f32_16x16x32_bf16 v[16:19], v[218:221], v[190:193], v[16:19]
	v_mfma_f32_16x16x32_bf16 v[4:7], v[210:213], v[202:205], v[4:7]
	v_mfma_f32_16x16x32_bf16 v[0:3], v[218:221], v[202:205], v[0:3]
	s_setprio 0
	s_add_i32 s68, s68, 2
	s_add_u32 s50, s50, 0x100
	s_addc_u32 s51, s51, 0
	s_add_u32 s66, s66, 0x100
	s_addc_u32 s67, s67, 0
	s_cmp_gt_u32 s68, 29
	s_cbranch_scc0 .Lrot_7
	s_barrier
	s_cmp_gt_i32 s4, 7
	s_cselect_b64 s[50:51], -1, 0
	s_cmp_lt_i32 s4, 8
	s_cbranch_scc1 .LBB0_802
	v_mul_f32_e32 v136, 0x3d372713, v124
	v_mul_f32_e32 v136, v124, v136
	v_mul_f32_e32 v146, 0x3d372713, v120
	v_fma_f32 v136, v124, v136, v124
	v_mul_f32_e32 v146, v120, v146
	v_fma_f32 v146, v120, v146, v120
	v_mul_f32_e32 v136, 0xbfcc422a, v136
	v_mul_f32_e32 v136, 0x3fb8aa3b, v136
	v_mul_f32_e32 v146, 0xbfcc422a, v146
	v_exp_f32_e32 v136, v136
	v_mul_f32_e32 v146, 0x3fb8aa3b, v146
	v_exp_f32_e32 v147, v146
	v_mul_f32_e32 v150, 0x3d372713, v122
	v_add_f32_e32 v136, 1.0, v136
	v_rcp_f32_e32 v146, v136
	v_add_f32_e32 v136, 1.0, v147
	v_rcp_f32_e32 v148, v136
	v_mul_f32_e32 v136, 0x3d372713, v125
	v_mul_f32_e32 v136, v125, v136
	v_fma_f32 v136, v125, v136, v125
	v_mul_f32_e32 v136, 0xbfcc422a, v136
	v_mul_f32_e32 v136, 0x3fb8aa3b, v136
	v_exp_f32_e32 v136, v136
	v_mul_f32_e32 v147, 0x3d372713, v121
	v_mul_f32_e32 v147, v121, v147
	v_fma_f32 v149, v121, v147, v121
	v_add_f32_e32 v136, 1.0, v136
	v_rcp_f32_e32 v147, v136
	v_mul_f32_e32 v136, 0xbfcc422a, v149
	v_mul_f32_e32 v149, 0x3d372713, v126
	v_mul_f32_e32 v149, v126, v149
	v_fma_f32 v149, v126, v149, v126
	v_mul_f32_e32 v150, v122, v150
	v_fma_f32 v150, v122, v150, v122
	v_mul_f32_e32 v149, 0xbfcc422a, v149
	v_mul_f32_e32 v149, 0x3fb8aa3b, v149
	v_mul_f32_e32 v150, 0xbfcc422a, v150
	v_exp_f32_e32 v149, v149
	v_mul_f32_e32 v150, 0x3fb8aa3b, v150
	v_exp_f32_e32 v151, v150
	v_mul_f32_e32 v158, 0x3d372713, v123
	v_add_f32_e32 v149, 1.0, v149
	v_rcp_f32_e32 v150, v149
	v_add_f32_e32 v149, 1.0, v151
	v_mul_f32_e32 v151, 0x3d372713, v127
	v_mul_f32_e32 v151, v127, v151
	v_fma_f32 v151, v127, v151, v127
	v_mul_f32_e32 v158, v123, v158
	v_fma_f32 v158, v123, v158, v123
	v_mul_f32_e32 v151, 0xbfcc422a, v151
	v_mul_f32_e32 v151, 0x3fb8aa3b, v151
	v_mul_f32_e32 v158, 0xbfcc422a, v158
	v_mul_f32_e32 v136, 0x3fb8aa3b, v136
	v_exp_f32_e32 v151, v151
	v_mul_f32_e32 v158, 0x3fb8aa3b, v158
	v_exp_f32_e32 v136, v136
	v_exp_f32_e32 v159, v158
	v_rcp_f32_e32 v158, v149
	v_add_f32_e32 v149, 1.0, v151
	v_add_f32_e32 v136, 1.0, v136
	v_rcp_f32_e32 v151, v149
	v_add_f32_e32 v149, 1.0, v159
	v_rcp_f32_e32 v159, v149
	v_rcp_f32_e32 v149, v136
	v_pk_mul_f32 v[126:127], v[126:127], v[150:151]
	v_pk_mul_f32 v[124:125], v[124:125], v[146:147]
	v_pk_mul_f32 v[122:123], v[122:123], v[158:159]
	v_pk_mul_f32 v[120:121], v[120:121], v[148:149]

; #define PG8_STAGE(bufoff, gbase, voff) do { _Pragma("unroll") for (int _i = 0; _i < 2; ++_i) \
;         __builtin_amdgcn_global_load_lds((const unsigned*)((const char*)(gbase) + (voff)[_i]), (LAS unsigned*)(lds + (bufoff) + ldsw + _i * 8192), 16, 0, 0); } while (0)
; #define PG8_WAIT_V(n) asm volatile("s_waitcnt vmcnt(" #n ")" ::: "memory")
; #define PG8_BAR __builtin_amdgcn_s_barrier()
; template <class Epi>
; __device__ __forceinline__ void gemm_phase(LAS unsigned char* lds, const bf16_t* A, int lda, const bf16_t* Bt, int ldb, int M, int N, int K, int asel, const Epi& E, const int fixed_round = -1) {
;     ...
;     for (int i = 0; i < 2; ++i) { int R, C; stage_rc(tid * 16 + i * 8192, R, C); const int Rb = Epi::PERM ? ((R & ~31) + perm32(R & 31)) : R;
;         voffA[i] = (unsigned)(R * lda + C) * 2u; voffB[i] = (unsigned)(Rb * ldb + C) * 2u; }
;     const size_t kstep = (size_t)(BK * 2);
;     const size_t hstepA = (size_t)HALF * lda * 2, hstepB = (size_t)HALF * ldb * 2;
;     const size_t tstepA = 2 * hstepA, tstepB = 2 * hstepB;
;     const unsigned ldsw = (unsigned)wid * 1024u;
;     const int aoff = lds_byte(wr * 64 + fr, fq * 8), boff = lds_byte(wc * 32 + fr, fq * 8);
;     ...
;     Unit cur, nxt; int ui = 0;
;     if (fixed_round < 0) { if (!S.next(0, cur)) return; }
;     else { const int c = blockIdx.x; cur.pm = 32 * fixed_round + 4 * (c & 7) + (c >> 6); cur.pn = (c >> 3) & 7; }
;     f32x4 acc[2][2][4][2];
; #pragma unroll
;     for (int a = 0; a < 2; ++a)
; #pragma unroll
;         for (int b = 0; b < 2; ++b)
; #pragma unroll
;             for (int m = 0; m < 4; ++m)
; #pragma unroll
;                 for (int n = 0; n < 2; ++n) acc[a][b][m][n] = (f32x4){0.f, 0.f, 0.f, 0.f};
;     bf16x8 At[4][2], B0[2][2], B1[2][2];
;     const char* cA = PG8_ABASE(cur); const char* cB = (const char*)Bt + (size_t)cur.pn * tstepB;
;     PG8_STAGE(PG8_SB(0, 0), cB, voffB); PG8_STAGE(PG8_SA(0, 0), cA, voffA); PG8_STAGE(PG8_SB(0, 1), cB + hstepB, voffB); PG8_STAGE(PG8_SA(0, 1), cA + hstepA, voffA);
;     if (wr == 1) PG8_BAR;
;     PG8_WAIT_V(4); PG8_BAR;
;     PG8_STAGE(PG8_SB(1, 0), cB + kstep, voffB); PG8_STAGE(PG8_SA(1, 0), cA + kstep, voffA); PG8_STAGE(PG8_SB(1, 1), cB + hstepB + kstep, voffB);
;     PG8_WAIT_V(6); PG8_BAR;
.LBB0_1080:
	v_bfe_u32 v155, v13, 4, 2
	v_and_b32_e32 v164, 15, v13
	v_lshlrev_b32_e32 v15, 4, v155
	v_lshlrev_b32_e32 v13, 2, v13
	s_mov_b64 s[42:43], 0x80
	s_and_b32 s33, s29, 3
	v_lshl_or_b32 v15, v164, 6, v15
	s_lshl_b32 s29, s40, 13
	v_and_b32_e32 v13, 32, v13
	s_add_i32 m0, s49, 0x18000
	v_lshl_add_u64 v[6:7], v[6:7], 0, s[42:43]
	s_lshl_b32 s51, s40, 6
	v_bitop3_b32 v16, v15, s29, v13 bitop3:0xde
	s_lshl_b32 s29, s33, 12
	s_waitcnt vmcnt(4)
	s_barrier
	global_load_lds_dwordx4 v[6:7], off
	v_lshl_add_u64 v[4:5], v[4:5], 0, s[42:43]
	s_add_i32 m0, s49, 0x1a000
	s_add_i32 s54, s49, 0x8000
	s_add_i32 s55, s49, 0xa000
	global_load_lds_dwordx4 v[4:5], off
	v_lshl_add_u64 v[2:3], v[2:3], 0, s[42:43]
	s_mov_b32 m0, s54
	s_add_u32 s40, s2, 0x80080
	global_load_lds_dwordx4 v[2:3], off
	v_lshl_add_u64 v[0:1], v[0:1], 0, s[42:43]
	s_mov_b32 m0, s55
	s_addc_u32 s41, s3, 0
	global_load_lds_dwordx4 v[0:1], off
	s_add_i32 m0, s49, 0x1c000
	v_lshl_add_u64 v[0:1], s[40:41], 0, v[130:131]
	global_load_lds_dwordx4 v[0:1], off
	v_lshl_add_u64 v[0:1], s[40:41], 0, v[134:135]
	s_add_i32 m0, s49, 0x1e000
	v_readlane_b32 s8, v255, 18
	global_load_lds_dwordx4 v[0:1], off
	v_lshlrev_b32_e32 v0, 15, v8
	v_and_b32_e32 v0, 0xffff0000, v0
	v_lshl_add_u32 v0, v9, 12, v0
	v_and_b32_e32 v1, 1, v8
	v_lshl_or_b32 v0, v1, 6, v0
	v_readlane_b32 s9, v255, 19
	s_add_u32 s22, s78, s8
	v_lshl_add_u32 v0, v10, 1, v0
	v_mov_b32_e32 v1, v131
	s_addc_u32 s23, s79, s9
	v_lshl_add_u64 v[136:137], s[22:23], 0, v[0:1]
	v_lshlrev_b32_e32 v0, 15, v11
	v_and_b32_e32 v0, 0xffff0000, v0
	v_lshl_add_u32 v0, v12, 12, v0
	v_and_b32_e32 v1, 1, v11
	s_waitcnt vmcnt(6)
	v_lshl_or_b32 v0, v1, 6, v0
	v_bitop3_b32 v13, v15, s29, v13 bitop3:0xde
	v_lshl_add_u32 v0, v14, 1, v0
	v_mov_b32_e32 v1, v131
	s_add_i32 s59, s81, s28
	s_add_i32 s61, s82, s28
	s_add_i32 s63, s83, s28
	s_add_i32 s65, s84, s28
	v_or_b32_e32 v158, s51, v164
	v_lshl_add_u64 v[138:139], s[22:23], 0, v[0:1]
	s_mov_b32 s56, -2
	s_mov_b64 s[22:23], 0x20580080
	v_add_u32_e32 v140, s81, v13
	v_add_u32_e32 v141, 0, v16
	s_add_i32 s57, s49, 0xc000
	s_add_i32 s58, s49, 0xe000
	v_add_u32_e32 v142, s82, v13
	s_add_i32 s60, s59, 0x2000
	s_add_i32 s62, s61, 0x2000
	v_add_u32_e32 v143, s83, v13
	v_add_u32_e32 v144, s84, v13
	s_add_i32 s64, s63, 0x2000
	s_add_i32 s66, s65, 0x2000
	v_mov_b32_e32 v0, v131
	v_mov_b32_e32 v2, v131
	v_mov_b32_e32 v3, v131
	v_mov_b32_e32 v4, v131
	v_mov_b32_e32 v5, v131
	v_mov_b32_e32 v6, v131
	v_mov_b32_e32 v7, v131
	v_mov_b32_e32 v12, v131
	v_mov_b32_e32 v13, v131
	v_mov_b32_e32 v14, v131
	v_mov_b32_e32 v15, v131
	v_mov_b32_e32 v20, v131
	v_mov_b32_e32 v21, v131
	v_mov_b32_e32 v22, v131
	v_mov_b32_e32 v23, v131
	v_mov_b32_e32 v28, v131
	v_mov_b32_e32 v29, v131
	v_mov_b32_e32 v30, v131
	v_mov_b32_e32 v31, v131
	v_mov_b32_e32 v36, v131
	v_mov_b32_e32 v37, v131
	v_mov_b32_e32 v38, v131
	v_mov_b32_e32 v39, v131
	v_mov_b32_e32 v44, v131
	v_mov_b32_e32 v45, v131
	v_mov_b32_e32 v46, v131
	v_mov_b32_e32 v47, v131
	v_mov_b32_e32 v52, v131
	v_mov_b32_e32 v53, v131
	v_mov_b32_e32 v54, v131
	v_mov_b32_e32 v55, v131
	v_mov_b32_e32 v8, v131
	v_mov_b32_e32 v9, v131
	v_mov_b32_e32 v10, v131
	v_mov_b32_e32 v11, v131
	v_mov_b32_e32 v16, v131
	v_mov_b32_e32 v17, v131
	v_mov_b32_e32 v18, v131
	v_mov_b32_e32 v19, v131
	v_mov_b32_e32 v24, v131
	v_mov_b32_e32 v25, v131
	v_mov_b32_e32 v26, v131
	v_mov_b32_e32 v27, v131
	v_mov_b32_e32 v32, v131
	v_mov_b32_e32 v33, v131
	v_mov_b32_e32 v34, v131
	v_mov_b32_e32 v35, v131
	v_mov_b32_e32 v40, v131
	v_mov_b32_e32 v41, v131
	v_mov_b32_e32 v42, v131
	v_mov_b32_e32 v43, v131
	v_mov_b32_e32 v48, v131
	v_mov_b32_e32 v49, v131
	v_mov_b32_e32 v50, v131
	v_mov_b32_e32 v51, v131
	v_mov_b32_e32 v56, v131
	v_mov_b32_e32 v57, v131
	v_mov_b32_e32 v58, v131
	v_mov_b32_e32 v59, v131
	v_mov_b32_e32 v60, v131
	v_mov_b32_e32 v61, v131
	v_mov_b32_e32 v62, v131
	v_mov_b32_e32 v63, v131
	v_mov_b32_e32 v64, v131
	v_mov_b32_e32 v65, v131
	v_mov_b32_e32 v66, v131
	v_mov_b32_e32 v67, v131
	v_mov_b32_e32 v68, v131
	v_mov_b32_e32 v69, v131
	v_mov_b32_e32 v70, v131
	v_mov_b32_e32 v71, v131
	v_mov_b32_e32 v76, v131
	v_mov_b32_e32 v77, v131
	v_mov_b32_e32 v78, v131
	v_mov_b32_e32 v79, v131
	v_mov_b32_e32 v84, v131
	v_mov_b32_e32 v85, v131
	v_mov_b32_e32 v86, v131
	v_mov_b32_e32 v87, v131
	v_mov_b32_e32 v92, v131
	v_mov_b32_e32 v93, v131
	v_mov_b32_e32 v94, v131
	v_mov_b32_e32 v95, v131
	v_mov_b32_e32 v100, v131
	v_mov_b32_e32 v101, v131
	v_mov_b32_e32 v102, v131
	v_mov_b32_e32 v103, v131
	v_mov_b32_e32 v108, v131
	v_mov_b32_e32 v109, v131
	v_mov_b32_e32 v110, v131
	v_mov_b32_e32 v111, v131
	v_mov_b32_e32 v116, v131
	v_mov_b32_e32 v117, v131
	v_mov_b32_e32 v118, v131
	v_mov_b32_e32 v119, v131
	v_mov_b32_e32 v72, v131
	v_mov_b32_e32 v73, v131
	v_mov_b32_e32 v74, v131
	v_mov_b32_e32 v75, v131
	v_mov_b32_e32 v80, v131
	v_mov_b32_e32 v81, v131
	v_mov_b32_e32 v82, v131
	v_mov_b32_e32 v83, v131
	v_mov_b32_e32 v88, v131
	v_mov_b32_e32 v89, v131
	v_mov_b32_e32 v90, v131
	v_mov_b32_e32 v91, v131
	v_mov_b32_e32 v96, v131
	v_mov_b32_e32 v97, v131
	v_mov_b32_e32 v98, v131
	v_mov_b32_e32 v99, v131
	v_mov_b32_e32 v104, v131
	v_mov_b32_e32 v105, v131
	v_mov_b32_e32 v106, v131
	v_mov_b32_e32 v107, v131
	v_mov_b32_e32 v112, v131
	v_mov_b32_e32 v113, v131
	v_mov_b32_e32 v114, v131
	v_mov_b32_e32 v115, v131
	v_mov_b32_e32 v120, v131
	v_mov_b32_e32 v121, v131
	v_mov_b32_e32 v122, v131
	v_mov_b32_e32 v123, v131
	v_mov_b32_e32 v124, v131
	v_mov_b32_e32 v125, v131
	v_mov_b32_e32 v126, v131
	v_mov_b32_e32 v127, v131
.Lrot_8:
	s_barrier
; #define PG8_STAGE(bufoff, gbase, voff) do { _Pragma("unroll") for (int _i = 0; _i < 2; ++_i) \
;         __builtin_amdgcn_global_load_lds((const unsigned*)((const char*)(gbase) + (voff)[_i]), (LAS unsigned*)(lds + (bufoff) + ldsw + _i * 8192), 16, 0, 0); } while (0)
; #define PG8_LDA(dst, b, h) do { _Pragma("unroll") for (int m = 0; m < 4; ++m) _Pragma("unroll") for (int k = 0; k < 2; ++k) dst[m][k] = *(const LAS bf16x8*)(lds + PG8_SA(b, h) + aoff + m * 2048 + k * 1024); } while (0)
; #define PG8_LDB(dst, b, h) do { _Pragma("unroll") for (int n = 0; n < 2; ++n) _Pragma("unroll") for (int k = 0; k < 2; ++k) dst[n][k] = *(const LAS bf16x8*)(lds + PG8_SB(b, h) + boff + n * 2048 + k * 1024); } while (0)
; #define PG8_WAIT_V(n) asm volatile("s_waitcnt vmcnt(" #n ")" ::: "memory")
; #define PG8_WAIT_L(n) asm volatile("s_waitcnt lgkmcnt(" #n ")" ::: "memory")
; #define PG8_BAR __builtin_amdgcn_s_barrier()
; #define PG8_SCHED __builtin_amdgcn_sched_barrier(0)
; template <class Epi>
; __device__ __forceinline__ void gemm_phase(LAS unsigned char* lds, const bf16_t* A, int lda, const bf16_t* Bt, int ldb, int M, int N, int K, int asel, const Epi& E, const int fixed_round = -1) {
;     ...
;             PG8_LDB(B0, 0, 0); PG8_SCHED; PG8_LDA(At, 0, 0); PG8_STAGE(PG8_SA(1, 1), a1 + hstepA, voffA);
;             PG8_WAIT_L(8); PG8_BAR; PG8_WAIT_L(0); PG8_MMA(0, 0, At, B0); PG8_BAR; PG8_SCHED;
;             PG8_LDB(B1, 0, 1); PG8_STAGE(PG8_SB(0, 0), b2, voffB);
;             PG8_BAR; PG8_WAIT_L(0); PG8_MMA(0, 1, At, B1); PG8_BAR;
;             PG8_LDA(At, 0, 1); PG8_STAGE(PG8_SA(0, 0), a2, voffA);
;             PG8_BAR; PG8_WAIT_L(0); PG8_MMA(1, 0, At, B0); PG8_BAR; PG8_SCHED;
;             PG8_STAGE(PG8_SB(0, 1), b2 + hstepB, voffB);
;             PG8_WAIT_V(6); PG8_BAR; PG8_MMA(1, 1, At, B1); PG8_BAR;
.LBB0_1081:
	s_add_u32 s28, s22, 0xdfa80080
	ds_read_b128 v[146:149], v140
	ds_read_b128 v[150:153], v140 offset:1024
	ds_read_b128 v[160:163], v140 offset:2048
	ds_read_b128 v[166:169], v140 offset:3072
	s_addc_u32 s29, s23, -1
	s_cmp_lg_u32 s56, 28
	s_cselect_b32 s28, s28, 0
	s_cselect_b32 s29, s29, 0
	s_add_u32 s46, s0, s28
	s_addc_u32 s47, s1, s29
	s_add_u32 s44, s2, s28
	s_addc_u32 s45, s3, s29
	s_mov_b32 m0, s57
	v_lshl_add_u64 v[156:157], v[136:137], 0, s[22:23]
	ds_read_b128 v[170:173], v141
	ds_read_b128 v[174:177], v141 offset:1024
	ds_read_b128 v[178:181], v141 offset:2048
	ds_read_b128 v[182:185], v141 offset:3072
	ds_read_b128 v[186:189], v141 offset:4096
	ds_read_b128 v[190:193], v141 offset:5120
	ds_read_b128 v[194:197], v141 offset:6144
	ds_read_b128 v[202:205], v141 offset:7168
	global_load_lds_dwordx4 v[156:157], off
	v_lshl_add_u64 v[156:157], v[138:139], 0, s[22:23]
	s_mov_b32 m0, s58
	s_nop 0
	global_load_lds_dwordx4 v[156:157], off
	s_waitcnt lgkmcnt(8)
	s_barrier
	s_waitcnt lgkmcnt(0)
	s_setprio 1
	s_waitcnt lgkmcnt(0)
	v_mfma_f32_16x16x32_bf16 v[124:127], v[146:149], v[170:173], v[124:127]
	v_mfma_f32_16x16x32_bf16 v[120:123], v[160:163], v[170:173], v[120:123]
	v_mfma_f32_16x16x32_bf16 v[112:115], v[146:149], v[178:181], v[112:115]
	v_mfma_f32_16x16x32_bf16 v[104:107], v[160:163], v[178:181], v[104:107]
	v_mfma_f32_16x16x32_bf16 v[96:99], v[146:149], v[186:189], v[96:99]
	v_mfma_f32_16x16x32_bf16 v[88:91], v[160:163], v[186:189], v[88:91]
	v_mfma_f32_16x16x32_bf16 v[80:83], v[146:149], v[194:197], v[80:83]
	v_mfma_f32_16x16x32_bf16 v[72:75], v[160:163], v[194:197], v[72:75]
	v_mfma_f32_16x16x32_bf16 v[124:127], v[150:153], v[174:177], v[124:127]
	v_mfma_f32_16x16x32_bf16 v[120:123], v[166:169], v[174:177], v[120:123]
	v_mfma_f32_16x16x32_bf16 v[112:115], v[150:153], v[182:185], v[112:115]
	v_mfma_f32_16x16x32_bf16 v[104:107], v[166:169], v[182:185], v[104:107]
	v_mfma_f32_16x16x32_bf16 v[96:99], v[150:153], v[190:193], v[96:99]
	v_mfma_f32_16x16x32_bf16 v[88:91], v[166:169], v[190:193], v[88:91]
	v_mfma_f32_16x16x32_bf16 v[80:83], v[150:153], v[202:205], v[80:83]
	v_mfma_f32_16x16x32_bf16 v[72:75], v[166:169], v[202:205], v[72:75]
	s_setprio 0
	s_barrier
	s_mov_b32 m0, s59
	s_add_u32 s98, s44, s42
	s_addc_u32 s99, s45, s43
	ds_read_b128 v[206:209], v142
	ds_read_b128 v[210:213], v142 offset:1024
	ds_read_b128 v[214:217], v142 offset:2048
	ds_read_b128 v[218:221], v142 offset:3072
	global_load_lds_dwordx4 v130, s[44:45]
	s_mov_b32 m0, s60
	s_nop 0
	global_load_lds_dwordx4 v134, s[44:45]
	s_barrier
	s_waitcnt lgkmcnt(0)
	s_setprio 1
	s_waitcnt lgkmcnt(0)
	v_mfma_f32_16x16x32_bf16 v[116:119], v[206:209], v[170:173], v[116:119]
	v_mfma_f32_16x16x32_bf16 v[108:111], v[214:217], v[170:173], v[108:111]
	v_mfma_f32_16x16x32_bf16 v[100:103], v[206:209], v[178:181], v[100:103]
	v_mfma_f32_16x16x32_bf16 v[92:95], v[214:217], v[178:181], v[92:95]
	v_mfma_f32_16x16x32_bf16 v[84:87], v[206:209], v[186:189], v[84:87]
	v_mfma_f32_16x16x32_bf16 v[76:79], v[214:217], v[186:189], v[76:79]
	v_mfma_f32_16x16x32_bf16 v[68:71], v[206:209], v[194:197], v[68:71]
	v_mfma_f32_16x16x32_bf16 v[64:67], v[214:217], v[194:197], v[64:67]
	v_mfma_f32_16x16x32_bf16 v[116:119], v[210:213], v[174:177], v[116:119]
	v_mfma_f32_16x16x32_bf16 v[108:111], v[218:221], v[174:177], v[108:111]
	v_mfma_f32_16x16x32_bf16 v[100:103], v[210:213], v[182:185], v[100:103]
	v_mfma_f32_16x16x32_bf16 v[92:95], v[218:221], v[182:185], v[92:95]
	v_mfma_f32_16x16x32_bf16 v[84:87], v[210:213], v[190:193], v[84:87]
	v_mfma_f32_16x16x32_bf16 v[76:79], v[218:221], v[190:193], v[76:79]
	v_mfma_f32_16x16x32_bf16 v[68:71], v[210:213], v[202:205], v[68:71]
	v_mfma_f32_16x16x32_bf16 v[64:67], v[218:221], v[202:205], v[64:67]
	s_setprio 0
	s_mov_b32 m0, s49
	s_add_u32 s100, s46, s42
	s_addc_u32 s101, s47, s43
	s_barrier
	ds_read_b128 v[170:173], v141 offset:16384
	ds_read_b128 v[174:177], v141 offset:17408
	ds_read_b128 v[178:181], v141 offset:18432
	ds_read_b128 v[182:185], v141 offset:19456
	ds_read_b128 v[186:189], v141 offset:20480
	ds_read_b128 v[190:193], v141 offset:21504
	ds_read_b128 v[194:197], v141 offset:22528
	ds_read_b128 v[202:205], v141 offset:23552
	global_load_lds_dwordx4 v128, s[46:47]
	s_mov_b32 m0, s50
	s_nop 0
	global_load_lds_dwordx4 v132, s[46:47]
	s_barrier
	s_waitcnt lgkmcnt(0)
	s_setprio 1
	s_waitcnt lgkmcnt(0)
	v_mfma_f32_16x16x32_bf16 v[60:63], v[146:149], v[170:173], v[60:63]
	v_mfma_f32_16x16x32_bf16 v[56:59], v[160:163], v[170:173], v[56:59]
	v_mfma_f32_16x16x32_bf16 v[48:51], v[146:149], v[178:181], v[48:51]
	v_mfma_f32_16x16x32_bf16 v[40:43], v[160:163], v[178:181], v[40:43]
	v_mfma_f32_16x16x32_bf16 v[32:35], v[146:149], v[186:189], v[32:35]
	v_mfma_f32_16x16x32_bf16 v[24:27], v[160:163], v[186:189], v[24:27]
	v_mfma_f32_16x16x32_bf16 v[16:19], v[146:149], v[194:197], v[16:19]
	v_mfma_f32_16x16x32_bf16 v[8:11], v[160:163], v[194:197], v[8:11]
	v_mfma_f32_16x16x32_bf16 v[60:63], v[150:153], v[174:177], v[60:63]
	v_mfma_f32_16x16x32_bf16 v[56:59], v[166:169], v[174:177], v[56:59]
	v_mfma_f32_16x16x32_bf16 v[48:51], v[150:153], v[182:185], v[48:51]
	v_mfma_f32_16x16x32_bf16 v[40:43], v[166:169], v[182:185], v[40:43]
	v_mfma_f32_16x16x32_bf16 v[32:35], v[150:153], v[190:193], v[32:35]
	v_mfma_f32_16x16x32_bf16 v[24:27], v[166:169], v[190:193], v[24:27]
	v_mfma_f32_16x16x32_bf16 v[16:19], v[150:153], v[202:205], v[16:19]
	v_mfma_f32_16x16x32_bf16 v[8:11], v[166:169], v[202:205], v[8:11]
	s_setprio 0
	s_barrier
	s_add_u32 s28, s44, 0x80000
	s_addc_u32 s29, s45, 0
	s_mov_b32 m0, s61
	s_nop 0
	global_load_lds_dwordx4 v130, s[28:29]
	s_mov_b32 m0, s62
	s_nop 0
	global_load_lds_dwordx4 v134, s[28:29]
	s_waitcnt vmcnt(6)
	s_barrier
; #define PG8_STAGE(bufoff, gbase, voff) do { _Pragma("unroll") for (int _i = 0; _i < 2; ++_i) \
;         __builtin_amdgcn_global_load_lds((const unsigned*)((const char*)(gbase) + (voff)[_i]), (LAS unsigned*)(lds + (bufoff) + ldsw + _i * 8192), 16, 0, 0); } while (0)
; #define PG8_LDA(dst, b, h) do { _Pragma("unroll") for (int m = 0; m < 4; ++m) _Pragma("unroll") for (int k = 0; k < 2; ++k) dst[m][k] = *(const LAS bf16x8*)(lds + PG8_SA(b, h) + aoff + m * 2048 + k * 1024); } while (0)
; #define PG8_LDB(dst, b, h) do { _Pragma("unroll") for (int n = 0; n < 2; ++n) _Pragma("unroll") for (int k = 0; k < 2; ++k) dst[n][k] = *(const LAS bf16x8*)(lds + PG8_SB(b, h) + boff + n * 2048 + k * 1024); } while (0)
; #define PG8_WAIT_V(n) asm volatile("s_waitcnt vmcnt(" #n ")" ::: "memory")
; #define PG8_WAIT_L(n) asm volatile("s_waitcnt lgkmcnt(" #n ")" ::: "memory")
; #define PG8_BAR __builtin_amdgcn_s_barrier()
; #define PG8_SCHED __builtin_amdgcn_sched_barrier(0)
; template <class Epi>
; __device__ __forceinline__ void gemm_phase(LAS unsigned char* lds, const bf16_t* A, int lda, const bf16_t* Bt, int ldb, int M, int N, int K, int asel, const Epi& E, const int fixed_round = -1) {
;     ...
;             PG8_WAIT_V(6); PG8_BAR; PG8_MMA(1, 1, At, B1); PG8_BAR;
;             PG8_LDB(B0, 1, 0); PG8_SCHED; PG8_LDA(At, 1, 0); PG8_STAGE(PG8_SA(0, 1), a2 + hstepA, voffA);
;             PG8_WAIT_L(8); PG8_BAR; PG8_WAIT_L(0); PG8_MMA(0, 0, At, B0); PG8_BAR; PG8_SCHED;
;             PG8_LDB(B1, 1, 1); PG8_STAGE(PG8_SB(1, 0), b3, voffB);
	s_setprio 1
	v_mfma_f32_16x16x32_bf16 v[52:55], v[206:209], v[170:173], v[52:55]
	v_mfma_f32_16x16x32_bf16 v[44:47], v[214:217], v[170:173], v[44:47]
	v_mfma_f32_16x16x32_bf16 v[36:39], v[206:209], v[178:181], v[36:39]
	v_mfma_f32_16x16x32_bf16 v[28:31], v[214:217], v[178:181], v[28:31]
	v_mfma_f32_16x16x32_bf16 v[20:23], v[206:209], v[186:189], v[20:23]
	v_mfma_f32_16x16x32_bf16 v[12:15], v[214:217], v[186:189], v[12:15]
	v_mfma_f32_16x16x32_bf16 v[4:7], v[206:209], v[194:197], v[4:7]
	v_mfma_f32_16x16x32_bf16 v[0:3], v[214:217], v[194:197], v[0:3]
	v_mfma_f32_16x16x32_bf16 v[52:55], v[210:213], v[174:177], v[52:55]
	v_mfma_f32_16x16x32_bf16 v[44:47], v[218:221], v[174:177], v[44:47]
	v_mfma_f32_16x16x32_bf16 v[36:39], v[210:213], v[182:185], v[36:39]
	v_mfma_f32_16x16x32_bf16 v[28:31], v[218:221], v[182:185], v[28:31]
	v_mfma_f32_16x16x32_bf16 v[20:23], v[210:213], v[190:193], v[20:23]
	v_mfma_f32_16x16x32_bf16 v[12:15], v[218:221], v[190:193], v[12:15]
	v_mfma_f32_16x16x32_bf16 v[4:7], v[210:213], v[202:205], v[4:7]
	v_mfma_f32_16x16x32_bf16 v[0:3], v[218:221], v[202:205], v[0:3]
	s_setprio 0
	s_barrier
	ds_read_b128 v[146:149], v143
	ds_read_b128 v[150:153], v143 offset:1024
	ds_read_b128 v[160:163], v143 offset:2048
	ds_read_b128 v[166:169], v143 offset:3072
	s_add_u32 s28, s46, 0x80000
	s_addc_u32 s29, s47, 0
	s_mov_b32 m0, s52
	ds_read_b128 v[170:173], v141 offset:32768
	ds_read_b128 v[174:177], v141 offset:33792
	ds_read_b128 v[178:181], v141 offset:34816
	ds_read_b128 v[182:185], v141 offset:35840
	ds_read_b128 v[186:189], v141 offset:36864
	ds_read_b128 v[190:193], v141 offset:37888
	ds_read_b128 v[194:197], v141 offset:38912
	ds_read_b128 v[202:205], v141 offset:39936
	global_load_lds_dwordx4 v128, s[28:29]
	s_mov_b32 m0, s53
	s_nop 0
	global_load_lds_dwordx4 v132, s[28:29]
	s_waitcnt lgkmcnt(8)
	s_barrier
	s_waitcnt lgkmcnt(0)
	s_setprio 1
	s_waitcnt lgkmcnt(0)
	v_mfma_f32_16x16x32_bf16 v[124:127], v[146:149], v[170:173], v[124:127]
	v_mfma_f32_16x16x32_bf16 v[120:123], v[160:163], v[170:173], v[120:123]
	v_mfma_f32_16x16x32_bf16 v[112:115], v[146:149], v[178:181], v[112:115]
	v_mfma_f32_16x16x32_bf16 v[104:107], v[160:163], v[178:181], v[104:107]
	v_mfma_f32_16x16x32_bf16 v[96:99], v[146:149], v[186:189], v[96:99]
	v_mfma_f32_16x16x32_bf16 v[88:91], v[160:163], v[186:189], v[88:91]
	v_mfma_f32_16x16x32_bf16 v[80:83], v[146:149], v[194:197], v[80:83]
	v_mfma_f32_16x16x32_bf16 v[72:75], v[160:163], v[194:197], v[72:75]
	v_mfma_f32_16x16x32_bf16 v[124:127], v[150:153], v[174:177], v[124:127]
	v_mfma_f32_16x16x32_bf16 v[120:123], v[166:169], v[174:177], v[120:123]
	v_mfma_f32_16x16x32_bf16 v[112:115], v[150:153], v[182:185], v[112:115]
	v_mfma_f32_16x16x32_bf16 v[104:107], v[166:169], v[182:185], v[104:107]
	v_mfma_f32_16x16x32_bf16 v[96:99], v[150:153], v[190:193], v[96:99]
	v_mfma_f32_16x16x32_bf16 v[88:91], v[166:169], v[190:193], v[88:91]
	v_mfma_f32_16x16x32_bf16 v[80:83], v[150:153], v[202:205], v[80:83]
	v_mfma_f32_16x16x32_bf16 v[72:75], v[166:169], v[202:205], v[72:75]
	s_setprio 0
	s_barrier
	s_mov_b32 m0, s63
	ds_read_b128 v[206:209], v144
	ds_read_b128 v[210:213], v144 offset:1024
	ds_read_b128 v[214:217], v144 offset:2048
	ds_read_b128 v[218:221], v144 offset:3072
	global_load_lds_dwordx4 v130, s[98:99]
	s_mov_b32 m0, s64
	s_nop 0
	global_load_lds_dwordx4 v134, s[98:99]
	s_barrier
; #define PG8_STAGE(bufoff, gbase, voff) do { _Pragma("unroll") for (int _i = 0; _i < 2; ++_i) \
;         __builtin_amdgcn_global_load_lds((const unsigned*)((const char*)(gbase) + (voff)[_i]), (LAS unsigned*)(lds + (bufoff) + ldsw + _i * 8192), 16, 0, 0); } while (0)
; #define PG8_LDA(dst, b, h) do { _Pragma("unroll") for (int m = 0; m < 4; ++m) _Pragma("unroll") for (int k = 0; k < 2; ++k) dst[m][k] = *(const LAS bf16x8*)(lds + PG8_SA(b, h) + aoff + m * 2048 + k * 1024); } while (0)
; #define PG8_WAIT_V(n) asm volatile("s_waitcnt vmcnt(" #n ")" ::: "memory")
; #define PG8_WAIT_L(n) asm volatile("s_waitcnt lgkmcnt(" #n ")" ::: "memory")
; #define PG8_BAR __builtin_amdgcn_s_barrier()
; #define PG8_SCHED __builtin_amdgcn_sched_barrier(0)
; template <class Epi>
; __device__ __forceinline__ void gemm_phase(LAS unsigned char* lds, const bf16_t* A, int lda, const bf16_t* Bt, int ldb, int M, int N, int K, int asel, const Epi& E, const int fixed_round = -1) {
;     ...
;             PG8_BAR; PG8_WAIT_L(0); PG8_MMA(0, 1, At, B1); PG8_BAR;
;             PG8_LDA(At, 1, 1); PG8_STAGE(PG8_SA(1, 0), a3, voffA);
;             PG8_BAR; PG8_WAIT_L(0); PG8_MMA(1, 0, At, B0); PG8_BAR; PG8_SCHED;
;             PG8_STAGE(PG8_SB(1, 1), b3 + hstepB, voffB);
;             PG8_WAIT_V(6); PG8_BAR; PG8_MMA(1, 1, At, B1); PG8_BAR;
;     ...
;     PG8_WAIT_V(0);
;     if (wr == 0) PG8_BAR;
;     PG8_BAR;
	s_waitcnt lgkmcnt(0)
	s_setprio 1
	s_waitcnt lgkmcnt(0)
	v_mfma_f32_16x16x32_bf16 v[116:119], v[206:209], v[170:173], v[116:119]
	v_mfma_f32_16x16x32_bf16 v[108:111], v[214:217], v[170:173], v[108:111]
	v_mfma_f32_16x16x32_bf16 v[100:103], v[206:209], v[178:181], v[100:103]
	v_mfma_f32_16x16x32_bf16 v[92:95], v[214:217], v[178:181], v[92:95]
	v_mfma_f32_16x16x32_bf16 v[84:87], v[206:209], v[186:189], v[84:87]
	v_mfma_f32_16x16x32_bf16 v[76:79], v[214:217], v[186:189], v[76:79]
	v_mfma_f32_16x16x32_bf16 v[68:71], v[206:209], v[194:197], v[68:71]
	v_mfma_f32_16x16x32_bf16 v[64:67], v[214:217], v[194:197], v[64:67]
	v_mfma_f32_16x16x32_bf16 v[116:119], v[210:213], v[174:177], v[116:119]
	v_mfma_f32_16x16x32_bf16 v[108:111], v[218:221], v[174:177], v[108:111]
	v_mfma_f32_16x16x32_bf16 v[100:103], v[210:213], v[182:185], v[100:103]
	v_mfma_f32_16x16x32_bf16 v[92:95], v[218:221], v[182:185], v[92:95]
	v_mfma_f32_16x16x32_bf16 v[84:87], v[210:213], v[190:193], v[84:87]
	v_mfma_f32_16x16x32_bf16 v[76:79], v[218:221], v[190:193], v[76:79]
	v_mfma_f32_16x16x32_bf16 v[68:71], v[210:213], v[202:205], v[68:71]
	v_mfma_f32_16x16x32_bf16 v[64:67], v[218:221], v[202:205], v[64:67]
	s_setprio 0
	s_mov_b32 m0, s54
	s_barrier
	ds_read_b128 v[170:173], v141 offset:49152
	ds_read_b128 v[174:177], v141 offset:50176
	ds_read_b128 v[178:181], v141 offset:51200
	ds_read_b128 v[182:185], v141 offset:52224
	ds_read_b128 v[186:189], v141 offset:53248
	ds_read_b128 v[190:193], v141 offset:54272
	ds_read_b128 v[194:197], v141 offset:55296
	ds_read_b128 v[202:205], v141 offset:56320
	global_load_lds_dwordx4 v128, s[100:101]
	s_mov_b32 m0, s55
	s_nop 0
	global_load_lds_dwordx4 v132, s[100:101]
	s_barrier
	s_waitcnt lgkmcnt(0)
	s_setprio 1
	s_waitcnt lgkmcnt(0)
	v_mfma_f32_16x16x32_bf16 v[60:63], v[146:149], v[170:173], v[60:63]
	v_mfma_f32_16x16x32_bf16 v[56:59], v[160:163], v[170:173], v[56:59]
	v_mfma_f32_16x16x32_bf16 v[48:51], v[146:149], v[178:181], v[48:51]
	v_mfma_f32_16x16x32_bf16 v[40:43], v[160:163], v[178:181], v[40:43]
	v_mfma_f32_16x16x32_bf16 v[32:35], v[146:149], v[186:189], v[32:35]
	v_mfma_f32_16x16x32_bf16 v[24:27], v[160:163], v[186:189], v[24:27]
	v_mfma_f32_16x16x32_bf16 v[16:19], v[146:149], v[194:197], v[16:19]
	v_mfma_f32_16x16x32_bf16 v[8:11], v[160:163], v[194:197], v[8:11]
	v_mfma_f32_16x16x32_bf16 v[60:63], v[150:153], v[174:177], v[60:63]
	v_mfma_f32_16x16x32_bf16 v[56:59], v[166:169], v[174:177], v[56:59]
	v_mfma_f32_16x16x32_bf16 v[48:51], v[150:153], v[182:185], v[48:51]
	v_mfma_f32_16x16x32_bf16 v[40:43], v[166:169], v[182:185], v[40:43]
	v_mfma_f32_16x16x32_bf16 v[32:35], v[150:153], v[190:193], v[32:35]
	v_mfma_f32_16x16x32_bf16 v[24:27], v[166:169], v[190:193], v[24:27]
	v_mfma_f32_16x16x32_bf16 v[16:19], v[150:153], v[202:205], v[16:19]
	v_mfma_f32_16x16x32_bf16 v[8:11], v[166:169], v[202:205], v[8:11]
	s_setprio 0
	s_barrier
	s_add_u32 s28, s44, 0x80080
	s_addc_u32 s29, s45, 0
	s_mov_b32 m0, s65
	s_nop 0
	global_load_lds_dwordx4 v130, s[28:29]
	s_mov_b32 m0, s66
	s_nop 0
	global_load_lds_dwordx4 v134, s[28:29]
	s_waitcnt vmcnt(6)
	s_barrier
	s_setprio 1
	v_mfma_f32_16x16x32_bf16 v[52:55], v[206:209], v[170:173], v[52:55]
	v_mfma_f32_16x16x32_bf16 v[44:47], v[214:217], v[170:173], v[44:47]
	v_mfma_f32_16x16x32_bf16 v[36:39], v[206:209], v[178:181], v[36:39]
	v_mfma_f32_16x16x32_bf16 v[28:31], v[214:217], v[178:181], v[28:31]
	v_mfma_f32_16x16x32_bf16 v[20:23], v[206:209], v[186:189], v[20:23]
	v_mfma_f32_16x16x32_bf16 v[12:15], v[214:217], v[186:189], v[12:15]
	v_mfma_f32_16x16x32_bf16 v[4:7], v[206:209], v[194:197], v[4:7]
	v_mfma_f32_16x16x32_bf16 v[0:3], v[214:217], v[194:197], v[0:3]
	v_mfma_f32_16x16x32_bf16 v[52:55], v[210:213], v[174:177], v[52:55]
	v_mfma_f32_16x16x32_bf16 v[44:47], v[218:221], v[174:177], v[44:47]
	v_mfma_f32_16x16x32_bf16 v[36:39], v[210:213], v[182:185], v[36:39]
	v_mfma_f32_16x16x32_bf16 v[28:31], v[218:221], v[182:185], v[28:31]
	v_mfma_f32_16x16x32_bf16 v[20:23], v[210:213], v[190:193], v[20:23]
	v_mfma_f32_16x16x32_bf16 v[12:15], v[218:221], v[190:193], v[12:15]
	v_mfma_f32_16x16x32_bf16 v[4:7], v[210:213], v[202:205], v[4:7]
	v_mfma_f32_16x16x32_bf16 v[0:3], v[218:221], v[202:205], v[0:3]
	s_setprio 0
	s_add_i32 s56, s56, 2
	s_add_u32 s22, s22, 0x100
	s_addc_u32 s23, s23, 0
	s_cmp_lt_u32 s56, 30
	s_cbranch_scc1 .Lrot_8
	s_barrier
	s_waitcnt vmcnt(0)
	s_cmpk_gt_u32 s48, 0xff
	s_cbranch_scc1 .LBB0_1084
	s_barrier

; #define PG8_STAGE(bufoff, gbase, voff) do { _Pragma("unroll") for (int _i = 0; _i < 2; ++_i) \
;         __builtin_amdgcn_global_load_lds((const unsigned*)((const char*)(gbase) + (voff)[_i]), (LAS unsigned*)(lds + (bufoff) + ldsw + _i * 8192), 16, 0, 0); } while (0)
; #define PG8_WAIT_V(n) asm volatile("s_waitcnt vmcnt(" #n ")" ::: "memory")
; #define PG8_BAR __builtin_amdgcn_s_barrier()
; template <class Epi>
; __device__ __forceinline__ void gemm_phase(LAS unsigned char* lds, const bf16_t* A, int lda, const bf16_t* Bt, int ldb, int M, int N, int K, int asel, const Epi& E, const int fixed_round = -1) {
;     ...
;     StaticOrder S; S.init(M, N, gridDim.x, blockIdx.x);
;     unsigned voffA[2], voffB[2];
; #pragma unroll
;     for (int i = 0; i < 2; ++i) { int R, C; stage_rc(tid * 16 + i * 8192, R, C); const int Rb = Epi::PERM ? ((R & ~31) + perm32(R & 31)) : R;
;         voffA[i] = (unsigned)(R * lda + C) * 2u; voffB[i] = (unsigned)(Rb * ldb + C) * 2u; }
;     const size_t kstep = (size_t)(BK * 2);
;     const size_t hstepA = (size_t)HALF * lda * 2, hstepB = (size_t)HALF * ldb * 2;
;     const size_t tstepA = 2 * hstepA, tstepB = 2 * hstepB;
;     const unsigned ldsw = (unsigned)wid * 1024u;
;     const int aoff = lds_byte(wr * 64 + fr, fq * 8), boff = lds_byte(wc * 32 + fr, fq * 8);
;     ...
;     Unit cur, nxt; int ui = 0;
;     if (fixed_round < 0) { if (!S.next(0, cur)) return; }
;     else { const int c = blockIdx.x; cur.pm = 32 * fixed_round + 4 * (c & 7) + (c >> 6); cur.pn = (c >> 3) & 7; }
;     f32x4 acc[2][2][4][2];
; #pragma unroll
;     for (int a = 0; a < 2; ++a)
; #pragma unroll
;         for (int b = 0; b < 2; ++b)
; #pragma unroll
;             for (int m = 0; m < 4; ++m)
; #pragma unroll
;                 for (int n = 0; n < 2; ++n) acc[a][b][m][n] = (f32x4){0.f, 0.f, 0.f, 0.f};
;     bf16x8 At[4][2], B0[2][2], B1[2][2];
;     const char* cA = PG8_ABASE(cur); const char* cB = (const char*)Bt + (size_t)cur.pn * tstepB;
;     PG8_STAGE(PG8_SB(0, 0), cB, voffB); PG8_STAGE(PG8_SA(0, 0), cA, voffA); PG8_STAGE(PG8_SB(0, 1), cB + hstepB, voffB); PG8_STAGE(PG8_SA(0, 1), cA + hstepA, voffA);
;     if (wr == 1) PG8_BAR;
;     PG8_WAIT_V(4); PG8_BAR;
;     PG8_STAGE(PG8_SB(1, 0), cB + kstep, voffB); PG8_STAGE(PG8_SA(1, 0), cA + kstep, voffA); PG8_STAGE(PG8_SB(1, 1), cB + hstepB + kstep, voffB);
;     PG8_WAIT_V(6); PG8_BAR;
.LBB0_1119:
	v_bfe_u32 v155, v12, 4, 2
	v_and_b32_e32 v164, 15, v12
	v_lshlrev_b32_e32 v15, 4, v155
	v_lshlrev_b32_e32 v12, 2, v12
	s_and_b32 s45, s23, 3
	v_lshl_or_b32 v15, v164, 6, v15
	s_lshl_b32 s4, s28, 13
	v_and_b32_e32 v12, 32, v12
	v_bitop3_b32 v16, v15, s4, v12 bitop3:0xde
	s_lshl_b32 s4, s45, 12
	v_bitop3_b32 v12, v15, s4, v12 bitop3:0xde
	s_mov_b64 s[4:5], 0x80
	s_add_i32 m0, s52, 0x18000
	v_lshl_add_u64 v[6:7], v[6:7], 0, s[4:5]
	s_waitcnt vmcnt(4)
	s_barrier
	global_load_lds_dwordx4 v[6:7], off
	v_lshl_add_u64 v[4:5], v[4:5], 0, s[4:5]
	s_add_i32 m0, s52, 0x1a000
	s_add_i32 s56, s52, 0x8000
	global_load_lds_dwordx4 v[4:5], off
	v_lshl_add_u64 v[2:3], v[2:3], 0, s[4:5]
	s_mov_b32 m0, s56
	s_add_i32 s57, s52, 0xa000
	global_load_lds_dwordx4 v[2:3], off
	v_lshl_add_u64 v[0:1], v[0:1], 0, s[4:5]
	s_mov_b32 m0, s57
	s_lshl_b32 s44, s28, 6
	global_load_lds_dwordx4 v[0:1], off
	s_add_i32 m0, s52, 0x1c000
	v_lshl_add_u64 v[0:1], s[40:41], 0, v[144:145]
	global_load_lds_dwordx4 v[0:1], off
	v_lshl_add_u64 v[0:1], s[40:41], 0, v[132:133]
	s_add_i32 m0, s52, 0x1e000
	s_add_u32 s6, s78, s24
	global_load_lds_dwordx4 v[0:1], off
	v_lshlrev_b32_e32 v0, 15, v8
	v_and_b32_e32 v0, 0xffff0000, v0
	v_lshl_add_u32 v0, v9, 12, v0
	v_and_b32_e32 v1, 1, v8
	v_lshl_or_b32 v0, v1, 6, v0
	v_lshl_add_u32 v0, v10, 1, v0
	v_mov_b32_e32 v1, v145
	s_addc_u32 s7, s79, s25
	v_lshl_add_u64 v[134:135], s[6:7], 0, v[0:1]
	v_lshlrev_b32_e32 v0, 15, v11
	v_and_b32_e32 v0, 0xffff0000, v0
	v_lshl_add_u32 v0, v13, 12, v0
	v_and_b32_e32 v1, 1, v11
	s_waitcnt vmcnt(6)
	v_lshl_or_b32 v0, v1, 6, v0
	v_lshl_add_u32 v0, v14, 1, v0
	v_mov_b32_e32 v1, v145
	s_add_i32 s59, s81, s22
	s_add_i32 s61, s82, s22
	s_add_i32 s63, s83, s22
	s_add_i32 s65, s84, s22
	v_or_b32_e32 v158, s44, v164
	v_lshl_add_u64 v[136:137], s[6:7], 0, v[0:1]
	s_mov_b32 s40, -2
	s_mov_b64 s[6:7], 0x20580080
	v_add_u32_e32 v138, s81, v12
	v_add_u32_e32 v139, 0, v16
	s_add_i32 s41, s52, 0xc000
	s_add_i32 s58, s52, 0xe000
	v_add_u32_e32 v140, s82, v12
	s_add_i32 s60, s59, 0x2000
	s_add_i32 s62, s61, 0x2000
	v_add_u32_e32 v141, s83, v12
	v_add_u32_e32 v142, s84, v12
	s_add_i32 s64, s63, 0x2000
	s_add_i32 s66, s65, 0x2000
	v_mov_b32_e32 v0, v145
	v_mov_b32_e32 v2, v145
	v_mov_b32_e32 v3, v145
	v_mov_b32_e32 v4, v145
	v_mov_b32_e32 v5, v145
	v_mov_b32_e32 v6, v145
	v_mov_b32_e32 v7, v145
	v_mov_b32_e32 v12, v145
	v_mov_b32_e32 v13, v145
	v_mov_b32_e32 v14, v145
	v_mov_b32_e32 v15, v145
	v_mov_b32_e32 v20, v145
	v_mov_b32_e32 v21, v145
	v_mov_b32_e32 v22, v145
	v_mov_b32_e32 v23, v145
	v_mov_b32_e32 v28, v145
	v_mov_b32_e32 v29, v145
	v_mov_b32_e32 v30, v145
	v_mov_b32_e32 v31, v145
	v_mov_b32_e32 v36, v145
	v_mov_b32_e32 v37, v145
	v_mov_b32_e32 v38, v145
	v_mov_b32_e32 v39, v145
	v_mov_b32_e32 v44, v145
	v_mov_b32_e32 v45, v145
	v_mov_b32_e32 v46, v145
	v_mov_b32_e32 v47, v145
	v_mov_b32_e32 v52, v145
	v_mov_b32_e32 v53, v145
	v_mov_b32_e32 v54, v145
	v_mov_b32_e32 v55, v145
	v_mov_b32_e32 v8, v145
	v_mov_b32_e32 v9, v145
	v_mov_b32_e32 v10, v145
	v_mov_b32_e32 v11, v145
	v_mov_b32_e32 v16, v145
	v_mov_b32_e32 v17, v145
	v_mov_b32_e32 v18, v145
	v_mov_b32_e32 v19, v145
	v_mov_b32_e32 v24, v145
	v_mov_b32_e32 v25, v145
	v_mov_b32_e32 v26, v145
	v_mov_b32_e32 v27, v145
	v_mov_b32_e32 v32, v145
	v_mov_b32_e32 v33, v145
	v_mov_b32_e32 v34, v145
	v_mov_b32_e32 v35, v145
	v_mov_b32_e32 v40, v145
	v_mov_b32_e32 v41, v145
	v_mov_b32_e32 v42, v145
	v_mov_b32_e32 v43, v145
	v_mov_b32_e32 v48, v145
	v_mov_b32_e32 v49, v145
	v_mov_b32_e32 v50, v145
	v_mov_b32_e32 v51, v145
	v_mov_b32_e32 v56, v145
	v_mov_b32_e32 v57, v145
	v_mov_b32_e32 v58, v145
	v_mov_b32_e32 v59, v145
	v_mov_b32_e32 v60, v145
	v_mov_b32_e32 v61, v145
	v_mov_b32_e32 v62, v145
	v_mov_b32_e32 v63, v145
	v_mov_b32_e32 v64, v145
	v_mov_b32_e32 v65, v145
	v_mov_b32_e32 v66, v145
	v_mov_b32_e32 v67, v145
	v_mov_b32_e32 v68, v145
	v_mov_b32_e32 v69, v145
	v_mov_b32_e32 v70, v145
	v_mov_b32_e32 v71, v145
	v_mov_b32_e32 v76, v145
	v_mov_b32_e32 v77, v145
	v_mov_b32_e32 v78, v145
	v_mov_b32_e32 v79, v145
	v_mov_b32_e32 v84, v145
	v_mov_b32_e32 v85, v145
	v_mov_b32_e32 v86, v145
	v_mov_b32_e32 v87, v145
	v_mov_b32_e32 v92, v145
	v_mov_b32_e32 v93, v145
	v_mov_b32_e32 v94, v145
	v_mov_b32_e32 v95, v145
	v_mov_b32_e32 v100, v145
	v_mov_b32_e32 v101, v145
	v_mov_b32_e32 v102, v145
	v_mov_b32_e32 v103, v145
	v_mov_b32_e32 v108, v145
	v_mov_b32_e32 v109, v145
	v_mov_b32_e32 v110, v145
	v_mov_b32_e32 v111, v145
	v_mov_b32_e32 v116, v145
	v_mov_b32_e32 v117, v145
	v_mov_b32_e32 v118, v145
	v_mov_b32_e32 v119, v145
	v_mov_b32_e32 v72, v145
	v_mov_b32_e32 v73, v145
	v_mov_b32_e32 v74, v145
	v_mov_b32_e32 v75, v145
	v_mov_b32_e32 v80, v145
	v_mov_b32_e32 v81, v145
	v_mov_b32_e32 v82, v145
	v_mov_b32_e32 v83, v145
	v_mov_b32_e32 v88, v145
	v_mov_b32_e32 v89, v145
	v_mov_b32_e32 v90, v145
	v_mov_b32_e32 v91, v145
	v_mov_b32_e32 v96, v145
	v_mov_b32_e32 v97, v145
	v_mov_b32_e32 v98, v145
	v_mov_b32_e32 v99, v145
	v_mov_b32_e32 v104, v145
	v_mov_b32_e32 v105, v145
	v_mov_b32_e32 v106, v145
	v_mov_b32_e32 v107, v145
	v_mov_b32_e32 v112, v145
	v_mov_b32_e32 v113, v145
	v_mov_b32_e32 v114, v145
	v_mov_b32_e32 v115, v145
	v_mov_b32_e32 v120, v145
	v_mov_b32_e32 v121, v145
	v_mov_b32_e32 v122, v145
	v_mov_b32_e32 v123, v145
	v_mov_b32_e32 v124, v145
	v_mov_b32_e32 v125, v145
	v_mov_b32_e32 v126, v145
	v_mov_b32_e32 v127, v145
.Lrot_9:
	s_barrier
; #define PG8_STAGE(bufoff, gbase, voff) do { _Pragma("unroll") for (int _i = 0; _i < 2; ++_i) \
;         __builtin_amdgcn_global_load_lds((const unsigned*)((const char*)(gbase) + (voff)[_i]), (LAS unsigned*)(lds + (bufoff) + ldsw + _i * 8192), 16, 0, 0); } while (0)
; #define PG8_LDA(dst, b, h) do { _Pragma("unroll") for (int m = 0; m < 4; ++m) _Pragma("unroll") for (int k = 0; k < 2; ++k) dst[m][k] = *(const LAS bf16x8*)(lds + PG8_SA(b, h) + aoff + m * 2048 + k * 1024); } while (0)
; #define PG8_LDB(dst, b, h) do { _Pragma("unroll") for (int n = 0; n < 2; ++n) _Pragma("unroll") for (int k = 0; k < 2; ++k) dst[n][k] = *(const LAS bf16x8*)(lds + PG8_SB(b, h) + boff + n * 2048 + k * 1024); } while (0)
; #define PG8_WAIT_V(n) asm volatile("s_waitcnt vmcnt(" #n ")" ::: "memory")
; #define PG8_WAIT_L(n) asm volatile("s_waitcnt lgkmcnt(" #n ")" ::: "memory")
; #define PG8_BAR __builtin_amdgcn_s_barrier()
; #define PG8_SCHED __builtin_amdgcn_sched_barrier(0)
; template <class Epi>
; __device__ __forceinline__ void gemm_phase(LAS unsigned char* lds, const bf16_t* A, int lda, const bf16_t* Bt, int ldb, int M, int N, int K, int asel, const Epi& E, const int fixed_round = -1) {
;     ...
;             const bool last = (t == nt - 2);
;             const char* a1 = cA + (size_t)(t + 1) * kstep;
;             const char* a2 = last ? nA : cA + (size_t)(t + 2) * kstep; const char* b2 = last ? nB : cB + (size_t)(t + 2) * kstep;
;             const char* a3 = a2 + kstep; const char* b3 = b2 + kstep;
;             PG8_LDB(B0, 0, 0); PG8_SCHED; PG8_LDA(At, 0, 0); PG8_STAGE(PG8_SA(1, 1), a1 + hstepA, voffA);
;             PG8_WAIT_L(8); PG8_BAR; PG8_WAIT_L(0); PG8_MMA(0, 0, At, B0); PG8_BAR; PG8_SCHED;
;             PG8_LDB(B1, 0, 1); PG8_STAGE(PG8_SB(0, 0), b2, voffB);
;             PG8_BAR; PG8_WAIT_L(0); PG8_MMA(0, 1, At, B1); PG8_BAR;
;             PG8_LDA(At, 0, 1); PG8_STAGE(PG8_SA(0, 0), a2, voffA);
;             PG8_BAR; PG8_WAIT_L(0); PG8_MMA(1, 0, At, B0); PG8_BAR; PG8_SCHED;
;             PG8_STAGE(PG8_SB(0, 1), b2 + hstepB, voffB);
;             PG8_WAIT_V(6); PG8_BAR; PG8_MMA(1, 1, At, B1); PG8_BAR;
.LBB0_1120:
	s_add_u32 s22, s6, 0xdfa80080
	ds_read_b128 v[146:149], v138
	ds_read_b128 v[150:153], v138 offset:1024
	ds_read_b128 v[160:163], v138 offset:2048
	ds_read_b128 v[166:169], v138 offset:3072
	s_addc_u32 s23, s7, -1
	s_cmp_lg_u32 s40, 28
	s_cselect_b32 s22, s22, 0
	s_cselect_b32 s23, s23, 0
	s_add_u32 s24, s0, s22
	s_addc_u32 s25, s1, s23
	s_add_u32 s22, s2, s22
	s_addc_u32 s23, s3, s23
	s_mov_b32 m0, s41
	v_lshl_add_u64 v[156:157], v[134:135], 0, s[6:7]
	ds_read_b128 v[170:173], v139
	ds_read_b128 v[174:177], v139 offset:1024
	ds_read_b128 v[178:181], v139 offset:2048
	ds_read_b128 v[182:185], v139 offset:3072
	ds_read_b128 v[186:189], v139 offset:4096
	ds_read_b128 v[190:193], v139 offset:5120
	ds_read_b128 v[194:197], v139 offset:6144
	ds_read_b128 v[202:205], v139 offset:7168
	global_load_lds_dwordx4 v[156:157], off
	v_lshl_add_u64 v[156:157], v[136:137], 0, s[6:7]
	s_mov_b32 m0, s58
	s_nop 0
	global_load_lds_dwordx4 v[156:157], off
	s_waitcnt lgkmcnt(8)
	s_barrier
	s_waitcnt lgkmcnt(0)
	s_setprio 1
	s_waitcnt lgkmcnt(0)
	v_mfma_f32_16x16x32_bf16 v[124:127], v[146:149], v[170:173], v[124:127]
	v_mfma_f32_16x16x32_bf16 v[120:123], v[160:163], v[170:173], v[120:123]
	v_mfma_f32_16x16x32_bf16 v[112:115], v[146:149], v[178:181], v[112:115]
	v_mfma_f32_16x16x32_bf16 v[104:107], v[160:163], v[178:181], v[104:107]
	v_mfma_f32_16x16x32_bf16 v[96:99], v[146:149], v[186:189], v[96:99]
	v_mfma_f32_16x16x32_bf16 v[88:91], v[160:163], v[186:189], v[88:91]
	v_mfma_f32_16x16x32_bf16 v[80:83], v[146:149], v[194:197], v[80:83]
	v_mfma_f32_16x16x32_bf16 v[72:75], v[160:163], v[194:197], v[72:75]
	v_mfma_f32_16x16x32_bf16 v[124:127], v[150:153], v[174:177], v[124:127]
	v_mfma_f32_16x16x32_bf16 v[120:123], v[166:169], v[174:177], v[120:123]
	v_mfma_f32_16x16x32_bf16 v[112:115], v[150:153], v[182:185], v[112:115]
	v_mfma_f32_16x16x32_bf16 v[104:107], v[166:169], v[182:185], v[104:107]
	v_mfma_f32_16x16x32_bf16 v[96:99], v[150:153], v[190:193], v[96:99]
	v_mfma_f32_16x16x32_bf16 v[88:91], v[166:169], v[190:193], v[88:91]
	v_mfma_f32_16x16x32_bf16 v[80:83], v[150:153], v[202:205], v[80:83]
	v_mfma_f32_16x16x32_bf16 v[72:75], v[166:169], v[202:205], v[72:75]
	s_setprio 0
	s_barrier
	s_mov_b32 m0, s59
	s_add_u32 s98, s22, s4
	s_addc_u32 s99, s23, s5
	ds_read_b128 v[206:209], v140
	ds_read_b128 v[210:213], v140 offset:1024
	ds_read_b128 v[214:217], v140 offset:2048
	ds_read_b128 v[218:221], v140 offset:3072
	global_load_lds_dwordx4 v144, s[22:23]
	s_mov_b32 m0, s60
	s_nop 0
	global_load_lds_dwordx4 v132, s[22:23]
	s_barrier
	s_waitcnt lgkmcnt(0)
	s_setprio 1
	s_waitcnt lgkmcnt(0)
	v_mfma_f32_16x16x32_bf16 v[116:119], v[206:209], v[170:173], v[116:119]
	v_mfma_f32_16x16x32_bf16 v[108:111], v[214:217], v[170:173], v[108:111]
	v_mfma_f32_16x16x32_bf16 v[100:103], v[206:209], v[178:181], v[100:103]
	v_mfma_f32_16x16x32_bf16 v[92:95], v[214:217], v[178:181], v[92:95]
	v_mfma_f32_16x16x32_bf16 v[84:87], v[206:209], v[186:189], v[84:87]
	v_mfma_f32_16x16x32_bf16 v[76:79], v[214:217], v[186:189], v[76:79]
	v_mfma_f32_16x16x32_bf16 v[68:71], v[206:209], v[194:197], v[68:71]
	v_mfma_f32_16x16x32_bf16 v[64:67], v[214:217], v[194:197], v[64:67]
	v_mfma_f32_16x16x32_bf16 v[116:119], v[210:213], v[174:177], v[116:119]
	v_mfma_f32_16x16x32_bf16 v[108:111], v[218:221], v[174:177], v[108:111]
	v_mfma_f32_16x16x32_bf16 v[100:103], v[210:213], v[182:185], v[100:103]
	v_mfma_f32_16x16x32_bf16 v[92:95], v[218:221], v[182:185], v[92:95]
	v_mfma_f32_16x16x32_bf16 v[84:87], v[210:213], v[190:193], v[84:87]
	v_mfma_f32_16x16x32_bf16 v[76:79], v[218:221], v[190:193], v[76:79]
	v_mfma_f32_16x16x32_bf16 v[68:71], v[210:213], v[202:205], v[68:71]
	v_mfma_f32_16x16x32_bf16 v[64:67], v[218:221], v[202:205], v[64:67]
	s_setprio 0
	s_mov_b32 m0, s52
	s_add_u32 s100, s24, s4
	s_addc_u32 s101, s25, s5
	s_barrier
	ds_read_b128 v[170:173], v139 offset:16384
	ds_read_b128 v[174:177], v139 offset:17408
	ds_read_b128 v[178:181], v139 offset:18432
	ds_read_b128 v[182:185], v139 offset:19456
	ds_read_b128 v[186:189], v139 offset:20480
	ds_read_b128 v[190:193], v139 offset:21504
	ds_read_b128 v[194:197], v139 offset:22528
	ds_read_b128 v[202:205], v139 offset:23552
	global_load_lds_dwordx4 v128, s[24:25]
	s_mov_b32 m0, s53
	s_nop 0
	global_load_lds_dwordx4 v130, s[24:25]
	s_barrier
	s_waitcnt lgkmcnt(0)
	s_setprio 1
	s_waitcnt lgkmcnt(0)
	v_mfma_f32_16x16x32_bf16 v[60:63], v[146:149], v[170:173], v[60:63]
	v_mfma_f32_16x16x32_bf16 v[56:59], v[160:163], v[170:173], v[56:59]
	v_mfma_f32_16x16x32_bf16 v[48:51], v[146:149], v[178:181], v[48:51]
	v_mfma_f32_16x16x32_bf16 v[40:43], v[160:163], v[178:181], v[40:43]
	v_mfma_f32_16x16x32_bf16 v[32:35], v[146:149], v[186:189], v[32:35]
	v_mfma_f32_16x16x32_bf16 v[24:27], v[160:163], v[186:189], v[24:27]
	v_mfma_f32_16x16x32_bf16 v[16:19], v[146:149], v[194:197], v[16:19]
	v_mfma_f32_16x16x32_bf16 v[8:11], v[160:163], v[194:197], v[8:11]
	v_mfma_f32_16x16x32_bf16 v[60:63], v[150:153], v[174:177], v[60:63]
	v_mfma_f32_16x16x32_bf16 v[56:59], v[166:169], v[174:177], v[56:59]
	v_mfma_f32_16x16x32_bf16 v[48:51], v[150:153], v[182:185], v[48:51]
	v_mfma_f32_16x16x32_bf16 v[40:43], v[166:169], v[182:185], v[40:43]
	v_mfma_f32_16x16x32_bf16 v[32:35], v[150:153], v[190:193], v[32:35]
	v_mfma_f32_16x16x32_bf16 v[24:27], v[166:169], v[190:193], v[24:27]
	v_mfma_f32_16x16x32_bf16 v[16:19], v[150:153], v[202:205], v[16:19]
	v_mfma_f32_16x16x32_bf16 v[8:11], v[166:169], v[202:205], v[8:11]
	s_setprio 0
	s_barrier
	s_add_u32 s28, s22, 0x80000
	s_addc_u32 s29, s23, 0
	s_mov_b32 m0, s61
	s_nop 0
	global_load_lds_dwordx4 v144, s[28:29]
	s_mov_b32 m0, s62
	s_nop 0
	global_load_lds_dwordx4 v132, s[28:29]
	s_waitcnt vmcnt(6)
	s_barrier
; #define PG8_STAGE(bufoff, gbase, voff) do { _Pragma("unroll") for (int _i = 0; _i < 2; ++_i) \
;         __builtin_amdgcn_global_load_lds((const unsigned*)((const char*)(gbase) + (voff)[_i]), (LAS unsigned*)(lds + (bufoff) + ldsw + _i * 8192), 16, 0, 0); } while (0)
; #define PG8_LDA(dst, b, h) do { _Pragma("unroll") for (int m = 0; m < 4; ++m) _Pragma("unroll") for (int k = 0; k < 2; ++k) dst[m][k] = *(const LAS bf16x8*)(lds + PG8_SA(b, h) + aoff + m * 2048 + k * 1024); } while (0)
; #define PG8_LDB(dst, b, h) do { _Pragma("unroll") for (int n = 0; n < 2; ++n) _Pragma("unroll") for (int k = 0; k < 2; ++k) dst[n][k] = *(const LAS bf16x8*)(lds + PG8_SB(b, h) + boff + n * 2048 + k * 1024); } while (0)
; #define PG8_WAIT_V(n) asm volatile("s_waitcnt vmcnt(" #n ")" ::: "memory")
; #define PG8_WAIT_L(n) asm volatile("s_waitcnt lgkmcnt(" #n ")" ::: "memory")
; #define PG8_BAR __builtin_amdgcn_s_barrier()
; #define PG8_SCHED __builtin_amdgcn_sched_barrier(0)
; template <class Epi>
; __device__ __forceinline__ void gemm_phase(LAS unsigned char* lds, const bf16_t* A, int lda, const bf16_t* Bt, int ldb, int M, int N, int K, int asel, const Epi& E, const int fixed_round = -1) {
;     ...
;             PG8_WAIT_V(6); PG8_BAR; PG8_MMA(1, 1, At, B1); PG8_BAR;
;             PG8_LDB(B0, 1, 0); PG8_SCHED; PG8_LDA(At, 1, 0); PG8_STAGE(PG8_SA(0, 1), a2 + hstepA, voffA);
;             PG8_WAIT_L(8); PG8_BAR; PG8_WAIT_L(0); PG8_MMA(0, 0, At, B0); PG8_BAR; PG8_SCHED;
;             PG8_LDB(B1, 1, 1); PG8_STAGE(PG8_SB(1, 0), b3, voffB);
	s_setprio 1
	v_mfma_f32_16x16x32_bf16 v[52:55], v[206:209], v[170:173], v[52:55]
	v_mfma_f32_16x16x32_bf16 v[44:47], v[214:217], v[170:173], v[44:47]
	v_mfma_f32_16x16x32_bf16 v[36:39], v[206:209], v[178:181], v[36:39]
	v_mfma_f32_16x16x32_bf16 v[28:31], v[214:217], v[178:181], v[28:31]
	v_mfma_f32_16x16x32_bf16 v[20:23], v[206:209], v[186:189], v[20:23]
	v_mfma_f32_16x16x32_bf16 v[12:15], v[214:217], v[186:189], v[12:15]
	v_mfma_f32_16x16x32_bf16 v[4:7], v[206:209], v[194:197], v[4:7]
	v_mfma_f32_16x16x32_bf16 v[0:3], v[214:217], v[194:197], v[0:3]
	v_mfma_f32_16x16x32_bf16 v[52:55], v[210:213], v[174:177], v[52:55]
	v_mfma_f32_16x16x32_bf16 v[44:47], v[218:221], v[174:177], v[44:47]
	v_mfma_f32_16x16x32_bf16 v[36:39], v[210:213], v[182:185], v[36:39]
	v_mfma_f32_16x16x32_bf16 v[28:31], v[218:221], v[182:185], v[28:31]
	v_mfma_f32_16x16x32_bf16 v[20:23], v[210:213], v[190:193], v[20:23]
	v_mfma_f32_16x16x32_bf16 v[12:15], v[218:221], v[190:193], v[12:15]
	v_mfma_f32_16x16x32_bf16 v[4:7], v[210:213], v[202:205], v[4:7]
	v_mfma_f32_16x16x32_bf16 v[0:3], v[218:221], v[202:205], v[0:3]
	s_setprio 0
	s_barrier
	ds_read_b128 v[146:149], v141
	ds_read_b128 v[150:153], v141 offset:1024
	ds_read_b128 v[160:163], v141 offset:2048
	ds_read_b128 v[166:169], v141 offset:3072
	s_add_u32 s24, s24, 0x80000
	s_addc_u32 s25, s25, 0
	s_mov_b32 m0, s54
	ds_read_b128 v[170:173], v139 offset:32768
	ds_read_b128 v[174:177], v139 offset:33792
	ds_read_b128 v[178:181], v139 offset:34816
	ds_read_b128 v[182:185], v139 offset:35840
	ds_read_b128 v[186:189], v139 offset:36864
	ds_read_b128 v[190:193], v139 offset:37888
	ds_read_b128 v[194:197], v139 offset:38912
	ds_read_b128 v[202:205], v139 offset:39936
	global_load_lds_dwordx4 v128, s[24:25]
	s_mov_b32 m0, s55
	s_nop 0
	global_load_lds_dwordx4 v130, s[24:25]
	s_waitcnt lgkmcnt(8)
	s_barrier
	s_waitcnt lgkmcnt(0)
	s_setprio 1
	s_waitcnt lgkmcnt(0)
	v_mfma_f32_16x16x32_bf16 v[124:127], v[146:149], v[170:173], v[124:127]
	v_mfma_f32_16x16x32_bf16 v[120:123], v[160:163], v[170:173], v[120:123]
	v_mfma_f32_16x16x32_bf16 v[112:115], v[146:149], v[178:181], v[112:115]
	v_mfma_f32_16x16x32_bf16 v[104:107], v[160:163], v[178:181], v[104:107]
	v_mfma_f32_16x16x32_bf16 v[96:99], v[146:149], v[186:189], v[96:99]
	v_mfma_f32_16x16x32_bf16 v[88:91], v[160:163], v[186:189], v[88:91]
	v_mfma_f32_16x16x32_bf16 v[80:83], v[146:149], v[194:197], v[80:83]
	v_mfma_f32_16x16x32_bf16 v[72:75], v[160:163], v[194:197], v[72:75]
	v_mfma_f32_16x16x32_bf16 v[124:127], v[150:153], v[174:177], v[124:127]
	v_mfma_f32_16x16x32_bf16 v[120:123], v[166:169], v[174:177], v[120:123]
	v_mfma_f32_16x16x32_bf16 v[112:115], v[150:153], v[182:185], v[112:115]
	v_mfma_f32_16x16x32_bf16 v[104:107], v[166:169], v[182:185], v[104:107]
	v_mfma_f32_16x16x32_bf16 v[96:99], v[150:153], v[190:193], v[96:99]
	v_mfma_f32_16x16x32_bf16 v[88:91], v[166:169], v[190:193], v[88:91]
	v_mfma_f32_16x16x32_bf16 v[80:83], v[150:153], v[202:205], v[80:83]
	v_mfma_f32_16x16x32_bf16 v[72:75], v[166:169], v[202:205], v[72:75]
	s_setprio 0
	s_barrier
	s_mov_b32 m0, s63
	ds_read_b128 v[206:209], v142
	ds_read_b128 v[210:213], v142 offset:1024
	ds_read_b128 v[214:217], v142 offset:2048
	ds_read_b128 v[218:221], v142 offset:3072
	global_load_lds_dwordx4 v144, s[98:99]
	s_mov_b32 m0, s64
	s_nop 0
	global_load_lds_dwordx4 v132, s[98:99]
	s_barrier
; #define PG8_STAGE(bufoff, gbase, voff) do { _Pragma("unroll") for (int _i = 0; _i < 2; ++_i) \
;         __builtin_amdgcn_global_load_lds((const unsigned*)((const char*)(gbase) + (voff)[_i]), (LAS unsigned*)(lds + (bufoff) + ldsw + _i * 8192), 16, 0, 0); } while (0)
; #define PG8_LDA(dst, b, h) do { _Pragma("unroll") for (int m = 0; m < 4; ++m) _Pragma("unroll") for (int k = 0; k < 2; ++k) dst[m][k] = *(const LAS bf16x8*)(lds + PG8_SA(b, h) + aoff + m * 2048 + k * 1024); } while (0)
; #define PG8_WAIT_V(n) asm volatile("s_waitcnt vmcnt(" #n ")" ::: "memory")
; #define PG8_WAIT_L(n) asm volatile("s_waitcnt lgkmcnt(" #n ")" ::: "memory")
; #define PG8_BAR __builtin_amdgcn_s_barrier()
; #define PG8_SCHED __builtin_amdgcn_sched_barrier(0)
; template <class Epi>
; __device__ __forceinline__ void gemm_phase(LAS unsigned char* lds, const bf16_t* A, int lda, const bf16_t* Bt, int ldb, int M, int N, int K, int asel, const Epi& E, const int fixed_round = -1) {
;     ...
;             PG8_BAR; PG8_WAIT_L(0); PG8_MMA(0, 1, At, B1); PG8_BAR;
;             PG8_LDA(At, 1, 1); PG8_STAGE(PG8_SA(1, 0), a3, voffA);
;             PG8_BAR; PG8_WAIT_L(0); PG8_MMA(1, 0, At, B0); PG8_BAR; PG8_SCHED;
;             PG8_STAGE(PG8_SB(1, 1), b3 + hstepB, voffB);
;             PG8_WAIT_V(6); PG8_BAR; PG8_MMA(1, 1, At, B1); PG8_BAR;
;     ...
;     PG8_WAIT_V(0);
;     if (wr == 0) PG8_BAR;
;     PG8_BAR;
	s_waitcnt lgkmcnt(0)
	s_setprio 1
	s_waitcnt lgkmcnt(0)
	v_mfma_f32_16x16x32_bf16 v[116:119], v[206:209], v[170:173], v[116:119]
	v_mfma_f32_16x16x32_bf16 v[108:111], v[214:217], v[170:173], v[108:111]
	v_mfma_f32_16x16x32_bf16 v[100:103], v[206:209], v[178:181], v[100:103]
	v_mfma_f32_16x16x32_bf16 v[92:95], v[214:217], v[178:181], v[92:95]
	v_mfma_f32_16x16x32_bf16 v[84:87], v[206:209], v[186:189], v[84:87]
	v_mfma_f32_16x16x32_bf16 v[76:79], v[214:217], v[186:189], v[76:79]
	v_mfma_f32_16x16x32_bf16 v[68:71], v[206:209], v[194:197], v[68:71]
	v_mfma_f32_16x16x32_bf16 v[64:67], v[214:217], v[194:197], v[64:67]
	v_mfma_f32_16x16x32_bf16 v[116:119], v[210:213], v[174:177], v[116:119]
	v_mfma_f32_16x16x32_bf16 v[108:111], v[218:221], v[174:177], v[108:111]
	v_mfma_f32_16x16x32_bf16 v[100:103], v[210:213], v[182:185], v[100:103]
	v_mfma_f32_16x16x32_bf16 v[92:95], v[218:221], v[182:185], v[92:95]
	v_mfma_f32_16x16x32_bf16 v[84:87], v[210:213], v[190:193], v[84:87]
	v_mfma_f32_16x16x32_bf16 v[76:79], v[218:221], v[190:193], v[76:79]
	v_mfma_f32_16x16x32_bf16 v[68:71], v[210:213], v[202:205], v[68:71]
	v_mfma_f32_16x16x32_bf16 v[64:67], v[218:221], v[202:205], v[64:67]
	s_setprio 0
	s_mov_b32 m0, s56
	s_barrier
	ds_read_b128 v[170:173], v139 offset:49152
	ds_read_b128 v[174:177], v139 offset:50176
	ds_read_b128 v[178:181], v139 offset:51200
	ds_read_b128 v[182:185], v139 offset:52224
	ds_read_b128 v[186:189], v139 offset:53248
	ds_read_b128 v[190:193], v139 offset:54272
	ds_read_b128 v[194:197], v139 offset:55296
	ds_read_b128 v[202:205], v139 offset:56320
	global_load_lds_dwordx4 v128, s[100:101]
	s_mov_b32 m0, s57
	s_nop 0
	global_load_lds_dwordx4 v130, s[100:101]
	s_barrier
	s_waitcnt lgkmcnt(0)
	s_setprio 1
	s_waitcnt lgkmcnt(0)
	v_mfma_f32_16x16x32_bf16 v[60:63], v[146:149], v[170:173], v[60:63]
	v_mfma_f32_16x16x32_bf16 v[56:59], v[160:163], v[170:173], v[56:59]
	v_mfma_f32_16x16x32_bf16 v[48:51], v[146:149], v[178:181], v[48:51]
	v_mfma_f32_16x16x32_bf16 v[40:43], v[160:163], v[178:181], v[40:43]
	v_mfma_f32_16x16x32_bf16 v[32:35], v[146:149], v[186:189], v[32:35]
	v_mfma_f32_16x16x32_bf16 v[24:27], v[160:163], v[186:189], v[24:27]
	v_mfma_f32_16x16x32_bf16 v[16:19], v[146:149], v[194:197], v[16:19]
	v_mfma_f32_16x16x32_bf16 v[8:11], v[160:163], v[194:197], v[8:11]
	v_mfma_f32_16x16x32_bf16 v[60:63], v[150:153], v[174:177], v[60:63]
	v_mfma_f32_16x16x32_bf16 v[56:59], v[166:169], v[174:177], v[56:59]
	v_mfma_f32_16x16x32_bf16 v[48:51], v[150:153], v[182:185], v[48:51]
	v_mfma_f32_16x16x32_bf16 v[40:43], v[166:169], v[182:185], v[40:43]
	v_mfma_f32_16x16x32_bf16 v[32:35], v[150:153], v[190:193], v[32:35]
	v_mfma_f32_16x16x32_bf16 v[24:27], v[166:169], v[190:193], v[24:27]
	v_mfma_f32_16x16x32_bf16 v[16:19], v[150:153], v[202:205], v[16:19]
	v_mfma_f32_16x16x32_bf16 v[8:11], v[166:169], v[202:205], v[8:11]
	s_setprio 0
	s_barrier
	s_add_u32 s22, s22, 0x80080
	s_addc_u32 s23, s23, 0
	s_mov_b32 m0, s65
	s_nop 0
	global_load_lds_dwordx4 v144, s[22:23]
	s_mov_b32 m0, s66
	s_nop 0
	global_load_lds_dwordx4 v132, s[22:23]
	s_waitcnt vmcnt(6)
	s_barrier
	s_setprio 1
	v_mfma_f32_16x16x32_bf16 v[52:55], v[206:209], v[170:173], v[52:55]
	v_mfma_f32_16x16x32_bf16 v[44:47], v[214:217], v[170:173], v[44:47]
	v_mfma_f32_16x16x32_bf16 v[36:39], v[206:209], v[178:181], v[36:39]
	v_mfma_f32_16x16x32_bf16 v[28:31], v[214:217], v[178:181], v[28:31]
	v_mfma_f32_16x16x32_bf16 v[20:23], v[206:209], v[186:189], v[20:23]
	v_mfma_f32_16x16x32_bf16 v[12:15], v[214:217], v[186:189], v[12:15]
	v_mfma_f32_16x16x32_bf16 v[4:7], v[206:209], v[194:197], v[4:7]
	v_mfma_f32_16x16x32_bf16 v[0:3], v[214:217], v[194:197], v[0:3]
	v_mfma_f32_16x16x32_bf16 v[52:55], v[210:213], v[174:177], v[52:55]
	v_mfma_f32_16x16x32_bf16 v[44:47], v[218:221], v[174:177], v[44:47]
	v_mfma_f32_16x16x32_bf16 v[36:39], v[210:213], v[182:185], v[36:39]
	v_mfma_f32_16x16x32_bf16 v[28:31], v[218:221], v[182:185], v[28:31]
	v_mfma_f32_16x16x32_bf16 v[20:23], v[210:213], v[190:193], v[20:23]
	v_mfma_f32_16x16x32_bf16 v[12:15], v[218:221], v[190:193], v[12:15]
	v_mfma_f32_16x16x32_bf16 v[4:7], v[210:213], v[202:205], v[4:7]
	v_mfma_f32_16x16x32_bf16 v[0:3], v[218:221], v[202:205], v[0:3]
	s_setprio 0
	s_add_i32 s40, s40, 2
	s_add_u32 s6, s6, 0x100
	s_addc_u32 s7, s7, 0
	s_cmp_lt_u32 s40, 30
	s_cbranch_scc1 .Lrot_9
	s_barrier
	s_waitcnt vmcnt(0)
	s_cmpk_gt_u32 s51, 0xff
	s_cbranch_scc1 .LBB0_1123
	s_barrier

; template <class Epi>
; __device__ __forceinline__ void gemm_phase(LAS unsigned char* lds, const bf16_t* A, int lda, const bf16_t* Bt, int ldb, int M, int N, int K, int asel, const Epi& E, const int fixed_round = -1) {
;     ...
;         const bool has_next = (fixed_round < 0) && S.next(ui + 1, nxt);
;         const char* nA = has_next ? PG8_ABASE(nxt) : cA; const char* nB = has_next ? (const char*)Bt + (size_t)nxt.pn * tstepB : cB;
;     ...
; #pragma unroll
;         for (int a = 0; a < 2; ++a)
; #pragma unroll
;             for (int b = 0; b < 2; ++b)
; #pragma unroll
;                 for (int m = 0; m < 4; ++m)
; #pragma unroll
;                     for (int n = 0; n < 2; ++n) acc[a][b][m][n] = (f32x4){0.f, 0.f, 0.f, 0.f};
;         cur = nxt; cA = nA; cB = nB; ++ui;
.LBB0_1222:
	s_ashr_i32 s29, s28, 31
	v_cmp_lt_i64_e32 vcc, s[40:41], v[140:141]
	s_lshl_b64 s[40:41], s[28:29], 20
	s_add_u32 s40, s38, s40
	s_addc_u32 s41, s39, s41
	s_and_b64 s[42:43], vcc, exec
	s_cselect_b32 s29, s41, s47
	s_cselect_b32 s66, s40, s46
	s_ashr_i32 s25, s24, 31
	s_lshl_b64 s[42:43], s[24:25], 20
	s_add_u32 s42, s52, s42
	s_addc_u32 s43, s53, s43
	s_and_b64 s[50:51], vcc, exec
	s_cselect_b32 s25, s43, s49
	s_cselect_b32 s67, s42, s48
	s_add_u32 s46, s46, 0x80080
	s_addc_u32 s47, s47, 0
	s_add_u32 s68, s48, 0x100
	v_mov_b32_e32 v0, 0
	s_addc_u32 s69, s49, 0
	s_mov_b32 s70, -2
	v_mov_b32_e32 v1, v0
	v_mov_b32_e32 v2, v0
	v_mov_b32_e32 v3, v0
	v_mov_b32_e32 v4, v0
	v_mov_b32_e32 v5, v0
	v_mov_b32_e32 v6, v0
	v_mov_b32_e32 v7, v0
	v_mov_b32_e32 v16, v0
	v_mov_b32_e32 v17, v0
	v_mov_b32_e32 v18, v0
	v_mov_b32_e32 v19, v0
	v_mov_b32_e32 v20, v0
	v_mov_b32_e32 v21, v0
	v_mov_b32_e32 v22, v0
	v_mov_b32_e32 v23, v0
	v_mov_b32_e32 v32, v0
	v_mov_b32_e32 v33, v0
	v_mov_b32_e32 v34, v0
	v_mov_b32_e32 v35, v0
	v_mov_b32_e32 v36, v0
	v_mov_b32_e32 v37, v0
	v_mov_b32_e32 v38, v0
	v_mov_b32_e32 v39, v0
	v_mov_b32_e32 v48, v0
	v_mov_b32_e32 v49, v0
	v_mov_b32_e32 v50, v0
	v_mov_b32_e32 v51, v0
	v_mov_b32_e32 v52, v0
	v_mov_b32_e32 v53, v0
	v_mov_b32_e32 v54, v0
	v_mov_b32_e32 v55, v0
	v_mov_b32_e32 v8, v0
	v_mov_b32_e32 v9, v0
	v_mov_b32_e32 v10, v0
	v_mov_b32_e32 v11, v0
	v_mov_b32_e32 v12, v0
	v_mov_b32_e32 v13, v0
	v_mov_b32_e32 v14, v0
	v_mov_b32_e32 v15, v0
	v_mov_b32_e32 v24, v0
	v_mov_b32_e32 v25, v0
	v_mov_b32_e32 v26, v0
	v_mov_b32_e32 v27, v0
	v_mov_b32_e32 v28, v0
	v_mov_b32_e32 v29, v0
	v_mov_b32_e32 v30, v0
	v_mov_b32_e32 v31, v0
	v_mov_b32_e32 v40, v0
	v_mov_b32_e32 v41, v0
	v_mov_b32_e32 v42, v0
	v_mov_b32_e32 v43, v0
	v_mov_b32_e32 v44, v0
	v_mov_b32_e32 v45, v0
	v_mov_b32_e32 v46, v0
	v_mov_b32_e32 v47, v0
	v_mov_b32_e32 v56, v0
	v_mov_b32_e32 v57, v0
	v_mov_b32_e32 v58, v0
	v_mov_b32_e32 v59, v0
	v_mov_b32_e32 v60, v0
	v_mov_b32_e32 v61, v0
	v_mov_b32_e32 v62, v0
	v_mov_b32_e32 v63, v0
	v_mov_b32_e32 v64, v0
	v_mov_b32_e32 v65, v0
	v_mov_b32_e32 v66, v0
	v_mov_b32_e32 v67, v0
	v_mov_b32_e32 v68, v0
	v_mov_b32_e32 v69, v0
	v_mov_b32_e32 v70, v0
	v_mov_b32_e32 v71, v0
	v_mov_b32_e32 v80, v0
	v_mov_b32_e32 v81, v0
	v_mov_b32_e32 v82, v0
	v_mov_b32_e32 v83, v0
	v_mov_b32_e32 v84, v0
	v_mov_b32_e32 v85, v0
	v_mov_b32_e32 v86, v0
	v_mov_b32_e32 v87, v0
	v_mov_b32_e32 v96, v0
	v_mov_b32_e32 v97, v0
	v_mov_b32_e32 v98, v0
	v_mov_b32_e32 v99, v0
	v_mov_b32_e32 v100, v0
	v_mov_b32_e32 v101, v0
	v_mov_b32_e32 v102, v0
	v_mov_b32_e32 v103, v0
	v_mov_b32_e32 v112, v0
	v_mov_b32_e32 v113, v0
	v_mov_b32_e32 v114, v0
	v_mov_b32_e32 v115, v0
	v_mov_b32_e32 v116, v0
	v_mov_b32_e32 v117, v0
	v_mov_b32_e32 v118, v0
	v_mov_b32_e32 v119, v0
	v_mov_b32_e32 v72, v0
	v_mov_b32_e32 v73, v0
	v_mov_b32_e32 v74, v0
	v_mov_b32_e32 v75, v0
	v_mov_b32_e32 v76, v0
	v_mov_b32_e32 v77, v0
	v_mov_b32_e32 v78, v0
	v_mov_b32_e32 v79, v0
	v_mov_b32_e32 v88, v0
	v_mov_b32_e32 v89, v0
	v_mov_b32_e32 v90, v0
	v_mov_b32_e32 v91, v0
	v_mov_b32_e32 v92, v0
	v_mov_b32_e32 v93, v0
	v_mov_b32_e32 v94, v0
	v_mov_b32_e32 v95, v0
	v_mov_b32_e32 v104, v0
	v_mov_b32_e32 v105, v0
	v_mov_b32_e32 v106, v0
	v_mov_b32_e32 v107, v0
	v_mov_b32_e32 v108, v0
	v_mov_b32_e32 v109, v0
	v_mov_b32_e32 v110, v0
	v_mov_b32_e32 v111, v0
	v_mov_b32_e32 v120, v0
	v_mov_b32_e32 v121, v0
	v_mov_b32_e32 v122, v0
	v_mov_b32_e32 v123, v0
	v_mov_b32_e32 v124, v0
	v_mov_b32_e32 v125, v0
	v_mov_b32_e32 v126, v0
	v_mov_b32_e32 v127, v0
	s_branch .LBB0_1223

; #define PG8_STAGE(bufoff, gbase, voff) do { _Pragma("unroll") for (int _i = 0; _i < 2; ++_i) \
;         __builtin_amdgcn_global_load_lds((const unsigned*)((const char*)(gbase) + (voff)[_i]), (LAS unsigned*)(lds + (bufoff) + ldsw + _i * 8192), 16, 0, 0); } while (0)
; #define PG8_LDA(dst, b, h) do { _Pragma("unroll") for (int m = 0; m < 4; ++m) _Pragma("unroll") for (int k = 0; k < 2; ++k) dst[m][k] = *(const LAS bf16x8*)(lds + PG8_SA(b, h) + aoff + m * 2048 + k * 1024); } while (0)
; #define PG8_LDB(dst, b, h) do { _Pragma("unroll") for (int n = 0; n < 2; ++n) _Pragma("unroll") for (int k = 0; k < 2; ++k) dst[n][k] = *(const LAS bf16x8*)(lds + PG8_SB(b, h) + boff + n * 2048 + k * 1024); } while (0)
; #define PG8_WAIT_V(n) asm volatile("s_waitcnt vmcnt(" #n ")" ::: "memory")
; #define PG8_WAIT_L(n) asm volatile("s_waitcnt lgkmcnt(" #n ")" ::: "memory")
; #define PG8_BAR __builtin_amdgcn_s_barrier()
; #define PG8_SCHED __builtin_amdgcn_sched_barrier(0)
; template <class Epi>
; __device__ __forceinline__ void gemm_phase(LAS unsigned char* lds, const bf16_t* A, int lda, const bf16_t* Bt, int ldb, int M, int N, int K, int asel, const Epi& E, const int fixed_round = -1) {
;     ...
;             const bool last = (t == nt - 2);
;             const char* a1 = cA + (size_t)(t + 1) * kstep;
;             const char* a2 = last ? nA : cA + (size_t)(t + 2) * kstep; const char* b2 = last ? nB : cB + (size_t)(t + 2) * kstep;
;             const char* a3 = a2 + kstep; const char* b3 = b2 + kstep;
;             PG8_LDB(B0, 0, 0); PG8_SCHED; PG8_LDA(At, 0, 0); PG8_STAGE(PG8_SA(1, 1), a1 + hstepA, voffA);
;             PG8_WAIT_L(8); PG8_BAR; PG8_WAIT_L(0); PG8_MMA(0, 0, At, B0); PG8_BAR; PG8_SCHED;
;             PG8_LDB(B1, 0, 1); PG8_STAGE(PG8_SB(0, 0), b2, voffB);
;             PG8_BAR; PG8_WAIT_L(0); PG8_MMA(0, 1, At, B1); PG8_BAR;
;             PG8_LDA(At, 0, 1); PG8_STAGE(PG8_SA(0, 0), a2, voffA);
;             PG8_BAR; PG8_WAIT_L(0); PG8_MMA(1, 0, At, B0); PG8_BAR; PG8_SCHED;
;             PG8_STAGE(PG8_SB(0, 1), b2 + hstepB, voffB);
;             PG8_WAIT_V(6); PG8_BAR; PG8_MMA(1, 1, At, B1); PG8_BAR;
.LBB0_1223:
	ds_read_b128 v[152:155], v149
	ds_read_b128 v[156:159], v149 offset:1024
	ds_read_b128 v[160:163], v149 offset:2048
	ds_read_b128 v[164:167], v149 offset:3072
	s_add_u32 s48, s46, 0xfff80080
	s_addc_u32 s49, s47, -1
	s_cmp_eq_u32 s70, 28
	s_cselect_b32 s51, s29, s49
	s_cselect_b32 s50, s66, s48
	s_cselect_b32 s49, s25, s69
	s_cselect_b32 s48, s67, s68
	s_add_i32 m0, s45, 0xc000
	ds_read_b128 v[168:171], v150
	ds_read_b128 v[172:175], v150 offset:1024
	ds_read_b128 v[176:179], v150 offset:2048
	ds_read_b128 v[180:183], v150 offset:3072
	ds_read_b128 v[184:187], v150 offset:4096
	ds_read_b128 v[188:191], v150 offset:5120
	ds_read_b128 v[192:195], v150 offset:6144
	ds_read_b128 v[196:199], v150 offset:7168
	global_load_lds_dwordx4 v136, s[46:47]
	s_add_i32 m0, s45, 0xe000
	s_nop 0
	global_load_lds_dwordx4 v138, s[46:47]
	s_waitcnt lgkmcnt(8)
	s_barrier
	s_waitcnt lgkmcnt(0)
	s_setprio 1
	s_waitcnt lgkmcnt(0)
	v_mfma_f32_16x16x32_bf16 v[124:127], v[152:155], v[168:171], v[124:127]
	v_mfma_f32_16x16x32_bf16 v[120:123], v[160:163], v[168:171], v[120:123]
	v_mfma_f32_16x16x32_bf16 v[108:111], v[152:155], v[176:179], v[108:111]
	v_mfma_f32_16x16x32_bf16 v[104:107], v[160:163], v[176:179], v[104:107]
	v_mfma_f32_16x16x32_bf16 v[92:95], v[152:155], v[184:187], v[92:95]
	v_mfma_f32_16x16x32_bf16 v[88:91], v[160:163], v[184:187], v[88:91]
	v_mfma_f32_16x16x32_bf16 v[76:79], v[152:155], v[192:195], v[76:79]
	v_mfma_f32_16x16x32_bf16 v[72:75], v[160:163], v[192:195], v[72:75]
	v_mfma_f32_16x16x32_bf16 v[124:127], v[156:159], v[172:175], v[124:127]
	v_mfma_f32_16x16x32_bf16 v[120:123], v[164:167], v[172:175], v[120:123]
	v_mfma_f32_16x16x32_bf16 v[108:111], v[156:159], v[180:183], v[108:111]
	v_mfma_f32_16x16x32_bf16 v[104:107], v[164:167], v[180:183], v[104:107]
	v_mfma_f32_16x16x32_bf16 v[92:95], v[156:159], v[188:191], v[92:95]
	v_mfma_f32_16x16x32_bf16 v[88:91], v[164:167], v[188:191], v[88:91]
	v_mfma_f32_16x16x32_bf16 v[76:79], v[156:159], v[196:199], v[76:79]
	v_mfma_f32_16x16x32_bf16 v[72:75], v[164:167], v[196:199], v[72:75]
	s_setprio 0
	s_barrier
	s_add_i32 s71, s81, s54
	s_add_u32 s98, s48, s2
	s_addc_u32 s99, s49, s3
	s_mov_b32 m0, s71
	ds_read_b128 v[202:205], v151
	ds_read_b128 v[206:209], v151 offset:1024
	ds_read_b128 v[210:213], v151 offset:2048
	ds_read_b128 v[214:217], v151 offset:3072
	global_load_lds_dwordx4 v130, s[48:49]
	s_add_i32 m0, s71, 0x2000
	s_nop 0
	global_load_lds_dwordx4 v134, s[48:49]
	s_barrier
	s_waitcnt lgkmcnt(0)
	s_setprio 1
	s_waitcnt lgkmcnt(0)
	v_mfma_f32_16x16x32_bf16 v[116:119], v[202:205], v[168:171], v[116:119]
	v_mfma_f32_16x16x32_bf16 v[112:115], v[210:213], v[168:171], v[112:115]
	v_mfma_f32_16x16x32_bf16 v[100:103], v[202:205], v[176:179], v[100:103]
	v_mfma_f32_16x16x32_bf16 v[96:99], v[210:213], v[176:179], v[96:99]
	v_mfma_f32_16x16x32_bf16 v[84:87], v[202:205], v[184:187], v[84:87]
	v_mfma_f32_16x16x32_bf16 v[80:83], v[210:213], v[184:187], v[80:83]
	v_mfma_f32_16x16x32_bf16 v[68:71], v[202:205], v[192:195], v[68:71]
	v_mfma_f32_16x16x32_bf16 v[64:67], v[210:213], v[192:195], v[64:67]
	v_mfma_f32_16x16x32_bf16 v[116:119], v[206:209], v[172:175], v[116:119]
	v_mfma_f32_16x16x32_bf16 v[112:115], v[214:217], v[172:175], v[112:115]
	v_mfma_f32_16x16x32_bf16 v[100:103], v[206:209], v[180:183], v[100:103]
	v_mfma_f32_16x16x32_bf16 v[96:99], v[214:217], v[180:183], v[96:99]
	v_mfma_f32_16x16x32_bf16 v[84:87], v[206:209], v[188:191], v[84:87]
	v_mfma_f32_16x16x32_bf16 v[80:83], v[214:217], v[188:191], v[80:83]
	v_mfma_f32_16x16x32_bf16 v[68:71], v[206:209], v[196:199], v[68:71]
	v_mfma_f32_16x16x32_bf16 v[64:67], v[214:217], v[196:199], v[64:67]
	s_setprio 0
	s_mov_b32 m0, s45
	s_add_u32 s100, s50, s2
	s_addc_u32 s101, s51, s3
	s_barrier
	ds_read_b128 v[168:171], v150 offset:16384
	ds_read_b128 v[172:175], v150 offset:17408
	ds_read_b128 v[176:179], v150 offset:18432
	ds_read_b128 v[180:183], v150 offset:19456
	ds_read_b128 v[184:187], v150 offset:20480
	ds_read_b128 v[188:191], v150 offset:21504
	ds_read_b128 v[192:195], v150 offset:22528
	ds_read_b128 v[196:199], v150 offset:23552
	global_load_lds_dwordx4 v128, s[50:51]
	s_mov_b32 m0, s55
	s_nop 0
	global_load_lds_dwordx4 v132, s[50:51]
	s_barrier
	s_waitcnt lgkmcnt(0)
	s_setprio 1
	s_waitcnt lgkmcnt(0)
	v_mfma_f32_16x16x32_bf16 v[60:63], v[152:155], v[168:171], v[60:63]
	v_mfma_f32_16x16x32_bf16 v[56:59], v[160:163], v[168:171], v[56:59]
	v_mfma_f32_16x16x32_bf16 v[44:47], v[152:155], v[176:179], v[44:47]
	v_mfma_f32_16x16x32_bf16 v[40:43], v[160:163], v[176:179], v[40:43]
	v_mfma_f32_16x16x32_bf16 v[28:31], v[152:155], v[184:187], v[28:31]
	v_mfma_f32_16x16x32_bf16 v[24:27], v[160:163], v[184:187], v[24:27]
	v_mfma_f32_16x16x32_bf16 v[12:15], v[152:155], v[192:195], v[12:15]
	v_mfma_f32_16x16x32_bf16 v[8:11], v[160:163], v[192:195], v[8:11]
	v_mfma_f32_16x16x32_bf16 v[60:63], v[156:159], v[172:175], v[60:63]
	v_mfma_f32_16x16x32_bf16 v[56:59], v[164:167], v[172:175], v[56:59]
	v_mfma_f32_16x16x32_bf16 v[44:47], v[156:159], v[180:183], v[44:47]
	v_mfma_f32_16x16x32_bf16 v[40:43], v[164:167], v[180:183], v[40:43]
	v_mfma_f32_16x16x32_bf16 v[28:31], v[156:159], v[188:191], v[28:31]
	v_mfma_f32_16x16x32_bf16 v[24:27], v[164:167], v[188:191], v[24:27]
	v_mfma_f32_16x16x32_bf16 v[12:15], v[156:159], v[196:199], v[12:15]
	v_mfma_f32_16x16x32_bf16 v[8:11], v[164:167], v[196:199], v[8:11]
	s_setprio 0
	s_barrier
	s_add_u32 s72, s48, 0x80000
	s_addc_u32 s73, s49, 0
	s_add_i32 s71, s82, s54
	s_mov_b32 m0, s71
	s_nop 0
	global_load_lds_dwordx4 v130, s[72:73]
	s_add_i32 m0, s71, 0x2000
	s_nop 0
	global_load_lds_dwordx4 v134, s[72:73]
	s_waitcnt vmcnt(6)
	s_barrier
; #define PG8_STAGE(bufoff, gbase, voff) do { _Pragma("unroll") for (int _i = 0; _i < 2; ++_i) \
;         __builtin_amdgcn_global_load_lds((const unsigned*)((const char*)(gbase) + (voff)[_i]), (LAS unsigned*)(lds + (bufoff) + ldsw + _i * 8192), 16, 0, 0); } while (0)
; #define PG8_LDA(dst, b, h) do { _Pragma("unroll") for (int m = 0; m < 4; ++m) _Pragma("unroll") for (int k = 0; k < 2; ++k) dst[m][k] = *(const LAS bf16x8*)(lds + PG8_SA(b, h) + aoff + m * 2048 + k * 1024); } while (0)
; #define PG8_LDB(dst, b, h) do { _Pragma("unroll") for (int n = 0; n < 2; ++n) _Pragma("unroll") for (int k = 0; k < 2; ++k) dst[n][k] = *(const LAS bf16x8*)(lds + PG8_SB(b, h) + boff + n * 2048 + k * 1024); } while (0)
; #define PG8_WAIT_V(n) asm volatile("s_waitcnt vmcnt(" #n ")" ::: "memory")
; #define PG8_WAIT_L(n) asm volatile("s_waitcnt lgkmcnt(" #n ")" ::: "memory")
; #define PG8_BAR __builtin_amdgcn_s_barrier()
; #define PG8_SCHED __builtin_amdgcn_sched_barrier(0)
; template <class Epi>
; __device__ __forceinline__ void gemm_phase(LAS unsigned char* lds, const bf16_t* A, int lda, const bf16_t* Bt, int ldb, int M, int N, int K, int asel, const Epi& E, const int fixed_round = -1) {
;     ...
;             PG8_WAIT_V(6); PG8_BAR; PG8_MMA(1, 1, At, B1); PG8_BAR;
;             PG8_LDB(B0, 1, 0); PG8_SCHED; PG8_LDA(At, 1, 0); PG8_STAGE(PG8_SA(0, 1), a2 + hstepA, voffA);
;             PG8_WAIT_L(8); PG8_BAR; PG8_WAIT_L(0); PG8_MMA(0, 0, At, B0); PG8_BAR; PG8_SCHED;
;             PG8_LDB(B1, 1, 1); PG8_STAGE(PG8_SB(1, 0), b3, voffB);
;             PG8_BAR; PG8_WAIT_L(0); PG8_MMA(0, 1, At, B1); PG8_BAR;
;             PG8_LDA(At, 1, 1); PG8_STAGE(PG8_SA(1, 0), a3, voffA);
	s_setprio 1
	v_mfma_f32_16x16x32_bf16 v[52:55], v[202:205], v[168:171], v[52:55]
	v_mfma_f32_16x16x32_bf16 v[48:51], v[210:213], v[168:171], v[48:51]
	v_mfma_f32_16x16x32_bf16 v[36:39], v[202:205], v[176:179], v[36:39]
	v_mfma_f32_16x16x32_bf16 v[32:35], v[210:213], v[176:179], v[32:35]
	v_mfma_f32_16x16x32_bf16 v[20:23], v[202:205], v[184:187], v[20:23]
	v_mfma_f32_16x16x32_bf16 v[16:19], v[210:213], v[184:187], v[16:19]
	v_mfma_f32_16x16x32_bf16 v[4:7], v[202:205], v[192:195], v[4:7]
	v_mfma_f32_16x16x32_bf16 v[0:3], v[210:213], v[192:195], v[0:3]
	v_mfma_f32_16x16x32_bf16 v[52:55], v[206:209], v[172:175], v[52:55]
	v_mfma_f32_16x16x32_bf16 v[48:51], v[214:217], v[172:175], v[48:51]
	v_mfma_f32_16x16x32_bf16 v[36:39], v[206:209], v[180:183], v[36:39]
	v_mfma_f32_16x16x32_bf16 v[32:35], v[214:217], v[180:183], v[32:35]
	v_mfma_f32_16x16x32_bf16 v[20:23], v[206:209], v[188:191], v[20:23]
	v_mfma_f32_16x16x32_bf16 v[16:19], v[214:217], v[188:191], v[16:19]
	v_mfma_f32_16x16x32_bf16 v[4:7], v[206:209], v[196:199], v[4:7]
	v_mfma_f32_16x16x32_bf16 v[0:3], v[214:217], v[196:199], v[0:3]
	s_setprio 0
	v_add_u32_e32 v164, s83, v147
	s_barrier
	ds_read_b128 v[152:155], v164
	ds_read_b128 v[156:159], v164 offset:1024
	ds_read_b128 v[160:163], v164 offset:2048
	ds_read_b128 v[164:167], v164 offset:3072
	s_add_u32 s50, s50, 0x80000
	s_addc_u32 s51, s51, 0
	s_mov_b32 m0, s56
	ds_read_b128 v[168:171], v150 offset:32768
	ds_read_b128 v[172:175], v150 offset:33792
	ds_read_b128 v[176:179], v150 offset:34816
	ds_read_b128 v[180:183], v150 offset:35840
	ds_read_b128 v[184:187], v150 offset:36864
	ds_read_b128 v[188:191], v150 offset:37888
	ds_read_b128 v[192:195], v150 offset:38912
	ds_read_b128 v[196:199], v150 offset:39936
	global_load_lds_dwordx4 v128, s[50:51]
	s_mov_b32 m0, s57
	s_nop 0
	global_load_lds_dwordx4 v132, s[50:51]
	s_waitcnt lgkmcnt(8)
	s_barrier
	s_waitcnt lgkmcnt(0)
	s_setprio 1
	s_waitcnt lgkmcnt(0)
	v_mfma_f32_16x16x32_bf16 v[124:127], v[152:155], v[168:171], v[124:127]
	v_mfma_f32_16x16x32_bf16 v[120:123], v[160:163], v[168:171], v[120:123]
	v_mfma_f32_16x16x32_bf16 v[108:111], v[152:155], v[176:179], v[108:111]
	v_mfma_f32_16x16x32_bf16 v[104:107], v[160:163], v[176:179], v[104:107]
	v_mfma_f32_16x16x32_bf16 v[92:95], v[152:155], v[184:187], v[92:95]
	v_mfma_f32_16x16x32_bf16 v[88:91], v[160:163], v[184:187], v[88:91]
	v_mfma_f32_16x16x32_bf16 v[76:79], v[152:155], v[192:195], v[76:79]
	v_mfma_f32_16x16x32_bf16 v[72:75], v[160:163], v[192:195], v[72:75]
	v_mfma_f32_16x16x32_bf16 v[124:127], v[156:159], v[172:175], v[124:127]
	v_mfma_f32_16x16x32_bf16 v[120:123], v[164:167], v[172:175], v[120:123]
	v_mfma_f32_16x16x32_bf16 v[108:111], v[156:159], v[180:183], v[108:111]
	v_mfma_f32_16x16x32_bf16 v[104:107], v[164:167], v[180:183], v[104:107]
	v_mfma_f32_16x16x32_bf16 v[92:95], v[156:159], v[188:191], v[92:95]
	v_mfma_f32_16x16x32_bf16 v[88:91], v[164:167], v[188:191], v[88:91]
	v_mfma_f32_16x16x32_bf16 v[76:79], v[156:159], v[196:199], v[76:79]
	v_mfma_f32_16x16x32_bf16 v[72:75], v[164:167], v[196:199], v[72:75]
	s_setprio 0
	s_barrier
	s_add_i32 s50, s83, s54
	v_add_u32_e32 v214, s84, v147
	s_mov_b32 m0, s50
	ds_read_b128 v[202:205], v214
	ds_read_b128 v[206:209], v214 offset:1024
	ds_read_b128 v[210:213], v214 offset:2048
	ds_read_b128 v[214:217], v214 offset:3072
	global_load_lds_dwordx4 v130, s[98:99]
	s_add_i32 m0, s50, 0x2000
	s_nop 0
	global_load_lds_dwordx4 v134, s[98:99]
	s_barrier
	s_waitcnt lgkmcnt(0)
	s_setprio 1
	s_waitcnt lgkmcnt(0)
	v_mfma_f32_16x16x32_bf16 v[116:119], v[202:205], v[168:171], v[116:119]
	v_mfma_f32_16x16x32_bf16 v[112:115], v[210:213], v[168:171], v[112:115]
	v_mfma_f32_16x16x32_bf16 v[100:103], v[202:205], v[176:179], v[100:103]
	v_mfma_f32_16x16x32_bf16 v[96:99], v[210:213], v[176:179], v[96:99]
	v_mfma_f32_16x16x32_bf16 v[84:87], v[202:205], v[184:187], v[84:87]
	v_mfma_f32_16x16x32_bf16 v[80:83], v[210:213], v[184:187], v[80:83]
	v_mfma_f32_16x16x32_bf16 v[68:71], v[202:205], v[192:195], v[68:71]
	v_mfma_f32_16x16x32_bf16 v[64:67], v[210:213], v[192:195], v[64:67]
	v_mfma_f32_16x16x32_bf16 v[116:119], v[206:209], v[172:175], v[116:119]
	v_mfma_f32_16x16x32_bf16 v[112:115], v[214:217], v[172:175], v[112:115]
	v_mfma_f32_16x16x32_bf16 v[100:103], v[206:209], v[180:183], v[100:103]
	v_mfma_f32_16x16x32_bf16 v[96:99], v[214:217], v[180:183], v[96:99]
	v_mfma_f32_16x16x32_bf16 v[84:87], v[206:209], v[188:191], v[84:87]
	v_mfma_f32_16x16x32_bf16 v[80:83], v[214:217], v[188:191], v[80:83]
	v_mfma_f32_16x16x32_bf16 v[68:71], v[206:209], v[196:199], v[68:71]
	v_mfma_f32_16x16x32_bf16 v[64:67], v[214:217], v[196:199], v[64:67]
	s_setprio 0
	s_mov_b32 m0, s59
	s_barrier
	ds_read_b128 v[168:171], v150 offset:49152
	ds_read_b128 v[172:175], v150 offset:50176
	ds_read_b128 v[176:179], v150 offset:51200
	ds_read_b128 v[180:183], v150 offset:52224
	ds_read_b128 v[184:187], v150 offset:53248
	ds_read_b128 v[188:191], v150 offset:54272
	ds_read_b128 v[192:195], v150 offset:55296
	ds_read_b128 v[196:199], v150 offset:56320
	global_load_lds_dwordx4 v128, s[100:101]
	s_mov_b32 m0, s60
	s_nop 0
	global_load_lds_dwordx4 v132, s[100:101]
	s_barrier
; __device__ __forceinline__ unsigned cvt_pk_bf16(float lo, float hi) { const bf16x2_t r = __builtin_convertvector((f32x2){lo, hi}, bf16x2_t); return __builtin_bit_cast(unsigned, r); }
; #define PG8_STAGE(bufoff, gbase, voff) do { _Pragma("unroll") for (int _i = 0; _i < 2; ++_i) \
;         __builtin_amdgcn_global_load_lds((const unsigned*)((const char*)(gbase) + (voff)[_i]), (LAS unsigned*)(lds + (bufoff) + ldsw + _i * 8192), 16, 0, 0); } while (0)
; #define PG8_WAIT_V(n) asm volatile("s_waitcnt vmcnt(" #n ")" ::: "memory")
; #define PG8_WAIT_L(n) asm volatile("s_waitcnt lgkmcnt(" #n ")" ::: "memory")
; #define PG8_BAR __builtin_amdgcn_s_barrier()
; #define PG8_SCHED __builtin_amdgcn_sched_barrier(0)
; template <class Epi>
; __device__ __forceinline__ void gemm_phase(LAS unsigned char* lds, const bf16_t* A, int lda, const bf16_t* Bt, int ldb, int M, int N, int K, int asel, const Epi& E, const int fixed_round = -1) {
;     ...
;             PG8_BAR; PG8_WAIT_L(0); PG8_MMA(1, 0, At, B0); PG8_BAR; PG8_SCHED;
;             PG8_STAGE(PG8_SB(1, 1), b3 + hstepB, voffB);
;             PG8_WAIT_V(6); PG8_BAR; PG8_MMA(1, 1, At, B1); PG8_BAR;
;     __device__ __forceinline__ void operator()(const AccT& acc, const Unit& u, int wr, int wc, int fr, int fq) const {
;         const int row0 = u.pm * BM + wr * 64 + fr, col0 = u.pn * BM + wc * 32 + 8 * fq;
; #pragma unroll
;         for (int ai = 0; ai < 2; ++ai)
; #pragma unroll
;             for (int m = 0; m < 4; ++m) { bf16_t* rowp = O + (size_t)(row0 + ai * HALF + m * 16) * DFF + col0;
; #pragma unroll
;                 for (int bj = 0; bj < 2; ++bj) { f32x4 v0 = acc[ai][bj][m][0], v1 = acc[ai][bj][m][1];
; #pragma unroll
;                     for (int j = 0; j < 4; ++j) { float a = fmaxf(v0[j], 0.f), b = fmaxf(v1[j], 0.f); v0[j] = a * a; v1[j] = b * b; }
;                     u32x4 w; w.x = cvt_pk_bf16(v0[0], v0[1]); w.y = cvt_pk_bf16(v0[2], v0[3]); w.z = cvt_pk_bf16(v1[0], v1[1]); w.w = cvt_pk_bf16(v1[2], v1[3]);
;                     *(u32x4*)(rowp + bj * HALF) = w; } }
	s_waitcnt lgkmcnt(0)
	s_setprio 1
	s_waitcnt lgkmcnt(0)
	v_mfma_f32_16x16x32_bf16 v[60:63], v[152:155], v[168:171], v[60:63]
	v_mfma_f32_16x16x32_bf16 v[56:59], v[160:163], v[168:171], v[56:59]
	v_mfma_f32_16x16x32_bf16 v[44:47], v[152:155], v[176:179], v[44:47]
	v_mfma_f32_16x16x32_bf16 v[40:43], v[160:163], v[176:179], v[40:43]
	v_mfma_f32_16x16x32_bf16 v[28:31], v[152:155], v[184:187], v[28:31]
	v_mfma_f32_16x16x32_bf16 v[24:27], v[160:163], v[184:187], v[24:27]
	v_mfma_f32_16x16x32_bf16 v[12:15], v[152:155], v[192:195], v[12:15]
	v_mfma_f32_16x16x32_bf16 v[8:11], v[160:163], v[192:195], v[8:11]
	v_mfma_f32_16x16x32_bf16 v[60:63], v[156:159], v[172:175], v[60:63]
	v_mfma_f32_16x16x32_bf16 v[56:59], v[164:167], v[172:175], v[56:59]
	v_mfma_f32_16x16x32_bf16 v[44:47], v[156:159], v[180:183], v[44:47]
	v_mfma_f32_16x16x32_bf16 v[40:43], v[164:167], v[180:183], v[40:43]
	v_mfma_f32_16x16x32_bf16 v[28:31], v[156:159], v[188:191], v[28:31]
	v_mfma_f32_16x16x32_bf16 v[24:27], v[164:167], v[188:191], v[24:27]
	v_mfma_f32_16x16x32_bf16 v[12:15], v[156:159], v[196:199], v[12:15]
	v_mfma_f32_16x16x32_bf16 v[8:11], v[164:167], v[196:199], v[8:11]
	s_setprio 0
	s_barrier
	s_add_u32 s48, s48, 0x80080
	s_addc_u32 s49, s49, 0
	s_add_i32 s50, s84, s54
	s_mov_b32 m0, s50
	s_nop 0
	global_load_lds_dwordx4 v130, s[48:49]
	s_add_i32 m0, s50, 0x2000
	s_nop 0
	global_load_lds_dwordx4 v134, s[48:49]
	s_waitcnt vmcnt(6)
	s_barrier
	s_setprio 1
	v_mfma_f32_16x16x32_bf16 v[52:55], v[202:205], v[168:171], v[52:55]
	v_mfma_f32_16x16x32_bf16 v[48:51], v[210:213], v[168:171], v[48:51]
	v_mfma_f32_16x16x32_bf16 v[36:39], v[202:205], v[176:179], v[36:39]
	v_mfma_f32_16x16x32_bf16 v[32:35], v[210:213], v[176:179], v[32:35]
	v_mfma_f32_16x16x32_bf16 v[20:23], v[202:205], v[184:187], v[20:23]
	v_mfma_f32_16x16x32_bf16 v[16:19], v[210:213], v[184:187], v[16:19]
	v_mfma_f32_16x16x32_bf16 v[4:7], v[202:205], v[192:195], v[4:7]
	v_mfma_f32_16x16x32_bf16 v[0:3], v[210:213], v[192:195], v[0:3]
	v_mfma_f32_16x16x32_bf16 v[52:55], v[206:209], v[172:175], v[52:55]
	v_mfma_f32_16x16x32_bf16 v[48:51], v[214:217], v[172:175], v[48:51]
	v_mfma_f32_16x16x32_bf16 v[36:39], v[206:209], v[180:183], v[36:39]
	v_mfma_f32_16x16x32_bf16 v[32:35], v[214:217], v[180:183], v[32:35]
	v_mfma_f32_16x16x32_bf16 v[20:23], v[206:209], v[188:191], v[20:23]
	v_mfma_f32_16x16x32_bf16 v[16:19], v[214:217], v[188:191], v[16:19]
	v_mfma_f32_16x16x32_bf16 v[4:7], v[206:209], v[196:199], v[4:7]
	v_mfma_f32_16x16x32_bf16 v[0:3], v[214:217], v[196:199], v[0:3]
	s_setprio 0
	s_add_i32 s70, s70, 2
	s_add_u32 s46, s46, 0x100
	s_addc_u32 s47, s47, 0
	s_add_u32 s68, s68, 0x100
	s_addc_u32 s69, s69, 0
	s_cmp_gt_u32 s70, 29
	s_cbranch_scc0 .Lrot_10
	s_barrier
	v_lshl_add_u32 v152, s44, 8, v146
	v_lshl_or_b32 v144, s65, 8, v148
	v_ashrrev_i32_e32 v153, 31, v152
	v_readlane_b32 s46, v254, 60
	v_ashrrev_i32_e32 v145, 31, v144
	v_lshlrev_b64 v[154:155], 14, v[152:153]
	v_readlane_b32 s47, v254, 61
	v_lshl_add_u64 v[154:155], s[46:47], 0, v[154:155]
	v_lshlrev_b64 v[156:157], 1, v[144:145]
	v_max_f32_e32 v120, 0, v120
	v_max_f32_e32 v121, 0, v121
	v_lshl_add_u64 v[144:145], v[154:155], 0, v[156:157]
	v_pk_mul_f32 v[154:155], v[120:121], v[120:121]
	v_max_f32_e32 v121, v122, v122
	v_max_f32_e32 v120, v126, v126
	v_max_f32_e32 v122, 0, v121
	v_max_f32_e32 v121, v127, v127
	v_max_f32_e32 v124, 0, v124
	v_max_f32_e32 v125, 0, v125
	v_max_f32_e32 v120, 0, v120
	v_max_f32_e32 v121, 0, v121
	v_max_f32_e32 v123, 0, v123
	v_pk_mul_f32 v[124:125], v[124:125], v[124:125]
	v_pk_mul_f32 v[126:127], v[120:121], v[120:121]
	v_pk_mul_f32 v[158:159], v[122:123], v[122:123]
	v_cvt_pk_bf16_f32 v120, v124, v125
	v_cvt_pk_bf16_f32 v121, v126, v127
	v_cvt_pk_bf16_f32 v122, v154, v155
	v_cvt_pk_bf16_f32 v123, v158, v159
	v_max_f32_e32 v112, 0, v112
	v_max_f32_e32 v113, 0, v113
	global_store_dwordx4 v[144:145], v[120:123], off
	s_nop 1
	v_pk_mul_f32 v[120:121], v[112:113], v[112:113]
	v_max_f32_e32 v113, v114, v114
	v_max_f32_e32 v112, v118, v118
	v_max_f32_e32 v114, 0, v113
	v_max_f32_e32 v113, v119, v119
	v_max_f32_e32 v116, 0, v116
	v_max_f32_e32 v117, 0, v117
	v_max_f32_e32 v112, 0, v112
	v_max_f32_e32 v113, 0, v113
	v_max_f32_e32 v115, 0, v115
	v_pk_mul_f32 v[116:117], v[116:117], v[116:117]
	v_pk_mul_f32 v[118:119], v[112:113], v[112:113]
	v_pk_mul_f32 v[122:123], v[114:115], v[114:115]
	v_cvt_pk_bf16_f32 v112, v116, v117
	v_cvt_pk_bf16_f32 v113, v118, v119
	v_cvt_pk_bf16_f32 v114, v120, v121
	v_cvt_pk_bf16_f32 v115, v122, v123
	v_max_f32_e32 v104, 0, v104
	v_max_f32_e32 v105, 0, v105
	global_store_dwordx4 v[144:145], v[112:115], off offset:256
	s_nop 1
	v_or_b32_e32 v112, 16, v152
	v_pk_mul_f32 v[114:115], v[104:105], v[104:105]
	v_max_f32_e32 v105, v106, v106
	v_ashrrev_i32_e32 v113, 31, v112
	v_max_f32_e32 v104, v110, v110
	v_max_f32_e32 v106, 0, v105
	v_max_f32_e32 v105, v111, v111
	v_lshlrev_b64 v[112:113], 14, v[112:113]
	v_max_f32_e32 v108, 0, v108
	v_max_f32_e32 v109, 0, v109
	v_max_f32_e32 v104, 0, v104
	v_max_f32_e32 v105, 0, v105
	v_max_f32_e32 v107, 0, v107
	v_lshl_add_u64 v[112:113], s[46:47], 0, v[112:113]
	v_pk_mul_f32 v[108:109], v[108:109], v[108:109]
	v_pk_mul_f32 v[110:111], v[104:105], v[104:105]
	v_pk_mul_f32 v[116:117], v[106:107], v[106:107]
	v_lshl_add_u64 v[112:113], v[112:113], 0, v[156:157]
	v_cvt_pk_bf16_f32 v104, v108, v109
	v_cvt_pk_bf16_f32 v105, v110, v111
	v_cvt_pk_bf16_f32 v106, v114, v115
	v_cvt_pk_bf16_f32 v107, v116, v117
	v_max_f32_e32 v96, 0, v96
	v_max_f32_e32 v97, 0, v97
	global_store_dwordx4 v[112:113], v[104:107], off
	s_nop 1
	v_pk_mul_f32 v[104:105], v[96:97], v[96:97]
	v_max_f32_e32 v97, v98, v98
; __device__ __forceinline__ unsigned cvt_pk_bf16(float lo, float hi) { const bf16x2_t r = __builtin_convertvector((f32x2){lo, hi}, bf16x2_t); return __builtin_bit_cast(unsigned, r); }
;     __device__ __forceinline__ void operator()(const AccT& acc, const Unit& u, int wr, int wc, int fr, int fq) const {
;         const int row0 = u.pm * BM + wr * 64 + fr, col0 = u.pn * BM + wc * 32 + 8 * fq;
; #pragma unroll
;         for (int ai = 0; ai < 2; ++ai)
; #pragma unroll
;             for (int m = 0; m < 4; ++m) { bf16_t* rowp = O + (size_t)(row0 + ai * HALF + m * 16) * DFF + col0;
; #pragma unroll
;                 for (int bj = 0; bj < 2; ++bj) { f32x4 v0 = acc[ai][bj][m][0], v1 = acc[ai][bj][m][1];
; #pragma unroll
;                     for (int j = 0; j < 4; ++j) { float a = fmaxf(v0[j], 0.f), b = fmaxf(v1[j], 0.f); v0[j] = a * a; v1[j] = b * b; }
;                     u32x4 w; w.x = cvt_pk_bf16(v0[0], v0[1]); w.y = cvt_pk_bf16(v0[2], v0[3]); w.z = cvt_pk_bf16(v1[0], v1[1]); w.w = cvt_pk_bf16(v1[2], v1[3]);
;                     *(u32x4*)(rowp + bj * HALF) = w; } }
	v_max_f32_e32 v96, v102, v102
	v_max_f32_e32 v98, 0, v97
	v_max_f32_e32 v97, v103, v103
	v_max_f32_e32 v100, 0, v100
	v_max_f32_e32 v101, 0, v101
	v_max_f32_e32 v96, 0, v96
	v_max_f32_e32 v97, 0, v97
	v_max_f32_e32 v99, 0, v99
	v_pk_mul_f32 v[100:101], v[100:101], v[100:101]
	v_pk_mul_f32 v[102:103], v[96:97], v[96:97]
	v_pk_mul_f32 v[106:107], v[98:99], v[98:99]
	v_cvt_pk_bf16_f32 v96, v100, v101
	v_cvt_pk_bf16_f32 v97, v102, v103
	v_cvt_pk_bf16_f32 v98, v104, v105
	v_cvt_pk_bf16_f32 v99, v106, v107
	v_max_f32_e32 v88, 0, v88
	v_max_f32_e32 v89, 0, v89
	global_store_dwordx4 v[112:113], v[96:99], off offset:256
	s_nop 1
	v_or_b32_e32 v96, 32, v152
	v_pk_mul_f32 v[98:99], v[88:89], v[88:89]
	v_max_f32_e32 v89, v90, v90
	v_ashrrev_i32_e32 v97, 31, v96
	v_max_f32_e32 v88, v94, v94
	v_max_f32_e32 v90, 0, v89
	v_max_f32_e32 v89, v95, v95
	v_lshlrev_b64 v[96:97], 14, v[96:97]
	v_max_f32_e32 v92, 0, v92
	v_max_f32_e32 v93, 0, v93
	v_max_f32_e32 v88, 0, v88
	v_max_f32_e32 v89, 0, v89
	v_max_f32_e32 v91, 0, v91
	v_lshl_add_u64 v[96:97], s[46:47], 0, v[96:97]
	v_pk_mul_f32 v[92:93], v[92:93], v[92:93]
	v_pk_mul_f32 v[94:95], v[88:89], v[88:89]
	v_pk_mul_f32 v[100:101], v[90:91], v[90:91]
	v_lshl_add_u64 v[96:97], v[96:97], 0, v[156:157]
	v_cvt_pk_bf16_f32 v88, v92, v93
	v_cvt_pk_bf16_f32 v89, v94, v95
	v_cvt_pk_bf16_f32 v90, v98, v99
	v_cvt_pk_bf16_f32 v91, v100, v101
	v_max_f32_e32 v80, 0, v80
	v_max_f32_e32 v81, 0, v81
	global_store_dwordx4 v[96:97], v[88:91], off
	s_nop 1
	v_pk_mul_f32 v[88:89], v[80:81], v[80:81]
	v_max_f32_e32 v81, v82, v82
	v_max_f32_e32 v80, v86, v86
	v_max_f32_e32 v82, 0, v81
	v_max_f32_e32 v81, v87, v87
	v_max_f32_e32 v84, 0, v84
	v_max_f32_e32 v85, 0, v85
	v_max_f32_e32 v80, 0, v80
	v_max_f32_e32 v81, 0, v81
	v_max_f32_e32 v83, 0, v83
	v_pk_mul_f32 v[84:85], v[84:85], v[84:85]
	v_pk_mul_f32 v[86:87], v[80:81], v[80:81]
	v_pk_mul_f32 v[90:91], v[82:83], v[82:83]
	v_cvt_pk_bf16_f32 v80, v84, v85
	v_cvt_pk_bf16_f32 v81, v86, v87
	v_cvt_pk_bf16_f32 v82, v88, v89
	v_cvt_pk_bf16_f32 v83, v90, v91
	v_max_f32_e32 v72, 0, v72
	v_max_f32_e32 v73, 0, v73
	global_store_dwordx4 v[96:97], v[80:83], off offset:256
	s_nop 1
	v_or_b32_e32 v80, 48, v152
	v_pk_mul_f32 v[82:83], v[72:73], v[72:73]
	v_max_f32_e32 v73, v74, v74
	v_ashrrev_i32_e32 v81, 31, v80
	v_max_f32_e32 v72, v78, v78
	v_max_f32_e32 v74, 0, v73
	v_max_f32_e32 v73, v79, v79
	v_lshlrev_b64 v[80:81], 14, v[80:81]
	v_max_f32_e32 v76, 0, v76
	v_max_f32_e32 v77, 0, v77
	v_max_f32_e32 v72, 0, v72
	v_max_f32_e32 v73, 0, v73
	v_max_f32_e32 v75, 0, v75
	v_lshl_add_u64 v[80:81], s[46:47], 0, v[80:81]
	v_pk_mul_f32 v[76:77], v[76:77], v[76:77]
	v_pk_mul_f32 v[78:79], v[72:73], v[72:73]
	v_pk_mul_f32 v[84:85], v[74:75], v[74:75]
	v_lshl_add_u64 v[80:81], v[80:81], 0, v[156:157]
	v_cvt_pk_bf16_f32 v72, v76, v77
	v_cvt_pk_bf16_f32 v73, v78, v79
	v_cvt_pk_bf16_f32 v74, v82, v83
	v_cvt_pk_bf16_f32 v75, v84, v85
	v_max_f32_e32 v64, 0, v64
	v_max_f32_e32 v65, 0, v65
	global_store_dwordx4 v[80:81], v[72:75], off
	s_nop 1
	v_pk_mul_f32 v[72:73], v[64:65], v[64:65]
	v_max_f32_e32 v65, v66, v66
	v_max_f32_e32 v64, v70, v70
	v_max_f32_e32 v66, 0, v65
	v_max_f32_e32 v65, v71, v71
	v_max_f32_e32 v68, 0, v68
	v_max_f32_e32 v69, 0, v69
	v_max_f32_e32 v64, 0, v64
	v_max_f32_e32 v65, 0, v65
	v_max_f32_e32 v67, 0, v67
	v_pk_mul_f32 v[68:69], v[68:69], v[68:69]
	v_pk_mul_f32 v[70:71], v[64:65], v[64:65]
	v_pk_mul_f32 v[74:75], v[66:67], v[66:67]
	v_cvt_pk_bf16_f32 v64, v68, v69
	v_cvt_pk_bf16_f32 v65, v70, v71
	v_cvt_pk_bf16_f32 v66, v72, v73
	v_cvt_pk_bf16_f32 v67, v74, v75
	v_max_f32_e32 v56, 0, v56
	v_max_f32_e32 v57, 0, v57
	global_store_dwordx4 v[80:81], v[64:67], off offset:256
	s_nop 1
	v_pk_mul_f32 v[66:67], v[56:57], v[56:57]
	v_max_f32_e32 v57, v58, v58
	v_max_f32_e32 v60, 0, v60
	v_max_f32_e32 v61, 0, v61
	v_max_f32_e32 v56, v62, v62
	v_max_f32_e32 v58, 0, v57
	v_max_f32_e32 v57, v63, v63
	v_pk_mul_f32 v[60:61], v[60:61], v[60:61]
	v_max_f32_e32 v56, 0, v56
	v_max_f32_e32 v57, 0, v57
	v_max_f32_e32 v59, 0, v59
	v_pk_mul_f32 v[62:63], v[56:57], v[56:57]
	v_pk_mul_f32 v[68:69], v[58:59], v[58:59]
	v_cvt_pk_bf16_f32 v56, v60, v61
	v_add_co_u32_e32 v60, vcc, s61, v144
	v_cvt_pk_bf16_f32 v57, v62, v63
	v_cvt_pk_bf16_f32 v58, v66, v67
	v_cvt_pk_bf16_f32 v59, v68, v69
	v_addc_co_u32_e32 v61, vcc, 0, v145, vcc
	v_max_f32_e32 v48, 0, v48
	v_max_f32_e32 v49, 0, v49
	global_store_dwordx4 v[60:61], v[56:59], off
	s_nop 1
	v_pk_mul_f32 v[56:57], v[48:49], v[48:49]
	v_max_f32_e32 v49, v50, v50
	v_max_f32_e32 v48, v54, v54
	v_max_f32_e32 v50, 0, v49
	v_max_f32_e32 v49, v55, v55
	v_max_f32_e32 v52, 0, v52
	v_max_f32_e32 v53, 0, v53
	v_max_f32_e32 v48, 0, v48
	v_max_f32_e32 v49, 0, v49
	v_max_f32_e32 v51, 0, v51
	s_mov_b64 s[46:47], 0x200000
	v_pk_mul_f32 v[52:53], v[52:53], v[52:53]
	v_pk_mul_f32 v[54:55], v[48:49], v[48:49]
; __device__ __forceinline__ unsigned cvt_pk_bf16(float lo, float hi) { const bf16x2_t r = __builtin_convertvector((f32x2){lo, hi}, bf16x2_t); return __builtin_bit_cast(unsigned, r); }
; #define PG8_WAIT_V(n) asm volatile("s_waitcnt vmcnt(" #n ")" ::: "memory")
; #define PG8_BAR __builtin_amdgcn_s_barrier()
; template <class Epi>
; __device__ __forceinline__ void gemm_phase(LAS unsigned char* lds, const bf16_t* A, int lda, const bf16_t* Bt, int ldb, int M, int N, int K, int asel, const Epi& E, const int fixed_round = -1) {
;     ...
;         if (!has_next) break;
; #pragma unroll
;         for (int a = 0; a < 2; ++a)
; #pragma unroll
;             for (int b = 0; b < 2; ++b)
; #pragma unroll
;                 for (int m = 0; m < 4; ++m)
; #pragma unroll
;                     for (int n = 0; n < 2; ++n) acc[a][b][m][n] = (f32x4){0.f, 0.f, 0.f, 0.f};
;         cur = nxt; cA = nA; cB = nB; ++ui;
;     }
;     PG8_WAIT_V(0);
;     if (wr == 0) PG8_BAR;
;     PG8_BAR;
;     __device__ __forceinline__ void operator()(const AccT& acc, const Unit& u, int wr, int wc, int fr, int fq) const {
;         const int row0 = u.pm * BM + wr * 64 + fr, col0 = u.pn * BM + wc * 32 + 8 * fq;
; #pragma unroll
;         for (int ai = 0; ai < 2; ++ai)
; #pragma unroll
;             for (int m = 0; m < 4; ++m) { bf16_t* rowp = O + (size_t)(row0 + ai * HALF + m * 16) * DFF + col0;
; #pragma unroll
;                 for (int bj = 0; bj < 2; ++bj) { f32x4 v0 = acc[ai][bj][m][0], v1 = acc[ai][bj][m][1];
; #pragma unroll
;                     for (int j = 0; j < 4; ++j) { float a = fmaxf(v0[j], 0.f), b = fmaxf(v1[j], 0.f); v0[j] = a * a; v1[j] = b * b; }
;                     u32x4 w; w.x = cvt_pk_bf16(v0[0], v0[1]); w.y = cvt_pk_bf16(v0[2], v0[3]); w.z = cvt_pk_bf16(v1[0], v1[1]); w.w = cvt_pk_bf16(v1[2], v1[3]);
;                     *(u32x4*)(rowp + bj * HALF) = w; } }
	v_pk_mul_f32 v[58:59], v[50:51], v[50:51]
	v_lshl_add_u64 v[64:65], v[144:145], 0, s[46:47]
	v_cvt_pk_bf16_f32 v48, v52, v53
	v_cvt_pk_bf16_f32 v49, v54, v55
	v_cvt_pk_bf16_f32 v50, v56, v57
	v_cvt_pk_bf16_f32 v51, v58, v59
	v_max_f32_e32 v40, 0, v40
	v_max_f32_e32 v41, 0, v41
	global_store_dwordx4 v[64:65], v[48:51], off offset:256
	s_nop 1
	v_pk_mul_f32 v[50:51], v[40:41], v[40:41]
	v_max_f32_e32 v41, v42, v42
	v_max_f32_e32 v44, 0, v44
	v_max_f32_e32 v45, 0, v45
	v_max_f32_e32 v40, v46, v46
	v_max_f32_e32 v42, 0, v41
	v_max_f32_e32 v41, v47, v47
	v_pk_mul_f32 v[44:45], v[44:45], v[44:45]
	v_max_f32_e32 v40, 0, v40
	v_max_f32_e32 v41, 0, v41
	v_max_f32_e32 v43, 0, v43
	v_pk_mul_f32 v[46:47], v[40:41], v[40:41]
	v_pk_mul_f32 v[52:53], v[42:43], v[42:43]
	v_cvt_pk_bf16_f32 v40, v44, v45
	v_add_co_u32_e32 v44, vcc, s62, v144
	v_cvt_pk_bf16_f32 v41, v46, v47
	v_cvt_pk_bf16_f32 v42, v50, v51
	v_cvt_pk_bf16_f32 v43, v52, v53
	v_addc_co_u32_e32 v45, vcc, 0, v145, vcc
	v_max_f32_e32 v32, 0, v32
	v_max_f32_e32 v33, 0, v33
	global_store_dwordx4 v[44:45], v[40:43], off
	s_nop 1
	v_pk_mul_f32 v[40:41], v[32:33], v[32:33]
	v_max_f32_e32 v33, v34, v34
	v_max_f32_e32 v32, v38, v38
	v_max_f32_e32 v34, 0, v33
	v_max_f32_e32 v33, v39, v39
	v_max_f32_e32 v36, 0, v36
	v_max_f32_e32 v37, 0, v37
	v_max_f32_e32 v32, 0, v32
	v_max_f32_e32 v33, 0, v33
	v_max_f32_e32 v35, 0, v35
	v_pk_mul_f32 v[36:37], v[36:37], v[36:37]
	v_pk_mul_f32 v[38:39], v[32:33], v[32:33]
	v_pk_mul_f32 v[42:43], v[34:35], v[34:35]
	v_lshl_add_u64 v[48:49], v[144:145], 0, s[4:5]
	v_cvt_pk_bf16_f32 v32, v36, v37
	v_cvt_pk_bf16_f32 v33, v38, v39
	v_cvt_pk_bf16_f32 v34, v40, v41
	v_cvt_pk_bf16_f32 v35, v42, v43
	v_max_f32_e32 v24, 0, v24
	v_max_f32_e32 v25, 0, v25
	global_store_dwordx4 v[48:49], v[32:35], off offset:256
	s_nop 1
	v_pk_mul_f32 v[34:35], v[24:25], v[24:25]
	v_max_f32_e32 v25, v26, v26
	v_max_f32_e32 v28, 0, v28
	v_max_f32_e32 v29, 0, v29
	v_max_f32_e32 v24, v30, v30
	v_max_f32_e32 v26, 0, v25
	v_max_f32_e32 v25, v31, v31
	v_pk_mul_f32 v[28:29], v[28:29], v[28:29]
	v_max_f32_e32 v24, 0, v24
	v_max_f32_e32 v25, 0, v25
	v_max_f32_e32 v27, 0, v27
	v_pk_mul_f32 v[30:31], v[24:25], v[24:25]
	v_pk_mul_f32 v[36:37], v[26:27], v[26:27]
	v_cvt_pk_bf16_f32 v24, v28, v29
	v_add_co_u32_e32 v28, vcc, s63, v144
	v_cvt_pk_bf16_f32 v25, v30, v31
	v_cvt_pk_bf16_f32 v26, v34, v35
	v_cvt_pk_bf16_f32 v27, v36, v37
	v_addc_co_u32_e32 v29, vcc, 0, v145, vcc
	v_max_f32_e32 v16, 0, v16
	v_max_f32_e32 v17, 0, v17
	global_store_dwordx4 v[28:29], v[24:27], off
	s_nop 1
	v_pk_mul_f32 v[24:25], v[16:17], v[16:17]
	v_max_f32_e32 v17, v18, v18
	v_max_f32_e32 v16, v22, v22
	v_max_f32_e32 v18, 0, v17
	v_max_f32_e32 v17, v23, v23
	v_max_f32_e32 v20, 0, v20
	v_max_f32_e32 v21, 0, v21
	v_max_f32_e32 v16, 0, v16
	v_max_f32_e32 v17, 0, v17
	v_max_f32_e32 v19, 0, v19
	v_pk_mul_f32 v[20:21], v[20:21], v[20:21]
	v_pk_mul_f32 v[22:23], v[16:17], v[16:17]
	v_pk_mul_f32 v[26:27], v[18:19], v[18:19]
	v_lshl_add_u64 v[32:33], v[144:145], 0, s[6:7]
	v_cvt_pk_bf16_f32 v16, v20, v21
	v_cvt_pk_bf16_f32 v17, v22, v23
	v_cvt_pk_bf16_f32 v18, v24, v25
	v_cvt_pk_bf16_f32 v19, v26, v27
	v_max_f32_e32 v8, 0, v8
	v_max_f32_e32 v9, 0, v9
	global_store_dwordx4 v[32:33], v[16:19], off offset:256
	s_nop 1
	v_pk_mul_f32 v[18:19], v[8:9], v[8:9]
	v_max_f32_e32 v9, v10, v10
	v_max_f32_e32 v12, 0, v12
	v_max_f32_e32 v13, 0, v13
	v_max_f32_e32 v8, v14, v14
	v_max_f32_e32 v10, 0, v9
	v_max_f32_e32 v9, v15, v15
	v_pk_mul_f32 v[12:13], v[12:13], v[12:13]
	v_max_f32_e32 v8, 0, v8
	v_max_f32_e32 v9, 0, v9
	v_max_f32_e32 v11, 0, v11
	v_pk_mul_f32 v[14:15], v[8:9], v[8:9]
	v_pk_mul_f32 v[20:21], v[10:11], v[10:11]
	v_cvt_pk_bf16_f32 v8, v12, v13
	v_add_co_u32_e32 v12, vcc, s64, v144
	v_cvt_pk_bf16_f32 v9, v14, v15
	v_cvt_pk_bf16_f32 v10, v18, v19
	v_cvt_pk_bf16_f32 v11, v20, v21
	v_addc_co_u32_e32 v13, vcc, 0, v145, vcc
	v_max_f32_e32 v0, 0, v0
	v_max_f32_e32 v1, 0, v1
	global_store_dwordx4 v[12:13], v[8:11], off
	s_nop 1
	v_pk_mul_f32 v[8:9], v[0:1], v[0:1]
	v_max_f32_e32 v1, v2, v2
	v_max_f32_e32 v0, v6, v6
	v_max_f32_e32 v2, 0, v1
	v_max_f32_e32 v1, v7, v7
	v_max_f32_e32 v4, 0, v4
	v_max_f32_e32 v5, 0, v5
	v_max_f32_e32 v0, 0, v0
	v_max_f32_e32 v1, 0, v1
	v_max_f32_e32 v3, 0, v3
	v_pk_mul_f32 v[4:5], v[4:5], v[4:5]
	v_pk_mul_f32 v[6:7], v[0:1], v[0:1]
	v_pk_mul_f32 v[10:11], v[2:3], v[2:3]
	v_lshl_add_u64 v[16:17], v[144:145], 0, s[22:23]
	v_cvt_pk_bf16_f32 v0, v4, v5
	v_cvt_pk_bf16_f32 v1, v6, v7
	v_cvt_pk_bf16_f32 v2, v8, v9
	v_cvt_pk_bf16_f32 v3, v10, v11
	s_and_b64 vcc, exec, s[0:1]
	s_mov_b32 s65, s24
	s_mov_b32 s44, s28
	s_mov_b64 s[48:49], s[42:43]
	s_mov_b64 s[46:47], s[40:41]
	s_mov_b64 s[70:71], s[26:27]
	global_store_dwordx4 v[16:17], v[0:3], off offset:256
	s_cbranch_vccz .LBB0_1216
	s_waitcnt vmcnt(0)
	s_cmpk_gt_u32 s33, 0xff
	s_cbranch_scc1 .LBB0_1227
	s_barrier

; #define PG8_STAGE(bufoff, gbase, voff) do { _Pragma("unroll") for (int _i = 0; _i < 2; ++_i) \
;         __builtin_amdgcn_global_load_lds((const unsigned*)((const char*)(gbase) + (voff)[_i]), (LAS unsigned*)(lds + (bufoff) + ldsw + _i * 8192), 16, 0, 0); } while (0)
; #define PG8_WAIT_V(n) asm volatile("s_waitcnt vmcnt(" #n ")" ::: "memory")
; #define PG8_BAR __builtin_amdgcn_s_barrier()
; template <class Epi>
; __device__ __forceinline__ void gemm_phase(LAS unsigned char* lds, const bf16_t* A, int lda, const bf16_t* Bt, int ldb, int M, int N, int K, int asel, const Epi& E, const int fixed_round = -1) {
;     ...
;     StaticOrder S; S.init(M, N, gridDim.x, blockIdx.x);
;     unsigned voffA[2], voffB[2];
; #pragma unroll
;     for (int i = 0; i < 2; ++i) { int R, C; stage_rc(tid * 16 + i * 8192, R, C); const int Rb = Epi::PERM ? ((R & ~31) + perm32(R & 31)) : R;
;         voffA[i] = (unsigned)(R * lda + C) * 2u; voffB[i] = (unsigned)(Rb * ldb + C) * 2u; }
;     const size_t kstep = (size_t)(BK * 2);
;     const size_t hstepA = (size_t)HALF * lda * 2, hstepB = (size_t)HALF * ldb * 2;
;     const size_t tstepA = 2 * hstepA, tstepB = 2 * hstepB;
;     const unsigned ldsw = (unsigned)wid * 1024u;
;     const int aoff = lds_byte(wr * 64 + fr, fq * 8), boff = lds_byte(wc * 32 + fr, fq * 8);
;     ...
;     Unit cur, nxt; int ui = 0;
;     if (fixed_round < 0) { if (!S.next(0, cur)) return; }
;     else { const int c = blockIdx.x; cur.pm = 32 * fixed_round + 4 * (c & 7) + (c >> 6); cur.pn = (c >> 3) & 7; }
;     f32x4 acc[2][2][4][2];
; #pragma unroll
;     for (int a = 0; a < 2; ++a)
; #pragma unroll
;         for (int b = 0; b < 2; ++b)
; #pragma unroll
;             for (int m = 0; m < 4; ++m)
; #pragma unroll
;                 for (int n = 0; n < 2; ++n) acc[a][b][m][n] = (f32x4){0.f, 0.f, 0.f, 0.f};
;     bf16x8 At[4][2], B0[2][2], B1[2][2];
;     const char* cA = PG8_ABASE(cur); const char* cB = (const char*)Bt + (size_t)cur.pn * tstepB;
;     PG8_STAGE(PG8_SB(0, 0), cB, voffB); PG8_STAGE(PG8_SA(0, 0), cA, voffA); PG8_STAGE(PG8_SB(0, 1), cB + hstepB, voffB); PG8_STAGE(PG8_SA(0, 1), cA + hstepA, voffA);
;     if (wr == 1) PG8_BAR;
;     PG8_WAIT_V(4); PG8_BAR;
;     PG8_STAGE(PG8_SB(1, 0), cB + kstep, voffB); PG8_STAGE(PG8_SA(1, 0), cA + kstep, voffA); PG8_STAGE(PG8_SB(1, 1), cB + hstepB + kstep, voffB);
;     PG8_WAIT_V(6); PG8_BAR;
.LBB0_1282:
	v_bfe_u32 v221, v13, 4, 2
	v_and_b32_e32 v223, 15, v13
	v_lshlrev_b32_e32 v15, 4, v221
	v_lshlrev_b32_e32 v13, 2, v13
	s_and_b32 s31, s0, 3
	v_lshl_or_b32 v15, v223, 6, v15
	s_lshl_b32 s0, s1, 13
	v_and_b32_e32 v13, 32, v13
	v_bitop3_b32 v16, v15, s0, v13 bitop3:0xde
	s_lshl_b32 s0, s31, 12
	s_lshl_b32 s30, s1, 6
	v_bitop3_b32 v13, v15, s0, v13 bitop3:0xde
	s_mov_b64 s[0:1], 0x80
	s_add_i32 m0, s40, 0x18000
	v_lshl_add_u64 v[6:7], v[6:7], 0, s[0:1]
	s_waitcnt vmcnt(4)
	s_barrier
	global_load_lds_dwordx4 v[6:7], off
	v_lshl_add_u64 v[4:5], v[4:5], 0, s[0:1]
	s_add_i32 m0, s40, 0x1a000
	s_add_i32 s44, s40, 0x8000
	s_add_i32 s45, s40, 0xa000
	global_load_lds_dwordx4 v[4:5], off
	v_lshl_add_u64 v[2:3], v[2:3], 0, s[0:1]
	s_mov_b32 m0, s44
	s_add_u32 s6, s2, 0x200080
	global_load_lds_dwordx4 v[2:3], off
	v_lshl_add_u64 v[0:1], v[0:1], 0, s[0:1]
	s_mov_b32 m0, s45
	s_addc_u32 s7, s3, 0
	global_load_lds_dwordx4 v[0:1], off
	s_add_i32 m0, s40, 0x1c000
	v_lshl_add_u64 v[0:1], s[6:7], 0, v[114:115]
	global_load_lds_dwordx4 v[0:1], off
	v_lshl_add_u64 v[0:1], s[6:7], 0, v[118:119]
	s_add_i32 m0, s40, 0x1e000
	v_readlane_b32 s12, v255, 26
	global_load_lds_dwordx4 v[0:1], off
	v_lshlrev_b32_e32 v0, 17, v8
	v_and_b32_e32 v0, 0xfffc0000, v0
	v_lshl_add_u32 v0, v9, 14, v0
	v_and_b32_e32 v1, 1, v8
	v_readlane_b32 s13, v255, 27
	s_add_u32 s16, s78, s12
	v_lshl_or_b32 v0, v1, 6, v0
	s_addc_u32 s17, s79, s13
	v_lshl_add_u32 v0, v10, 1, v0
	v_mov_b32_e32 v1, v115
	v_lshl_add_u64 v[0:1], s[16:17], 0, v[0:1]
	s_mov_b64 s[22:23], 0x18700080
	v_lshl_add_u64 v[120:121], v[0:1], 0, s[22:23]
	v_lshlrev_b32_e32 v0, 17, v11
	v_and_b32_e32 v0, 0xfffc0000, v0
	v_lshl_add_u32 v0, v12, 14, v0
	v_and_b32_e32 v1, 1, v11
	v_lshl_or_b32 v0, v1, 6, v0
	v_lshl_add_u32 v0, v14, 1, v0
	v_mov_b32_e32 v1, v115
	v_lshl_add_u64 v[0:1], s[16:17], 0, v[0:1]
	v_lshl_add_u64 v[122:123], v[0:1], 0, s[22:23]
	s_add_u32 s22, s78, s8
	s_addc_u32 s23, s79, 0
	s_waitcnt vmcnt(6)
	s_add_u32 s28, s22, 0xa500100
	s_addc_u32 s29, s23, 0
	s_add_i32 s49, s81, s24
	s_add_i32 s51, s82, s24
	s_add_i32 s53, s83, s24
	s_add_i32 s55, s84, s24
	v_or_b32_e32 v203, s30, v223
	s_mov_b32 s46, -2
	s_mov_b64 s[22:23], 0
	v_add_u32_e32 v124, s81, v13
	v_add_u32_e32 v125, 0, v16
	s_add_i32 s47, s40, 0xc000
	s_add_i32 s48, s40, 0xe000
	v_add_u32_e32 v126, s82, v13
	s_add_i32 s50, s49, 0x2000
	s_add_i32 s52, s51, 0x2000
	v_add_u32_e32 v127, s83, v13
	v_add_u32_e32 v144, s84, v13
	s_add_i32 s54, s53, 0x2000
	s_add_i32 s56, s55, 0x2000
	v_mov_b32_e32 v0, v115
	v_mov_b32_e32 v1, v115
	v_mov_b32_e32 v2, v115
	v_mov_b32_e32 v3, v115
	v_mov_b32_e32 v4, v115
	v_mov_b32_e32 v5, v115
	v_mov_b32_e32 v6, v115
	v_mov_b32_e32 v7, v115
	v_mov_b32_e32 v16, v115
	v_mov_b32_e32 v17, v115
	v_mov_b32_e32 v18, v115
	v_mov_b32_e32 v19, v115
	v_mov_b32_e32 v20, v115
	v_mov_b32_e32 v21, v115
	v_mov_b32_e32 v22, v115
	v_mov_b32_e32 v23, v115
	v_mov_b32_e32 v32, v115
	v_mov_b32_e32 v33, v115
	v_mov_b32_e32 v34, v115
	v_mov_b32_e32 v35, v115
	v_mov_b32_e32 v36, v115
	v_mov_b32_e32 v37, v115
	v_mov_b32_e32 v38, v115
	v_mov_b32_e32 v39, v115
	v_mov_b32_e32 v48, v115
	v_mov_b32_e32 v49, v115
	v_mov_b32_e32 v50, v115
	v_mov_b32_e32 v51, v115
	v_mov_b32_e32 v52, v115
	v_mov_b32_e32 v53, v115
	v_mov_b32_e32 v54, v115
	v_mov_b32_e32 v55, v115
	v_mov_b32_e32 v8, v115
	v_mov_b32_e32 v9, v115
	v_mov_b32_e32 v10, v115
	v_mov_b32_e32 v11, v115
	v_mov_b32_e32 v12, v115
	v_mov_b32_e32 v13, v115
	v_mov_b32_e32 v14, v115
	v_mov_b32_e32 v15, v115
	v_mov_b32_e32 v24, v115
	v_mov_b32_e32 v25, v115
	v_mov_b32_e32 v26, v115
	v_mov_b32_e32 v27, v115
	v_mov_b32_e32 v28, v115
	v_mov_b32_e32 v29, v115
	v_mov_b32_e32 v30, v115
	v_mov_b32_e32 v31, v115
	v_mov_b32_e32 v40, v115
	v_mov_b32_e32 v41, v115
	v_mov_b32_e32 v42, v115
	v_mov_b32_e32 v43, v115
	v_mov_b32_e32 v44, v115
	v_mov_b32_e32 v45, v115
	v_mov_b32_e32 v46, v115
	v_mov_b32_e32 v47, v115
	v_mov_b32_e32 v56, v115
	v_mov_b32_e32 v57, v115
	v_mov_b32_e32 v58, v115
	v_mov_b32_e32 v59, v115
	v_mov_b32_e32 v60, v115
	v_mov_b32_e32 v61, v115
	v_mov_b32_e32 v62, v115
	v_mov_b32_e32 v63, v115
	v_mov_b32_e32 v64, v115
	v_mov_b32_e32 v65, v115
	v_mov_b32_e32 v66, v115
	v_mov_b32_e32 v67, v115
	v_mov_b32_e32 v68, v115
	v_mov_b32_e32 v69, v115
	v_mov_b32_e32 v70, v115
	v_mov_b32_e32 v71, v115
	v_mov_b32_e32 v80, v115
	v_mov_b32_e32 v81, v115
	v_mov_b32_e32 v82, v115
	v_mov_b32_e32 v83, v115
	v_mov_b32_e32 v84, v115
	v_mov_b32_e32 v85, v115
	v_mov_b32_e32 v86, v115
	v_mov_b32_e32 v87, v115
	v_mov_b32_e32 v96, v115
	v_mov_b32_e32 v97, v115
	v_mov_b32_e32 v98, v115
	v_mov_b32_e32 v99, v115
	v_mov_b32_e32 v100, v115
	v_mov_b32_e32 v101, v115
	v_mov_b32_e32 v102, v115
	v_mov_b32_e32 v103, v115
	v_mov_b32_e32 v128, v115
	v_mov_b32_e32 v129, v115
	v_mov_b32_e32 v130, v115
	v_mov_b32_e32 v131, v115
	v_mov_b32_e32 v132, v115
	v_mov_b32_e32 v133, v115
	v_mov_b32_e32 v134, v115
	v_mov_b32_e32 v135, v115
	v_mov_b32_e32 v72, v115
	v_mov_b32_e32 v73, v115
	v_mov_b32_e32 v74, v115
	v_mov_b32_e32 v75, v115
	v_mov_b32_e32 v76, v115
	v_mov_b32_e32 v77, v115
	v_mov_b32_e32 v78, v115
	v_mov_b32_e32 v79, v115
	v_mov_b32_e32 v88, v115
	v_mov_b32_e32 v89, v115
	v_mov_b32_e32 v90, v115
	v_mov_b32_e32 v91, v115
	v_mov_b32_e32 v92, v115
	v_mov_b32_e32 v93, v115
	v_mov_b32_e32 v94, v115
	v_mov_b32_e32 v95, v115
	v_mov_b32_e32 v104, v115
	v_mov_b32_e32 v105, v115
	v_mov_b32_e32 v106, v115
	v_mov_b32_e32 v107, v115
	v_mov_b32_e32 v108, v115
	v_mov_b32_e32 v109, v115
	v_mov_b32_e32 v110, v115
	v_mov_b32_e32 v111, v115
	v_mov_b32_e32 v136, v115
	v_mov_b32_e32 v137, v115
	v_mov_b32_e32 v138, v115
	v_mov_b32_e32 v139, v115
	v_mov_b32_e32 v140, v115
	v_mov_b32_e32 v141, v115
	v_mov_b32_e32 v142, v115
	v_mov_b32_e32 v143, v115
; #define PG8_STAGE(bufoff, gbase, voff) do { _Pragma("unroll") for (int _i = 0; _i < 2; ++_i) \
;         __builtin_amdgcn_global_load_lds((const unsigned*)((const char*)(gbase) + (voff)[_i]), (LAS unsigned*)(lds + (bufoff) + ldsw + _i * 8192), 16, 0, 0); } while (0)
; #define PG8_LDA(dst, b, h) do { _Pragma("unroll") for (int m = 0; m < 4; ++m) _Pragma("unroll") for (int k = 0; k < 2; ++k) dst[m][k] = *(const LAS bf16x8*)(lds + PG8_SA(b, h) + aoff + m * 2048 + k * 1024); } while (0)
; #define PG8_LDB(dst, b, h) do { _Pragma("unroll") for (int n = 0; n < 2; ++n) _Pragma("unroll") for (int k = 0; k < 2; ++k) dst[n][k] = *(const LAS bf16x8*)(lds + PG8_SB(b, h) + boff + n * 2048 + k * 1024); } while (0)
; #define PG8_WAIT_L(n) asm volatile("s_waitcnt lgkmcnt(" #n ")" ::: "memory")
; #define PG8_BAR __builtin_amdgcn_s_barrier()
; #define PG8_SCHED __builtin_amdgcn_sched_barrier(0)
; template <class Epi>
; __device__ __forceinline__ void gemm_phase(LAS unsigned char* lds, const bf16_t* A, int lda, const bf16_t* Bt, int ldb, int M, int N, int K, int asel, const Epi& E, const int fixed_round = -1) {
;     ...
;             const bool last = (t == nt - 2);
;             const char* a1 = cA + (size_t)(t + 1) * kstep;
;             const char* a2 = last ? nA : cA + (size_t)(t + 2) * kstep; const char* b2 = last ? nB : cB + (size_t)(t + 2) * kstep;
;             const char* a3 = a2 + kstep; const char* b3 = b2 + kstep;
;             PG8_LDB(B0, 0, 0); PG8_SCHED; PG8_LDA(At, 0, 0); PG8_STAGE(PG8_SA(1, 1), a1 + hstepA, voffA);
;             PG8_WAIT_L(8); PG8_BAR; PG8_WAIT_L(0); PG8_MMA(0, 0, At, B0); PG8_BAR; PG8_SCHED;
;             PG8_LDB(B1, 0, 1); PG8_STAGE(PG8_SB(0, 0), b2, voffB);
;             PG8_BAR; PG8_WAIT_L(0); PG8_MMA(0, 1, At, B1); PG8_BAR;
;             PG8_LDA(At, 0, 1); PG8_STAGE(PG8_SA(0, 0), a2, voffA);
;             PG8_BAR; PG8_WAIT_L(0); PG8_MMA(1, 0, At, B0); PG8_BAR; PG8_SCHED;
.Lrot_11:
	s_barrier
.LBB0_1283:
	s_add_u32 s24, s16, s22
	ds_read_b128 v[146:149], v124
	ds_read_b128 v[150:153], v124 offset:1024
	ds_read_b128 v[154:157], v124 offset:2048
	ds_read_b128 v[158:161], v124 offset:3072
	s_addc_u32 s25, s17, s23
	s_add_u32 s24, s24, 0x18500100
	s_addc_u32 s25, s25, 0
	s_add_u32 s57, s28, s22
	s_addc_u32 s58, s29, s23
	s_cmpk_eq_i32 s22, 0x3f00
	s_cselect_b32 s27, s87, s25
	s_cselect_b32 s26, s86, s24
	s_cselect_b32 s25, s3, s58
	s_cselect_b32 s24, s2, s57
	s_mov_b32 m0, s47
	v_lshl_add_u64 v[194:195], v[120:121], 0, s[22:23]
	ds_read_b128 v[162:165], v125
	ds_read_b128 v[166:169], v125 offset:1024
	ds_read_b128 v[170:173], v125 offset:2048
	ds_read_b128 v[174:177], v125 offset:3072
	ds_read_b128 v[178:181], v125 offset:4096
	ds_read_b128 v[182:185], v125 offset:5120
	ds_read_b128 v[186:189], v125 offset:6144
	ds_read_b128 v[190:193], v125 offset:7168
	global_load_lds_dwordx4 v[194:195], off
	v_lshl_add_u64 v[194:195], v[122:123], 0, s[22:23]
	s_mov_b32 m0, s48
	s_nop 0
	global_load_lds_dwordx4 v[194:195], off
	s_waitcnt lgkmcnt(8)
	s_barrier
	s_waitcnt lgkmcnt(0)
	s_setprio 1
	s_waitcnt lgkmcnt(0)
	v_mfma_f32_16x16x32_bf16 v[140:143], v[146:149], v[162:165], v[140:143]
	v_mfma_f32_16x16x32_bf16 v[136:139], v[154:157], v[162:165], v[136:139]
	v_mfma_f32_16x16x32_bf16 v[108:111], v[146:149], v[170:173], v[108:111]
	v_mfma_f32_16x16x32_bf16 v[104:107], v[154:157], v[170:173], v[104:107]
	v_mfma_f32_16x16x32_bf16 v[92:95], v[146:149], v[178:181], v[92:95]
	v_mfma_f32_16x16x32_bf16 v[88:91], v[154:157], v[178:181], v[88:91]
	v_mfma_f32_16x16x32_bf16 v[76:79], v[146:149], v[186:189], v[76:79]
	v_mfma_f32_16x16x32_bf16 v[72:75], v[154:157], v[186:189], v[72:75]
	v_mfma_f32_16x16x32_bf16 v[140:143], v[150:153], v[166:169], v[140:143]
	v_mfma_f32_16x16x32_bf16 v[136:139], v[158:161], v[166:169], v[136:139]
	v_mfma_f32_16x16x32_bf16 v[108:111], v[150:153], v[174:177], v[108:111]
	v_mfma_f32_16x16x32_bf16 v[104:107], v[158:161], v[174:177], v[104:107]
	v_mfma_f32_16x16x32_bf16 v[92:95], v[150:153], v[182:185], v[92:95]
	v_mfma_f32_16x16x32_bf16 v[88:91], v[158:161], v[182:185], v[88:91]
	v_mfma_f32_16x16x32_bf16 v[76:79], v[150:153], v[190:193], v[76:79]
	v_mfma_f32_16x16x32_bf16 v[72:75], v[158:161], v[190:193], v[72:75]
	s_setprio 0
	s_barrier
	s_mov_b32 m0, s49
	s_add_u32 s98, s24, s0
	s_addc_u32 s99, s25, s1
	ds_read_b128 v[194:197], v126
	ds_read_b128 v[204:207], v126 offset:1024
	ds_read_b128 v[208:211], v126 offset:2048
	ds_read_b128 v[212:215], v126 offset:3072
	global_load_lds_dwordx4 v114, s[24:25]
	s_mov_b32 m0, s50
	s_nop 0
	global_load_lds_dwordx4 v118, s[24:25]
	s_barrier
	s_waitcnt lgkmcnt(0)
	s_setprio 1
	s_waitcnt lgkmcnt(0)
	v_mfma_f32_16x16x32_bf16 v[132:135], v[194:197], v[162:165], v[132:135]
	v_mfma_f32_16x16x32_bf16 v[128:131], v[208:211], v[162:165], v[128:131]
	v_mfma_f32_16x16x32_bf16 v[100:103], v[194:197], v[170:173], v[100:103]
	v_mfma_f32_16x16x32_bf16 v[96:99], v[208:211], v[170:173], v[96:99]
	v_mfma_f32_16x16x32_bf16 v[84:87], v[194:197], v[178:181], v[84:87]
	v_mfma_f32_16x16x32_bf16 v[80:83], v[208:211], v[178:181], v[80:83]
	v_mfma_f32_16x16x32_bf16 v[68:71], v[194:197], v[186:189], v[68:71]
	v_mfma_f32_16x16x32_bf16 v[64:67], v[208:211], v[186:189], v[64:67]
	v_mfma_f32_16x16x32_bf16 v[132:135], v[204:207], v[166:169], v[132:135]
	v_mfma_f32_16x16x32_bf16 v[128:131], v[212:215], v[166:169], v[128:131]
	v_mfma_f32_16x16x32_bf16 v[100:103], v[204:207], v[174:177], v[100:103]
	v_mfma_f32_16x16x32_bf16 v[96:99], v[212:215], v[174:177], v[96:99]
	v_mfma_f32_16x16x32_bf16 v[84:87], v[204:207], v[182:185], v[84:87]
	v_mfma_f32_16x16x32_bf16 v[80:83], v[212:215], v[182:185], v[80:83]
	v_mfma_f32_16x16x32_bf16 v[68:71], v[204:207], v[190:193], v[68:71]
	v_mfma_f32_16x16x32_bf16 v[64:67], v[212:215], v[190:193], v[64:67]
	s_setprio 0
	s_mov_b32 m0, s40
	s_add_u32 s100, s26, s0
	s_addc_u32 s101, s27, s1
	s_barrier
	ds_read_b128 v[162:165], v125 offset:16384
	ds_read_b128 v[166:169], v125 offset:17408
	ds_read_b128 v[170:173], v125 offset:18432
	ds_read_b128 v[174:177], v125 offset:19456
	ds_read_b128 v[178:181], v125 offset:20480
	ds_read_b128 v[182:185], v125 offset:21504
	ds_read_b128 v[186:189], v125 offset:22528
	ds_read_b128 v[190:193], v125 offset:23552
	global_load_lds_dwordx4 v112, s[26:27]
	s_mov_b32 m0, s41
	s_nop 0
	global_load_lds_dwordx4 v116, s[26:27]
	s_barrier
	s_waitcnt lgkmcnt(0)
	s_setprio 1
	s_waitcnt lgkmcnt(0)
	v_mfma_f32_16x16x32_bf16 v[60:63], v[146:149], v[162:165], v[60:63]
	v_mfma_f32_16x16x32_bf16 v[56:59], v[154:157], v[162:165], v[56:59]
	v_mfma_f32_16x16x32_bf16 v[44:47], v[146:149], v[170:173], v[44:47]
	v_mfma_f32_16x16x32_bf16 v[40:43], v[154:157], v[170:173], v[40:43]
	v_mfma_f32_16x16x32_bf16 v[28:31], v[146:149], v[178:181], v[28:31]
	v_mfma_f32_16x16x32_bf16 v[24:27], v[154:157], v[178:181], v[24:27]
	v_mfma_f32_16x16x32_bf16 v[12:15], v[146:149], v[186:189], v[12:15]
	v_mfma_f32_16x16x32_bf16 v[8:11], v[154:157], v[186:189], v[8:11]
	v_mfma_f32_16x16x32_bf16 v[60:63], v[150:153], v[166:169], v[60:63]
	v_mfma_f32_16x16x32_bf16 v[56:59], v[158:161], v[166:169], v[56:59]
	v_mfma_f32_16x16x32_bf16 v[44:47], v[150:153], v[174:177], v[44:47]
	v_mfma_f32_16x16x32_bf16 v[40:43], v[158:161], v[174:177], v[40:43]
	v_mfma_f32_16x16x32_bf16 v[28:31], v[150:153], v[182:185], v[28:31]
	v_mfma_f32_16x16x32_bf16 v[24:27], v[158:161], v[182:185], v[24:27]
	v_mfma_f32_16x16x32_bf16 v[12:15], v[150:153], v[190:193], v[12:15]
	v_mfma_f32_16x16x32_bf16 v[8:11], v[158:161], v[190:193], v[8:11]
	s_setprio 0
	s_barrier
; #define PG8_STAGE(bufoff, gbase, voff) do { _Pragma("unroll") for (int _i = 0; _i < 2; ++_i) \
;         __builtin_amdgcn_global_load_lds((const unsigned*)((const char*)(gbase) + (voff)[_i]), (LAS unsigned*)(lds + (bufoff) + ldsw + _i * 8192), 16, 0, 0); } while (0)
; #define PG8_LDA(dst, b, h) do { _Pragma("unroll") for (int m = 0; m < 4; ++m) _Pragma("unroll") for (int k = 0; k < 2; ++k) dst[m][k] = *(const LAS bf16x8*)(lds + PG8_SA(b, h) + aoff + m * 2048 + k * 1024); } while (0)
; #define PG8_LDB(dst, b, h) do { _Pragma("unroll") for (int n = 0; n < 2; ++n) _Pragma("unroll") for (int k = 0; k < 2; ++k) dst[n][k] = *(const LAS bf16x8*)(lds + PG8_SB(b, h) + boff + n * 2048 + k * 1024); } while (0)
; #define PG8_WAIT_V(n) asm volatile("s_waitcnt vmcnt(" #n ")" ::: "memory")
; #define PG8_WAIT_L(n) asm volatile("s_waitcnt lgkmcnt(" #n ")" ::: "memory")
; #define PG8_BAR __builtin_amdgcn_s_barrier()
; #define PG8_SCHED __builtin_amdgcn_sched_barrier(0)
; template <class Epi>
; __device__ __forceinline__ void gemm_phase(LAS unsigned char* lds, const bf16_t* A, int lda, const bf16_t* Bt, int ldb, int M, int N, int K, int asel, const Epi& E, const int fixed_round = -1) {
;     ...
;             PG8_STAGE(PG8_SB(0, 1), b2 + hstepB, voffB);
;             PG8_WAIT_V(6); PG8_BAR; PG8_MMA(1, 1, At, B1); PG8_BAR;
;             PG8_LDB(B0, 1, 0); PG8_SCHED; PG8_LDA(At, 1, 0); PG8_STAGE(PG8_SA(0, 1), a2 + hstepA, voffA);
;             PG8_WAIT_L(8); PG8_BAR; PG8_WAIT_L(0); PG8_MMA(0, 0, At, B0); PG8_BAR; PG8_SCHED;
;             PG8_LDB(B1, 1, 1); PG8_STAGE(PG8_SB(1, 0), b3, voffB);
	s_add_u32 s58, s24, 0x200000
	s_addc_u32 s59, s25, 0
	s_mov_b32 m0, s51
	s_nop 0
	global_load_lds_dwordx4 v114, s[58:59]
	s_mov_b32 m0, s52
	s_nop 0
	global_load_lds_dwordx4 v118, s[58:59]
	s_waitcnt vmcnt(6)
	s_barrier
	s_setprio 1
	v_mfma_f32_16x16x32_bf16 v[52:55], v[194:197], v[162:165], v[52:55]
	v_mfma_f32_16x16x32_bf16 v[48:51], v[208:211], v[162:165], v[48:51]
	v_mfma_f32_16x16x32_bf16 v[36:39], v[194:197], v[170:173], v[36:39]
	v_mfma_f32_16x16x32_bf16 v[32:35], v[208:211], v[170:173], v[32:35]
	v_mfma_f32_16x16x32_bf16 v[20:23], v[194:197], v[178:181], v[20:23]
	v_mfma_f32_16x16x32_bf16 v[16:19], v[208:211], v[178:181], v[16:19]
	v_mfma_f32_16x16x32_bf16 v[4:7], v[194:197], v[186:189], v[4:7]
	v_mfma_f32_16x16x32_bf16 v[0:3], v[208:211], v[186:189], v[0:3]
	v_mfma_f32_16x16x32_bf16 v[52:55], v[204:207], v[166:169], v[52:55]
	v_mfma_f32_16x16x32_bf16 v[48:51], v[212:215], v[166:169], v[48:51]
	v_mfma_f32_16x16x32_bf16 v[36:39], v[204:207], v[174:177], v[36:39]
	v_mfma_f32_16x16x32_bf16 v[32:35], v[212:215], v[174:177], v[32:35]
	v_mfma_f32_16x16x32_bf16 v[20:23], v[204:207], v[182:185], v[20:23]
	v_mfma_f32_16x16x32_bf16 v[16:19], v[212:215], v[182:185], v[16:19]
	v_mfma_f32_16x16x32_bf16 v[4:7], v[204:207], v[190:193], v[4:7]
	v_mfma_f32_16x16x32_bf16 v[0:3], v[212:215], v[190:193], v[0:3]
	s_setprio 0
	s_barrier
	ds_read_b128 v[146:149], v127
	ds_read_b128 v[150:153], v127 offset:1024
	ds_read_b128 v[154:157], v127 offset:2048
	ds_read_b128 v[158:161], v127 offset:3072
	s_add_u32 s26, s26, 0x200000
	s_addc_u32 s27, s27, 0
	s_mov_b32 m0, s42
	ds_read_b128 v[162:165], v125 offset:32768
	ds_read_b128 v[166:169], v125 offset:33792
	ds_read_b128 v[170:173], v125 offset:34816
	ds_read_b128 v[174:177], v125 offset:35840
	ds_read_b128 v[178:181], v125 offset:36864
	ds_read_b128 v[182:185], v125 offset:37888
	ds_read_b128 v[186:189], v125 offset:38912
	ds_read_b128 v[190:193], v125 offset:39936
	global_load_lds_dwordx4 v112, s[26:27]
	s_mov_b32 m0, s43
	s_nop 0
	global_load_lds_dwordx4 v116, s[26:27]
	s_waitcnt lgkmcnt(8)
	s_barrier
	s_waitcnt lgkmcnt(0)
	s_setprio 1
	s_waitcnt lgkmcnt(0)
	v_mfma_f32_16x16x32_bf16 v[140:143], v[146:149], v[162:165], v[140:143]
	v_mfma_f32_16x16x32_bf16 v[136:139], v[154:157], v[162:165], v[136:139]
	v_mfma_f32_16x16x32_bf16 v[108:111], v[146:149], v[170:173], v[108:111]
	v_mfma_f32_16x16x32_bf16 v[104:107], v[154:157], v[170:173], v[104:107]
	v_mfma_f32_16x16x32_bf16 v[92:95], v[146:149], v[178:181], v[92:95]
	v_mfma_f32_16x16x32_bf16 v[88:91], v[154:157], v[178:181], v[88:91]
	v_mfma_f32_16x16x32_bf16 v[76:79], v[146:149], v[186:189], v[76:79]
	v_mfma_f32_16x16x32_bf16 v[72:75], v[154:157], v[186:189], v[72:75]
	v_mfma_f32_16x16x32_bf16 v[140:143], v[150:153], v[166:169], v[140:143]
	v_mfma_f32_16x16x32_bf16 v[136:139], v[158:161], v[166:169], v[136:139]
	v_mfma_f32_16x16x32_bf16 v[108:111], v[150:153], v[174:177], v[108:111]
	v_mfma_f32_16x16x32_bf16 v[104:107], v[158:161], v[174:177], v[104:107]
	v_mfma_f32_16x16x32_bf16 v[92:95], v[150:153], v[182:185], v[92:95]
	v_mfma_f32_16x16x32_bf16 v[88:91], v[158:161], v[182:185], v[88:91]
	v_mfma_f32_16x16x32_bf16 v[76:79], v[150:153], v[190:193], v[76:79]
	v_mfma_f32_16x16x32_bf16 v[72:75], v[158:161], v[190:193], v[72:75]
	s_setprio 0
	s_barrier
	s_mov_b32 m0, s53
	ds_read_b128 v[194:197], v144
	ds_read_b128 v[204:207], v144 offset:1024
	ds_read_b128 v[208:211], v144 offset:2048
	ds_read_b128 v[212:215], v144 offset:3072
	global_load_lds_dwordx4 v114, s[98:99]
	s_mov_b32 m0, s54
	s_nop 0
	global_load_lds_dwordx4 v118, s[98:99]
	s_barrier
; #define PG8_STAGE(bufoff, gbase, voff) do { _Pragma("unroll") for (int _i = 0; _i < 2; ++_i) \
;         __builtin_amdgcn_global_load_lds((const unsigned*)((const char*)(gbase) + (voff)[_i]), (LAS unsigned*)(lds + (bufoff) + ldsw + _i * 8192), 16, 0, 0); } while (0)
; #define PG8_LDA(dst, b, h) do { _Pragma("unroll") for (int m = 0; m < 4; ++m) _Pragma("unroll") for (int k = 0; k < 2; ++k) dst[m][k] = *(const LAS bf16x8*)(lds + PG8_SA(b, h) + aoff + m * 2048 + k * 1024); } while (0)
; #define PG8_WAIT_V(n) asm volatile("s_waitcnt vmcnt(" #n ")" ::: "memory")
; #define PG8_WAIT_L(n) asm volatile("s_waitcnt lgkmcnt(" #n ")" ::: "memory")
; #define PG8_BAR __builtin_amdgcn_s_barrier()
; #define PG8_SCHED __builtin_amdgcn_sched_barrier(0)
; template <class Epi>
; __device__ __forceinline__ void gemm_phase(LAS unsigned char* lds, const bf16_t* A, int lda, const bf16_t* Bt, int ldb, int M, int N, int K, int asel, const Epi& E, const int fixed_round = -1) {
;     ...
;             PG8_BAR; PG8_WAIT_L(0); PG8_MMA(0, 1, At, B1); PG8_BAR;
;             PG8_LDA(At, 1, 1); PG8_STAGE(PG8_SA(1, 0), a3, voffA);
;             PG8_BAR; PG8_WAIT_L(0); PG8_MMA(1, 0, At, B0); PG8_BAR; PG8_SCHED;
;             PG8_STAGE(PG8_SB(1, 1), b3 + hstepB, voffB);
;             PG8_WAIT_V(6); PG8_BAR; PG8_MMA(1, 1, At, B1); PG8_BAR;
;     ...
;     PG8_WAIT_V(0);
;     if (wr == 0) PG8_BAR;
;     PG8_BAR;
	s_waitcnt lgkmcnt(0)
	s_setprio 1
	s_waitcnt lgkmcnt(0)
	v_mfma_f32_16x16x32_bf16 v[132:135], v[194:197], v[162:165], v[132:135]
	v_mfma_f32_16x16x32_bf16 v[128:131], v[208:211], v[162:165], v[128:131]
	v_mfma_f32_16x16x32_bf16 v[100:103], v[194:197], v[170:173], v[100:103]
	v_mfma_f32_16x16x32_bf16 v[96:99], v[208:211], v[170:173], v[96:99]
	v_mfma_f32_16x16x32_bf16 v[84:87], v[194:197], v[178:181], v[84:87]
	v_mfma_f32_16x16x32_bf16 v[80:83], v[208:211], v[178:181], v[80:83]
	v_mfma_f32_16x16x32_bf16 v[68:71], v[194:197], v[186:189], v[68:71]
	v_mfma_f32_16x16x32_bf16 v[64:67], v[208:211], v[186:189], v[64:67]
	v_mfma_f32_16x16x32_bf16 v[132:135], v[204:207], v[166:169], v[132:135]
	v_mfma_f32_16x16x32_bf16 v[128:131], v[212:215], v[166:169], v[128:131]
	v_mfma_f32_16x16x32_bf16 v[100:103], v[204:207], v[174:177], v[100:103]
	v_mfma_f32_16x16x32_bf16 v[96:99], v[212:215], v[174:177], v[96:99]
	v_mfma_f32_16x16x32_bf16 v[84:87], v[204:207], v[182:185], v[84:87]
	v_mfma_f32_16x16x32_bf16 v[80:83], v[212:215], v[182:185], v[80:83]
	v_mfma_f32_16x16x32_bf16 v[68:71], v[204:207], v[190:193], v[68:71]
	v_mfma_f32_16x16x32_bf16 v[64:67], v[212:215], v[190:193], v[64:67]
	s_setprio 0
	s_mov_b32 m0, s44
	s_barrier
	ds_read_b128 v[162:165], v125 offset:49152
	ds_read_b128 v[166:169], v125 offset:50176
	ds_read_b128 v[170:173], v125 offset:51200
	ds_read_b128 v[174:177], v125 offset:52224
	ds_read_b128 v[178:181], v125 offset:53248
	ds_read_b128 v[182:185], v125 offset:54272
	ds_read_b128 v[186:189], v125 offset:55296
	ds_read_b128 v[190:193], v125 offset:56320
	global_load_lds_dwordx4 v112, s[100:101]
	s_mov_b32 m0, s45
	s_nop 0
	global_load_lds_dwordx4 v116, s[100:101]
	s_barrier
	s_waitcnt lgkmcnt(0)
	s_setprio 1
	s_waitcnt lgkmcnt(0)
	v_mfma_f32_16x16x32_bf16 v[60:63], v[146:149], v[162:165], v[60:63]
	v_mfma_f32_16x16x32_bf16 v[56:59], v[154:157], v[162:165], v[56:59]
	v_mfma_f32_16x16x32_bf16 v[44:47], v[146:149], v[170:173], v[44:47]
	v_mfma_f32_16x16x32_bf16 v[40:43], v[154:157], v[170:173], v[40:43]
	v_mfma_f32_16x16x32_bf16 v[28:31], v[146:149], v[178:181], v[28:31]
	v_mfma_f32_16x16x32_bf16 v[24:27], v[154:157], v[178:181], v[24:27]
	v_mfma_f32_16x16x32_bf16 v[12:15], v[146:149], v[186:189], v[12:15]
	v_mfma_f32_16x16x32_bf16 v[8:11], v[154:157], v[186:189], v[8:11]
	v_mfma_f32_16x16x32_bf16 v[60:63], v[150:153], v[166:169], v[60:63]
	v_mfma_f32_16x16x32_bf16 v[56:59], v[158:161], v[166:169], v[56:59]
	v_mfma_f32_16x16x32_bf16 v[44:47], v[150:153], v[174:177], v[44:47]
	v_mfma_f32_16x16x32_bf16 v[40:43], v[158:161], v[174:177], v[40:43]
	v_mfma_f32_16x16x32_bf16 v[28:31], v[150:153], v[182:185], v[28:31]
	v_mfma_f32_16x16x32_bf16 v[24:27], v[158:161], v[182:185], v[24:27]
	v_mfma_f32_16x16x32_bf16 v[12:15], v[150:153], v[190:193], v[12:15]
	v_mfma_f32_16x16x32_bf16 v[8:11], v[158:161], v[190:193], v[8:11]
	s_setprio 0
	s_barrier
	s_add_u32 s24, s24, 0x200080
	s_addc_u32 s25, s25, 0
	s_mov_b32 m0, s55
	s_nop 0
	global_load_lds_dwordx4 v114, s[24:25]
	s_mov_b32 m0, s56
	s_nop 0
	global_load_lds_dwordx4 v118, s[24:25]
	s_waitcnt vmcnt(6)
	s_barrier
	s_setprio 1
	v_mfma_f32_16x16x32_bf16 v[52:55], v[194:197], v[162:165], v[52:55]
	v_mfma_f32_16x16x32_bf16 v[48:51], v[208:211], v[162:165], v[48:51]
	v_mfma_f32_16x16x32_bf16 v[36:39], v[194:197], v[170:173], v[36:39]
	v_mfma_f32_16x16x32_bf16 v[32:35], v[208:211], v[170:173], v[32:35]
	v_mfma_f32_16x16x32_bf16 v[20:23], v[194:197], v[178:181], v[20:23]
	v_mfma_f32_16x16x32_bf16 v[16:19], v[208:211], v[178:181], v[16:19]
	v_mfma_f32_16x16x32_bf16 v[4:7], v[194:197], v[186:189], v[4:7]
	v_mfma_f32_16x16x32_bf16 v[0:3], v[208:211], v[186:189], v[0:3]
	v_mfma_f32_16x16x32_bf16 v[52:55], v[204:207], v[166:169], v[52:55]
	v_mfma_f32_16x16x32_bf16 v[48:51], v[212:215], v[166:169], v[48:51]
	v_mfma_f32_16x16x32_bf16 v[36:39], v[204:207], v[174:177], v[36:39]
	v_mfma_f32_16x16x32_bf16 v[32:35], v[212:215], v[174:177], v[32:35]
	v_mfma_f32_16x16x32_bf16 v[20:23], v[204:207], v[182:185], v[20:23]
	v_mfma_f32_16x16x32_bf16 v[16:19], v[212:215], v[182:185], v[16:19]
	v_mfma_f32_16x16x32_bf16 v[4:7], v[204:207], v[190:193], v[4:7]
	v_mfma_f32_16x16x32_bf16 v[0:3], v[212:215], v[190:193], v[0:3]
	s_setprio 0
	s_add_i32 s46, s46, 2
	s_add_u32 s22, s22, 0x100
	s_addc_u32 s23, s23, 0
	s_cmpk_lt_u32 s46, 0x7e
	s_cbranch_scc1 .Lrot_11
	s_barrier
	s_waitcnt vmcnt(0)
	v_readlane_b32 s48, v254, 0
	s_cmpk_gt_u32 s33, 0xff
	v_readlane_b32 s54, v254, 6
	v_readlane_b32 s55, v254, 7
	v_readlane_b32 s49, v254, 1
	v_readlane_b32 s50, v254, 2
	v_readlane_b32 s51, v254, 3
	v_readlane_b32 s52, v254, 4
	v_readlane_b32 s53, v254, 5
	s_cbranch_scc1 .LBB0_1286
	s_barrier

; #define PG8_STAGE(bufoff, gbase, voff) do { _Pragma("unroll") for (int _i = 0; _i < 2; ++_i) \
;         __builtin_amdgcn_global_load_lds((const unsigned*)((const char*)(gbase) + (voff)[_i]), (LAS unsigned*)(lds + (bufoff) + ldsw + _i * 8192), 16, 0, 0); } while (0)
; #define PG8_WAIT_V(n) asm volatile("s_waitcnt vmcnt(" #n ")" ::: "memory")
; #define PG8_BAR __builtin_amdgcn_s_barrier()
; template <class Epi>
; __device__ __forceinline__ void gemm_phase(LAS unsigned char* lds, const bf16_t* A, int lda, const bf16_t* Bt, int ldb, int M, int N, int K, int asel, const Epi& E, const int fixed_round = -1) {
;     ...
;     StaticOrder S; S.init(M, N, gridDim.x, blockIdx.x);
;     unsigned voffA[2], voffB[2];
; #pragma unroll
;     for (int i = 0; i < 2; ++i) { int R, C; stage_rc(tid * 16 + i * 8192, R, C); const int Rb = Epi::PERM ? ((R & ~31) + perm32(R & 31)) : R;
;         voffA[i] = (unsigned)(R * lda + C) * 2u; voffB[i] = (unsigned)(Rb * ldb + C) * 2u; }
;     const size_t kstep = (size_t)(BK * 2);
;     const size_t hstepA = (size_t)HALF * lda * 2, hstepB = (size_t)HALF * ldb * 2;
;     const size_t tstepA = 2 * hstepA, tstepB = 2 * hstepB;
;     const unsigned ldsw = (unsigned)wid * 1024u;
;     const int aoff = lds_byte(wr * 64 + fr, fq * 8), boff = lds_byte(wc * 32 + fr, fq * 8);
;     ...
;     Unit cur, nxt; int ui = 0;
;     if (fixed_round < 0) { if (!S.next(0, cur)) return; }
;     else { const int c = blockIdx.x; cur.pm = 32 * fixed_round + 4 * (c & 7) + (c >> 6); cur.pn = (c >> 3) & 7; }
;     f32x4 acc[2][2][4][2];
; #pragma unroll
;     for (int a = 0; a < 2; ++a)
; #pragma unroll
;         for (int b = 0; b < 2; ++b)
; #pragma unroll
;             for (int m = 0; m < 4; ++m)
; #pragma unroll
;                 for (int n = 0; n < 2; ++n) acc[a][b][m][n] = (f32x4){0.f, 0.f, 0.f, 0.f};
;     bf16x8 At[4][2], B0[2][2], B1[2][2];
;     const char* cA = PG8_ABASE(cur); const char* cB = (const char*)Bt + (size_t)cur.pn * tstepB;
;     PG8_STAGE(PG8_SB(0, 0), cB, voffB); PG8_STAGE(PG8_SA(0, 0), cA, voffA); PG8_STAGE(PG8_SB(0, 1), cB + hstepB, voffB); PG8_STAGE(PG8_SA(0, 1), cA + hstepA, voffA);
;     if (wr == 1) PG8_BAR;
;     PG8_WAIT_V(4); PG8_BAR;
;     PG8_STAGE(PG8_SB(1, 0), cB + kstep, voffB); PG8_STAGE(PG8_SA(1, 0), cA + kstep, voffA); PG8_STAGE(PG8_SB(1, 1), cB + hstepB + kstep, voffB);
;     PG8_WAIT_V(6); PG8_BAR;
.LBB0_1321:
	v_bfe_u32 v223, v12, 4, 2
	v_and_b32_e32 v220, 15, v12
	v_lshlrev_b32_e32 v15, 4, v223
	v_lshlrev_b32_e32 v12, 2, v12
	s_and_b32 s17, s0, 3
	v_lshl_or_b32 v15, v220, 6, v15
	s_lshl_b32 s0, s1, 13
	v_and_b32_e32 v12, 32, v12
	v_bitop3_b32 v16, v15, s0, v12 bitop3:0xde
	s_lshl_b32 s0, s17, 12
	s_lshl_b32 s16, s1, 6
	v_bitop3_b32 v12, v15, s0, v12 bitop3:0xde
	s_mov_b64 s[0:1], 0x80
	s_add_i32 m0, s19, 0x18000
	v_lshl_add_u64 v[6:7], v[6:7], 0, s[0:1]
	s_waitcnt vmcnt(4)
	s_barrier
	global_load_lds_dwordx4 v[6:7], off
	v_lshl_add_u64 v[4:5], v[4:5], 0, s[0:1]
	s_add_i32 m0, s19, 0x1a000
	s_add_i32 s36, s19, 0x8000
	global_load_lds_dwordx4 v[4:5], off
	v_lshl_add_u64 v[2:3], v[2:3], 0, s[0:1]
	s_mov_b32 m0, s36
	s_add_i32 s37, s19, 0xa000
	global_load_lds_dwordx4 v[2:3], off
	v_lshl_add_u64 v[0:1], v[0:1], 0, s[0:1]
	s_mov_b32 m0, s37
	v_or_b32_e32 v221, s16, v220
	global_load_lds_dwordx4 v[0:1], off
	s_add_i32 m0, s19, 0x1c000
	v_lshl_add_u64 v[0:1], s[6:7], 0, v[202:203]
	global_load_lds_dwordx4 v[0:1], off
	v_lshl_add_u64 v[0:1], s[6:7], 0, v[116:117]
	s_add_i32 m0, s19, 0x1e000
	s_add_u32 s4, s78, s34
	global_load_lds_dwordx4 v[0:1], off
	v_lshlrev_b32_e32 v0, 17, v8
	v_and_b32_e32 v0, 0xfffc0000, v0
	v_lshl_add_u32 v0, v9, 14, v0
	v_and_b32_e32 v1, 1, v8
	v_lshl_or_b32 v0, v1, 6, v0
	s_addc_u32 s5, s79, s35
	v_lshl_add_u32 v0, v10, 1, v0
	v_mov_b32_e32 v1, v203
	v_lshl_add_u64 v[0:1], s[4:5], 0, v[0:1]
	s_mov_b64 s[6:7], 0x18700080
	v_lshl_add_u64 v[118:119], v[0:1], 0, s[6:7]
	v_lshlrev_b32_e32 v0, 17, v11
	v_and_b32_e32 v0, 0xfffc0000, v0
	v_lshl_add_u32 v0, v13, 14, v0
	v_and_b32_e32 v1, 1, v11
	v_lshl_or_b32 v0, v1, 6, v0
	s_waitcnt vmcnt(6)
	v_lshl_add_u32 v0, v14, 1, v0
	v_mov_b32_e32 v1, v203
	v_lshl_add_u64 v[0:1], s[4:5], 0, v[0:1]
	s_add_i32 s41, s81, s8
	s_add_i32 s43, s82, s8
	s_add_i32 s45, s83, s8
	s_add_i32 s47, s84, s8
	v_lshl_add_u64 v[120:121], v[0:1], 0, s[6:7]
	s_mov_b32 s34, -2
	s_mov_b64 s[6:7], 0
	v_add_u32_e32 v122, s81, v12
	v_add_u32_e32 v123, 0, v16
	s_add_i32 s35, s19, 0xc000
	s_add_i32 s40, s19, 0xe000
	v_add_u32_e32 v124, s82, v12
	s_add_i32 s42, s41, 0x2000
	s_add_i32 s44, s43, 0x2000
	v_add_u32_e32 v125, s83, v12
	v_add_u32_e32 v126, s84, v12
	s_add_i32 s46, s45, 0x2000
	s_add_i32 s48, s47, 0x2000
	v_mov_b32_e32 v0, v203
	v_mov_b32_e32 v1, v203
	v_mov_b32_e32 v2, v203
	v_mov_b32_e32 v3, v203
	v_mov_b32_e32 v4, v203
	v_mov_b32_e32 v5, v203
	v_mov_b32_e32 v6, v203
	v_mov_b32_e32 v7, v203
	v_mov_b32_e32 v16, v203
	v_mov_b32_e32 v17, v203
	v_mov_b32_e32 v18, v203
	v_mov_b32_e32 v19, v203
	v_mov_b32_e32 v20, v203
	v_mov_b32_e32 v21, v203
	v_mov_b32_e32 v22, v203
	v_mov_b32_e32 v23, v203
	v_mov_b32_e32 v32, v203
	v_mov_b32_e32 v33, v203
	v_mov_b32_e32 v34, v203
	v_mov_b32_e32 v35, v203
	v_mov_b32_e32 v36, v203
	v_mov_b32_e32 v37, v203
	v_mov_b32_e32 v38, v203
	v_mov_b32_e32 v39, v203
	v_mov_b32_e32 v48, v203
	v_mov_b32_e32 v49, v203
	v_mov_b32_e32 v50, v203
	v_mov_b32_e32 v51, v203
	v_mov_b32_e32 v52, v203
	v_mov_b32_e32 v53, v203
	v_mov_b32_e32 v54, v203
	v_mov_b32_e32 v55, v203
	v_mov_b32_e32 v8, v203
	v_mov_b32_e32 v9, v203
	v_mov_b32_e32 v10, v203
	v_mov_b32_e32 v11, v203
	v_mov_b32_e32 v12, v203
	v_mov_b32_e32 v13, v203
	v_mov_b32_e32 v14, v203
	v_mov_b32_e32 v15, v203
	v_mov_b32_e32 v24, v203
	v_mov_b32_e32 v25, v203
	v_mov_b32_e32 v26, v203
	v_mov_b32_e32 v27, v203
	v_mov_b32_e32 v28, v203
	v_mov_b32_e32 v29, v203
	v_mov_b32_e32 v30, v203
	v_mov_b32_e32 v31, v203
	v_mov_b32_e32 v40, v203
	v_mov_b32_e32 v41, v203
	v_mov_b32_e32 v42, v203
	v_mov_b32_e32 v43, v203
	v_mov_b32_e32 v44, v203
	v_mov_b32_e32 v45, v203
	v_mov_b32_e32 v46, v203
	v_mov_b32_e32 v47, v203
	v_mov_b32_e32 v56, v203
	v_mov_b32_e32 v57, v203
	v_mov_b32_e32 v58, v203
	v_mov_b32_e32 v59, v203
	v_mov_b32_e32 v60, v203
	v_mov_b32_e32 v61, v203
	v_mov_b32_e32 v62, v203
	v_mov_b32_e32 v63, v203
	v_mov_b32_e32 v64, v203
	v_mov_b32_e32 v65, v203
	v_mov_b32_e32 v66, v203
	v_mov_b32_e32 v67, v203
	v_mov_b32_e32 v68, v203
	v_mov_b32_e32 v69, v203
	v_mov_b32_e32 v70, v203
	v_mov_b32_e32 v71, v203
	v_mov_b32_e32 v80, v203
	v_mov_b32_e32 v81, v203
	v_mov_b32_e32 v82, v203
	v_mov_b32_e32 v83, v203
	v_mov_b32_e32 v84, v203
	v_mov_b32_e32 v85, v203
	v_mov_b32_e32 v86, v203
	v_mov_b32_e32 v87, v203
	v_mov_b32_e32 v96, v203
	v_mov_b32_e32 v97, v203
	v_mov_b32_e32 v98, v203
	v_mov_b32_e32 v99, v203
	v_mov_b32_e32 v100, v203
	v_mov_b32_e32 v101, v203
	v_mov_b32_e32 v102, v203
	v_mov_b32_e32 v103, v203
	v_mov_b32_e32 v128, v203
	v_mov_b32_e32 v129, v203
	v_mov_b32_e32 v130, v203
	v_mov_b32_e32 v131, v203
	v_mov_b32_e32 v132, v203
	v_mov_b32_e32 v133, v203
	v_mov_b32_e32 v134, v203
	v_mov_b32_e32 v135, v203
	v_mov_b32_e32 v72, v203
	v_mov_b32_e32 v73, v203
	v_mov_b32_e32 v74, v203
	v_mov_b32_e32 v75, v203
	v_mov_b32_e32 v76, v203
	v_mov_b32_e32 v77, v203
	v_mov_b32_e32 v78, v203
	v_mov_b32_e32 v79, v203
	v_mov_b32_e32 v88, v203
	v_mov_b32_e32 v89, v203
	v_mov_b32_e32 v90, v203
	v_mov_b32_e32 v91, v203
	v_mov_b32_e32 v92, v203
	v_mov_b32_e32 v93, v203
	v_mov_b32_e32 v94, v203
	v_mov_b32_e32 v95, v203
	v_mov_b32_e32 v104, v203
	v_mov_b32_e32 v105, v203
	v_mov_b32_e32 v106, v203
	v_mov_b32_e32 v107, v203
	v_mov_b32_e32 v108, v203
	v_mov_b32_e32 v109, v203
	v_mov_b32_e32 v110, v203
	v_mov_b32_e32 v111, v203
	v_mov_b32_e32 v136, v203
	v_mov_b32_e32 v137, v203
	v_mov_b32_e32 v138, v203
	v_mov_b32_e32 v139, v203
	v_mov_b32_e32 v140, v203
	v_mov_b32_e32 v141, v203
	v_mov_b32_e32 v142, v203
	v_mov_b32_e32 v143, v203
.Lrot_12:
	s_barrier
; #define PG8_STAGE(bufoff, gbase, voff) do { _Pragma("unroll") for (int _i = 0; _i < 2; ++_i) \
;         __builtin_amdgcn_global_load_lds((const unsigned*)((const char*)(gbase) + (voff)[_i]), (LAS unsigned*)(lds + (bufoff) + ldsw + _i * 8192), 16, 0, 0); } while (0)
; #define PG8_LDA(dst, b, h) do { _Pragma("unroll") for (int m = 0; m < 4; ++m) _Pragma("unroll") for (int k = 0; k < 2; ++k) dst[m][k] = *(const LAS bf16x8*)(lds + PG8_SA(b, h) + aoff + m * 2048 + k * 1024); } while (0)
; #define PG8_LDB(dst, b, h) do { _Pragma("unroll") for (int n = 0; n < 2; ++n) _Pragma("unroll") for (int k = 0; k < 2; ++k) dst[n][k] = *(const LAS bf16x8*)(lds + PG8_SB(b, h) + boff + n * 2048 + k * 1024); } while (0)
; #define PG8_WAIT_L(n) asm volatile("s_waitcnt lgkmcnt(" #n ")" ::: "memory")
; #define PG8_BAR __builtin_amdgcn_s_barrier()
; #define PG8_SCHED __builtin_amdgcn_sched_barrier(0)
; template <class Epi>
; __device__ __forceinline__ void gemm_phase(LAS unsigned char* lds, const bf16_t* A, int lda, const bf16_t* Bt, int ldb, int M, int N, int K, int asel, const Epi& E, const int fixed_round = -1) {
;     ...
;             const bool last = (t == nt - 2);
;             const char* a1 = cA + (size_t)(t + 1) * kstep;
;             const char* a2 = last ? nA : cA + (size_t)(t + 2) * kstep; const char* b2 = last ? nB : cB + (size_t)(t + 2) * kstep;
;             const char* a3 = a2 + kstep; const char* b3 = b2 + kstep;
;             PG8_LDB(B0, 0, 0); PG8_SCHED; PG8_LDA(At, 0, 0); PG8_STAGE(PG8_SA(1, 1), a1 + hstepA, voffA);
;             PG8_WAIT_L(8); PG8_BAR; PG8_WAIT_L(0); PG8_MMA(0, 0, At, B0); PG8_BAR; PG8_SCHED;
;             PG8_LDB(B1, 0, 1); PG8_STAGE(PG8_SB(0, 0), b2, voffB);
;             PG8_BAR; PG8_WAIT_L(0); PG8_MMA(0, 1, At, B1); PG8_BAR;
;             PG8_LDA(At, 0, 1); PG8_STAGE(PG8_SA(0, 0), a2, voffA);
;             PG8_BAR; PG8_WAIT_L(0); PG8_MMA(1, 0, At, B0); PG8_BAR; PG8_SCHED;
.LBB0_1322:
	s_add_u32 s8, s4, s6
	ds_read_b128 v[144:147], v122
	ds_read_b128 v[148:151], v122 offset:1024
	ds_read_b128 v[152:155], v122 offset:2048
	ds_read_b128 v[156:159], v122 offset:3072
	s_addc_u32 s9, s5, s7
	s_add_u32 s8, s8, 0x18500100
	s_addc_u32 s9, s9, 0
	s_add_u32 s49, s28, s6
	s_addc_u32 s50, s29, s7
	s_cmpk_eq_i32 s6, 0x3f00
	s_cselect_b32 s13, s11, s9
	s_cselect_b32 s12, s10, s8
	s_cselect_b32 s9, s3, s50
	s_cselect_b32 s8, s2, s49
	s_mov_b32 m0, s35
	v_lshl_add_u64 v[192:193], v[118:119], 0, s[6:7]
	ds_read_b128 v[160:163], v123
	ds_read_b128 v[164:167], v123 offset:1024
	ds_read_b128 v[168:171], v123 offset:2048
	ds_read_b128 v[172:175], v123 offset:3072
	ds_read_b128 v[176:179], v123 offset:4096
	ds_read_b128 v[180:183], v123 offset:5120
	ds_read_b128 v[184:187], v123 offset:6144
	ds_read_b128 v[188:191], v123 offset:7168
	global_load_lds_dwordx4 v[192:193], off
	v_lshl_add_u64 v[192:193], v[120:121], 0, s[6:7]
	s_mov_b32 m0, s40
	s_nop 0
	global_load_lds_dwordx4 v[192:193], off
	s_waitcnt lgkmcnt(8)
	s_barrier
	s_waitcnt lgkmcnt(0)
	s_setprio 1
	s_waitcnt lgkmcnt(0)
	v_mfma_f32_16x16x32_bf16 v[140:143], v[144:147], v[160:163], v[140:143]
	v_mfma_f32_16x16x32_bf16 v[136:139], v[152:155], v[160:163], v[136:139]
	v_mfma_f32_16x16x32_bf16 v[108:111], v[144:147], v[168:171], v[108:111]
	v_mfma_f32_16x16x32_bf16 v[104:107], v[152:155], v[168:171], v[104:107]
	v_mfma_f32_16x16x32_bf16 v[92:95], v[144:147], v[176:179], v[92:95]
	v_mfma_f32_16x16x32_bf16 v[88:91], v[152:155], v[176:179], v[88:91]
	v_mfma_f32_16x16x32_bf16 v[76:79], v[144:147], v[184:187], v[76:79]
	v_mfma_f32_16x16x32_bf16 v[72:75], v[152:155], v[184:187], v[72:75]
	v_mfma_f32_16x16x32_bf16 v[140:143], v[148:151], v[164:167], v[140:143]
	v_mfma_f32_16x16x32_bf16 v[136:139], v[156:159], v[164:167], v[136:139]
	v_mfma_f32_16x16x32_bf16 v[108:111], v[148:151], v[172:175], v[108:111]
	v_mfma_f32_16x16x32_bf16 v[104:107], v[156:159], v[172:175], v[104:107]
	v_mfma_f32_16x16x32_bf16 v[92:95], v[148:151], v[180:183], v[92:95]
	v_mfma_f32_16x16x32_bf16 v[88:91], v[156:159], v[180:183], v[88:91]
	v_mfma_f32_16x16x32_bf16 v[76:79], v[148:151], v[188:191], v[76:79]
	v_mfma_f32_16x16x32_bf16 v[72:75], v[156:159], v[188:191], v[72:75]
	s_setprio 0
	s_barrier
	s_mov_b32 m0, s41
	s_add_u32 s98, s8, s0
	s_addc_u32 s99, s9, s1
	ds_read_b128 v[192:195], v124
	ds_read_b128 v[196:199], v124 offset:1024
	ds_read_b128 v[204:207], v124 offset:2048
	ds_read_b128 v[208:211], v124 offset:3072
	global_load_lds_dwordx4 v202, s[8:9]
	s_mov_b32 m0, s42
	s_nop 0
	global_load_lds_dwordx4 v116, s[8:9]
	s_barrier
	s_waitcnt lgkmcnt(0)
	s_setprio 1
	s_waitcnt lgkmcnt(0)
	v_mfma_f32_16x16x32_bf16 v[132:135], v[192:195], v[160:163], v[132:135]
	v_mfma_f32_16x16x32_bf16 v[128:131], v[204:207], v[160:163], v[128:131]
	v_mfma_f32_16x16x32_bf16 v[100:103], v[192:195], v[168:171], v[100:103]
	v_mfma_f32_16x16x32_bf16 v[96:99], v[204:207], v[168:171], v[96:99]
	v_mfma_f32_16x16x32_bf16 v[84:87], v[192:195], v[176:179], v[84:87]
	v_mfma_f32_16x16x32_bf16 v[80:83], v[204:207], v[176:179], v[80:83]
	v_mfma_f32_16x16x32_bf16 v[68:71], v[192:195], v[184:187], v[68:71]
	v_mfma_f32_16x16x32_bf16 v[64:67], v[204:207], v[184:187], v[64:67]
	v_mfma_f32_16x16x32_bf16 v[132:135], v[196:199], v[164:167], v[132:135]
	v_mfma_f32_16x16x32_bf16 v[128:131], v[208:211], v[164:167], v[128:131]
	v_mfma_f32_16x16x32_bf16 v[100:103], v[196:199], v[172:175], v[100:103]
	v_mfma_f32_16x16x32_bf16 v[96:99], v[208:211], v[172:175], v[96:99]
	v_mfma_f32_16x16x32_bf16 v[84:87], v[196:199], v[180:183], v[84:87]
	v_mfma_f32_16x16x32_bf16 v[80:83], v[208:211], v[180:183], v[80:83]
	v_mfma_f32_16x16x32_bf16 v[68:71], v[196:199], v[188:191], v[68:71]
	v_mfma_f32_16x16x32_bf16 v[64:67], v[208:211], v[188:191], v[64:67]
	s_setprio 0
	s_mov_b32 m0, s19
	s_add_u32 s100, s12, s0
	s_addc_u32 s101, s13, s1
	s_barrier
	ds_read_b128 v[160:163], v123 offset:16384
	ds_read_b128 v[164:167], v123 offset:17408
	ds_read_b128 v[168:171], v123 offset:18432
	ds_read_b128 v[172:175], v123 offset:19456
	ds_read_b128 v[176:179], v123 offset:20480
	ds_read_b128 v[180:183], v123 offset:21504
	ds_read_b128 v[184:187], v123 offset:22528
	ds_read_b128 v[188:191], v123 offset:23552
	global_load_lds_dwordx4 v112, s[12:13]
	s_mov_b32 m0, s30
	s_nop 0
	global_load_lds_dwordx4 v114, s[12:13]
	s_barrier
	s_waitcnt lgkmcnt(0)
	s_setprio 1
	s_waitcnt lgkmcnt(0)
	v_mfma_f32_16x16x32_bf16 v[60:63], v[144:147], v[160:163], v[60:63]
	v_mfma_f32_16x16x32_bf16 v[56:59], v[152:155], v[160:163], v[56:59]
	v_mfma_f32_16x16x32_bf16 v[44:47], v[144:147], v[168:171], v[44:47]
	v_mfma_f32_16x16x32_bf16 v[40:43], v[152:155], v[168:171], v[40:43]
	v_mfma_f32_16x16x32_bf16 v[28:31], v[144:147], v[176:179], v[28:31]
	v_mfma_f32_16x16x32_bf16 v[24:27], v[152:155], v[176:179], v[24:27]
	v_mfma_f32_16x16x32_bf16 v[12:15], v[144:147], v[184:187], v[12:15]
	v_mfma_f32_16x16x32_bf16 v[8:11], v[152:155], v[184:187], v[8:11]
	v_mfma_f32_16x16x32_bf16 v[60:63], v[148:151], v[164:167], v[60:63]
	v_mfma_f32_16x16x32_bf16 v[56:59], v[156:159], v[164:167], v[56:59]
	v_mfma_f32_16x16x32_bf16 v[44:47], v[148:151], v[172:175], v[44:47]
	v_mfma_f32_16x16x32_bf16 v[40:43], v[156:159], v[172:175], v[40:43]
	v_mfma_f32_16x16x32_bf16 v[28:31], v[148:151], v[180:183], v[28:31]
	v_mfma_f32_16x16x32_bf16 v[24:27], v[156:159], v[180:183], v[24:27]
	v_mfma_f32_16x16x32_bf16 v[12:15], v[148:151], v[188:191], v[12:15]
	v_mfma_f32_16x16x32_bf16 v[8:11], v[156:159], v[188:191], v[8:11]
	s_setprio 0
	s_barrier
; #define PG8_STAGE(bufoff, gbase, voff) do { _Pragma("unroll") for (int _i = 0; _i < 2; ++_i) \
;         __builtin_amdgcn_global_load_lds((const unsigned*)((const char*)(gbase) + (voff)[_i]), (LAS unsigned*)(lds + (bufoff) + ldsw + _i * 8192), 16, 0, 0); } while (0)
; #define PG8_LDA(dst, b, h) do { _Pragma("unroll") for (int m = 0; m < 4; ++m) _Pragma("unroll") for (int k = 0; k < 2; ++k) dst[m][k] = *(const LAS bf16x8*)(lds + PG8_SA(b, h) + aoff + m * 2048 + k * 1024); } while (0)
; #define PG8_LDB(dst, b, h) do { _Pragma("unroll") for (int n = 0; n < 2; ++n) _Pragma("unroll") for (int k = 0; k < 2; ++k) dst[n][k] = *(const LAS bf16x8*)(lds + PG8_SB(b, h) + boff + n * 2048 + k * 1024); } while (0)
; #define PG8_WAIT_V(n) asm volatile("s_waitcnt vmcnt(" #n ")" ::: "memory")
; #define PG8_WAIT_L(n) asm volatile("s_waitcnt lgkmcnt(" #n ")" ::: "memory")
; #define PG8_BAR __builtin_amdgcn_s_barrier()
; #define PG8_SCHED __builtin_amdgcn_sched_barrier(0)
; template <class Epi>
; __device__ __forceinline__ void gemm_phase(LAS unsigned char* lds, const bf16_t* A, int lda, const bf16_t* Bt, int ldb, int M, int N, int K, int asel, const Epi& E, const int fixed_round = -1) {
;     ...
;             PG8_STAGE(PG8_SB(0, 1), b2 + hstepB, voffB);
;             PG8_WAIT_V(6); PG8_BAR; PG8_MMA(1, 1, At, B1); PG8_BAR;
;             PG8_LDB(B0, 1, 0); PG8_SCHED; PG8_LDA(At, 1, 0); PG8_STAGE(PG8_SA(0, 1), a2 + hstepA, voffA);
;             PG8_WAIT_L(8); PG8_BAR; PG8_WAIT_L(0); PG8_MMA(0, 0, At, B0); PG8_BAR; PG8_SCHED;
;             PG8_LDB(B1, 1, 1); PG8_STAGE(PG8_SB(1, 0), b3, voffB);
	s_add_u32 s50, s8, 0x200000
	s_addc_u32 s51, s9, 0
	s_mov_b32 m0, s43
	s_nop 0
	global_load_lds_dwordx4 v202, s[50:51]
	s_mov_b32 m0, s44
	s_nop 0
	global_load_lds_dwordx4 v116, s[50:51]
	s_waitcnt vmcnt(6)
	s_barrier
	s_setprio 1
	v_mfma_f32_16x16x32_bf16 v[52:55], v[192:195], v[160:163], v[52:55]
	v_mfma_f32_16x16x32_bf16 v[48:51], v[204:207], v[160:163], v[48:51]
	v_mfma_f32_16x16x32_bf16 v[36:39], v[192:195], v[168:171], v[36:39]
	v_mfma_f32_16x16x32_bf16 v[32:35], v[204:207], v[168:171], v[32:35]
	v_mfma_f32_16x16x32_bf16 v[20:23], v[192:195], v[176:179], v[20:23]
	v_mfma_f32_16x16x32_bf16 v[16:19], v[204:207], v[176:179], v[16:19]
	v_mfma_f32_16x16x32_bf16 v[4:7], v[192:195], v[184:187], v[4:7]
	v_mfma_f32_16x16x32_bf16 v[0:3], v[204:207], v[184:187], v[0:3]
	v_mfma_f32_16x16x32_bf16 v[52:55], v[196:199], v[164:167], v[52:55]
	v_mfma_f32_16x16x32_bf16 v[48:51], v[208:211], v[164:167], v[48:51]
	v_mfma_f32_16x16x32_bf16 v[36:39], v[196:199], v[172:175], v[36:39]
	v_mfma_f32_16x16x32_bf16 v[32:35], v[208:211], v[172:175], v[32:35]
	v_mfma_f32_16x16x32_bf16 v[20:23], v[196:199], v[180:183], v[20:23]
	v_mfma_f32_16x16x32_bf16 v[16:19], v[208:211], v[180:183], v[16:19]
	v_mfma_f32_16x16x32_bf16 v[4:7], v[196:199], v[188:191], v[4:7]
	v_mfma_f32_16x16x32_bf16 v[0:3], v[208:211], v[188:191], v[0:3]
	s_setprio 0
	s_barrier
	ds_read_b128 v[144:147], v125
	ds_read_b128 v[148:151], v125 offset:1024
	ds_read_b128 v[152:155], v125 offset:2048
	ds_read_b128 v[156:159], v125 offset:3072
	s_add_u32 s12, s12, 0x200000
	s_addc_u32 s13, s13, 0
	s_mov_b32 m0, s31
	ds_read_b128 v[160:163], v123 offset:32768
	ds_read_b128 v[164:167], v123 offset:33792
	ds_read_b128 v[168:171], v123 offset:34816
	ds_read_b128 v[172:175], v123 offset:35840
	ds_read_b128 v[176:179], v123 offset:36864
	ds_read_b128 v[180:183], v123 offset:37888
	ds_read_b128 v[184:187], v123 offset:38912
	ds_read_b128 v[188:191], v123 offset:39936
	global_load_lds_dwordx4 v112, s[12:13]
	s_mov_b32 m0, s33
	s_nop 0
	global_load_lds_dwordx4 v114, s[12:13]
	s_waitcnt lgkmcnt(8)
	s_barrier
	s_waitcnt lgkmcnt(0)
	s_setprio 1
	s_waitcnt lgkmcnt(0)
	v_mfma_f32_16x16x32_bf16 v[140:143], v[144:147], v[160:163], v[140:143]
	v_mfma_f32_16x16x32_bf16 v[136:139], v[152:155], v[160:163], v[136:139]
	v_mfma_f32_16x16x32_bf16 v[108:111], v[144:147], v[168:171], v[108:111]
	v_mfma_f32_16x16x32_bf16 v[104:107], v[152:155], v[168:171], v[104:107]
	v_mfma_f32_16x16x32_bf16 v[92:95], v[144:147], v[176:179], v[92:95]
	v_mfma_f32_16x16x32_bf16 v[88:91], v[152:155], v[176:179], v[88:91]
	v_mfma_f32_16x16x32_bf16 v[76:79], v[144:147], v[184:187], v[76:79]
	v_mfma_f32_16x16x32_bf16 v[72:75], v[152:155], v[184:187], v[72:75]
	v_mfma_f32_16x16x32_bf16 v[140:143], v[148:151], v[164:167], v[140:143]
	v_mfma_f32_16x16x32_bf16 v[136:139], v[156:159], v[164:167], v[136:139]
	v_mfma_f32_16x16x32_bf16 v[108:111], v[148:151], v[172:175], v[108:111]
	v_mfma_f32_16x16x32_bf16 v[104:107], v[156:159], v[172:175], v[104:107]
	v_mfma_f32_16x16x32_bf16 v[92:95], v[148:151], v[180:183], v[92:95]
	v_mfma_f32_16x16x32_bf16 v[88:91], v[156:159], v[180:183], v[88:91]
	v_mfma_f32_16x16x32_bf16 v[76:79], v[148:151], v[188:191], v[76:79]
	v_mfma_f32_16x16x32_bf16 v[72:75], v[156:159], v[188:191], v[72:75]
	s_setprio 0
	s_barrier
	s_mov_b32 m0, s45
	ds_read_b128 v[192:195], v126
	ds_read_b128 v[196:199], v126 offset:1024
	ds_read_b128 v[204:207], v126 offset:2048
	ds_read_b128 v[208:211], v126 offset:3072
	global_load_lds_dwordx4 v202, s[98:99]
	s_mov_b32 m0, s46
	s_nop 0
	global_load_lds_dwordx4 v116, s[98:99]
	s_barrier
; #define PG8_STAGE(bufoff, gbase, voff) do { _Pragma("unroll") for (int _i = 0; _i < 2; ++_i) \
;         __builtin_amdgcn_global_load_lds((const unsigned*)((const char*)(gbase) + (voff)[_i]), (LAS unsigned*)(lds + (bufoff) + ldsw + _i * 8192), 16, 0, 0); } while (0)
; #define PG8_LDA(dst, b, h) do { _Pragma("unroll") for (int m = 0; m < 4; ++m) _Pragma("unroll") for (int k = 0; k < 2; ++k) dst[m][k] = *(const LAS bf16x8*)(lds + PG8_SA(b, h) + aoff + m * 2048 + k * 1024); } while (0)
; #define PG8_WAIT_V(n) asm volatile("s_waitcnt vmcnt(" #n ")" ::: "memory")
; #define PG8_WAIT_L(n) asm volatile("s_waitcnt lgkmcnt(" #n ")" ::: "memory")
; #define PG8_BAR __builtin_amdgcn_s_barrier()
; #define PG8_SCHED __builtin_amdgcn_sched_barrier(0)
; template <class Epi>
; __device__ __forceinline__ void gemm_phase(LAS unsigned char* lds, const bf16_t* A, int lda, const bf16_t* Bt, int ldb, int M, int N, int K, int asel, const Epi& E, const int fixed_round = -1) {
;     ...
;             PG8_BAR; PG8_WAIT_L(0); PG8_MMA(0, 1, At, B1); PG8_BAR;
;             PG8_LDA(At, 1, 1); PG8_STAGE(PG8_SA(1, 0), a3, voffA);
;             PG8_BAR; PG8_WAIT_L(0); PG8_MMA(1, 0, At, B0); PG8_BAR; PG8_SCHED;
;             PG8_STAGE(PG8_SB(1, 1), b3 + hstepB, voffB);
;             PG8_WAIT_V(6); PG8_BAR; PG8_MMA(1, 1, At, B1); PG8_BAR;
;     ...
;     PG8_WAIT_V(0);
;     if (wr == 0) PG8_BAR;
;     PG8_BAR;
	s_waitcnt lgkmcnt(0)
	s_setprio 1
	s_waitcnt lgkmcnt(0)
	v_mfma_f32_16x16x32_bf16 v[132:135], v[192:195], v[160:163], v[132:135]
	v_mfma_f32_16x16x32_bf16 v[128:131], v[204:207], v[160:163], v[128:131]
	v_mfma_f32_16x16x32_bf16 v[100:103], v[192:195], v[168:171], v[100:103]
	v_mfma_f32_16x16x32_bf16 v[96:99], v[204:207], v[168:171], v[96:99]
	v_mfma_f32_16x16x32_bf16 v[84:87], v[192:195], v[176:179], v[84:87]
	v_mfma_f32_16x16x32_bf16 v[80:83], v[204:207], v[176:179], v[80:83]
	v_mfma_f32_16x16x32_bf16 v[68:71], v[192:195], v[184:187], v[68:71]
	v_mfma_f32_16x16x32_bf16 v[64:67], v[204:207], v[184:187], v[64:67]
	v_mfma_f32_16x16x32_bf16 v[132:135], v[196:199], v[164:167], v[132:135]
	v_mfma_f32_16x16x32_bf16 v[128:131], v[208:211], v[164:167], v[128:131]
	v_mfma_f32_16x16x32_bf16 v[100:103], v[196:199], v[172:175], v[100:103]
	v_mfma_f32_16x16x32_bf16 v[96:99], v[208:211], v[172:175], v[96:99]
	v_mfma_f32_16x16x32_bf16 v[84:87], v[196:199], v[180:183], v[84:87]
	v_mfma_f32_16x16x32_bf16 v[80:83], v[208:211], v[180:183], v[80:83]
	v_mfma_f32_16x16x32_bf16 v[68:71], v[196:199], v[188:191], v[68:71]
	v_mfma_f32_16x16x32_bf16 v[64:67], v[208:211], v[188:191], v[64:67]
	s_setprio 0
	s_mov_b32 m0, s36
	s_barrier
	ds_read_b128 v[160:163], v123 offset:49152
	ds_read_b128 v[164:167], v123 offset:50176
	ds_read_b128 v[168:171], v123 offset:51200
	ds_read_b128 v[172:175], v123 offset:52224
	ds_read_b128 v[176:179], v123 offset:53248
	ds_read_b128 v[180:183], v123 offset:54272
	ds_read_b128 v[184:187], v123 offset:55296
	ds_read_b128 v[188:191], v123 offset:56320
	global_load_lds_dwordx4 v112, s[100:101]
	s_mov_b32 m0, s37
	s_nop 0
	global_load_lds_dwordx4 v114, s[100:101]
	s_barrier
	s_waitcnt lgkmcnt(0)
	s_setprio 1
	s_waitcnt lgkmcnt(0)
	v_mfma_f32_16x16x32_bf16 v[60:63], v[144:147], v[160:163], v[60:63]
	v_mfma_f32_16x16x32_bf16 v[56:59], v[152:155], v[160:163], v[56:59]
	v_mfma_f32_16x16x32_bf16 v[44:47], v[144:147], v[168:171], v[44:47]
	v_mfma_f32_16x16x32_bf16 v[40:43], v[152:155], v[168:171], v[40:43]
	v_mfma_f32_16x16x32_bf16 v[28:31], v[144:147], v[176:179], v[28:31]
	v_mfma_f32_16x16x32_bf16 v[24:27], v[152:155], v[176:179], v[24:27]
	v_mfma_f32_16x16x32_bf16 v[12:15], v[144:147], v[184:187], v[12:15]
	v_mfma_f32_16x16x32_bf16 v[8:11], v[152:155], v[184:187], v[8:11]
	v_mfma_f32_16x16x32_bf16 v[60:63], v[148:151], v[164:167], v[60:63]
	v_mfma_f32_16x16x32_bf16 v[56:59], v[156:159], v[164:167], v[56:59]
	v_mfma_f32_16x16x32_bf16 v[44:47], v[148:151], v[172:175], v[44:47]
	v_mfma_f32_16x16x32_bf16 v[40:43], v[156:159], v[172:175], v[40:43]
	v_mfma_f32_16x16x32_bf16 v[28:31], v[148:151], v[180:183], v[28:31]
	v_mfma_f32_16x16x32_bf16 v[24:27], v[156:159], v[180:183], v[24:27]
	v_mfma_f32_16x16x32_bf16 v[12:15], v[148:151], v[188:191], v[12:15]
	v_mfma_f32_16x16x32_bf16 v[8:11], v[156:159], v[188:191], v[8:11]
	s_setprio 0
	s_barrier
	s_add_u32 s8, s8, 0x200080
	s_addc_u32 s9, s9, 0
	s_mov_b32 m0, s47
	s_nop 0
	global_load_lds_dwordx4 v202, s[8:9]
	s_mov_b32 m0, s48
	s_nop 0
	global_load_lds_dwordx4 v116, s[8:9]
	s_waitcnt vmcnt(6)
	s_barrier
	s_setprio 1
	v_mfma_f32_16x16x32_bf16 v[52:55], v[192:195], v[160:163], v[52:55]
	v_mfma_f32_16x16x32_bf16 v[48:51], v[204:207], v[160:163], v[48:51]
	v_mfma_f32_16x16x32_bf16 v[36:39], v[192:195], v[168:171], v[36:39]
	v_mfma_f32_16x16x32_bf16 v[32:35], v[204:207], v[168:171], v[32:35]
	v_mfma_f32_16x16x32_bf16 v[20:23], v[192:195], v[176:179], v[20:23]
	v_mfma_f32_16x16x32_bf16 v[16:19], v[204:207], v[176:179], v[16:19]
	v_mfma_f32_16x16x32_bf16 v[4:7], v[192:195], v[184:187], v[4:7]
	v_mfma_f32_16x16x32_bf16 v[0:3], v[204:207], v[184:187], v[0:3]
	v_mfma_f32_16x16x32_bf16 v[52:55], v[196:199], v[164:167], v[52:55]
	v_mfma_f32_16x16x32_bf16 v[48:51], v[208:211], v[164:167], v[48:51]
	v_mfma_f32_16x16x32_bf16 v[36:39], v[196:199], v[172:175], v[36:39]
	v_mfma_f32_16x16x32_bf16 v[32:35], v[208:211], v[172:175], v[32:35]
	v_mfma_f32_16x16x32_bf16 v[20:23], v[196:199], v[180:183], v[20:23]
	v_mfma_f32_16x16x32_bf16 v[16:19], v[208:211], v[180:183], v[16:19]
	v_mfma_f32_16x16x32_bf16 v[4:7], v[196:199], v[188:191], v[4:7]
	v_mfma_f32_16x16x32_bf16 v[0:3], v[208:211], v[188:191], v[0:3]
	s_setprio 0
	s_add_i32 s34, s34, 2
	s_add_u32 s6, s6, 0x100
	s_addc_u32 s7, s7, 0
	s_cmpk_lt_u32 s34, 0x7e
	s_cbranch_scc1 .Lrot_12
	s_barrier
	s_waitcnt vmcnt(0)
	s_cmpk_gt_u32 s18, 0xff
	s_cbranch_scc1 .LBB0_1325
	s_barrier
